# XCD-local fast path for 7 grid barriers (runtime-verified placement) + K-tiled ACT layout + 8B-aligned MFMA blocks
# speedup vs baseline: 1.0214x; 1.0214x over previous
_Z8mega_fwd4Args:
	s_load_dwordx8 s[68:75], s[0:1], 0xe0
	s_load_dwordx8 s[4:11], s[0:1], 0xc0
	s_load_dword s3, s[0:1], 0x100
	v_and_b32_e32 v188, 0x3ff, v0
	v_cmp_gt_u32_e32 vcc, 16, v188
	s_waitcnt lgkmcnt(0)
	v_writelane_b32 v242, s4, 0
	s_nop 1
	v_writelane_b32 v242, s5, 1
	v_writelane_b32 v242, s6, 2
	v_writelane_b32 v242, s7, 3
	v_writelane_b32 v242, s8, 4
	v_writelane_b32 v242, s9, 5
	v_writelane_b32 v242, s10, 6
	v_writelane_b32 v242, s11, 7
	s_add_u32 s4, s0, 0xf8
	v_writelane_b32 v242, s3, 8
	s_addc_u32 s5, s1, 0
	v_writelane_b32 v242, s4, 9
	s_nop 1
	v_writelane_b32 v242, s5, 10
	s_and_saveexec_b64 s[4:5], vcc
	v_lshl_add_u32 v1, v188, 2, 0
	v_add_u32_e32 v1, 0x20140, v1
	v_mov_b32_e32 v2, 0
	ds_write_b32 v1, v2
	s_or_b64 exec, exec, s[4:5]
	s_waitcnt lgkmcnt(0)
	s_barrier
	s_add_u32 s58, s72, 0x5c0000
	s_getreg_b32 s3, hwreg(HW_REG_XCC_ID, 0, 4)
	s_addc_u32 s59, s73, 0
	s_and_b32 s57, s3, 15
	v_cmp_eq_u32_e64 s[6:7], 0, v188
	s_mov_b64 s[4:5], exec
	s_nop 0
	v_writelane_b32 v242, s6, 11
	s_nop 1
	v_writelane_b32 v242, s7, 12
	s_and_b64 s[6:7], s[4:5], s[6:7]
	s_mov_b64 exec, s[6:7]
	s_cbranch_execz .LBB0_5
	s_mov_b64 s[6:7], exec
	v_mbcnt_lo_u32_b32 v1, s6, 0
	v_mbcnt_hi_u32_b32 v1, s7, v1
	v_cmp_eq_u32_e32 vcc, 0, v1
	s_and_b64 s[8:9], exec, vcc
	s_mov_b64 exec, s[8:9]
	s_cbranch_execz .LBB0_5
	s_lshl_b32 s3, s57, 8
	s_bcnt1_i32_b64 s6, s[6:7]
	v_mov_b32_e32 v1, s3
	v_mov_b32_e32 v2, s6
	global_atomic_add v1, v2, s[58:59] offset:1024
	s_and_b32 s3, s2, 7
	s_lshl_b32 s3, s3, 2
	s_add_u32 s3, s3, 0x3600
	s_lshl_b32 s6, 1, s57
	v_mov_b32_e32 v1, s3
	v_mov_b32_e32 v2, s6
	global_atomic_or v1, v2, s[58:59]

.LBB0_160:
	s_or_b64 exec, exec, s[0:1]
	v_mov_b32_e32 v16, 0x3600
	global_load_dwordx4 v[4:7], v16, s[94:95] sc1
	global_load_dwordx4 v[8:11], v16, s[94:95] offset:16 sc1
	s_mov_b32 s98, 1
	s_waitcnt vmcnt(0)
	v_readfirstlane_b32 s99, v4
	s_nop 3
	s_bcnt1_i32_b32 s99, s99
	s_cmp_eq_u32 s99, 1
	s_cselect_b32 s98, s98, 0
	v_readfirstlane_b32 s99, v5
	s_nop 3
	s_bcnt1_i32_b32 s99, s99
	s_cmp_eq_u32 s99, 1
	s_cselect_b32 s98, s98, 0
	v_readfirstlane_b32 s99, v6
	s_nop 3
	s_bcnt1_i32_b32 s99, s99
	s_cmp_eq_u32 s99, 1
	s_cselect_b32 s98, s98, 0
	v_readfirstlane_b32 s99, v7
	s_nop 3
	s_bcnt1_i32_b32 s99, s99
	s_cmp_eq_u32 s99, 1
	s_cselect_b32 s98, s98, 0
	v_readfirstlane_b32 s99, v8
	s_nop 3
	s_bcnt1_i32_b32 s99, s99
	s_cmp_eq_u32 s99, 1
	s_cselect_b32 s98, s98, 0
	v_readfirstlane_b32 s99, v9
	s_nop 3
	s_bcnt1_i32_b32 s99, s99
	s_cmp_eq_u32 s99, 1
	s_cselect_b32 s98, s98, 0
	v_readfirstlane_b32 s99, v10
	s_nop 3
	s_bcnt1_i32_b32 s99, s99
	s_cmp_eq_u32 s99, 1
	s_cselect_b32 s98, s98, 0
	v_readfirstlane_b32 s99, v11
	s_nop 3
	s_bcnt1_i32_b32 s99, s99
	s_cmp_eq_u32 s99, 1
	s_cselect_b32 s98, s98, 0
	v_mov_b32_e32 v66, v188
	s_movk_i32 s0, 0x800
	s_waitcnt lgkmcnt(0)
	s_barrier
	s_ashr_i32 s84, s2, 5
	v_readfirstlane_b32 s10, v66
	v_cmp_gt_i32_e32 vcc, s0, v66
	s_and_saveexec_b64 s[0:1], vcc
	s_cbranch_execz .LBB0_163
	s_mul_i32 s4, s84, 0x9000
	s_mul_hi_i32 s5, s84, 0x9000
	v_ashrrev_i32_e32 v67, 31, v66
	s_add_u32 s4, s72, s4
	v_add_u32_e32 v2, 0xfffffe00, v66
	v_lshlrev_b64 v[0:1], 2, v[66:67]
	s_addc_u32 s5, s73, s5
	s_mov_b64 s[6:7], 0
	s_movk_i32 s11, 0x5ff
	s_mov_b64 s[8:9], s[22:23]

.LBB0_239:
	s_lshl_b32 s6, s6, 5
	s_and_b32 s10, s6, 0x60
	s_mov_b64 s[6:7], 0x80
	s_add_i32 m0, s35, 0x18000
	v_lshl_add_u64 v[6:7], v[6:7], 0, s[6:7]
	s_lshl_b32 s9, s8, 13
	s_lshl_b32 s18, s10, 7
	s_waitcnt vmcnt(2)
	s_barrier
	global_load_lds_dwordx4 v[6:7], off
	v_lshl_add_u64 v[4:5], v[4:5], 0, s[6:7]
	s_add_i32 m0, s35, 0x1a000
	s_add_i32 s53, s35, 0x8000
	s_add_i32 s54, s35, 0xa000
	global_load_lds_dwordx4 v[4:5], off
	v_lshl_add_u64 v[0:1], v[0:1], 0, s[6:7]
	s_mov_b32 m0, s53
	s_add_u32 s14, s42, 0x40080
	global_load_lds_dwordx4 v[0:1], off
	v_lshl_add_u64 v[0:1], v[2:3], 0, s[6:7]
	s_mov_b32 m0, s54
	s_addc_u32 s15, s43, 0
	global_load_lds_dwordx4 v[0:1], off
	s_add_i32 m0, s35, 0x1c000
	v_lshl_add_u64 v[0:1], s[14:15], 0, v[132:133]
	global_load_lds_dwordx4 v[0:1], off
	v_lshl_add_u64 v[0:1], s[14:15], 0, v[128:129]
	s_add_i32 m0, s35, 0x1e000
	s_cmpk_lt_u32 s1, 0x100
	global_load_lds_dwordx4 v[0:1], off
	v_lshrrev_b32_e32 v1, 1, v9
	v_and_b32_e32 v1, 24, v1
	v_and_b32_e32 v0, 15, v9
	v_lshlrev_b32_e32 v2, 1, v1
	v_lshl_or_b32 v144, s8, 6, v0
	v_lshl_or_b32 v0, v0, 6, v2
	v_lshlrev_b32_e32 v2, 2, v9
	v_and_b32_e32 v2, 32, v2
	v_bitop3_b32 v3, v0, s9, v2 bitop3:0xde
	v_bitop3_b32 v145, v0, s18, v2 bitop3:0xde
	v_lshlrev_b32_e32 v0, 14, v13
	v_and_b32_e32 v0, 0xffff8000, v0
	v_or_b32_e32 v146, s10, v1
	v_and_b32_e32 v227, 64, v146
	v_and_b32_e32 v146, 63, v146
	v_lshlrev_b32_e32 v146, 1, v146
	v_lshl_or_b32 v146, v227, 9, v146
	v_lshl_add_u32 v0, v12, 11, v0
	v_and_b32_e32 v1, 1, v13
	v_lshl_or_b32 v0, v1, 6, v0
	v_lshl_add_u32 v136, v14, 1, v0
	v_lshlrev_b32_e32 v0, 14, v8
	v_and_b32_e32 v0, 0xffff8000, v0
	s_waitcnt vmcnt(6)
	v_lshl_add_u32 v0, v10, 11, v0
	v_and_b32_e32 v1, 1, v8
	s_cselect_b64 s[8:9], -1, 0
	v_lshl_or_b32 v0, v1, 6, v0
	s_add_i32 s61, 0, 0x10000
	s_add_i32 s62, 0, 0x14000
	s_sext_i32_i16 s64, s0
	s_ashr_i32 s55, s74, 31
	s_mov_b32 s60, s74
	v_mov_b32_e32 v137, v133
	v_lshl_add_u32 v138, v11, 1, v0
	v_mov_b32_e32 v139, v133
	v_mov_b64_e32 v[140:141], 0xb00
	v_mov_b64_e32 v[142:143], 0xaff
	v_add_u32_e32 v147, s61, v145
	v_add_u32_e32 v148, s62, v145
	v_add_u32_e32 v149, 0, v3
	s_mov_b32 s10, 0xbfb8aa3b
	s_movk_i32 s63, 0x80
	s_barrier
	s_branch .LBB0_242

.LBB0_245:
	ds_read_b128 v[150:153], v147
	ds_read_b128 v[154:157], v147 offset:1024
	ds_read_b128 v[158:161], v147 offset:2048
	ds_read_b128 v[162:165], v147 offset:3072
	ds_read_b128 v[166:169], v148
	ds_read_b128 v[170:173], v148 offset:1024
	ds_read_b128 v[174:177], v148 offset:2048
	ds_read_b128 v[178:181], v148 offset:3072
	s_add_u32 s28, s40, 0xfffc0080
	s_addc_u32 s29, s41, -1
	s_cmp_eq_u32 s77, 12
	s_cselect_b32 s47, s19, s29
	s_cselect_b32 s46, s65, s28
	s_cselect_b32 s43, s15, s76
	s_cselect_b32 s42, s66, s67
	v_lshl_add_u64 v[186:187], s[40:41], 0, v[136:137]
	s_add_i32 m0, s35, 0xc000
	ds_read_b128 v[182:185], v149
	ds_read_b128 v[190:193], v149 offset:1024
	ds_read_b128 v[194:197], v149 offset:2048
	ds_read_b128 v[198:201], v149 offset:3072
	ds_read_b128 v[202:205], v149 offset:4096
	ds_read_b128 v[206:209], v149 offset:5120
	ds_read_b128 v[210:213], v149 offset:6144
	ds_read_b128 v[214:217], v149 offset:7168
	global_load_lds_dwordx4 v[186:187], off
	v_lshl_add_u64 v[186:187], s[40:41], 0, v[138:139]
	s_add_i32 m0, s35, 0xe000
	s_nop 0
	global_load_lds_dwordx4 v[186:187], off
	s_waitcnt vmcnt(8)
	s_waitcnt lgkmcnt(0)
	s_nop 0
	s_barrier
	s_setprio 1
	s_waitcnt lgkmcnt(0)
	v_mfma_f32_16x16x32_bf16 v[124:127], v[150:153], v[182:185], v[124:127]
	v_mfma_f32_16x16x32_bf16 v[116:119], v[158:161], v[182:185], v[116:119]
	v_mfma_f32_16x16x32_bf16 v[108:111], v[150:153], v[194:197], v[108:111]
	v_mfma_f32_16x16x32_bf16 v[100:103], v[158:161], v[194:197], v[100:103]
	v_mfma_f32_16x16x32_bf16 v[92:95], v[150:153], v[202:205], v[92:95]
	v_mfma_f32_16x16x32_bf16 v[84:87], v[158:161], v[202:205], v[84:87]
	v_mfma_f32_16x16x32_bf16 v[76:79], v[150:153], v[210:213], v[76:79]
	v_mfma_f32_16x16x32_bf16 v[68:71], v[158:161], v[210:213], v[68:71]
	v_mfma_f32_16x16x32_bf16 v[124:127], v[154:157], v[190:193], v[124:127]
	v_mfma_f32_16x16x32_bf16 v[116:119], v[162:165], v[190:193], v[116:119]
	v_mfma_f32_16x16x32_bf16 v[108:111], v[154:157], v[198:201], v[108:111]
	v_mfma_f32_16x16x32_bf16 v[100:103], v[162:165], v[198:201], v[100:103]
	v_mfma_f32_16x16x32_bf16 v[92:95], v[154:157], v[206:209], v[92:95]
	v_mfma_f32_16x16x32_bf16 v[84:87], v[162:165], v[206:209], v[84:87]
	v_mfma_f32_16x16x32_bf16 v[76:79], v[154:157], v[214:217], v[76:79]
	v_mfma_f32_16x16x32_bf16 v[68:71], v[162:165], v[214:217], v[68:71]
	s_setprio 0
	s_setprio 1
	v_mfma_f32_16x16x32_bf16 v[120:123], v[166:169], v[182:185], v[120:123]
	v_mfma_f32_16x16x32_bf16 v[112:115], v[174:177], v[182:185], v[112:115]
	v_mfma_f32_16x16x32_bf16 v[104:107], v[166:169], v[194:197], v[104:107]
	v_mfma_f32_16x16x32_bf16 v[96:99], v[174:177], v[194:197], v[96:99]
	v_mfma_f32_16x16x32_bf16 v[88:91], v[166:169], v[202:205], v[88:91]
	v_mfma_f32_16x16x32_bf16 v[80:83], v[174:177], v[202:205], v[80:83]
	v_mfma_f32_16x16x32_bf16 v[72:75], v[166:169], v[210:213], v[72:75]
	v_mfma_f32_16x16x32_bf16 v[64:67], v[174:177], v[210:213], v[64:67]
	v_mfma_f32_16x16x32_bf16 v[120:123], v[170:173], v[190:193], v[120:123]
	v_mfma_f32_16x16x32_bf16 v[112:115], v[178:181], v[190:193], v[112:115]
	v_mfma_f32_16x16x32_bf16 v[104:107], v[170:173], v[198:201], v[104:107]
	v_mfma_f32_16x16x32_bf16 v[96:99], v[178:181], v[198:201], v[96:99]
	v_mfma_f32_16x16x32_bf16 v[88:91], v[170:173], v[206:209], v[88:91]
	v_mfma_f32_16x16x32_bf16 v[80:83], v[178:181], v[206:209], v[80:83]
	v_mfma_f32_16x16x32_bf16 v[72:75], v[170:173], v[214:217], v[72:75]
	v_mfma_f32_16x16x32_bf16 v[64:67], v[178:181], v[214:217], v[64:67]
	s_setprio 0
	s_barrier
	s_add_i32 s28, s61, s12
	v_lshl_add_u64 v[186:187], s[42:43], 0, v[132:133]
	s_mov_b32 m0, s28
	ds_read_b128 v[182:185], v149 offset:16384
	ds_read_b128 v[190:193], v149 offset:17408
	ds_read_b128 v[194:197], v149 offset:18432
	ds_read_b128 v[198:201], v149 offset:19456
	ds_read_b128 v[202:205], v149 offset:20480
	ds_read_b128 v[206:209], v149 offset:21504
	ds_read_b128 v[210:213], v149 offset:22528
	ds_read_b128 v[214:217], v149 offset:23552
	global_load_lds_dwordx4 v[186:187], off
	s_add_i32 m0, s28, 0x2000
	s_add_u32 s28, s42, 0x40000
	v_lshl_add_u64 v[218:219], s[42:43], 0, v[128:129]
	s_addc_u32 s29, s43, 0
	s_add_i32 s33, s62, s12
	global_load_lds_dwordx4 v[218:219], off
	v_lshl_add_u64 v[220:221], s[28:29], 0, v[132:133]
	s_mov_b32 m0, s33
	v_lshl_add_u64 v[222:223], s[46:47], 0, v[130:131]
	global_load_lds_dwordx4 v[220:221], off
	v_lshl_add_u64 v[220:221], s[28:29], 0, v[128:129]
	s_add_i32 m0, s33, 0x2000
	s_nop 0
	global_load_lds_dwordx4 v[220:221], off
	v_lshl_add_u64 v[220:221], s[46:47], 0, v[134:135]
	s_mov_b32 m0, s35
	s_nop 0
	global_load_lds_dwordx4 v[220:221], off
	s_mov_b32 m0, s39
	s_nop 0
	global_load_lds_dwordx4 v[222:223], off
	s_waitcnt vmcnt(8)
	s_waitcnt lgkmcnt(0)
	s_nop 0
	s_barrier
	s_setprio 1
	s_waitcnt lgkmcnt(0)
	v_mfma_f32_16x16x32_bf16 v[60:63], v[150:153], v[182:185], v[60:63]
	v_mfma_f32_16x16x32_bf16 v[52:55], v[158:161], v[182:185], v[52:55]
	v_mfma_f32_16x16x32_bf16 v[44:47], v[150:153], v[194:197], v[44:47]
	v_mfma_f32_16x16x32_bf16 v[36:39], v[158:161], v[194:197], v[36:39]
	v_mfma_f32_16x16x32_bf16 v[28:31], v[150:153], v[202:205], v[28:31]
	v_mfma_f32_16x16x32_bf16 v[20:23], v[158:161], v[202:205], v[20:23]
	v_mfma_f32_16x16x32_bf16 v[12:15], v[150:153], v[210:213], v[12:15]
	v_mfma_f32_16x16x32_bf16 v[4:7], v[158:161], v[210:213], v[4:7]
	v_mfma_f32_16x16x32_bf16 v[60:63], v[154:157], v[190:193], v[60:63]
	v_mfma_f32_16x16x32_bf16 v[52:55], v[162:165], v[190:193], v[52:55]
	v_mfma_f32_16x16x32_bf16 v[44:47], v[154:157], v[198:201], v[44:47]
	v_mfma_f32_16x16x32_bf16 v[36:39], v[162:165], v[198:201], v[36:39]
	v_mfma_f32_16x16x32_bf16 v[28:31], v[154:157], v[206:209], v[28:31]
	v_mfma_f32_16x16x32_bf16 v[20:23], v[162:165], v[206:209], v[20:23]
	v_mfma_f32_16x16x32_bf16 v[12:15], v[154:157], v[214:217], v[12:15]
	v_mfma_f32_16x16x32_bf16 v[4:7], v[162:165], v[214:217], v[4:7]
	s_setprio 0
	s_setprio 1
	v_mfma_f32_16x16x32_bf16 v[56:59], v[166:169], v[182:185], v[56:59]
	v_mfma_f32_16x16x32_bf16 v[48:51], v[174:177], v[182:185], v[48:51]
	v_mfma_f32_16x16x32_bf16 v[40:43], v[166:169], v[194:197], v[40:43]
	v_mfma_f32_16x16x32_bf16 v[32:35], v[174:177], v[194:197], v[32:35]
	v_mfma_f32_16x16x32_bf16 v[24:27], v[166:169], v[202:205], v[24:27]
	v_mfma_f32_16x16x32_bf16 v[16:19], v[174:177], v[202:205], v[16:19]
	v_mfma_f32_16x16x32_bf16 v[8:11], v[166:169], v[210:213], v[8:11]
	v_mfma_f32_16x16x32_bf16 v[0:3], v[174:177], v[210:213], v[0:3]
	v_mfma_f32_16x16x32_bf16 v[56:59], v[170:173], v[190:193], v[56:59]
	v_mfma_f32_16x16x32_bf16 v[48:51], v[178:181], v[190:193], v[48:51]
	v_mfma_f32_16x16x32_bf16 v[40:43], v[170:173], v[198:201], v[40:43]
	v_mfma_f32_16x16x32_bf16 v[32:35], v[178:181], v[198:201], v[32:35]
	v_mfma_f32_16x16x32_bf16 v[24:27], v[170:173], v[206:209], v[24:27]
	v_mfma_f32_16x16x32_bf16 v[16:19], v[178:181], v[206:209], v[16:19]
	v_mfma_f32_16x16x32_bf16 v[8:11], v[170:173], v[214:217], v[8:11]
	v_mfma_f32_16x16x32_bf16 v[0:3], v[178:181], v[214:217], v[0:3]
	s_setprio 0
	s_barrier
	s_add_i32 s33, 0, 0x18000
	s_add_i32 s56, 0, 0x1c000
	v_add_u32_e32 v162, s33, v145
	v_add_u32_e32 v178, s56, v145
	ds_read_b128 v[150:153], v162
	ds_read_b128 v[154:157], v162 offset:1024
	ds_read_b128 v[158:161], v162 offset:2048
	ds_read_b128 v[162:165], v162 offset:3072
	ds_read_b128 v[166:169], v178
	ds_read_b128 v[170:173], v178 offset:1024
	ds_read_b128 v[174:177], v178 offset:2048
	ds_read_b128 v[178:181], v178 offset:3072
	s_add_u32 s28, s46, 0x40000
	s_addc_u32 s29, s47, 0
	s_mov_b32 m0, s50
	v_lshl_add_u64 v[224:225], s[28:29], 0, v[134:135]
	ds_read_b128 v[182:185], v149 offset:32768
	ds_read_b128 v[190:193], v149 offset:33792
	ds_read_b128 v[194:197], v149 offset:34816
	ds_read_b128 v[198:201], v149 offset:35840
	ds_read_b128 v[202:205], v149 offset:36864
	ds_read_b128 v[206:209], v149 offset:37888
	ds_read_b128 v[210:213], v149 offset:38912
	ds_read_b128 v[214:217], v149 offset:39936
	global_load_lds_dwordx4 v[224:225], off
	v_lshl_add_u64 v[224:225], s[28:29], 0, v[130:131]
	s_mov_b32 m0, s51
	s_nop 0
	global_load_lds_dwordx4 v[224:225], off
	s_waitcnt vmcnt(8)
	s_waitcnt lgkmcnt(0)
	s_nop 0
	s_barrier
	s_setprio 1
	s_waitcnt lgkmcnt(0)
	v_mfma_f32_16x16x32_bf16 v[124:127], v[150:153], v[182:185], v[124:127]
	v_mfma_f32_16x16x32_bf16 v[116:119], v[158:161], v[182:185], v[116:119]
	v_mfma_f32_16x16x32_bf16 v[108:111], v[150:153], v[194:197], v[108:111]
	v_mfma_f32_16x16x32_bf16 v[100:103], v[158:161], v[194:197], v[100:103]
	v_mfma_f32_16x16x32_bf16 v[92:95], v[150:153], v[202:205], v[92:95]
	v_mfma_f32_16x16x32_bf16 v[84:87], v[158:161], v[202:205], v[84:87]
	v_mfma_f32_16x16x32_bf16 v[76:79], v[150:153], v[210:213], v[76:79]
	v_mfma_f32_16x16x32_bf16 v[68:71], v[158:161], v[210:213], v[68:71]
	v_mfma_f32_16x16x32_bf16 v[124:127], v[154:157], v[190:193], v[124:127]
	v_mfma_f32_16x16x32_bf16 v[116:119], v[162:165], v[190:193], v[116:119]
	v_mfma_f32_16x16x32_bf16 v[108:111], v[154:157], v[198:201], v[108:111]
	v_mfma_f32_16x16x32_bf16 v[100:103], v[162:165], v[198:201], v[100:103]
	v_mfma_f32_16x16x32_bf16 v[92:95], v[154:157], v[206:209], v[92:95]
	v_mfma_f32_16x16x32_bf16 v[84:87], v[162:165], v[206:209], v[84:87]
	v_mfma_f32_16x16x32_bf16 v[76:79], v[154:157], v[214:217], v[76:79]
	v_mfma_f32_16x16x32_bf16 v[68:71], v[162:165], v[214:217], v[68:71]
	s_setprio 0
	s_setprio 1
	v_mfma_f32_16x16x32_bf16 v[120:123], v[166:169], v[182:185], v[120:123]
	v_mfma_f32_16x16x32_bf16 v[112:115], v[174:177], v[182:185], v[112:115]
	v_mfma_f32_16x16x32_bf16 v[104:107], v[166:169], v[194:197], v[104:107]
	v_mfma_f32_16x16x32_bf16 v[96:99], v[174:177], v[194:197], v[96:99]
	v_mfma_f32_16x16x32_bf16 v[88:91], v[166:169], v[202:205], v[88:91]
	v_mfma_f32_16x16x32_bf16 v[80:83], v[174:177], v[202:205], v[80:83]
	v_mfma_f32_16x16x32_bf16 v[72:75], v[166:169], v[210:213], v[72:75]
	v_mfma_f32_16x16x32_bf16 v[64:67], v[174:177], v[210:213], v[64:67]
	v_mfma_f32_16x16x32_bf16 v[120:123], v[170:173], v[190:193], v[120:123]
	v_mfma_f32_16x16x32_bf16 v[112:115], v[178:181], v[190:193], v[112:115]
	v_mfma_f32_16x16x32_bf16 v[104:107], v[170:173], v[198:201], v[104:107]
	v_mfma_f32_16x16x32_bf16 v[96:99], v[178:181], v[198:201], v[96:99]
	v_mfma_f32_16x16x32_bf16 v[88:91], v[170:173], v[206:209], v[88:91]
	v_mfma_f32_16x16x32_bf16 v[80:83], v[178:181], v[206:209], v[80:83]
	v_mfma_f32_16x16x32_bf16 v[72:75], v[170:173], v[214:217], v[72:75]
	v_mfma_f32_16x16x32_bf16 v[64:67], v[178:181], v[214:217], v[64:67]
	s_setprio 0
	s_barrier
	s_add_i32 s28, s33, s12
	v_lshl_add_u64 v[186:187], v[186:187], 0, s[6:7]
	s_mov_b32 m0, s28
	ds_read_b128 v[182:185], v149 offset:49152
	ds_read_b128 v[190:193], v149 offset:50176
	ds_read_b128 v[194:197], v149 offset:51200
	ds_read_b128 v[198:201], v149 offset:52224
	ds_read_b128 v[202:205], v149 offset:53248
	ds_read_b128 v[206:209], v149 offset:54272
	ds_read_b128 v[210:213], v149 offset:55296
	ds_read_b128 v[214:217], v149 offset:56320
	global_load_lds_dwordx4 v[186:187], off
	s_add_i32 m0, s28, 0x2000
	s_add_u32 s28, s42, 0x40080
	v_lshl_add_u64 v[186:187], v[218:219], 0, s[6:7]
	s_addc_u32 s29, s43, 0
	s_add_i32 s33, s56, s12
	global_load_lds_dwordx4 v[186:187], off
	v_lshl_add_u64 v[186:187], s[28:29], 0, v[132:133]
	s_mov_b32 m0, s33
	s_nop 0
	global_load_lds_dwordx4 v[186:187], off
	v_lshl_add_u64 v[186:187], s[28:29], 0, v[128:129]
	s_add_i32 m0, s33, 0x2000
	s_nop 0
	global_load_lds_dwordx4 v[186:187], off
	v_lshl_add_u64 v[186:187], v[220:221], 0, s[6:7]
	s_mov_b32 m0, s53
	s_nop 0
	global_load_lds_dwordx4 v[186:187], off
	v_lshl_add_u64 v[186:187], v[222:223], 0, s[6:7]
	s_mov_b32 m0, s54
	s_nop 0
	global_load_lds_dwordx4 v[186:187], off
	s_waitcnt vmcnt(8)
	s_waitcnt lgkmcnt(0)
	s_barrier
	s_setprio 1
	s_waitcnt lgkmcnt(0)
	v_mfma_f32_16x16x32_bf16 v[60:63], v[150:153], v[182:185], v[60:63]
	v_mfma_f32_16x16x32_bf16 v[52:55], v[158:161], v[182:185], v[52:55]
	v_mfma_f32_16x16x32_bf16 v[44:47], v[150:153], v[194:197], v[44:47]
	v_mfma_f32_16x16x32_bf16 v[36:39], v[158:161], v[194:197], v[36:39]
	v_mfma_f32_16x16x32_bf16 v[28:31], v[150:153], v[202:205], v[28:31]
	v_mfma_f32_16x16x32_bf16 v[20:23], v[158:161], v[202:205], v[20:23]
	v_mfma_f32_16x16x32_bf16 v[12:15], v[150:153], v[210:213], v[12:15]
	v_mfma_f32_16x16x32_bf16 v[4:7], v[158:161], v[210:213], v[4:7]
	v_mfma_f32_16x16x32_bf16 v[60:63], v[154:157], v[190:193], v[60:63]
	v_mfma_f32_16x16x32_bf16 v[52:55], v[162:165], v[190:193], v[52:55]
	v_mfma_f32_16x16x32_bf16 v[44:47], v[154:157], v[198:201], v[44:47]
	v_mfma_f32_16x16x32_bf16 v[36:39], v[162:165], v[198:201], v[36:39]
	v_mfma_f32_16x16x32_bf16 v[28:31], v[154:157], v[206:209], v[28:31]
	v_mfma_f32_16x16x32_bf16 v[20:23], v[162:165], v[206:209], v[20:23]
	v_mfma_f32_16x16x32_bf16 v[12:15], v[154:157], v[214:217], v[12:15]
	v_mfma_f32_16x16x32_bf16 v[4:7], v[162:165], v[214:217], v[4:7]
	s_setprio 0
	s_setprio 1
	v_mfma_f32_16x16x32_bf16 v[56:59], v[166:169], v[182:185], v[56:59]
	v_mfma_f32_16x16x32_bf16 v[48:51], v[174:177], v[182:185], v[48:51]
	v_mfma_f32_16x16x32_bf16 v[40:43], v[166:169], v[194:197], v[40:43]
	v_mfma_f32_16x16x32_bf16 v[32:35], v[174:177], v[194:197], v[32:35]
	v_mfma_f32_16x16x32_bf16 v[24:27], v[166:169], v[202:205], v[24:27]
	v_mfma_f32_16x16x32_bf16 v[16:19], v[174:177], v[202:205], v[16:19]
	v_mfma_f32_16x16x32_bf16 v[8:11], v[166:169], v[210:213], v[8:11]
	v_mfma_f32_16x16x32_bf16 v[0:3], v[174:177], v[210:213], v[0:3]
	v_mfma_f32_16x16x32_bf16 v[56:59], v[170:173], v[190:193], v[56:59]
	v_mfma_f32_16x16x32_bf16 v[48:51], v[178:181], v[190:193], v[48:51]
	v_mfma_f32_16x16x32_bf16 v[40:43], v[170:173], v[198:201], v[40:43]
	v_mfma_f32_16x16x32_bf16 v[32:35], v[178:181], v[198:201], v[32:35]
	v_mfma_f32_16x16x32_bf16 v[24:27], v[170:173], v[206:209], v[24:27]
	v_mfma_f32_16x16x32_bf16 v[16:19], v[178:181], v[206:209], v[16:19]
	v_mfma_f32_16x16x32_bf16 v[8:11], v[170:173], v[214:217], v[8:11]
	v_mfma_f32_16x16x32_bf16 v[0:3], v[178:181], v[214:217], v[0:3]
	s_setprio 0
	s_barrier
	s_add_i32 s77, s77, 2
	s_add_u32 s40, s40, 0x100
	s_addc_u32 s41, s41, 0
	s_add_u32 s67, s67, 0x100
	s_addc_u32 s76, s76, 0
	s_cmp_gt_u32 s77, 13
	s_cbranch_scc0 .LBB0_245
	s_and_b64 vcc, exec, s[8:9]
	s_cbranch_vccz .LBB0_248
	s_barrier
.LBB0_248:
	v_pk_mul_f32 v[122:123], v[126:127], v[122:123]
	v_pk_mul_f32 v[126:127], v[126:127], s[10:11] op_sel_hi:[1,0]
	v_pk_mul_f32 v[120:121], v[124:125], v[120:121]
	v_exp_f32_e32 v126, v126
	v_exp_f32_e32 v127, v127
	v_pk_mul_f32 v[124:125], v[124:125], s[10:11] op_sel_hi:[1,0]
	v_pk_mul_f32 v[154:155], v[118:119], s[10:11] op_sel_hi:[1,0]
	v_exp_f32_e32 v124, v124
	v_pk_add_f32 v[126:127], v[126:127], 1.0 op_sel_hi:[1,0]
	v_exp_f32_e32 v125, v125
	v_rcp_f32_e32 v126, v126
	v_rcp_f32_e32 v127, v127
	v_exp_f32_e32 v154, v154
	v_pk_add_f32 v[124:125], v[124:125], 1.0 op_sel_hi:[1,0]
	v_exp_f32_e32 v155, v155
	v_pk_mul_f32 v[122:123], v[126:127], v[122:123]
	v_pk_mul_f32 v[126:127], v[116:117], s[10:11] op_sel_hi:[1,0]
	v_rcp_f32_e32 v124, v124
	v_rcp_f32_e32 v125, v125
	v_exp_f32_e32 v126, v126
	v_exp_f32_e32 v127, v127
	v_pk_mul_f32 v[106:107], v[110:111], v[106:107]
	v_pk_mul_f32 v[110:111], v[110:111], s[10:11] op_sel_hi:[1,0]
	v_pk_mul_f32 v[120:121], v[124:125], v[120:121]
	v_pk_add_f32 v[124:125], v[126:127], 1.0 op_sel_hi:[1,0]
	v_exp_f32_e32 v110, v110
	v_exp_f32_e32 v111, v111
	v_rcp_f32_e32 v124, v124
	v_pk_add_f32 v[126:127], v[154:155], 1.0 op_sel_hi:[1,0]
	v_rcp_f32_e32 v125, v125
	v_rcp_f32_e32 v126, v126
	v_rcp_f32_e32 v127, v127
	v_pk_mul_f32 v[112:113], v[116:117], v[112:113]
	v_pk_mul_f32 v[104:105], v[108:109], v[104:105]
	v_pk_mul_f32 v[108:109], v[108:109], s[10:11] op_sel_hi:[1,0]
	v_pk_add_f32 v[110:111], v[110:111], 1.0 op_sel_hi:[1,0]
	v_lshl_or_b32 v152, s64, 16, v146
	v_pk_mul_f32 v[114:115], v[118:119], v[114:115]
	v_pk_mul_f32 v[112:113], v[124:125], v[112:113]
	v_exp_f32_e32 v108, v108
	v_exp_f32_e32 v109, v109
	v_rcp_f32_e32 v110, v110
	v_rcp_f32_e32 v111, v111
	s_mul_i32 s32, s38, 0x2c00
	v_add_u32_e32 v150, s32, v144
	v_ashrrev_i32_e32 v153, 31, v152
	v_pk_mul_f32 v[114:115], v[126:127], v[114:115]
	v_cvt_pk_bf16_f32 v116, v120, v121
	v_cvt_pk_bf16_f32 v117, v122, v123
	v_cvt_pk_bf16_f32 v118, v112, v113
	v_mov_b64_e32 v[112:113], s[20:21]
	v_cvt_pk_bf16_f32 v119, v114, v115
	v_mad_i64_i32 v[120:121], s[28:29], v150, s63, v[112:113]
	v_lshlrev_b64 v[114:115], 0, v[152:153]
	v_lshl_add_u64 v[120:121], v[120:121], 0, v[114:115]
	global_store_dwordx4 v[120:121], v[116:119], off
	v_pk_add_f32 v[108:109], v[108:109], 1.0 op_sel_hi:[1,0]
	v_pk_mul_f32 v[106:107], v[110:111], v[106:107]
	v_pk_mul_f32 v[110:111], v[100:101], s[10:11] op_sel_hi:[1,0]
	v_pk_mul_f32 v[116:117], v[102:103], s[10:11] op_sel_hi:[1,0]
	v_rcp_f32_e32 v108, v108
	v_rcp_f32_e32 v109, v109
	v_exp_f32_e32 v110, v110
	v_exp_f32_e32 v111, v111
	v_exp_f32_e32 v116, v116
	v_exp_f32_e32 v117, v117
	v_pk_mul_f32 v[90:91], v[94:95], v[90:91]
	v_pk_mul_f32 v[94:95], v[94:95], s[10:11] op_sel_hi:[1,0]
	v_pk_mul_f32 v[104:105], v[108:109], v[104:105]
	v_exp_f32_e32 v94, v94
	v_exp_f32_e32 v95, v95
	v_pk_add_f32 v[108:109], v[110:111], 1.0 op_sel_hi:[1,0]
	v_pk_add_f32 v[110:111], v[116:117], 1.0 op_sel_hi:[1,0]
	v_rcp_f32_e32 v108, v108
	v_rcp_f32_e32 v110, v110
	v_rcp_f32_e32 v111, v111
	v_rcp_f32_e32 v109, v109
	v_pk_mul_f32 v[88:89], v[92:93], v[88:89]
	v_pk_mul_f32 v[92:93], v[92:93], s[10:11] op_sel_hi:[1,0]
	v_pk_add_f32 v[94:95], v[94:95], 1.0 op_sel_hi:[1,0]
	v_pk_mul_f32 v[98:99], v[102:103], v[98:99]
	v_pk_mul_f32 v[96:97], v[100:101], v[96:97]
	v_exp_f32_e32 v92, v92
	v_exp_f32_e32 v93, v93
	v_rcp_f32_e32 v94, v94
	v_rcp_f32_e32 v95, v95
	v_pk_mul_f32 v[100:101], v[110:111], v[98:99]
	v_pk_mul_f32 v[98:99], v[108:109], v[96:97]
	v_or_b32_e32 v102, 16, v150
	v_cvt_pk_bf16_f32 v96, v104, v105
	v_cvt_pk_bf16_f32 v97, v106, v107
	v_cvt_pk_bf16_f32 v98, v98, v99
	v_cvt_pk_bf16_f32 v99, v100, v101
	v_mad_i64_i32 v[100:101], s[28:29], v102, s63, v[112:113]
	v_lshl_add_u64 v[100:101], v[100:101], 0, v[114:115]
	global_store_dwordx4 v[100:101], v[96:99], off
	v_pk_add_f32 v[92:93], v[92:93], 1.0 op_sel_hi:[1,0]
	v_pk_mul_f32 v[90:91], v[94:95], v[90:91]
	v_pk_mul_f32 v[94:95], v[84:85], s[10:11] op_sel_hi:[1,0]
	v_pk_mul_f32 v[96:97], v[86:87], s[10:11] op_sel_hi:[1,0]
	v_rcp_f32_e32 v92, v92
	v_rcp_f32_e32 v93, v93
	v_exp_f32_e32 v94, v94
	v_exp_f32_e32 v95, v95
	v_exp_f32_e32 v96, v96
	v_exp_f32_e32 v97, v97
	v_pk_mul_f32 v[74:75], v[78:79], v[74:75]
	v_pk_mul_f32 v[78:79], v[78:79], s[10:11] op_sel_hi:[1,0]
	v_pk_mul_f32 v[88:89], v[92:93], v[88:89]
	v_exp_f32_e32 v78, v78
	v_exp_f32_e32 v79, v79
	v_pk_add_f32 v[92:93], v[94:95], 1.0 op_sel_hi:[1,0]
	v_pk_add_f32 v[94:95], v[96:97], 1.0 op_sel_hi:[1,0]
	v_rcp_f32_e32 v92, v92
	v_rcp_f32_e32 v94, v94
	v_rcp_f32_e32 v95, v95
	v_rcp_f32_e32 v93, v93
	v_pk_mul_f32 v[72:73], v[76:77], v[72:73]
	v_pk_mul_f32 v[76:77], v[76:77], s[10:11] op_sel_hi:[1,0]
	v_pk_add_f32 v[78:79], v[78:79], 1.0 op_sel_hi:[1,0]
	v_pk_mul_f32 v[82:83], v[86:87], v[82:83]
	v_pk_mul_f32 v[80:81], v[84:85], v[80:81]
	v_exp_f32_e32 v76, v76
	v_exp_f32_e32 v77, v77
	v_rcp_f32_e32 v78, v78
	v_rcp_f32_e32 v79, v79
	v_pk_mul_f32 v[84:85], v[94:95], v[82:83]
	v_pk_mul_f32 v[82:83], v[92:93], v[80:81]
	v_or_b32_e32 v86, 32, v150
	v_cvt_pk_bf16_f32 v80, v88, v89
	v_cvt_pk_bf16_f32 v81, v90, v91
	v_cvt_pk_bf16_f32 v82, v82, v83
	v_cvt_pk_bf16_f32 v83, v84, v85
	v_mad_i64_i32 v[84:85], s[28:29], v86, s63, v[112:113]
	v_lshl_add_u64 v[84:85], v[84:85], 0, v[114:115]
	global_store_dwordx4 v[84:85], v[80:83], off
	v_pk_add_f32 v[76:77], v[76:77], 1.0 op_sel_hi:[1,0]
	v_pk_mul_f32 v[74:75], v[78:79], v[74:75]
	v_pk_mul_f32 v[78:79], v[68:69], s[10:11] op_sel_hi:[1,0]
	v_pk_mul_f32 v[80:81], v[70:71], s[10:11] op_sel_hi:[1,0]
	v_rcp_f32_e32 v76, v76
	v_rcp_f32_e32 v77, v77
	v_exp_f32_e32 v78, v78
	v_exp_f32_e32 v79, v79
	v_exp_f32_e32 v80, v80
	v_exp_f32_e32 v81, v81
	v_pk_mul_f32 v[58:59], v[62:63], v[58:59]
	v_pk_mul_f32 v[62:63], v[62:63], s[10:11] op_sel_hi:[1,0]
	v_pk_mul_f32 v[72:73], v[76:77], v[72:73]
	v_exp_f32_e32 v62, v62
	v_exp_f32_e32 v63, v63
	v_pk_add_f32 v[76:77], v[78:79], 1.0 op_sel_hi:[1,0]
	v_pk_add_f32 v[78:79], v[80:81], 1.0 op_sel_hi:[1,0]
	v_rcp_f32_e32 v76, v76
	v_rcp_f32_e32 v78, v78
	v_rcp_f32_e32 v79, v79
	v_rcp_f32_e32 v77, v77
	v_pk_mul_f32 v[56:57], v[60:61], v[56:57]
	v_pk_mul_f32 v[60:61], v[60:61], s[10:11] op_sel_hi:[1,0]
	v_pk_add_f32 v[62:63], v[62:63], 1.0 op_sel_hi:[1,0]
	v_pk_mul_f32 v[66:67], v[70:71], v[66:67]
	v_pk_mul_f32 v[64:65], v[68:69], v[64:65]
	v_exp_f32_e32 v60, v60
	v_exp_f32_e32 v61, v61
	v_rcp_f32_e32 v62, v62
	v_rcp_f32_e32 v63, v63
	v_pk_mul_f32 v[68:69], v[78:79], v[66:67]
	v_pk_mul_f32 v[66:67], v[76:77], v[64:65]
	v_or_b32_e32 v70, 48, v150
	v_cvt_pk_bf16_f32 v64, v72, v73
	v_cvt_pk_bf16_f32 v65, v74, v75
	v_cvt_pk_bf16_f32 v66, v66, v67
	v_cvt_pk_bf16_f32 v67, v68, v69
	v_mad_i64_i32 v[68:69], s[28:29], v70, s63, v[112:113]
	v_lshl_add_u64 v[68:69], v[68:69], 0, v[114:115]
	global_store_dwordx4 v[68:69], v[64:67], off
	v_pk_add_f32 v[60:61], v[60:61], 1.0 op_sel_hi:[1,0]
	v_pk_mul_f32 v[58:59], v[62:63], v[58:59]
	v_pk_mul_f32 v[62:63], v[52:53], s[10:11] op_sel_hi:[1,0]
	v_pk_mul_f32 v[64:65], v[54:55], s[10:11] op_sel_hi:[1,0]
	v_rcp_f32_e32 v60, v60
	v_rcp_f32_e32 v61, v61
	v_exp_f32_e32 v62, v62
	v_exp_f32_e32 v63, v63
	v_exp_f32_e32 v64, v64
	v_exp_f32_e32 v65, v65
	v_pk_mul_f32 v[42:43], v[46:47], v[42:43]
	v_pk_mul_f32 v[46:47], v[46:47], s[10:11] op_sel_hi:[1,0]
	v_pk_mul_f32 v[56:57], v[60:61], v[56:57]
	v_exp_f32_e32 v46, v46
	v_exp_f32_e32 v47, v47
	v_pk_add_f32 v[60:61], v[62:63], 1.0 op_sel_hi:[1,0]
	v_pk_add_f32 v[62:63], v[64:65], 1.0 op_sel_hi:[1,0]
	v_rcp_f32_e32 v60, v60
	v_rcp_f32_e32 v62, v62
	v_rcp_f32_e32 v63, v63
	v_rcp_f32_e32 v61, v61
	v_pk_mul_f32 v[40:41], v[44:45], v[40:41]
	v_pk_mul_f32 v[44:45], v[44:45], s[10:11] op_sel_hi:[1,0]
	v_pk_add_f32 v[46:47], v[46:47], 1.0 op_sel_hi:[1,0]
	v_pk_mul_f32 v[50:51], v[54:55], v[50:51]
	v_pk_mul_f32 v[48:49], v[52:53], v[48:49]
	v_exp_f32_e32 v44, v44
	v_exp_f32_e32 v45, v45
	v_rcp_f32_e32 v46, v46
	v_rcp_f32_e32 v47, v47
	v_add_u32_e32 v66, 0x80, v150
	v_pk_mul_f32 v[52:53], v[62:63], v[50:51]
	v_pk_mul_f32 v[50:51], v[60:61], v[48:49]
	v_cvt_pk_bf16_f32 v48, v56, v57
	v_cvt_pk_bf16_f32 v49, v58, v59
	v_pk_add_f32 v[44:45], v[44:45], 1.0 op_sel_hi:[1,0]
	v_cvt_pk_bf16_f32 v50, v50, v51
	v_cvt_pk_bf16_f32 v51, v52, v53
	v_mad_i64_i32 v[52:53], s[28:29], v66, s63, v[112:113]
	v_lshl_add_u64 v[52:53], v[52:53], 0, v[114:115]
	global_store_dwordx4 v[52:53], v[48:51], off
	v_pk_mul_f32 v[42:43], v[46:47], v[42:43]
	v_pk_mul_f32 v[46:47], v[36:37], s[10:11] op_sel_hi:[1,0]
	v_pk_mul_f32 v[48:49], v[38:39], s[10:11] op_sel_hi:[1,0]
	v_rcp_f32_e32 v44, v44
	v_rcp_f32_e32 v45, v45
	v_exp_f32_e32 v46, v46
	v_exp_f32_e32 v47, v47
	v_exp_f32_e32 v48, v48
	v_exp_f32_e32 v49, v49
	v_pk_mul_f32 v[26:27], v[30:31], v[26:27]
	v_pk_mul_f32 v[30:31], v[30:31], s[10:11] op_sel_hi:[1,0]
	v_pk_mul_f32 v[40:41], v[44:45], v[40:41]
	v_exp_f32_e32 v30, v30
	v_exp_f32_e32 v31, v31
	v_pk_add_f32 v[44:45], v[46:47], 1.0 op_sel_hi:[1,0]
	v_pk_add_f32 v[46:47], v[48:49], 1.0 op_sel_hi:[1,0]
	v_rcp_f32_e32 v44, v44
	v_rcp_f32_e32 v46, v46
	v_rcp_f32_e32 v47, v47
	v_rcp_f32_e32 v45, v45
	v_pk_mul_f32 v[24:25], v[28:29], v[24:25]
	v_pk_mul_f32 v[28:29], v[28:29], s[10:11] op_sel_hi:[1,0]
	v_pk_add_f32 v[30:31], v[30:31], 1.0 op_sel_hi:[1,0]
	v_pk_mul_f32 v[34:35], v[38:39], v[34:35]
	v_pk_mul_f32 v[32:33], v[36:37], v[32:33]
	v_exp_f32_e32 v28, v28
	v_exp_f32_e32 v29, v29
	v_rcp_f32_e32 v30, v30
	v_rcp_f32_e32 v31, v31
	v_pk_mul_f32 v[36:37], v[46:47], v[34:35]
	v_pk_mul_f32 v[34:35], v[44:45], v[32:33]
	v_add_u32_e32 v38, 0x90, v150
	v_cvt_pk_bf16_f32 v32, v40, v41
	v_cvt_pk_bf16_f32 v33, v42, v43
	v_cvt_pk_bf16_f32 v34, v34, v35
	v_cvt_pk_bf16_f32 v35, v36, v37
	v_mad_i64_i32 v[36:37], s[28:29], v38, s63, v[112:113]
	v_lshl_add_u64 v[36:37], v[36:37], 0, v[114:115]
	global_store_dwordx4 v[36:37], v[32:35], off
	v_pk_add_f32 v[28:29], v[28:29], 1.0 op_sel_hi:[1,0]
	v_pk_mul_f32 v[26:27], v[30:31], v[26:27]
	v_pk_mul_f32 v[30:31], v[20:21], s[10:11] op_sel_hi:[1,0]
	v_pk_mul_f32 v[32:33], v[22:23], s[10:11] op_sel_hi:[1,0]
	v_rcp_f32_e32 v28, v28
	v_rcp_f32_e32 v29, v29
	v_exp_f32_e32 v30, v30
	v_exp_f32_e32 v31, v31
	v_exp_f32_e32 v32, v32
	v_exp_f32_e32 v33, v33
	v_pk_mul_f32 v[10:11], v[14:15], v[10:11]
	v_pk_mul_f32 v[14:15], v[14:15], s[10:11] op_sel_hi:[1,0]
	v_pk_mul_f32 v[24:25], v[28:29], v[24:25]
	v_exp_f32_e32 v14, v14
	v_exp_f32_e32 v15, v15
	v_pk_add_f32 v[28:29], v[30:31], 1.0 op_sel_hi:[1,0]
	v_pk_add_f32 v[30:31], v[32:33], 1.0 op_sel_hi:[1,0]
	v_rcp_f32_e32 v28, v28
	v_rcp_f32_e32 v30, v30
	v_rcp_f32_e32 v31, v31
	v_rcp_f32_e32 v29, v29
	v_pk_mul_f32 v[8:9], v[12:13], v[8:9]
	v_pk_mul_f32 v[12:13], v[12:13], s[10:11] op_sel_hi:[1,0]
	v_pk_add_f32 v[14:15], v[14:15], 1.0 op_sel_hi:[1,0]
	v_pk_mul_f32 v[18:19], v[22:23], v[18:19]
	v_pk_mul_f32 v[16:17], v[20:21], v[16:17]
	v_exp_f32_e32 v12, v12
	v_exp_f32_e32 v13, v13
	v_rcp_f32_e32 v14, v14
	v_rcp_f32_e32 v15, v15
	v_pk_mul_f32 v[20:21], v[30:31], v[18:19]
	v_pk_mul_f32 v[18:19], v[28:29], v[16:17]
	v_add_u32_e32 v22, 0xa0, v150
	v_cvt_pk_bf16_f32 v16, v24, v25
	v_cvt_pk_bf16_f32 v17, v26, v27
	v_cvt_pk_bf16_f32 v18, v18, v19
	v_cvt_pk_bf16_f32 v19, v20, v21
	v_mad_i64_i32 v[20:21], s[28:29], v22, s63, v[112:113]
	v_lshl_add_u64 v[20:21], v[20:21], 0, v[114:115]
	global_store_dwordx4 v[20:21], v[16:19], off
	v_pk_add_f32 v[12:13], v[12:13], 1.0 op_sel_hi:[1,0]
	v_pk_mul_f32 v[10:11], v[14:15], v[10:11]
	v_pk_mul_f32 v[14:15], v[4:5], s[10:11] op_sel_hi:[1,0]
	v_pk_mul_f32 v[16:17], v[6:7], s[10:11] op_sel_hi:[1,0]
	v_rcp_f32_e32 v12, v12
	v_rcp_f32_e32 v13, v13
	v_exp_f32_e32 v14, v14
	v_exp_f32_e32 v15, v15
	v_exp_f32_e32 v16, v16
	v_exp_f32_e32 v17, v17
	v_pk_mul_f32 v[8:9], v[12:13], v[8:9]
	v_pk_add_f32 v[12:13], v[14:15], 1.0 op_sel_hi:[1,0]
	v_pk_mul_f32 v[2:3], v[6:7], v[2:3]
	v_pk_add_f32 v[14:15], v[16:17], 1.0 op_sel_hi:[1,0]
	v_rcp_f32_e32 v12, v12
	v_rcp_f32_e32 v14, v14
	v_rcp_f32_e32 v15, v15
	v_rcp_f32_e32 v13, v13
	v_pk_mul_f32 v[0:1], v[4:5], v[0:1]
	v_add_u32_e32 v6, 0xb0, v150
	v_pk_mul_f32 v[4:5], v[14:15], v[2:3]
	v_pk_mul_f32 v[2:3], v[12:13], v[0:1]
	v_cvt_pk_bf16_f32 v0, v8, v9
	v_cvt_pk_bf16_f32 v1, v10, v11
	s_andn2_b64 vcc, exec, s[0:1]
	v_cvt_pk_bf16_f32 v2, v2, v3
	v_cvt_pk_bf16_f32 v3, v4, v5
	v_mad_i64_i32 v[4:5], s[28:29], v6, s63, v[112:113]
	v_lshl_add_u64 v[4:5], v[4:5], 0, v[114:115]
	s_mov_b64 s[0:1], -1
	global_store_dwordx4 v[4:5], v[0:3], off
	s_cbranch_vccnz .LBB0_241
	s_andn2_b64 vcc, exec, s[4:5]
	s_cbranch_vccnz .LBB0_240
	s_barrier
	s_branch .LBB0_240

.LBB0_284:
	s_andn2_saveexec_b64 s[6:7], s[6:7]
	s_cbranch_execz .LBB0_304
	s_mov_b64 s[6:7], exec
	s_cmp_lg_u32 s98, 0
	s_cbranch_scc1 .LBB0_301
	buffer_wbl2 sc1
	s_waitcnt lgkmcnt(0)
	s_waitcnt vmcnt(0)
	v_mbcnt_lo_u32_b32 v1, s6, 0
	v_mbcnt_hi_u32_b32 v1, s7, v1
	v_cmp_eq_u32_e32 vcc, 0, v1
	s_and_saveexec_b64 s[8:9], vcc
	s_cbranch_execz .LBB0_287
	s_bcnt1_i32_b64 s3, s[6:7]
	v_mov_b32_e32 v2, 0x5c3000
	v_mov_b32_e32 v3, s3
	global_atomic_add v2, v2, v3, s[72:73] offset:1024 sc0

.LBB0_309:
	v_ashrrev_i32_e32 v1, 31, v8
	v_lshrrev_b32_e32 v1, 26, v1
	v_add_u32_e32 v1, v8, v1
	v_ashrrev_i32_e32 v9, 6, v1
	v_bfe_i32 v1, v8, 27, 1
	v_lshlrev_b32_e32 v0, 4, v8
	v_lshrrev_b32_e32 v1, 22, v1
	v_add_u32_e32 v1, v0, v1
	v_and_b32_e32 v1, 0xfffffc00, v1
	v_sub_u32_e32 v1, v0, v1
	v_lshrrev_b32_e32 v2, 4, v1
	v_bitop3_b32 v1, v2, v1, 32 bitop3:0x6c
	v_ashrrev_i32_e32 v3, 31, v1
	v_lshrrev_b32_e32 v3, 26, v3
	v_lshlrev_b32_e32 v2, 3, v9
	v_add_u32_e32 v3, v1, v3
	v_and_b32_e32 v2, -16, v2
	v_ashrrev_i32_e32 v11, 6, v3
	v_and_b32_e32 v3, 0xc0, v3
	v_add_u32_e32 v2, v11, v2
	v_lshlrev_b32_e32 v4, 5, v9
	v_sub_u32_e32 v1, v1, v3
	v_mov_b32_e32 v3, 1
	s_ashr_i32 s7, s5, 3
	v_and_b32_e32 v10, 32, v4
	v_ashrrev_i16_sdwa v1, v3, sext(v1) dst_sel:DWORD dst_unused:UNUSED_PAD src0_sel:DWORD src1_sel:BYTE_0
	v_lshlrev_b32_e32 v4, 1, v2
	v_lshrrev_b32_e32 v5, 2, v2
	v_and_b32_e32 v6, 3, v11
	s_mov_b32 s5, 0xffffe0
	v_bfe_i32 v12, v1, 0, 16
	v_and_b32_e32 v4, 24, v4
	v_and_b32_e32 v5, 4, v5
	v_and_or_b32 v6, v2, s5, v6
	s_movk_i32 s0, 0xb00
	v_add_u32_e32 v1, v10, v12
	v_or3_b32 v4, v6, v5, v4
	v_mul_lo_u32 v2, v2, s0
	s_add_u32 s12, s72, 0x1100000
	v_add_lshl_u32 v128, v1, v2, 1
	v_mul_u32_u24_e32 v2, 0xb00, v4
	v_add_u32_e32 v0, 0x2000, v0
	s_addc_u32 s13, s73, 0
	v_add_lshl_u32 v130, v2, v1, 1
	v_ashrrev_i32_e32 v1, 31, v0
	s_add_i32 s6, s6, s7
	v_lshrrev_b32_e32 v1, 22, v1
	s_ashr_i32 s7, s6, 31
	v_add_u32_e32 v1, v0, v1
	s_lshr_b32 s7, s7, 27
	v_ashrrev_i32_e32 v13, 10, v1
	s_add_i32 s7, s6, s7
	v_mul_i32_i24_e32 v1, 0x400, v13
	s_ashr_i32 s8, s7, 5
	s_andn2_b32 s7, s7, 31
	v_sub_u32_e32 v0, v0, v1
	s_sub_i32 s6, s6, s7
	v_lshrrev_b32_e32 v1, 4, v0
	s_bfe_i32 s7, s6, 0x80000
	v_bitop3_b32 v0, v1, v0, 32 bitop3:0x6c
	s_bfe_u32 s7, s7, 0x3000c
	v_ashrrev_i32_e32 v2, 31, v0
	s_add_i32 s7, s6, s7
	v_lshrrev_b32_e32 v2, 26, v2
	s_bfe_i32 s9, s7, 0x80000
	s_and_b32 s7, s7, 0xf8
	v_lshlrev_b32_e32 v1, 3, v13
	v_add_u32_e32 v2, v0, v2
	s_sub_i32 s6, s6, s7
	v_and_b32_e32 v1, -16, v1
	v_ashrrev_i32_e32 v14, 6, v2
	v_lshlrev_b32_e32 v4, 5, v13
	s_lshl_b32 s8, s8, 3
	s_sext_i32_i16 s9, s9
	s_sext_i32_i8 s6, s6
	s_ashr_i32 s1, s4, 6
	v_add_u32_e32 v1, v14, v1
	v_and_b32_e32 v15, 32, v4
	v_and_b32_e32 v2, 0xc0, v2
	v_and_b32_e32 v4, 3, v14
	s_add_i32 s85, s8, s6
	s_ashr_i32 s6, s9, 3
	v_sub_u32_e32 v0, v0, v2
	v_and_or_b32 v4, v1, s5, v4
	s_ashr_i32 s5, s4, 8
	s_lshl_b32 s34, s1, 10
	s_lshr_b32 s10, s9, 3
	s_mul_hi_i32 s7, s6, 0x160000
	s_mul_i32 s6, s6, 0x160000
	v_ashrrev_i16_sdwa v0, v3, sext(v0) dst_sel:DWORD dst_unused:UNUSED_PAD src0_sel:DWORD src1_sel:BYTE_0
	v_lshlrev_b32_e32 v2, 1, v1
	v_lshrrev_b32_e32 v3, 2, v1
	s_add_u32 s50, s12, s6
	v_bfe_i32 v16, v0, 0, 16
	v_and_b32_e32 v2, 24, v2
	v_and_b32_e32 v3, 4, v3
	s_addc_u32 s51, s13, s7
	s_add_i32 s35, s34, 0
	v_add_u32_e32 v0, v15, v16
	v_or3_b32 v2, v4, v3, v2
	v_mul_lo_u32 v1, v1, s0
	s_add_i32 m0, s35, 0x10000
	v_add_lshl_u32 v132, v0, v1, 1
	v_mul_u32_u24_e32 v1, 0xb00, v2
	global_load_lds_dwordx4 v130, s[50:51]
	s_add_i32 m0, s35, 0x12000
	v_add_lshl_u32 v134, v1, v0, 1
	s_add_u32 s6, s50, 0xb0000
	global_load_lds_dwordx4 v134, s[50:51]
	s_addc_u32 s7, s51, 0
	s_add_i32 m0, s35, 0x14000
	s_mul_i32 s11, s85, 0x160000
	global_load_lds_dwordx4 v130, s[6:7]
	s_add_i32 m0, s35, 0x16000
	s_mul_hi_i32 s8, s85, 0x160000
	s_add_u32 s46, s20, s11
	s_addc_u32 s47, s21, s8
	s_add_i32 s60, s35, 0x2000
	global_load_lds_dwordx4 v134, s[6:7]
	s_mov_b32 m0, s35
	s_add_u32 s6, s46, 0x4000
	v_and_b32_e32 v229, 63, v188
	v_lshrrev_b32_e32 v230, 6, v188
	v_lshrrev_b32_e32 v231, 2, v229
	v_lshlrev_b32_e32 v231, 7, v231
	v_and_b32_e32 v232, 3, v229
	v_lshlrev_b32_e32 v232, 4, v232
	v_lshrrev_b32_e32 v233, 5, v229
	v_lshlrev_b32_e32 v233, 5, v233
	v_xor_b32_e32 v232, v232, v233
	v_or_b32_e32 v231, v231, v232
	v_lshrrev_b32_e32 v232, 1, v230
	v_lshl_or_b32 v231, v232, 11, v231
	v_and_b32_e32 v232, 1, v230
	v_lshl_or_b32 v128, v232, 6, v231
	v_add_u32_e32 v132, 0x2000, v128
	global_load_lds_dwordx4 v128, s[46:47]
	s_mov_b32 m0, s60
	s_addc_u32 s7, s47, 0
	s_add_i32 s61, s35, 0x4000
	global_load_lds_dwordx4 v132, s[46:47]
	s_mov_b32 m0, s61
	s_add_i32 s62, s35, 0x6000
	global_load_lds_dwordx4 v128, s[6:7]
	s_mov_b32 m0, s62
	v_mov_b32_e32 v131, 0
	global_load_lds_dwordx4 v132, s[6:7]
	v_mov_b32_e32 v135, v131
	v_mov_b32_e32 v129, v131
	v_mov_b32_e32 v133, v131
	s_cmp_eq_u32 s5, 1
	s_mov_b32 s63, 0
	v_lshl_add_u64 v[6:7], s[50:51], 0, v[130:131]
	v_lshl_add_u64 v[4:5], s[50:51], 0, v[134:135]
	v_lshl_add_u64 v[0:1], s[46:47], 0, v[128:129]
	s_cselect_b64 s[6:7], -1, 0
	s_cmp_lg_u32 s5, 1
	v_lshl_add_u64 v[2:3], s[46:47], 0, v[132:133]
	s_cbranch_scc1 .LBB0_311
	s_barrier
.LBB0_311:
	s_lshl_b32 s1, s1, 5
	s_mov_b64 s[8:9], 0x80
	s_mov_b64 s[92:93], 0x8000
	s_and_b32 s1, s1, 0x60
	s_add_i32 m0, s35, 0x18000
	v_lshl_add_u64 v[6:7], v[6:7], 0, s[8:9]
	s_lshl_b32 s11, s5, 13
	s_lshl_b32 s18, s1, 7
	s_waitcnt vmcnt(2)
	s_barrier
	global_load_lds_dwordx4 v[6:7], off
	v_lshl_add_u64 v[4:5], v[4:5], 0, s[8:9]
	s_add_i32 m0, s35, 0x1a000
	s_add_i32 s64, s35, 0x8000
	s_add_i32 s65, s35, 0xa000
	global_load_lds_dwordx4 v[4:5], off
	v_lshl_add_u64 v[0:1], v[0:1], 0, s[92:93]
	s_mov_b32 m0, s64
	s_add_u32 s14, s50, 0xb0080
	global_load_lds_dwordx4 v[0:1], off
	v_lshl_add_u64 v[0:1], v[2:3], 0, s[92:93]
	s_mov_b32 m0, s65
	s_addc_u32 s15, s51, 0
	global_load_lds_dwordx4 v[0:1], off
	s_add_i32 m0, s35, 0x1c000
	v_lshl_add_u64 v[0:1], s[14:15], 0, v[130:131]
	global_load_lds_dwordx4 v[0:1], off
	v_lshl_add_u64 v[0:1], s[14:15], 0, v[134:135]
	s_add_i32 m0, s35, 0x1e000
	s_cmpk_lt_u32 s4, 0x100
	global_load_lds_dwordx4 v[0:1], off
	v_lshrrev_b32_e32 v1, 1, v8
	v_and_b32_e32 v1, 24, v1
	v_and_b32_e32 v0, 15, v8
	v_lshlrev_b32_e32 v2, 1, v1
	v_lshl_or_b32 v146, s5, 6, v0
	v_lshl_or_b32 v0, v0, 6, v2
	v_lshlrev_b32_e32 v2, 2, v8
	v_and_b32_e32 v2, 32, v2
	v_bitop3_b32 v3, v0, s11, v2 bitop3:0xde
	v_bitop3_b32 v147, v0, s18, v2 bitop3:0xde
	v_or_b32_e32 v148, s1, v1
	v_lshrrev_b32_e32 v1, 1, v9
	v_mul_lo_u32 v0, v11, s0
	s_mov_b32 s1, 0xb000
	v_mad_u64_u32 v[0:1], s[4:5], v1, s1, v[0:1]
	v_or_b32_e32 v0, v0, v10
	s_mov_b64 s[14:15], 0xb0080
	v_add_lshl_u32 v0, v0, v12, 1
	v_mov_b32_e32 v1, v131
	v_lshl_add_u64 v[136:137], v[0:1], 0, s[14:15]
	v_add_u32_e32 v136, 0xc000, v128
	v_mov_b32_e32 v137, 0
	v_lshrrev_b32_e32 v1, 1, v13
	v_mul_lo_u32 v0, v14, s0
	v_mad_u64_u32 v[0:1], s[0:1], v1, s1, v[0:1]
	s_waitcnt vmcnt(6)
	v_or_b32_e32 v0, v0, v15
	s_sext_i32_i8 s88, s10
	s_cselect_b64 s[10:11], -1, 0
	v_add_lshl_u32 v0, v0, v16, 1
	v_mov_b32_e32 v1, v131
	s_add_i32 s76, 0, 0x10000
	s_add_i32 s77, 0, 0x14000
	s_ashr_i32 s66, s74, 31
	s_mov_b32 s67, s74
	v_lshl_add_u64 v[138:139], v[0:1], 0, s[14:15]
	v_add_u32_e32 v138, 0xc000, v132
	v_mov_b32_e32 v139, 0
	v_mov_b64_e32 v[140:141], 0x200
	v_mov_b64_e32 v[142:143], 0x1ff
	v_add_u32_e32 v149, s76, v147
	v_add_u32_e32 v150, s77, v147
	v_add_u32_e32 v151, 0, v3
	s_mov_b64 s[14:15], 0x40000
	s_mov_b32 s78, 0x40000
	s_mov_b64 s[18:19], 0x48000
	s_mov_b32 s79, 0x48000
	s_mov_b64 s[38:39], 0x50000
	s_mov_b32 s80, 0x50000
	s_mov_b64 s[40:41], 0x58000
	s_mov_b32 s81, 0x58000
	s_barrier
	s_branch .LBB0_314

.LBB0_325:
	ds_read_b128 v[152:155], v149
	ds_read_b128 v[156:159], v149 offset:1024
	ds_read_b128 v[160:163], v149 offset:2048
	ds_read_b128 v[164:167], v149 offset:3072
	ds_read_b128 v[168:171], v150
	ds_read_b128 v[172:175], v150 offset:1024
	ds_read_b128 v[176:179], v150 offset:2048
	ds_read_b128 v[180:183], v150 offset:3072
	s_add_u32 s50, s46, 0x10000
	s_addc_u32 s51, s47, 0
	s_cmp_eq_u32 s91, 40
	s_cselect_b32 s55, s5, s51
	s_cselect_b32 s54, s4, s50
	s_cselect_b32 s53, s43, s90
	s_cselect_b32 s52, s42, s89
	v_lshl_add_u64 v[144:145], s[46:47], 0, v[136:137]
	s_add_i32 m0, s35, 0xc000
	ds_read_b128 v[184:187], v151
	ds_read_b128 v[190:193], v151 offset:1024
	ds_read_b128 v[194:197], v151 offset:2048
	ds_read_b128 v[198:201], v151 offset:3072
	ds_read_b128 v[202:205], v151 offset:4096
	ds_read_b128 v[206:209], v151 offset:5120
	ds_read_b128 v[210:213], v151 offset:6144
	ds_read_b128 v[214:217], v151 offset:7168
	global_load_lds_dwordx4 v[144:145], off
	v_lshl_add_u64 v[144:145], s[46:47], 0, v[138:139]
	s_add_i32 m0, s35, 0xe000
	s_nop 0
	global_load_lds_dwordx4 v[144:145], off
	s_waitcnt vmcnt(8)
	s_waitcnt lgkmcnt(0)
	s_barrier
	s_setprio 1
	s_waitcnt lgkmcnt(0)
	v_mfma_f32_16x16x32_bf16 v[124:127], v[152:155], v[184:187], v[124:127]
	v_mfma_f32_16x16x32_bf16 v[120:123], v[160:163], v[184:187], v[120:123]
	v_mfma_f32_16x16x32_bf16 v[116:119], v[152:155], v[194:197], v[116:119]
	v_mfma_f32_16x16x32_bf16 v[108:111], v[160:163], v[194:197], v[108:111]
	v_mfma_f32_16x16x32_bf16 v[100:103], v[152:155], v[202:205], v[100:103]
	v_mfma_f32_16x16x32_bf16 v[92:95], v[160:163], v[202:205], v[92:95]
	v_mfma_f32_16x16x32_bf16 v[84:87], v[152:155], v[210:213], v[84:87]
	v_mfma_f32_16x16x32_bf16 v[76:79], v[160:163], v[210:213], v[76:79]
	v_mfma_f32_16x16x32_bf16 v[124:127], v[156:159], v[190:193], v[124:127]
	v_mfma_f32_16x16x32_bf16 v[120:123], v[164:167], v[190:193], v[120:123]
	v_mfma_f32_16x16x32_bf16 v[116:119], v[156:159], v[198:201], v[116:119]
	v_mfma_f32_16x16x32_bf16 v[108:111], v[164:167], v[198:201], v[108:111]
	v_mfma_f32_16x16x32_bf16 v[100:103], v[156:159], v[206:209], v[100:103]
	v_mfma_f32_16x16x32_bf16 v[92:95], v[164:167], v[206:209], v[92:95]
	v_mfma_f32_16x16x32_bf16 v[84:87], v[156:159], v[214:217], v[84:87]
	v_mfma_f32_16x16x32_bf16 v[76:79], v[164:167], v[214:217], v[76:79]
	s_setprio 0
	s_setprio 1
	v_mfma_f32_16x16x32_bf16 v[112:115], v[168:171], v[184:187], v[112:115]
	v_mfma_f32_16x16x32_bf16 v[104:107], v[176:179], v[184:187], v[104:107]
	v_mfma_f32_16x16x32_bf16 v[96:99], v[168:171], v[194:197], v[96:99]
	v_mfma_f32_16x16x32_bf16 v[88:91], v[176:179], v[194:197], v[88:91]
	v_mfma_f32_16x16x32_bf16 v[80:83], v[168:171], v[202:205], v[80:83]
	v_mfma_f32_16x16x32_bf16 v[72:75], v[176:179], v[202:205], v[72:75]
	v_mfma_f32_16x16x32_bf16 v[68:71], v[168:171], v[210:213], v[68:71]
	v_mfma_f32_16x16x32_bf16 v[64:67], v[176:179], v[210:213], v[64:67]
	v_mfma_f32_16x16x32_bf16 v[112:115], v[172:175], v[190:193], v[112:115]
	v_mfma_f32_16x16x32_bf16 v[104:107], v[180:183], v[190:193], v[104:107]
	v_mfma_f32_16x16x32_bf16 v[96:99], v[172:175], v[198:201], v[96:99]
	v_mfma_f32_16x16x32_bf16 v[88:91], v[180:183], v[198:201], v[88:91]
	v_mfma_f32_16x16x32_bf16 v[80:83], v[172:175], v[206:209], v[80:83]
	v_mfma_f32_16x16x32_bf16 v[72:75], v[180:183], v[206:209], v[72:75]
	v_mfma_f32_16x16x32_bf16 v[68:71], v[172:175], v[214:217], v[68:71]
	v_mfma_f32_16x16x32_bf16 v[64:67], v[180:183], v[214:217], v[64:67]
	s_setprio 0
	s_barrier
	s_add_i32 s28, s76, s34
	v_lshl_add_u64 v[144:145], s[52:53], 0, v[130:131]
	s_mov_b32 m0, s28
	ds_read_b128 v[184:187], v151 offset:16384
	ds_read_b128 v[190:193], v151 offset:17408
	ds_read_b128 v[194:197], v151 offset:18432
	ds_read_b128 v[198:201], v151 offset:19456
	ds_read_b128 v[202:205], v151 offset:20480
	ds_read_b128 v[206:209], v151 offset:21504
	ds_read_b128 v[210:213], v151 offset:22528
	ds_read_b128 v[214:217], v151 offset:23552
	global_load_lds_dwordx4 v[144:145], off
	s_add_i32 m0, s28, 0x2000
	s_add_u32 s28, s52, 0xb0000
	v_lshl_add_u64 v[218:219], s[52:53], 0, v[134:135]
	s_addc_u32 s29, s53, 0
	s_add_i32 s33, s77, s34
	global_load_lds_dwordx4 v[218:219], off
	v_lshl_add_u64 v[220:221], s[28:29], 0, v[130:131]
	s_mov_b32 m0, s33
	v_lshl_add_u64 v[222:223], s[54:55], 0, v[132:133]
	global_load_lds_dwordx4 v[220:221], off
	v_lshl_add_u64 v[220:221], s[28:29], 0, v[134:135]
	s_add_i32 m0, s33, 0x2000
	s_nop 0
	global_load_lds_dwordx4 v[220:221], off
	v_lshl_add_u64 v[220:221], s[54:55], 0, v[128:129]
	s_mov_b32 m0, s35
	s_nop 0
	global_load_lds_dwordx4 v[220:221], off
	s_mov_b32 m0, s60
	s_nop 0
	global_load_lds_dwordx4 v[222:223], off
	s_waitcnt vmcnt(8)
	s_waitcnt lgkmcnt(0)
	s_nop 0
	s_barrier
	s_setprio 1
	s_waitcnt lgkmcnt(0)
	v_mfma_f32_16x16x32_bf16 v[60:63], v[152:155], v[184:187], v[60:63]
	v_mfma_f32_16x16x32_bf16 v[56:59], v[160:163], v[184:187], v[56:59]
	v_mfma_f32_16x16x32_bf16 v[52:55], v[152:155], v[194:197], v[52:55]
	v_mfma_f32_16x16x32_bf16 v[44:47], v[160:163], v[194:197], v[44:47]
	v_mfma_f32_16x16x32_bf16 v[36:39], v[152:155], v[202:205], v[36:39]
	v_mfma_f32_16x16x32_bf16 v[28:31], v[160:163], v[202:205], v[28:31]
	v_mfma_f32_16x16x32_bf16 v[20:23], v[152:155], v[210:213], v[20:23]
	v_mfma_f32_16x16x32_bf16 v[12:15], v[160:163], v[210:213], v[12:15]
	v_mfma_f32_16x16x32_bf16 v[60:63], v[156:159], v[190:193], v[60:63]
	v_mfma_f32_16x16x32_bf16 v[56:59], v[164:167], v[190:193], v[56:59]
	v_mfma_f32_16x16x32_bf16 v[52:55], v[156:159], v[198:201], v[52:55]
	v_mfma_f32_16x16x32_bf16 v[44:47], v[164:167], v[198:201], v[44:47]
	v_mfma_f32_16x16x32_bf16 v[36:39], v[156:159], v[206:209], v[36:39]
	v_mfma_f32_16x16x32_bf16 v[28:31], v[164:167], v[206:209], v[28:31]
	v_mfma_f32_16x16x32_bf16 v[20:23], v[156:159], v[214:217], v[20:23]
	v_mfma_f32_16x16x32_bf16 v[12:15], v[164:167], v[214:217], v[12:15]
	s_setprio 0
	s_setprio 1
	v_mfma_f32_16x16x32_bf16 v[48:51], v[168:171], v[184:187], v[48:51]
	v_mfma_f32_16x16x32_bf16 v[40:43], v[176:179], v[184:187], v[40:43]
	v_mfma_f32_16x16x32_bf16 v[32:35], v[168:171], v[194:197], v[32:35]
	v_mfma_f32_16x16x32_bf16 v[24:27], v[176:179], v[194:197], v[24:27]
	v_mfma_f32_16x16x32_bf16 v[16:19], v[168:171], v[202:205], v[16:19]
	v_mfma_f32_16x16x32_bf16 v[8:11], v[176:179], v[202:205], v[8:11]
	v_mfma_f32_16x16x32_bf16 v[4:7], v[168:171], v[210:213], v[4:7]
	v_mfma_f32_16x16x32_bf16 v[0:3], v[176:179], v[210:213], v[0:3]
	v_mfma_f32_16x16x32_bf16 v[48:51], v[172:175], v[190:193], v[48:51]
	v_mfma_f32_16x16x32_bf16 v[40:43], v[180:183], v[190:193], v[40:43]
	v_mfma_f32_16x16x32_bf16 v[32:35], v[172:175], v[198:201], v[32:35]
	v_mfma_f32_16x16x32_bf16 v[24:27], v[180:183], v[198:201], v[24:27]
	v_mfma_f32_16x16x32_bf16 v[16:19], v[172:175], v[206:209], v[16:19]
	v_mfma_f32_16x16x32_bf16 v[8:11], v[180:183], v[206:209], v[8:11]
	v_mfma_f32_16x16x32_bf16 v[4:7], v[172:175], v[214:217], v[4:7]
	v_mfma_f32_16x16x32_bf16 v[0:3], v[180:183], v[214:217], v[0:3]
	s_setprio 0
	s_barrier
	s_add_i32 s33, 0, 0x18000
	s_add_i32 s46, 0, 0x1c000
	v_add_u32_e32 v164, s33, v147
	v_add_u32_e32 v180, s46, v147
	ds_read_b128 v[152:155], v164
	ds_read_b128 v[156:159], v164 offset:1024
	ds_read_b128 v[160:163], v164 offset:2048
	ds_read_b128 v[164:167], v164 offset:3072
	ds_read_b128 v[168:171], v180
	ds_read_b128 v[172:175], v180 offset:1024
	ds_read_b128 v[176:179], v180 offset:2048
	ds_read_b128 v[180:183], v180 offset:3072
	s_add_u32 s28, s54, 0x4000
	s_addc_u32 s29, s55, 0
	s_mov_b32 m0, s61
	v_lshl_add_u64 v[224:225], s[28:29], 0, v[128:129]
	ds_read_b128 v[184:187], v151 offset:32768
	ds_read_b128 v[190:193], v151 offset:33792
	ds_read_b128 v[194:197], v151 offset:34816
	ds_read_b128 v[198:201], v151 offset:35840
	ds_read_b128 v[202:205], v151 offset:36864
	ds_read_b128 v[206:209], v151 offset:37888
	ds_read_b128 v[210:213], v151 offset:38912
	ds_read_b128 v[214:217], v151 offset:39936
	global_load_lds_dwordx4 v[224:225], off
	v_lshl_add_u64 v[224:225], s[28:29], 0, v[132:133]
	s_mov_b32 m0, s62
	s_nop 0
	global_load_lds_dwordx4 v[224:225], off
	s_waitcnt vmcnt(8)
	s_waitcnt lgkmcnt(0)
	s_nop 0
	s_barrier
	s_setprio 1
	s_waitcnt lgkmcnt(0)
	v_mfma_f32_16x16x32_bf16 v[124:127], v[152:155], v[184:187], v[124:127]
	v_mfma_f32_16x16x32_bf16 v[120:123], v[160:163], v[184:187], v[120:123]
	v_mfma_f32_16x16x32_bf16 v[116:119], v[152:155], v[194:197], v[116:119]
	v_mfma_f32_16x16x32_bf16 v[108:111], v[160:163], v[194:197], v[108:111]
	v_mfma_f32_16x16x32_bf16 v[100:103], v[152:155], v[202:205], v[100:103]
	v_mfma_f32_16x16x32_bf16 v[92:95], v[160:163], v[202:205], v[92:95]
	v_mfma_f32_16x16x32_bf16 v[84:87], v[152:155], v[210:213], v[84:87]
	v_mfma_f32_16x16x32_bf16 v[76:79], v[160:163], v[210:213], v[76:79]
	v_mfma_f32_16x16x32_bf16 v[124:127], v[156:159], v[190:193], v[124:127]
	v_mfma_f32_16x16x32_bf16 v[120:123], v[164:167], v[190:193], v[120:123]
	v_mfma_f32_16x16x32_bf16 v[116:119], v[156:159], v[198:201], v[116:119]
	v_mfma_f32_16x16x32_bf16 v[108:111], v[164:167], v[198:201], v[108:111]
	v_mfma_f32_16x16x32_bf16 v[100:103], v[156:159], v[206:209], v[100:103]
	v_mfma_f32_16x16x32_bf16 v[92:95], v[164:167], v[206:209], v[92:95]
	v_mfma_f32_16x16x32_bf16 v[84:87], v[156:159], v[214:217], v[84:87]
	v_mfma_f32_16x16x32_bf16 v[76:79], v[164:167], v[214:217], v[76:79]
	s_setprio 0
	s_setprio 1
	v_mfma_f32_16x16x32_bf16 v[112:115], v[168:171], v[184:187], v[112:115]
	v_mfma_f32_16x16x32_bf16 v[104:107], v[176:179], v[184:187], v[104:107]
	v_mfma_f32_16x16x32_bf16 v[96:99], v[168:171], v[194:197], v[96:99]
	v_mfma_f32_16x16x32_bf16 v[88:91], v[176:179], v[194:197], v[88:91]
	v_mfma_f32_16x16x32_bf16 v[80:83], v[168:171], v[202:205], v[80:83]
	v_mfma_f32_16x16x32_bf16 v[72:75], v[176:179], v[202:205], v[72:75]
	v_mfma_f32_16x16x32_bf16 v[68:71], v[168:171], v[210:213], v[68:71]
	v_mfma_f32_16x16x32_bf16 v[64:67], v[176:179], v[210:213], v[64:67]
	v_mfma_f32_16x16x32_bf16 v[112:115], v[172:175], v[190:193], v[112:115]
	v_mfma_f32_16x16x32_bf16 v[104:107], v[180:183], v[190:193], v[104:107]
	v_mfma_f32_16x16x32_bf16 v[96:99], v[172:175], v[198:201], v[96:99]
	v_mfma_f32_16x16x32_bf16 v[88:91], v[180:183], v[198:201], v[88:91]
	v_mfma_f32_16x16x32_bf16 v[80:83], v[172:175], v[206:209], v[80:83]
	v_mfma_f32_16x16x32_bf16 v[72:75], v[180:183], v[206:209], v[72:75]
	v_mfma_f32_16x16x32_bf16 v[68:71], v[172:175], v[214:217], v[68:71]
	v_mfma_f32_16x16x32_bf16 v[64:67], v[180:183], v[214:217], v[64:67]
	s_setprio 0
	s_barrier
	s_add_i32 s28, s33, s34
	v_lshl_add_u64 v[144:145], v[144:145], 0, s[8:9]
	s_mov_b32 m0, s28
	ds_read_b128 v[184:187], v151 offset:49152
	ds_read_b128 v[190:193], v151 offset:50176
	ds_read_b128 v[194:197], v151 offset:51200
	ds_read_b128 v[198:201], v151 offset:52224
	ds_read_b128 v[202:205], v151 offset:53248
	ds_read_b128 v[206:209], v151 offset:54272
	ds_read_b128 v[210:213], v151 offset:55296
	ds_read_b128 v[214:217], v151 offset:56320
	global_load_lds_dwordx4 v[144:145], off
	s_add_i32 m0, s28, 0x2000
	s_add_u32 s28, s52, 0xb0080
	v_lshl_add_u64 v[144:145], v[218:219], 0, s[8:9]
	s_addc_u32 s29, s53, 0
	s_add_i32 s33, s46, s34
	global_load_lds_dwordx4 v[144:145], off
	v_lshl_add_u64 v[144:145], s[28:29], 0, v[130:131]
	s_mov_b32 m0, s33
	s_nop 0
	global_load_lds_dwordx4 v[144:145], off
	v_lshl_add_u64 v[144:145], s[28:29], 0, v[134:135]
	s_add_i32 m0, s33, 0x2000
	s_nop 0
	global_load_lds_dwordx4 v[144:145], off
	v_lshl_add_u64 v[144:145], v[220:221], 0, s[92:93]
	s_mov_b32 m0, s64
	s_nop 0
	global_load_lds_dwordx4 v[144:145], off
	v_lshl_add_u64 v[144:145], v[222:223], 0, s[92:93]
	s_mov_b32 m0, s65
	s_nop 0
	global_load_lds_dwordx4 v[144:145], off
	s_waitcnt vmcnt(8)
	s_waitcnt lgkmcnt(0)
	s_barrier
	s_setprio 1
	s_waitcnt lgkmcnt(0)
	v_mfma_f32_16x16x32_bf16 v[60:63], v[152:155], v[184:187], v[60:63]
	v_mfma_f32_16x16x32_bf16 v[56:59], v[160:163], v[184:187], v[56:59]
	v_mfma_f32_16x16x32_bf16 v[52:55], v[152:155], v[194:197], v[52:55]
	v_mfma_f32_16x16x32_bf16 v[44:47], v[160:163], v[194:197], v[44:47]
	v_mfma_f32_16x16x32_bf16 v[36:39], v[152:155], v[202:205], v[36:39]
	v_mfma_f32_16x16x32_bf16 v[28:31], v[160:163], v[202:205], v[28:31]
	v_mfma_f32_16x16x32_bf16 v[20:23], v[152:155], v[210:213], v[20:23]
	v_mfma_f32_16x16x32_bf16 v[12:15], v[160:163], v[210:213], v[12:15]
	v_mfma_f32_16x16x32_bf16 v[60:63], v[156:159], v[190:193], v[60:63]
	v_mfma_f32_16x16x32_bf16 v[56:59], v[164:167], v[190:193], v[56:59]
	v_mfma_f32_16x16x32_bf16 v[52:55], v[156:159], v[198:201], v[52:55]
	v_mfma_f32_16x16x32_bf16 v[44:47], v[164:167], v[198:201], v[44:47]
	v_mfma_f32_16x16x32_bf16 v[36:39], v[156:159], v[206:209], v[36:39]
	v_mfma_f32_16x16x32_bf16 v[28:31], v[164:167], v[206:209], v[28:31]
	v_mfma_f32_16x16x32_bf16 v[20:23], v[156:159], v[214:217], v[20:23]
	v_mfma_f32_16x16x32_bf16 v[12:15], v[164:167], v[214:217], v[12:15]
	s_setprio 0
	s_setprio 1
	v_mfma_f32_16x16x32_bf16 v[48:51], v[168:171], v[184:187], v[48:51]
	v_mfma_f32_16x16x32_bf16 v[40:43], v[176:179], v[184:187], v[40:43]
	v_mfma_f32_16x16x32_bf16 v[32:35], v[168:171], v[194:197], v[32:35]
	v_mfma_f32_16x16x32_bf16 v[24:27], v[176:179], v[194:197], v[24:27]
	v_mfma_f32_16x16x32_bf16 v[16:19], v[168:171], v[202:205], v[16:19]
	v_mfma_f32_16x16x32_bf16 v[8:11], v[176:179], v[202:205], v[8:11]
	v_mfma_f32_16x16x32_bf16 v[4:7], v[168:171], v[210:213], v[4:7]
	v_mfma_f32_16x16x32_bf16 v[0:3], v[176:179], v[210:213], v[0:3]
	v_mfma_f32_16x16x32_bf16 v[48:51], v[172:175], v[190:193], v[48:51]
	v_mfma_f32_16x16x32_bf16 v[40:43], v[180:183], v[190:193], v[40:43]
	v_mfma_f32_16x16x32_bf16 v[32:35], v[172:175], v[198:201], v[32:35]
	v_mfma_f32_16x16x32_bf16 v[24:27], v[180:183], v[198:201], v[24:27]
	v_mfma_f32_16x16x32_bf16 v[16:19], v[172:175], v[206:209], v[16:19]
	v_mfma_f32_16x16x32_bf16 v[8:11], v[180:183], v[206:209], v[8:11]
	v_mfma_f32_16x16x32_bf16 v[4:7], v[172:175], v[214:217], v[4:7]
	v_mfma_f32_16x16x32_bf16 v[0:3], v[180:183], v[214:217], v[0:3]
	s_setprio 0
	s_barrier
	s_add_i32 s91, s91, 2
	s_add_u32 s89, s89, 0x100
	s_addc_u32 s90, s90, 0
	s_cmp_gt_u32 s91, 41
	s_mov_b64 s[46:47], s[50:51]
	s_cbranch_scc0 .LBB0_325
	s_and_b64 vcc, exec, s[10:11]
	s_cbranch_vccz .LBB0_328
	s_barrier

.LBB0_562:
	ds_read_b128 v[40:43], v187
	ds_read_b128 v[44:47], v187 offset:1024
	ds_read_b128 v[56:59], v187 offset:2048
	ds_read_b128 v[60:63], v187 offset:3072
	ds_read_b128 v[168:171], v190
	ds_read_b128 v[172:175], v190 offset:1024
	ds_read_b128 v[192:195], v190 offset:2048
	ds_read_b128 v[196:199], v190 offset:3072
	s_add_u32 s28, s8, 0xfffc0080
	s_addc_u32 s29, s9, -1
	s_cmp_eq_u32 s66, 12
	s_cselect_b32 s63, s7, s29
	s_cselect_b32 s62, s10, s28
	s_cselect_b32 s61, s47, s65
	s_cselect_b32 s60, s51, s64
	v_lshl_add_u64 v[232:233], s[8:9], 0, v[160:161]
	s_add_i32 m0, s82, 0xc000
	ds_read_b128 v[200:203], v191
	ds_read_b128 v[204:207], v191 offset:1024
	ds_read_b128 v[208:211], v191 offset:2048
	ds_read_b128 v[212:215], v191 offset:3072
	ds_read_b128 v[216:219], v191 offset:4096
	ds_read_b128 v[220:223], v191 offset:5120
	ds_read_b128 v[224:227], v191 offset:6144
	ds_read_b128 v[228:231], v191 offset:7168
	global_load_lds_dwordx4 v[232:233], off
	v_lshl_add_u64 v[232:233], s[8:9], 0, v[162:163]
	s_add_i32 m0, s82, 0xe000
	s_nop 0
	global_load_lds_dwordx4 v[232:233], off
	s_waitcnt vmcnt(8)
	s_waitcnt lgkmcnt(0)
	s_nop 0
	s_barrier
	s_setprio 1
	s_waitcnt lgkmcnt(0)
	v_mfma_f32_16x16x32_bf16 v[140:143], v[40:43], v[200:203], v[140:143]
	v_mfma_f32_16x16x32_bf16 v[136:139], v[56:59], v[200:203], v[136:139]
	v_mfma_f32_16x16x32_bf16 v[124:127], v[40:43], v[208:211], v[124:127]
	v_mfma_f32_16x16x32_bf16 v[120:123], v[56:59], v[208:211], v[120:123]
	v_mfma_f32_16x16x32_bf16 v[108:111], v[40:43], v[216:219], v[108:111]
	v_mfma_f32_16x16x32_bf16 v[104:107], v[56:59], v[216:219], v[104:107]
	v_mfma_f32_16x16x32_bf16 v[92:95], v[40:43], v[224:227], v[92:95]
	v_mfma_f32_16x16x32_bf16 v[88:91], v[56:59], v[224:227], v[88:91]
	v_mfma_f32_16x16x32_bf16 v[140:143], v[44:47], v[204:207], v[140:143]
	v_mfma_f32_16x16x32_bf16 v[136:139], v[60:63], v[204:207], v[136:139]
	v_mfma_f32_16x16x32_bf16 v[124:127], v[44:47], v[212:215], v[124:127]
	v_mfma_f32_16x16x32_bf16 v[120:123], v[60:63], v[212:215], v[120:123]
	v_mfma_f32_16x16x32_bf16 v[108:111], v[44:47], v[220:223], v[108:111]
	v_mfma_f32_16x16x32_bf16 v[104:107], v[60:63], v[220:223], v[104:107]
	v_mfma_f32_16x16x32_bf16 v[92:95], v[44:47], v[228:231], v[92:95]
	v_mfma_f32_16x16x32_bf16 v[88:91], v[60:63], v[228:231], v[88:91]
	s_setprio 0
	s_setprio 1
	v_mfma_f32_16x16x32_bf16 v[132:135], v[168:171], v[200:203], v[132:135]
	v_mfma_f32_16x16x32_bf16 v[128:131], v[192:195], v[200:203], v[128:131]
	v_mfma_f32_16x16x32_bf16 v[116:119], v[168:171], v[208:211], v[116:119]
	v_mfma_f32_16x16x32_bf16 v[112:115], v[192:195], v[208:211], v[112:115]
	v_mfma_f32_16x16x32_bf16 v[100:103], v[168:171], v[216:219], v[100:103]
	v_mfma_f32_16x16x32_bf16 v[96:99], v[192:195], v[216:219], v[96:99]
	v_mfma_f32_16x16x32_bf16 v[84:87], v[168:171], v[224:227], v[84:87]
	v_mfma_f32_16x16x32_bf16 v[80:83], v[192:195], v[224:227], v[80:83]
	v_mfma_f32_16x16x32_bf16 v[132:135], v[172:175], v[204:207], v[132:135]
	v_mfma_f32_16x16x32_bf16 v[128:131], v[196:199], v[204:207], v[128:131]
	v_mfma_f32_16x16x32_bf16 v[116:119], v[172:175], v[212:215], v[116:119]
	v_mfma_f32_16x16x32_bf16 v[112:115], v[196:199], v[212:215], v[112:115]
	v_mfma_f32_16x16x32_bf16 v[100:103], v[172:175], v[220:223], v[100:103]
	v_mfma_f32_16x16x32_bf16 v[96:99], v[196:199], v[220:223], v[96:99]
	v_mfma_f32_16x16x32_bf16 v[84:87], v[172:175], v[228:231], v[84:87]
	v_mfma_f32_16x16x32_bf16 v[80:83], v[196:199], v[228:231], v[80:83]
	s_setprio 0
	s_barrier
	s_add_i32 s28, s13, s41
	v_lshl_add_u64 v[232:233], s[60:61], 0, v[146:147]
	s_mov_b32 m0, s28
	ds_read_b128 v[200:203], v191 offset:16384
	ds_read_b128 v[204:207], v191 offset:17408
	ds_read_b128 v[208:211], v191 offset:18432
	ds_read_b128 v[212:215], v191 offset:19456
	ds_read_b128 v[216:219], v191 offset:20480
	ds_read_b128 v[220:223], v191 offset:21504
	ds_read_b128 v[224:227], v191 offset:22528
	ds_read_b128 v[228:231], v191 offset:23552
	global_load_lds_dwordx4 v[232:233], off
	s_add_i32 m0, s28, 0x2000
	s_add_u32 s28, s60, 0x40000
	v_lshl_add_u64 v[234:235], s[60:61], 0, v[150:151]
	s_addc_u32 s29, s61, 0
	s_add_i32 s33, s34, s41
	global_load_lds_dwordx4 v[234:235], off
	v_lshl_add_u64 v[236:237], s[28:29], 0, v[146:147]
	s_mov_b32 m0, s33
	v_lshl_add_u64 v[238:239], s[62:63], 0, v[148:149]
	global_load_lds_dwordx4 v[236:237], off
	v_lshl_add_u64 v[236:237], s[28:29], 0, v[150:151]
	s_add_i32 m0, s33, 0x2000
	s_nop 0
	global_load_lds_dwordx4 v[236:237], off
	v_lshl_add_u64 v[236:237], s[62:63], 0, v[144:145]
	s_mov_b32 m0, s82
	s_nop 0
	global_load_lds_dwordx4 v[236:237], off
	s_mov_b32 m0, s83
	s_nop 0
	global_load_lds_dwordx4 v[238:239], off
	s_waitcnt vmcnt(8)
	s_waitcnt lgkmcnt(0)
	s_nop 0
	s_barrier
	s_setprio 1
	s_waitcnt lgkmcnt(0)
	v_mfma_f32_16x16x32_bf16 v[76:79], v[40:43], v[200:203], v[76:79]
	v_mfma_f32_16x16x32_bf16 v[72:75], v[56:59], v[200:203], v[72:75]
	v_mfma_f32_16x16x32_bf16 v[52:55], v[40:43], v[208:211], v[52:55]
	v_mfma_f32_16x16x32_bf16 v[48:51], v[56:59], v[208:211], v[48:51]
	v_mfma_f32_16x16x32_bf16 v[28:31], v[40:43], v[216:219], v[28:31]
	v_mfma_f32_16x16x32_bf16 v[24:27], v[56:59], v[216:219], v[24:27]
	v_mfma_f32_16x16x32_bf16 v[12:15], v[40:43], v[224:227], v[12:15]
	v_mfma_f32_16x16x32_bf16 v[8:11], v[56:59], v[224:227], v[8:11]
	v_mfma_f32_16x16x32_bf16 v[76:79], v[44:47], v[204:207], v[76:79]
	v_mfma_f32_16x16x32_bf16 v[72:75], v[60:63], v[204:207], v[72:75]
	v_mfma_f32_16x16x32_bf16 v[52:55], v[44:47], v[212:215], v[52:55]
	v_mfma_f32_16x16x32_bf16 v[48:51], v[60:63], v[212:215], v[48:51]
	v_mfma_f32_16x16x32_bf16 v[28:31], v[44:47], v[220:223], v[28:31]
	v_mfma_f32_16x16x32_bf16 v[24:27], v[60:63], v[220:223], v[24:27]
	v_mfma_f32_16x16x32_bf16 v[12:15], v[44:47], v[228:231], v[12:15]
	v_mfma_f32_16x16x32_bf16 v[8:11], v[60:63], v[228:231], v[8:11]
	s_setprio 0
	s_setprio 1
	v_mfma_f32_16x16x32_bf16 v[36:39], v[168:171], v[208:211], v[36:39]
	v_mfma_f32_16x16x32_bf16 v[32:35], v[192:195], v[208:211], v[32:35]
	v_mfma_f32_16x16x32_bf16 v[20:23], v[168:171], v[216:219], v[20:23]
	v_mfma_f32_16x16x32_bf16 v[16:19], v[192:195], v[216:219], v[16:19]
	v_mfma_f32_16x16x32_bf16 v[4:7], v[168:171], v[224:227], v[4:7]
	v_mfma_f32_16x16x32_bf16 v[0:3], v[192:195], v[224:227], v[0:3]
	v_mfma_f32_16x16x32_bf16 v[40:43], v[168:171], v[200:203], v[68:71]
	v_mfma_f32_16x16x32_bf16 v[44:47], v[192:195], v[200:203], v[64:67]
	v_mfma_f32_16x16x32_bf16 v[36:39], v[172:175], v[212:215], v[36:39]
	v_mfma_f32_16x16x32_bf16 v[32:35], v[196:199], v[212:215], v[32:35]
	v_mfma_f32_16x16x32_bf16 v[20:23], v[172:175], v[220:223], v[20:23]
	v_mfma_f32_16x16x32_bf16 v[16:19], v[196:199], v[220:223], v[16:19]
	v_mfma_f32_16x16x32_bf16 v[4:7], v[172:175], v[228:231], v[4:7]
	v_mfma_f32_16x16x32_bf16 v[0:3], v[196:199], v[228:231], v[0:3]
	v_mfma_f32_16x16x32_bf16 v[40:43], v[172:175], v[204:207], v[40:43]
	v_mfma_f32_16x16x32_bf16 v[44:47], v[196:199], v[204:207], v[44:47]
	s_setprio 0
	s_barrier
	s_add_i32 s33, 0, 0x18000
	s_add_i32 s56, 0, 0x1c000
	v_add_u32_e32 v68, s33, v176
	v_add_u32_e32 v152, s56, v176
	ds_read_b128 v[56:59], v68
	ds_read_b128 v[60:63], v68 offset:1024
	ds_read_b128 v[64:67], v68 offset:2048
	ds_read_b128 v[68:71], v68 offset:3072
	ds_read_b128 v[168:171], v152
	ds_read_b128 v[172:175], v152 offset:1024
	ds_read_b128 v[192:195], v152 offset:2048
	ds_read_b128 v[196:199], v152 offset:3072
	s_add_u32 s28, s62, 0x40000
	s_addc_u32 s29, s63, 0
	s_mov_b32 m0, s92
	v_lshl_add_u64 v[240:241], s[28:29], 0, v[144:145]
	ds_read_b128 v[200:203], v191 offset:32768
	ds_read_b128 v[204:207], v191 offset:33792
	ds_read_b128 v[208:211], v191 offset:34816
	ds_read_b128 v[212:215], v191 offset:35840
	ds_read_b128 v[216:219], v191 offset:36864
	ds_read_b128 v[220:223], v191 offset:37888
	ds_read_b128 v[224:227], v191 offset:38912
	ds_read_b128 v[228:231], v191 offset:39936
	global_load_lds_dwordx4 v[240:241], off
	v_lshl_add_u64 v[240:241], s[28:29], 0, v[148:149]
	s_mov_b32 m0, s93
	s_nop 0
	global_load_lds_dwordx4 v[240:241], off
	s_waitcnt vmcnt(8)
	s_waitcnt lgkmcnt(0)
	s_nop 0
	s_barrier
	s_setprio 1
	s_waitcnt lgkmcnt(0)
	v_mfma_f32_16x16x32_bf16 v[140:143], v[56:59], v[200:203], v[140:143]
	v_mfma_f32_16x16x32_bf16 v[136:139], v[64:67], v[200:203], v[136:139]
	v_mfma_f32_16x16x32_bf16 v[124:127], v[56:59], v[208:211], v[124:127]
	v_mfma_f32_16x16x32_bf16 v[120:123], v[64:67], v[208:211], v[120:123]
	v_mfma_f32_16x16x32_bf16 v[108:111], v[56:59], v[216:219], v[108:111]
	v_mfma_f32_16x16x32_bf16 v[104:107], v[64:67], v[216:219], v[104:107]
	v_mfma_f32_16x16x32_bf16 v[92:95], v[56:59], v[224:227], v[92:95]
	v_mfma_f32_16x16x32_bf16 v[88:91], v[64:67], v[224:227], v[88:91]
	v_mfma_f32_16x16x32_bf16 v[140:143], v[60:63], v[204:207], v[140:143]
	v_mfma_f32_16x16x32_bf16 v[136:139], v[68:71], v[204:207], v[136:139]
	v_mfma_f32_16x16x32_bf16 v[124:127], v[60:63], v[212:215], v[124:127]
	v_mfma_f32_16x16x32_bf16 v[120:123], v[68:71], v[212:215], v[120:123]
	v_mfma_f32_16x16x32_bf16 v[108:111], v[60:63], v[220:223], v[108:111]
	v_mfma_f32_16x16x32_bf16 v[104:107], v[68:71], v[220:223], v[104:107]
	v_mfma_f32_16x16x32_bf16 v[92:95], v[60:63], v[228:231], v[92:95]
	v_mfma_f32_16x16x32_bf16 v[88:91], v[68:71], v[228:231], v[88:91]
	s_setprio 0
	s_setprio 1
	v_mfma_f32_16x16x32_bf16 v[132:135], v[168:171], v[200:203], v[132:135]
	v_mfma_f32_16x16x32_bf16 v[128:131], v[192:195], v[200:203], v[128:131]
	v_mfma_f32_16x16x32_bf16 v[116:119], v[168:171], v[208:211], v[116:119]
	v_mfma_f32_16x16x32_bf16 v[112:115], v[192:195], v[208:211], v[112:115]
	v_mfma_f32_16x16x32_bf16 v[100:103], v[168:171], v[216:219], v[100:103]
	v_mfma_f32_16x16x32_bf16 v[96:99], v[192:195], v[216:219], v[96:99]
	v_mfma_f32_16x16x32_bf16 v[84:87], v[168:171], v[224:227], v[84:87]
	v_mfma_f32_16x16x32_bf16 v[80:83], v[192:195], v[224:227], v[80:83]
	v_mfma_f32_16x16x32_bf16 v[132:135], v[172:175], v[204:207], v[132:135]
	v_mfma_f32_16x16x32_bf16 v[128:131], v[196:199], v[204:207], v[128:131]
	v_mfma_f32_16x16x32_bf16 v[116:119], v[172:175], v[212:215], v[116:119]
	v_mfma_f32_16x16x32_bf16 v[112:115], v[196:199], v[212:215], v[112:115]
	v_mfma_f32_16x16x32_bf16 v[100:103], v[172:175], v[220:223], v[100:103]
	v_mfma_f32_16x16x32_bf16 v[96:99], v[196:199], v[220:223], v[96:99]
	v_mfma_f32_16x16x32_bf16 v[84:87], v[172:175], v[228:231], v[84:87]
	v_mfma_f32_16x16x32_bf16 v[80:83], v[196:199], v[228:231], v[80:83]
	s_setprio 0
	s_barrier
	s_add_i32 s28, s33, s41
	v_lshl_add_u64 v[232:233], v[232:233], 0, s[16:17]
	s_mov_b32 m0, s28
	ds_read_b128 v[200:203], v191 offset:49152
	ds_read_b128 v[204:207], v191 offset:50176
	ds_read_b128 v[208:211], v191 offset:51200
	ds_read_b128 v[212:215], v191 offset:52224
	ds_read_b128 v[216:219], v191 offset:53248
	ds_read_b128 v[220:223], v191 offset:54272
	ds_read_b128 v[224:227], v191 offset:55296
	ds_read_b128 v[228:231], v191 offset:56320
	global_load_lds_dwordx4 v[232:233], off
	s_add_i32 m0, s28, 0x2000
	s_add_u32 s28, s60, 0x40080
	v_lshl_add_u64 v[232:233], v[234:235], 0, s[16:17]
	s_addc_u32 s29, s61, 0
	s_add_i32 s33, s56, s41
	global_load_lds_dwordx4 v[232:233], off
	v_lshl_add_u64 v[232:233], s[28:29], 0, v[146:147]
	s_mov_b32 m0, s33
	s_nop 0
	global_load_lds_dwordx4 v[232:233], off
	v_lshl_add_u64 v[232:233], s[28:29], 0, v[150:151]
	s_add_i32 m0, s33, 0x2000
	s_nop 0
	global_load_lds_dwordx4 v[232:233], off
	v_lshl_add_u64 v[232:233], v[236:237], 0, s[16:17]
	s_mov_b32 m0, s3
	s_nop 0
	global_load_lds_dwordx4 v[232:233], off
	v_lshl_add_u64 v[232:233], v[238:239], 0, s[16:17]
	s_mov_b32 m0, s78
	s_nop 0
	global_load_lds_dwordx4 v[232:233], off
	s_waitcnt vmcnt(8)
	s_waitcnt lgkmcnt(0)
	s_barrier
	s_setprio 1
	s_waitcnt lgkmcnt(0)
	v_mfma_f32_16x16x32_bf16 v[76:79], v[56:59], v[200:203], v[76:79]
	v_mfma_f32_16x16x32_bf16 v[72:75], v[64:67], v[200:203], v[72:75]
	v_mfma_f32_16x16x32_bf16 v[52:55], v[56:59], v[208:211], v[52:55]
	v_mfma_f32_16x16x32_bf16 v[48:51], v[64:67], v[208:211], v[48:51]
	v_mfma_f32_16x16x32_bf16 v[28:31], v[56:59], v[216:219], v[28:31]
	v_mfma_f32_16x16x32_bf16 v[24:27], v[64:67], v[216:219], v[24:27]
	v_mfma_f32_16x16x32_bf16 v[12:15], v[56:59], v[224:227], v[12:15]
	v_mfma_f32_16x16x32_bf16 v[8:11], v[64:67], v[224:227], v[8:11]
	v_mfma_f32_16x16x32_bf16 v[76:79], v[60:63], v[204:207], v[76:79]
	v_mfma_f32_16x16x32_bf16 v[72:75], v[68:71], v[204:207], v[72:75]
	v_mfma_f32_16x16x32_bf16 v[52:55], v[60:63], v[212:215], v[52:55]
	v_mfma_f32_16x16x32_bf16 v[48:51], v[68:71], v[212:215], v[48:51]
	v_mfma_f32_16x16x32_bf16 v[28:31], v[60:63], v[220:223], v[28:31]
	v_mfma_f32_16x16x32_bf16 v[24:27], v[68:71], v[220:223], v[24:27]
	v_mfma_f32_16x16x32_bf16 v[12:15], v[60:63], v[228:231], v[12:15]
	v_mfma_f32_16x16x32_bf16 v[8:11], v[68:71], v[228:231], v[8:11]
	s_setprio 0
	s_setprio 1
	v_mfma_f32_16x16x32_bf16 v[40:43], v[168:171], v[200:203], v[40:43]
	v_mfma_f32_16x16x32_bf16 v[68:71], v[172:175], v[204:207], v[40:43]
	v_mfma_f32_16x16x32_bf16 v[40:43], v[192:195], v[200:203], v[44:47]
	v_mfma_f32_16x16x32_bf16 v[36:39], v[168:171], v[208:211], v[36:39]
	v_mfma_f32_16x16x32_bf16 v[32:35], v[192:195], v[208:211], v[32:35]
	v_mfma_f32_16x16x32_bf16 v[20:23], v[168:171], v[216:219], v[20:23]
	v_mfma_f32_16x16x32_bf16 v[16:19], v[192:195], v[216:219], v[16:19]
	v_mfma_f32_16x16x32_bf16 v[4:7], v[168:171], v[224:227], v[4:7]
	v_mfma_f32_16x16x32_bf16 v[0:3], v[192:195], v[224:227], v[0:3]
	v_mfma_f32_16x16x32_bf16 v[64:67], v[196:199], v[204:207], v[40:43]
	v_mfma_f32_16x16x32_bf16 v[36:39], v[172:175], v[212:215], v[36:39]
	v_mfma_f32_16x16x32_bf16 v[32:35], v[196:199], v[212:215], v[32:35]
	v_mfma_f32_16x16x32_bf16 v[20:23], v[172:175], v[220:223], v[20:23]
	v_mfma_f32_16x16x32_bf16 v[16:19], v[196:199], v[220:223], v[16:19]
	v_mfma_f32_16x16x32_bf16 v[4:7], v[172:175], v[228:231], v[4:7]
	v_mfma_f32_16x16x32_bf16 v[0:3], v[196:199], v[228:231], v[0:3]
	s_setprio 0
	s_barrier
	s_add_i32 s66, s66, 2
	s_add_u32 s8, s8, 0x100
	s_addc_u32 s9, s9, 0
	s_add_u32 s64, s64, 0x100
	s_addc_u32 s65, s65, 0
	s_cmp_gt_u32 s66, 13
	s_cbranch_scc0 .LBB0_562
	s_and_b64 vcc, exec, s[18:19]
	s_cbranch_vccz .LBB0_565
	s_barrier

.LBB0_859:
	s_add_u32 s16, s10, s14
	ds_read_b128 v[82:85], v79
	ds_read_b128 v[86:89], v79 offset:1024
	ds_read_b128 v[90:93], v79 offset:2048
	ds_read_b128 v[94:97], v79 offset:3072
	s_addc_u32 s17, s11, s15
	s_add_u32 s16, s16, 0xb000100
	s_addc_u32 s17, s17, 0
	s_add_u32 s28, s63, s14
	s_addc_u32 s29, s64, s15
	s_cmpk_eq_i32 s14, 0x300
	s_cselect_b32 s19, s7, s17
	s_cselect_b32 s18, s6, s16
	s_cselect_b32 s17, s5, s29
	s_cselect_b32 s16, s4, s28
	s_mov_b32 m0, s66
	v_lshl_add_u64 v[130:131], v[72:73], 0, s[14:15]
	ds_read_b128 v[98:101], v80
	ds_read_b128 v[102:105], v80 offset:1024
	ds_read_b128 v[106:109], v80 offset:2048
	ds_read_b128 v[110:113], v80 offset:3072
	ds_read_b128 v[114:117], v80 offset:4096
	ds_read_b128 v[118:121], v80 offset:5120
	ds_read_b128 v[122:125], v80 offset:6144
	ds_read_b128 v[126:129], v80 offset:7168
	global_load_lds_dwordx4 v[130:131], off
	v_lshl_add_u64 v[130:131], v[74:75], 0, s[14:15]
	s_mov_b32 m0, s67
	s_nop 0
	global_load_lds_dwordx4 v[130:131], off
	s_waitcnt vmcnt(8)
	s_waitcnt lgkmcnt(0)
	s_barrier
	s_setprio 1
	s_waitcnt lgkmcnt(0)
	v_mfma_f32_16x16x32_bf16 v[60:63], v[82:85], v[98:101], v[60:63]
	v_mfma_f32_16x16x32_bf16 v[56:59], v[90:93], v[98:101], v[56:59]
	v_mfma_f32_16x16x32_bf16 v[52:55], v[82:85], v[106:109], v[52:55]
	v_mfma_f32_16x16x32_bf16 v[48:51], v[90:93], v[106:109], v[48:51]
	v_mfma_f32_16x16x32_bf16 v[44:47], v[82:85], v[114:117], v[44:47]
	v_mfma_f32_16x16x32_bf16 v[40:43], v[90:93], v[114:117], v[40:43]
	v_mfma_f32_16x16x32_bf16 v[36:39], v[82:85], v[122:125], v[36:39]
	v_mfma_f32_16x16x32_bf16 v[32:35], v[90:93], v[122:125], v[32:35]
	v_mfma_f32_16x16x32_bf16 v[60:63], v[86:89], v[102:105], v[60:63]
	v_mfma_f32_16x16x32_bf16 v[56:59], v[94:97], v[102:105], v[56:59]
	v_mfma_f32_16x16x32_bf16 v[52:55], v[86:89], v[110:113], v[52:55]
	v_mfma_f32_16x16x32_bf16 v[48:51], v[94:97], v[110:113], v[48:51]
	v_mfma_f32_16x16x32_bf16 v[44:47], v[86:89], v[118:121], v[44:47]
	v_mfma_f32_16x16x32_bf16 v[40:43], v[94:97], v[118:121], v[40:43]
	v_mfma_f32_16x16x32_bf16 v[36:39], v[86:89], v[126:129], v[36:39]
	v_mfma_f32_16x16x32_bf16 v[32:35], v[94:97], v[126:129], v[32:35]
	s_setprio 0
	s_setprio 1
	s_setprio 0
	s_barrier
	s_mov_b32 m0, s76
	v_lshl_add_u64 v[130:131], s[16:17], 0, v[68:69]
	s_add_u32 s28, s16, 0x20000
	ds_read_b128 v[98:101], v80 offset:16384
	ds_read_b128 v[102:105], v80 offset:17408
	ds_read_b128 v[106:109], v80 offset:18432
	ds_read_b128 v[110:113], v80 offset:19456
	ds_read_b128 v[114:117], v80 offset:20480
	ds_read_b128 v[118:121], v80 offset:21504
	ds_read_b128 v[122:125], v80 offset:22528
	ds_read_b128 v[126:129], v80 offset:23552
	global_load_lds_dwordx4 v[130:131], off
	v_lshl_add_u64 v[132:133], s[16:17], 0, v[64:65]
	s_mov_b32 m0, s77
	s_addc_u32 s29, s17, 0
	global_load_lds_dwordx4 v[132:133], off
	v_lshl_add_u64 v[134:135], s[28:29], 0, v[68:69]
	s_mov_b32 m0, s35
	v_lshl_add_u64 v[136:137], s[18:19], 0, v[66:67]
	global_load_lds_dwordx4 v[134:135], off
	v_lshl_add_u64 v[134:135], s[28:29], 0, v[64:65]
	s_mov_b32 m0, s46
	s_nop 0
	global_load_lds_dwordx4 v[134:135], off
	v_lshl_add_u64 v[134:135], s[18:19], 0, v[70:71]
	s_mov_b32 m0, s1
	s_nop 0
	global_load_lds_dwordx4 v[134:135], off
	s_mov_b32 m0, s51
	s_nop 0
	global_load_lds_dwordx4 v[136:137], off
	s_waitcnt vmcnt(8)
	s_waitcnt lgkmcnt(0)
	s_nop 0
	s_barrier
	s_setprio 1
	s_waitcnt lgkmcnt(0)
	v_mfma_f32_16x16x32_bf16 v[28:31], v[82:85], v[98:101], v[28:31]
	v_mfma_f32_16x16x32_bf16 v[24:27], v[90:93], v[98:101], v[24:27]
	v_mfma_f32_16x16x32_bf16 v[20:23], v[82:85], v[106:109], v[20:23]
	v_mfma_f32_16x16x32_bf16 v[16:19], v[90:93], v[106:109], v[16:19]
	v_mfma_f32_16x16x32_bf16 v[12:15], v[82:85], v[114:117], v[12:15]
	v_mfma_f32_16x16x32_bf16 v[8:11], v[90:93], v[114:117], v[8:11]
	v_mfma_f32_16x16x32_bf16 v[4:7], v[82:85], v[122:125], v[4:7]
	v_mfma_f32_16x16x32_bf16 v[0:3], v[90:93], v[122:125], v[0:3]
	v_mfma_f32_16x16x32_bf16 v[28:31], v[86:89], v[102:105], v[28:31]
	v_mfma_f32_16x16x32_bf16 v[24:27], v[94:97], v[102:105], v[24:27]
	v_mfma_f32_16x16x32_bf16 v[20:23], v[86:89], v[110:113], v[20:23]
	v_mfma_f32_16x16x32_bf16 v[16:19], v[94:97], v[110:113], v[16:19]
	v_mfma_f32_16x16x32_bf16 v[12:15], v[86:89], v[118:121], v[12:15]
	v_mfma_f32_16x16x32_bf16 v[8:11], v[94:97], v[118:121], v[8:11]
	v_mfma_f32_16x16x32_bf16 v[4:7], v[86:89], v[126:129], v[4:7]
	v_mfma_f32_16x16x32_bf16 v[0:3], v[94:97], v[126:129], v[0:3]
	s_setprio 0
	s_setprio 1
	s_setprio 0
	s_barrier
	ds_read_b128 v[82:85], v81
	ds_read_b128 v[86:89], v81 offset:1024
	ds_read_b128 v[90:93], v81 offset:2048
	ds_read_b128 v[94:97], v81 offset:3072
	s_add_u32 s18, s18, 0x28000
	s_addc_u32 s19, s19, 0
	s_mov_b32 m0, s52
	v_lshl_add_u64 v[138:139], s[18:19], 0, v[70:71]
	ds_read_b128 v[98:101], v80 offset:32768
	ds_read_b128 v[102:105], v80 offset:33792
	ds_read_b128 v[106:109], v80 offset:34816
	ds_read_b128 v[110:113], v80 offset:35840
	ds_read_b128 v[114:117], v80 offset:36864
	ds_read_b128 v[118:121], v80 offset:37888
	ds_read_b128 v[122:125], v80 offset:38912
	ds_read_b128 v[126:129], v80 offset:39936
	global_load_lds_dwordx4 v[138:139], off
	v_lshl_add_u64 v[138:139], s[18:19], 0, v[66:67]
	s_mov_b32 m0, s53
	s_nop 0
	global_load_lds_dwordx4 v[138:139], off
	s_waitcnt vmcnt(8)
	s_waitcnt lgkmcnt(0)
	s_nop 0
	s_barrier
	s_setprio 1
	s_waitcnt lgkmcnt(0)
	v_mfma_f32_16x16x32_bf16 v[60:63], v[82:85], v[98:101], v[60:63]
	v_mfma_f32_16x16x32_bf16 v[56:59], v[90:93], v[98:101], v[56:59]
	v_mfma_f32_16x16x32_bf16 v[52:55], v[82:85], v[106:109], v[52:55]
	v_mfma_f32_16x16x32_bf16 v[48:51], v[90:93], v[106:109], v[48:51]
	v_mfma_f32_16x16x32_bf16 v[44:47], v[82:85], v[114:117], v[44:47]
	v_mfma_f32_16x16x32_bf16 v[40:43], v[90:93], v[114:117], v[40:43]
	v_mfma_f32_16x16x32_bf16 v[36:39], v[82:85], v[122:125], v[36:39]
	v_mfma_f32_16x16x32_bf16 v[32:35], v[90:93], v[122:125], v[32:35]
	v_mfma_f32_16x16x32_bf16 v[60:63], v[86:89], v[102:105], v[60:63]
	v_mfma_f32_16x16x32_bf16 v[56:59], v[94:97], v[102:105], v[56:59]
	v_mfma_f32_16x16x32_bf16 v[52:55], v[86:89], v[110:113], v[52:55]
	v_mfma_f32_16x16x32_bf16 v[48:51], v[94:97], v[110:113], v[48:51]
	v_mfma_f32_16x16x32_bf16 v[44:47], v[86:89], v[118:121], v[44:47]
	v_mfma_f32_16x16x32_bf16 v[40:43], v[94:97], v[118:121], v[40:43]
	v_mfma_f32_16x16x32_bf16 v[36:39], v[86:89], v[126:129], v[36:39]
	v_mfma_f32_16x16x32_bf16 v[32:35], v[94:97], v[126:129], v[32:35]
	s_setprio 0
	s_setprio 1
	s_setprio 0
	s_barrier
	s_mov_b32 m0, s78
	v_lshl_add_u64 v[130:131], v[130:131], 0, s[8:9]
	s_add_u32 s16, s16, 0x20080
	ds_read_b128 v[98:101], v80 offset:49152
	ds_read_b128 v[102:105], v80 offset:50176
	ds_read_b128 v[106:109], v80 offset:51200
	ds_read_b128 v[110:113], v80 offset:52224
	ds_read_b128 v[114:117], v80 offset:53248
	ds_read_b128 v[118:121], v80 offset:54272
	ds_read_b128 v[122:125], v80 offset:55296
	ds_read_b128 v[126:129], v80 offset:56320
	global_load_lds_dwordx4 v[130:131], off
	v_lshl_add_u64 v[130:131], v[132:133], 0, s[8:9]
	s_mov_b32 m0, s79
	s_addc_u32 s17, s17, 0
	global_load_lds_dwordx4 v[130:131], off
	v_lshl_add_u64 v[130:131], s[16:17], 0, v[68:69]
	s_mov_b32 m0, s61
	s_nop 0
	global_load_lds_dwordx4 v[130:131], off
	v_lshl_add_u64 v[130:131], s[16:17], 0, v[64:65]
	s_mov_b32 m0, s62
	s_nop 0
	global_load_lds_dwordx4 v[130:131], off
	v_lshl_add_u64 v[130:131], v[134:135], 0, s[8:9]
	s_mov_b32 m0, s55
	s_nop 0
	global_load_lds_dwordx4 v[130:131], off
	v_lshl_add_u64 v[130:131], v[136:137], 0, s[8:9]
	s_mov_b32 m0, s60
	s_nop 0
	global_load_lds_dwordx4 v[130:131], off
	s_waitcnt vmcnt(8)
	s_waitcnt lgkmcnt(0)
	s_barrier
	s_setprio 1
	s_waitcnt lgkmcnt(0)
	v_mfma_f32_16x16x32_bf16 v[28:31], v[82:85], v[98:101], v[28:31]
	v_mfma_f32_16x16x32_bf16 v[24:27], v[90:93], v[98:101], v[24:27]
	v_mfma_f32_16x16x32_bf16 v[20:23], v[82:85], v[106:109], v[20:23]
	v_mfma_f32_16x16x32_bf16 v[16:19], v[90:93], v[106:109], v[16:19]
	v_mfma_f32_16x16x32_bf16 v[12:15], v[82:85], v[114:117], v[12:15]
	v_mfma_f32_16x16x32_bf16 v[8:11], v[90:93], v[114:117], v[8:11]
	v_mfma_f32_16x16x32_bf16 v[4:7], v[82:85], v[122:125], v[4:7]
	v_mfma_f32_16x16x32_bf16 v[0:3], v[90:93], v[122:125], v[0:3]
	v_mfma_f32_16x16x32_bf16 v[28:31], v[86:89], v[102:105], v[28:31]
	v_mfma_f32_16x16x32_bf16 v[24:27], v[94:97], v[102:105], v[24:27]
	v_mfma_f32_16x16x32_bf16 v[20:23], v[86:89], v[110:113], v[20:23]
	v_mfma_f32_16x16x32_bf16 v[16:19], v[94:97], v[110:113], v[16:19]
	v_mfma_f32_16x16x32_bf16 v[12:15], v[86:89], v[118:121], v[12:15]
	v_mfma_f32_16x16x32_bf16 v[8:11], v[94:97], v[118:121], v[8:11]
	v_mfma_f32_16x16x32_bf16 v[4:7], v[86:89], v[126:129], v[4:7]
	v_mfma_f32_16x16x32_bf16 v[0:3], v[94:97], v[126:129], v[0:3]
	s_setprio 0
	s_setprio 1
	s_setprio 0
	s_barrier
	s_add_i32 s65, s65, 2
	s_add_u32 s14, s14, 0x100
	s_addc_u32 s15, s15, 0
	s_cmp_lt_u32 s65, 6
	s_cbranch_scc1 .LBB0_859
	s_waitcnt vmcnt(0)
	s_cmpk_gt_u32 s13, 0xff
	s_cbranch_scc1 .LBB0_862
	s_barrier

.LBB0_871:
	s_add_u32 s33, s42, s52
	s_addc_u32 s56, s43, s53
	s_add_u32 s54, s33, 0x100
	s_addc_u32 s55, s56, 0
	s_and_b64 s[28:29], s[50:51], exec
	s_cselect_b32 s55, s81, s55
	s_cselect_b32 s54, s82, s54
	s_add_u32 s28, s18, s52
	s_addc_u32 s29, s19, s53
	s_add_u32 s52, s28, 0x100
	s_addc_u32 s53, s29, 0
	s_and_b64 s[28:29], s[50:51], exec
	s_cselect_b32 s61, s83, s53
	s_cselect_b32 s60, s84, s52
	s_add_u32 s64, s33, 0x20080
	ds_read_b128 v[128:131], v192
	ds_read_b128 v[132:135], v192 offset:1024
	ds_read_b128 v[136:139], v192 offset:2048
	ds_read_b128 v[140:143], v192 offset:3072
	ds_read_b128 v[144:147], v193
	ds_read_b128 v[148:151], v193 offset:1024
	ds_read_b128 v[152:155], v193 offset:2048
	ds_read_b128 v[156:159], v193 offset:3072
	s_addc_u32 s65, s56, 0
	s_add_i32 s97, s77, s13
	s_add_i32 s29, s1, 0xe000
	s_add_i32 s28, s97, 0x2000
	s_add_u32 s62, s60, 0x20000
	s_addc_u32 s63, s61, 0
	s_add_i32 vcc_hi, s78, s13
	s_add_i32 vcc_lo, vcc_hi, 0x2000
	s_add_i32 s96, 0, 0x18000
	s_add_i32 s95, 0, 0x1c000
	s_add_u32 s52, s54, 0x20000
	s_addc_u32 s53, s55, 0
	s_add_i32 s94, s96, s13
	s_add_i32 s92, s94, 0x2000
	s_add_u32 s50, s60, 0x20080
	s_addc_u32 s51, s61, 0
	s_add_i32 s93, s95, s13
	s_add_i32 s85, s93, 0x2000
	s_mov_b32 m0, s79
	v_lshl_add_u64 v[186:187], s[64:65], 0, v[166:167]
	ds_read_b128 v[196:199], v194
	ds_read_b128 v[200:203], v194 offset:1024
	ds_read_b128 v[204:207], v194 offset:2048
	ds_read_b128 v[208:211], v194 offset:3072
	ds_read_b128 v[212:215], v194 offset:4096
	ds_read_b128 v[216:219], v194 offset:5120
	ds_read_b128 v[220:223], v194 offset:6144
	ds_read_b128 v[224:227], v194 offset:7168
	global_load_lds_dwordx4 v[186:187], off
	v_lshl_add_u64 v[186:187], s[64:65], 0, v[162:163]
	s_mov_b32 m0, s29
	s_nop 0
	global_load_lds_dwordx4 v[186:187], off
	s_waitcnt vmcnt(8)
	s_waitcnt lgkmcnt(0)
	s_nop 0
	s_barrier
	s_setprio 1
	s_waitcnt lgkmcnt(0)
	v_mfma_f32_16x16x32_bf16 v[124:127], v[128:131], v[196:199], v[124:127]
	v_mfma_f32_16x16x32_bf16 v[120:123], v[136:139], v[196:199], v[120:123]
	v_mfma_f32_16x16x32_bf16 v[116:119], v[128:131], v[204:207], v[116:119]
	v_mfma_f32_16x16x32_bf16 v[112:115], v[136:139], v[204:207], v[112:115]
	v_mfma_f32_16x16x32_bf16 v[108:111], v[128:131], v[212:215], v[108:111]
	v_mfma_f32_16x16x32_bf16 v[96:99], v[136:139], v[212:215], v[96:99]
	v_mfma_f32_16x16x32_bf16 v[76:79], v[128:131], v[220:223], v[76:79]
	v_mfma_f32_16x16x32_bf16 v[72:75], v[136:139], v[220:223], v[72:75]
	v_mfma_f32_16x16x32_bf16 v[124:127], v[132:135], v[200:203], v[124:127]
	v_mfma_f32_16x16x32_bf16 v[120:123], v[140:143], v[200:203], v[120:123]
	v_mfma_f32_16x16x32_bf16 v[116:119], v[132:135], v[208:211], v[116:119]
	v_mfma_f32_16x16x32_bf16 v[112:115], v[140:143], v[208:211], v[112:115]
	v_mfma_f32_16x16x32_bf16 v[108:111], v[132:135], v[216:219], v[108:111]
	v_mfma_f32_16x16x32_bf16 v[96:99], v[140:143], v[216:219], v[96:99]
	v_mfma_f32_16x16x32_bf16 v[76:79], v[132:135], v[224:227], v[76:79]
	v_mfma_f32_16x16x32_bf16 v[72:75], v[140:143], v[224:227], v[72:75]
	s_setprio 0
	s_setprio 1
	v_mfma_f32_16x16x32_bf16 v[104:107], v[144:147], v[196:199], v[104:107]
	v_mfma_f32_16x16x32_bf16 v[100:103], v[152:155], v[196:199], v[100:103]
	v_mfma_f32_16x16x32_bf16 v[92:95], v[144:147], v[204:207], v[92:95]
	v_mfma_f32_16x16x32_bf16 v[88:91], v[152:155], v[204:207], v[88:91]
	v_mfma_f32_16x16x32_bf16 v[84:87], v[144:147], v[212:215], v[84:87]
	v_mfma_f32_16x16x32_bf16 v[80:83], v[152:155], v[212:215], v[80:83]
	v_mfma_f32_16x16x32_bf16 v[68:71], v[144:147], v[220:223], v[68:71]
	v_mfma_f32_16x16x32_bf16 v[64:67], v[152:155], v[220:223], v[64:67]
	v_mfma_f32_16x16x32_bf16 v[104:107], v[148:151], v[200:203], v[104:107]
	v_mfma_f32_16x16x32_bf16 v[100:103], v[156:159], v[200:203], v[100:103]
	v_mfma_f32_16x16x32_bf16 v[92:95], v[148:151], v[208:211], v[92:95]
	v_mfma_f32_16x16x32_bf16 v[88:91], v[156:159], v[208:211], v[88:91]
	v_mfma_f32_16x16x32_bf16 v[84:87], v[148:151], v[216:219], v[84:87]
	v_mfma_f32_16x16x32_bf16 v[80:83], v[156:159], v[216:219], v[80:83]
	v_mfma_f32_16x16x32_bf16 v[68:71], v[148:151], v[224:227], v[68:71]
	v_mfma_f32_16x16x32_bf16 v[64:67], v[156:159], v[224:227], v[64:67]
	s_setprio 0
	s_barrier
	s_mov_b32 m0, s97
	v_lshl_add_u64 v[186:187], s[60:61], 0, v[164:165]
	ds_read_b128 v[196:199], v194 offset:16384
	ds_read_b128 v[200:203], v194 offset:17408
	ds_read_b128 v[204:207], v194 offset:18432
	ds_read_b128 v[208:211], v194 offset:19456
	ds_read_b128 v[212:215], v194 offset:20480
	ds_read_b128 v[216:219], v194 offset:21504
	ds_read_b128 v[220:223], v194 offset:22528
	ds_read_b128 v[224:227], v194 offset:23552
	global_load_lds_dwordx4 v[186:187], off
	v_lshl_add_u64 v[228:229], s[60:61], 0, v[160:161]
	s_mov_b32 m0, s28
	v_lshl_add_u64 v[230:231], s[62:63], 0, v[164:165]
	global_load_lds_dwordx4 v[228:229], off
	s_mov_b32 m0, vcc_hi
	v_lshl_add_u64 v[232:233], s[54:55], 0, v[162:163]
	global_load_lds_dwordx4 v[230:231], off
	v_lshl_add_u64 v[230:231], s[62:63], 0, v[160:161]
	s_mov_b32 m0, vcc_lo
	s_nop 0
	global_load_lds_dwordx4 v[230:231], off
	v_lshl_add_u64 v[230:231], s[54:55], 0, v[166:167]
	s_mov_b32 m0, s1
	s_nop 0
	global_load_lds_dwordx4 v[230:231], off
	s_mov_b32 m0, s34
	s_nop 0
	global_load_lds_dwordx4 v[232:233], off
	s_waitcnt vmcnt(8)
	s_waitcnt lgkmcnt(0)
	s_barrier
	s_setprio 1
	s_waitcnt lgkmcnt(0)
	v_mfma_f32_16x16x32_bf16 v[60:63], v[128:131], v[196:199], v[60:63]
	v_mfma_f32_16x16x32_bf16 v[56:59], v[136:139], v[196:199], v[56:59]
	v_mfma_f32_16x16x32_bf16 v[48:51], v[128:131], v[204:207], v[48:51]
	v_mfma_f32_16x16x32_bf16 v[40:43], v[136:139], v[204:207], v[40:43]
	v_mfma_f32_16x16x32_bf16 v[32:35], v[128:131], v[212:215], v[32:35]
	v_mfma_f32_16x16x32_bf16 v[24:27], v[136:139], v[212:215], v[24:27]
	v_mfma_f32_16x16x32_bf16 v[16:19], v[128:131], v[220:223], v[16:19]
	v_mfma_f32_16x16x32_bf16 v[8:11], v[136:139], v[220:223], v[8:11]
	v_mfma_f32_16x16x32_bf16 v[60:63], v[132:135], v[200:203], v[60:63]
	v_mfma_f32_16x16x32_bf16 v[56:59], v[140:143], v[200:203], v[56:59]
	v_mfma_f32_16x16x32_bf16 v[48:51], v[132:135], v[208:211], v[48:51]
	v_mfma_f32_16x16x32_bf16 v[40:43], v[140:143], v[208:211], v[40:43]
	v_mfma_f32_16x16x32_bf16 v[32:35], v[132:135], v[216:219], v[32:35]
	v_mfma_f32_16x16x32_bf16 v[24:27], v[140:143], v[216:219], v[24:27]
	v_mfma_f32_16x16x32_bf16 v[16:19], v[132:135], v[224:227], v[16:19]
	v_mfma_f32_16x16x32_bf16 v[8:11], v[140:143], v[224:227], v[8:11]
	s_setprio 0
	s_setprio 1
	v_mfma_f32_16x16x32_bf16 v[52:55], v[144:147], v[196:199], v[52:55]
	v_mfma_f32_16x16x32_bf16 v[44:47], v[152:155], v[196:199], v[44:47]
	v_mfma_f32_16x16x32_bf16 v[36:39], v[144:147], v[204:207], v[36:39]
	v_mfma_f32_16x16x32_bf16 v[28:31], v[152:155], v[204:207], v[28:31]
	v_mfma_f32_16x16x32_bf16 v[20:23], v[144:147], v[212:215], v[20:23]
	v_mfma_f32_16x16x32_bf16 v[12:15], v[152:155], v[212:215], v[12:15]
	v_mfma_f32_16x16x32_bf16 v[4:7], v[144:147], v[220:223], v[4:7]
	v_mfma_f32_16x16x32_bf16 v[0:3], v[152:155], v[220:223], v[0:3]
	v_mfma_f32_16x16x32_bf16 v[52:55], v[148:151], v[200:203], v[52:55]
	v_mfma_f32_16x16x32_bf16 v[44:47], v[156:159], v[200:203], v[44:47]
	v_mfma_f32_16x16x32_bf16 v[36:39], v[148:151], v[208:211], v[36:39]
	v_mfma_f32_16x16x32_bf16 v[28:31], v[156:159], v[208:211], v[28:31]
	v_mfma_f32_16x16x32_bf16 v[20:23], v[148:151], v[216:219], v[20:23]
	v_mfma_f32_16x16x32_bf16 v[12:15], v[156:159], v[216:219], v[12:15]
	v_mfma_f32_16x16x32_bf16 v[4:7], v[148:151], v[224:227], v[4:7]
	v_mfma_f32_16x16x32_bf16 v[0:3], v[156:159], v[224:227], v[0:3]
	s_setprio 0
	s_barrier
	v_add_u32_e32 v140, s96, v190
	v_add_u32_e32 v156, s95, v190
	ds_read_b128 v[128:131], v140
	ds_read_b128 v[132:135], v140 offset:1024
	ds_read_b128 v[136:139], v140 offset:2048
	ds_read_b128 v[140:143], v140 offset:3072
	ds_read_b128 v[144:147], v156
	ds_read_b128 v[148:151], v156 offset:1024
	ds_read_b128 v[152:155], v156 offset:2048
	ds_read_b128 v[156:159], v156 offset:3072
	s_mov_b32 m0, s35
	v_lshl_add_u64 v[234:235], s[52:53], 0, v[166:167]
	ds_read_b128 v[196:199], v194 offset:32768
	ds_read_b128 v[200:203], v194 offset:33792
	ds_read_b128 v[204:207], v194 offset:34816
	ds_read_b128 v[208:211], v194 offset:35840
	ds_read_b128 v[212:215], v194 offset:36864
	ds_read_b128 v[216:219], v194 offset:37888
	ds_read_b128 v[220:223], v194 offset:38912
	ds_read_b128 v[224:227], v194 offset:39936
	global_load_lds_dwordx4 v[234:235], off
	v_lshl_add_u64 v[234:235], s[52:53], 0, v[162:163]
	s_mov_b32 m0, s66
	s_nop 0
	global_load_lds_dwordx4 v[234:235], off
	s_waitcnt vmcnt(8)
	s_waitcnt lgkmcnt(0)
	s_barrier
	s_setprio 1
	s_waitcnt lgkmcnt(0)
	v_mfma_f32_16x16x32_bf16 v[124:127], v[128:131], v[196:199], v[124:127]
	v_mfma_f32_16x16x32_bf16 v[120:123], v[136:139], v[196:199], v[120:123]
	v_mfma_f32_16x16x32_bf16 v[116:119], v[128:131], v[204:207], v[116:119]
	v_mfma_f32_16x16x32_bf16 v[112:115], v[136:139], v[204:207], v[112:115]
	v_mfma_f32_16x16x32_bf16 v[108:111], v[128:131], v[212:215], v[108:111]
	v_mfma_f32_16x16x32_bf16 v[96:99], v[136:139], v[212:215], v[96:99]
	v_mfma_f32_16x16x32_bf16 v[76:79], v[128:131], v[220:223], v[76:79]
	v_mfma_f32_16x16x32_bf16 v[72:75], v[136:139], v[220:223], v[72:75]
	v_mfma_f32_16x16x32_bf16 v[124:127], v[132:135], v[200:203], v[124:127]
	v_mfma_f32_16x16x32_bf16 v[120:123], v[140:143], v[200:203], v[120:123]
	v_mfma_f32_16x16x32_bf16 v[116:119], v[132:135], v[208:211], v[116:119]
	v_mfma_f32_16x16x32_bf16 v[112:115], v[140:143], v[208:211], v[112:115]
	v_mfma_f32_16x16x32_bf16 v[108:111], v[132:135], v[216:219], v[108:111]
	v_mfma_f32_16x16x32_bf16 v[96:99], v[140:143], v[216:219], v[96:99]
	v_mfma_f32_16x16x32_bf16 v[76:79], v[132:135], v[224:227], v[76:79]
	v_mfma_f32_16x16x32_bf16 v[72:75], v[140:143], v[224:227], v[72:75]
	s_setprio 0
	s_setprio 1
	v_mfma_f32_16x16x32_bf16 v[104:107], v[144:147], v[196:199], v[104:107]
	v_mfma_f32_16x16x32_bf16 v[100:103], v[152:155], v[196:199], v[100:103]
	v_mfma_f32_16x16x32_bf16 v[92:95], v[144:147], v[204:207], v[92:95]
	v_mfma_f32_16x16x32_bf16 v[88:91], v[152:155], v[204:207], v[88:91]
	v_mfma_f32_16x16x32_bf16 v[84:87], v[144:147], v[212:215], v[84:87]
	v_mfma_f32_16x16x32_bf16 v[80:83], v[152:155], v[212:215], v[80:83]
	v_mfma_f32_16x16x32_bf16 v[68:71], v[144:147], v[220:223], v[68:71]
	v_mfma_f32_16x16x32_bf16 v[64:67], v[152:155], v[220:223], v[64:67]
	v_mfma_f32_16x16x32_bf16 v[104:107], v[148:151], v[200:203], v[104:107]
	v_mfma_f32_16x16x32_bf16 v[100:103], v[156:159], v[200:203], v[100:103]
	v_mfma_f32_16x16x32_bf16 v[92:95], v[148:151], v[208:211], v[92:95]
	v_mfma_f32_16x16x32_bf16 v[88:91], v[156:159], v[208:211], v[88:91]
	v_mfma_f32_16x16x32_bf16 v[84:87], v[148:151], v[216:219], v[84:87]
	v_mfma_f32_16x16x32_bf16 v[80:83], v[156:159], v[216:219], v[80:83]
	v_mfma_f32_16x16x32_bf16 v[68:71], v[148:151], v[224:227], v[68:71]
	v_mfma_f32_16x16x32_bf16 v[64:67], v[156:159], v[224:227], v[64:67]
	s_setprio 0
	s_barrier
	s_mov_b32 m0, s94
	v_lshl_add_u64 v[186:187], v[186:187], 0, s[6:7]
	ds_read_b128 v[196:199], v194 offset:49152
	ds_read_b128 v[200:203], v194 offset:50176
	ds_read_b128 v[204:207], v194 offset:51200
	ds_read_b128 v[208:211], v194 offset:52224
	ds_read_b128 v[212:215], v194 offset:53248
	ds_read_b128 v[216:219], v194 offset:54272
	ds_read_b128 v[220:223], v194 offset:55296
	ds_read_b128 v[224:227], v194 offset:56320
	global_load_lds_dwordx4 v[186:187], off
	v_lshl_add_u64 v[186:187], v[228:229], 0, s[6:7]
	s_mov_b32 m0, s92
	s_nop 0
	global_load_lds_dwordx4 v[186:187], off
	v_lshl_add_u64 v[186:187], s[50:51], 0, v[164:165]
	s_mov_b32 m0, s93
	s_nop 0
	global_load_lds_dwordx4 v[186:187], off
	v_lshl_add_u64 v[186:187], s[50:51], 0, v[160:161]
	s_mov_b32 m0, s85
	s_nop 0
	global_load_lds_dwordx4 v[186:187], off
	v_lshl_add_u64 v[186:187], v[230:231], 0, s[6:7]
	s_mov_b32 m0, s67
	s_nop 0
	global_load_lds_dwordx4 v[186:187], off
	v_lshl_add_u64 v[186:187], v[232:233], 0, s[6:7]
	s_mov_b32 m0, s76
	s_nop 0
	global_load_lds_dwordx4 v[186:187], off
	s_waitcnt vmcnt(8)
	s_waitcnt lgkmcnt(0)
	s_barrier
	s_setprio 1
	s_waitcnt lgkmcnt(0)
	v_mfma_f32_16x16x32_bf16 v[60:63], v[128:131], v[196:199], v[60:63]
	v_mfma_f32_16x16x32_bf16 v[56:59], v[136:139], v[196:199], v[56:59]
	v_mfma_f32_16x16x32_bf16 v[48:51], v[128:131], v[204:207], v[48:51]
	v_mfma_f32_16x16x32_bf16 v[40:43], v[136:139], v[204:207], v[40:43]
	v_mfma_f32_16x16x32_bf16 v[32:35], v[128:131], v[212:215], v[32:35]
	v_mfma_f32_16x16x32_bf16 v[24:27], v[136:139], v[212:215], v[24:27]
	v_mfma_f32_16x16x32_bf16 v[16:19], v[128:131], v[220:223], v[16:19]
	v_mfma_f32_16x16x32_bf16 v[8:11], v[136:139], v[220:223], v[8:11]
	v_mfma_f32_16x16x32_bf16 v[60:63], v[132:135], v[200:203], v[60:63]
	v_mfma_f32_16x16x32_bf16 v[56:59], v[140:143], v[200:203], v[56:59]
	v_mfma_f32_16x16x32_bf16 v[48:51], v[132:135], v[208:211], v[48:51]
	v_mfma_f32_16x16x32_bf16 v[40:43], v[140:143], v[208:211], v[40:43]
	v_mfma_f32_16x16x32_bf16 v[32:35], v[132:135], v[216:219], v[32:35]
	v_mfma_f32_16x16x32_bf16 v[24:27], v[140:143], v[216:219], v[24:27]
	v_mfma_f32_16x16x32_bf16 v[16:19], v[132:135], v[224:227], v[16:19]
	v_mfma_f32_16x16x32_bf16 v[8:11], v[140:143], v[224:227], v[8:11]
	s_setprio 0
	s_setprio 1
	v_mfma_f32_16x16x32_bf16 v[52:55], v[144:147], v[196:199], v[52:55]
	v_mfma_f32_16x16x32_bf16 v[44:47], v[152:155], v[196:199], v[44:47]
	v_mfma_f32_16x16x32_bf16 v[36:39], v[144:147], v[204:207], v[36:39]
	v_mfma_f32_16x16x32_bf16 v[28:31], v[152:155], v[204:207], v[28:31]
	v_mfma_f32_16x16x32_bf16 v[20:23], v[144:147], v[212:215], v[20:23]
	v_mfma_f32_16x16x32_bf16 v[12:15], v[152:155], v[212:215], v[12:15]
	v_mfma_f32_16x16x32_bf16 v[4:7], v[144:147], v[220:223], v[4:7]
	v_mfma_f32_16x16x32_bf16 v[0:3], v[152:155], v[220:223], v[0:3]
	v_mfma_f32_16x16x32_bf16 v[52:55], v[148:151], v[200:203], v[52:55]
	v_mfma_f32_16x16x32_bf16 v[44:47], v[156:159], v[200:203], v[44:47]
	v_mfma_f32_16x16x32_bf16 v[36:39], v[148:151], v[208:211], v[36:39]
	v_mfma_f32_16x16x32_bf16 v[28:31], v[156:159], v[208:211], v[28:31]
	v_mfma_f32_16x16x32_bf16 v[20:23], v[148:151], v[216:219], v[20:23]
	v_mfma_f32_16x16x32_bf16 v[12:15], v[156:159], v[216:219], v[12:15]
	v_mfma_f32_16x16x32_bf16 v[4:7], v[148:151], v[224:227], v[4:7]
	v_mfma_f32_16x16x32_bf16 v[0:3], v[156:159], v[224:227], v[0:3]
	s_setprio 0
	s_barrier
	s_mov_b64 s[50:51], -1
	s_andn2_b64 vcc, exec, s[46:47]
	s_mov_b64 s[46:47], 0
	s_mov_b64 s[52:53], 0x100
	s_cbranch_vccz .LBB0_871
	v_or_b32_e32 v168, s80, v191
	v_readlane_b32 s48, v242, 16
	v_lshlrev_b64 v[136:137], 2, v[168:169]
	v_readlane_b32 s52, v242, 20
	v_readlane_b32 s53, v242, 21
	v_readlane_b32 s54, v242, 22
	v_readlane_b32 s55, v242, 23
	v_lshl_add_u64 v[128:129], s[52:53], 0, v[136:137]
	global_load_dwordx4 v[148:151], v[128:129], off
	global_load_dwordx4 v[144:147], v[128:129], off offset:16
	global_load_dwordx4 v[132:135], v[128:129], off offset:512
	s_nop 0
	global_load_dwordx4 v[128:131], v[128:129], off offset:528
	v_lshl_add_u64 v[136:137], s[54:55], 0, v[136:137]
	global_load_dwordx4 v[156:159], v[136:137], off
	global_load_dwordx4 v[152:155], v[136:137], off offset:16
	global_load_dwordx4 v[140:143], v[136:137], off offset:512
	s_nop 0
	global_load_dwordx4 v[136:139], v[136:137], off offset:528
	v_lshlrev_b64 v[186:187], 1, v[168:169]
	v_lshl_add_u64 v[196:197], v[170:171], 0, v[186:187]
	v_lshl_add_u64 v[198:199], v[172:173], 0, v[186:187]
	v_lshl_add_u64 v[200:201], v[174:175], 0, v[186:187]
	s_movk_i32 s80, 0x100
	s_and_b64 vcc, exec, s[14:15]
	s_mov_b64 s[18:19], s[10:11]
	s_mov_b64 s[42:43], s[16:17]
	v_readlane_b32 s49, v242, 17
	v_readlane_b32 s50, v242, 18
	v_readlane_b32 s51, v242, 19
	v_readlane_b32 s56, v242, 24
	v_readlane_b32 s57, v242, 25
	v_readlane_b32 s58, v242, 26
	v_readlane_b32 s59, v242, 27
	v_readlane_b32 s60, v242, 28
	v_readlane_b32 s61, v242, 29
	v_readlane_b32 s62, v242, 30
	v_readlane_b32 s63, v242, 31
	s_waitcnt vmcnt(0)
	v_pk_add_f32 v[126:127], v[126:127], v[150:151]
	v_pk_add_f32 v[124:125], v[124:125], v[148:149]
	v_pk_add_f32 v[122:123], v[122:123], v[146:147]
	v_pk_add_f32 v[120:121], v[120:121], v[144:145]
	v_pk_add_f32 v[82:83], v[82:83], v[130:131]
	v_pk_add_f32 v[80:81], v[80:81], v[128:129]
	v_pk_add_f32 v[106:107], v[106:107], v[134:135]
	v_pk_add_f32 v[104:105], v[104:105], v[132:133]
	v_pk_add_f32 v[102:103], v[102:103], v[130:131]
	v_pk_add_f32 v[100:101], v[100:101], v[128:129]
	v_pk_mul_f32 v[126:127], v[158:159], v[126:127]
	v_pk_mul_f32 v[124:125], v[156:157], v[124:125]
	v_pk_mul_f32 v[122:123], v[154:155], v[122:123]
	v_pk_mul_f32 v[120:121], v[152:153], v[120:121]
	v_pk_mul_f32 v[202:203], v[138:139], v[82:83]
	v_pk_mul_f32 v[204:205], v[136:137], v[80:81]
	v_cvt_pk_bf16_f32 v80, v124, v125
	v_cvt_pk_bf16_f32 v81, v126, v127
	v_cvt_pk_bf16_f32 v82, v120, v121
	v_cvt_pk_bf16_f32 v83, v122, v123
	v_pk_add_f32 v[118:119], v[118:119], v[150:151]
	v_pk_add_f32 v[116:117], v[116:117], v[148:149]
	v_pk_add_f32 v[114:115], v[114:115], v[146:147]
	v_pk_add_f32 v[112:113], v[112:113], v[144:145]
	v_pk_mul_f32 v[106:107], v[142:143], v[106:107]
	v_pk_mul_f32 v[104:105], v[140:141], v[104:105]
	v_pk_mul_f32 v[102:103], v[138:139], v[102:103]
	v_pk_mul_f32 v[100:101], v[136:137], v[100:101]
	global_store_dwordx4 v[196:197], v[80:83], off
	v_pk_add_f32 v[94:95], v[94:95], v[134:135]
	v_pk_add_f32 v[92:93], v[92:93], v[132:133]
	v_cvt_pk_bf16_f32 v80, v104, v105
	v_cvt_pk_bf16_f32 v81, v106, v107
	v_cvt_pk_bf16_f32 v82, v100, v101
	v_cvt_pk_bf16_f32 v83, v102, v103
	v_pk_add_f32 v[90:91], v[90:91], v[130:131]
	v_pk_add_f32 v[88:89], v[88:89], v[128:129]
	v_pk_mul_f32 v[118:119], v[158:159], v[118:119]
	v_pk_mul_f32 v[116:117], v[156:157], v[116:117]
	v_pk_mul_f32 v[114:115], v[154:155], v[114:115]
	v_pk_mul_f32 v[112:113], v[152:153], v[112:113]
	global_store_dwordx4 v[196:197], v[80:83], off offset:256
	v_pk_add_f32 v[110:111], v[110:111], v[150:151]
	v_pk_add_f32 v[108:109], v[108:109], v[148:149]
	v_cvt_pk_bf16_f32 v80, v116, v117
	v_cvt_pk_bf16_f32 v81, v118, v119
	v_cvt_pk_bf16_f32 v82, v112, v113
	v_cvt_pk_bf16_f32 v83, v114, v115
	v_pk_add_f32 v[98:99], v[98:99], v[146:147]
	v_pk_add_f32 v[96:97], v[96:97], v[144:145]
	v_pk_mul_f32 v[94:95], v[142:143], v[94:95]
	v_pk_mul_f32 v[92:93], v[140:141], v[92:93]
	v_pk_mul_f32 v[90:91], v[138:139], v[90:91]
	v_pk_mul_f32 v[88:89], v[136:137], v[88:89]
	global_store_dwordx4 v[198:199], v[80:83], off
	v_pk_add_f32 v[86:87], v[86:87], v[134:135]
	v_pk_add_f32 v[84:85], v[84:85], v[132:133]
	v_cvt_pk_bf16_f32 v80, v92, v93
	v_cvt_pk_bf16_f32 v81, v94, v95
	v_cvt_pk_bf16_f32 v82, v88, v89
	v_cvt_pk_bf16_f32 v83, v90, v91
	v_pk_mul_f32 v[110:111], v[158:159], v[110:111]
	v_pk_mul_f32 v[108:109], v[156:157], v[108:109]
	v_pk_mul_f32 v[98:99], v[154:155], v[98:99]
	v_pk_mul_f32 v[96:97], v[152:153], v[96:97]
	global_store_dwordx4 v[198:199], v[80:83], off offset:256
	v_pk_mul_f32 v[86:87], v[142:143], v[86:87]
	v_pk_mul_f32 v[84:85], v[140:141], v[84:85]
	v_cvt_pk_bf16_f32 v80, v108, v109
	v_cvt_pk_bf16_f32 v81, v110, v111
	v_cvt_pk_bf16_f32 v82, v96, v97
	v_cvt_pk_bf16_f32 v83, v98, v99
	global_store_dwordx4 v[200:201], v[80:83], off
	v_pk_add_f32 v[78:79], v[78:79], v[150:151]
	v_pk_add_f32 v[76:77], v[76:77], v[148:149]
	v_cvt_pk_bf16_f32 v80, v84, v85
	v_cvt_pk_bf16_f32 v81, v86, v87
	v_cvt_pk_bf16_f32 v82, v204, v205
	v_cvt_pk_bf16_f32 v83, v202, v203
	v_pk_add_f32 v[74:75], v[74:75], v[146:147]
	v_pk_add_f32 v[72:73], v[72:73], v[144:145]
	global_store_dwordx4 v[200:201], v[80:83], off offset:256
	v_pk_mul_f32 v[78:79], v[158:159], v[78:79]
	v_pk_mul_f32 v[76:77], v[156:157], v[76:77]
	v_lshl_add_u64 v[80:81], v[176:177], 0, v[186:187]
	v_pk_mul_f32 v[82:83], v[154:155], v[74:75]
	v_pk_mul_f32 v[74:75], v[152:153], v[72:73]
	v_cvt_pk_bf16_f32 v72, v76, v77
	v_cvt_pk_bf16_f32 v73, v78, v79
	v_pk_add_f32 v[66:67], v[66:67], v[130:131]
	v_pk_add_f32 v[64:65], v[64:65], v[128:129]
	v_cvt_pk_bf16_f32 v74, v74, v75
	v_cvt_pk_bf16_f32 v75, v82, v83
	global_store_dwordx4 v[80:81], v[72:75], off
	v_pk_add_f32 v[70:71], v[70:71], v[134:135]
	v_pk_add_f32 v[68:69], v[68:69], v[132:133]
	v_pk_mul_f32 v[72:73], v[138:139], v[66:67]
	v_pk_mul_f32 v[66:67], v[136:137], v[64:65]
	v_pk_mul_f32 v[70:71], v[142:143], v[70:71]
	v_pk_mul_f32 v[68:69], v[140:141], v[68:69]
	v_pk_add_f32 v[62:63], v[62:63], v[150:151]
	v_cvt_pk_bf16_f32 v64, v68, v69
	v_cvt_pk_bf16_f32 v65, v70, v71
	v_cvt_pk_bf16_f32 v66, v66, v67
	v_cvt_pk_bf16_f32 v67, v72, v73
	v_pk_add_f32 v[60:61], v[60:61], v[148:149]
	v_pk_add_f32 v[58:59], v[58:59], v[146:147]
	v_pk_add_f32 v[56:57], v[56:57], v[144:145]
	global_store_dwordx4 v[80:81], v[64:67], off offset:256
	v_pk_mul_f32 v[62:63], v[158:159], v[62:63]
	v_pk_mul_f32 v[60:61], v[156:157], v[60:61]
	v_lshl_add_u64 v[64:65], v[178:179], 0, v[186:187]
	v_pk_mul_f32 v[66:67], v[154:155], v[58:59]
	v_pk_mul_f32 v[58:59], v[152:153], v[56:57]
	v_cvt_pk_bf16_f32 v56, v60, v61
	v_cvt_pk_bf16_f32 v57, v62, v63
	v_pk_add_f32 v[46:47], v[46:47], v[130:131]
	v_pk_add_f32 v[44:45], v[44:45], v[128:129]
	v_cvt_pk_bf16_f32 v58, v58, v59
	v_cvt_pk_bf16_f32 v59, v66, v67
	global_store_dwordx4 v[64:65], v[56:59], off
	v_pk_add_f32 v[54:55], v[54:55], v[134:135]
	v_pk_add_f32 v[52:53], v[52:53], v[132:133]
	v_pk_mul_f32 v[56:57], v[138:139], v[46:47]
	v_pk_mul_f32 v[46:47], v[136:137], v[44:45]
	v_pk_mul_f32 v[54:55], v[142:143], v[54:55]
	v_pk_mul_f32 v[52:53], v[140:141], v[52:53]
	v_pk_add_f32 v[48:49], v[48:49], v[148:149]
	v_cvt_pk_bf16_f32 v44, v52, v53
	v_cvt_pk_bf16_f32 v45, v54, v55
	v_cvt_pk_bf16_f32 v46, v46, v47
	v_cvt_pk_bf16_f32 v47, v56, v57
	global_store_dwordx4 v[64:65], v[44:47], off offset:256
	v_pk_add_f32 v[42:43], v[42:43], v[146:147]
	v_pk_add_f32 v[40:41], v[40:41], v[144:145]
	v_pk_add_f32 v[46:47], v[50:51], v[150:151]
	v_lshl_add_u64 v[44:45], v[180:181], 0, v[186:187]
	v_pk_mul_f32 v[46:47], v[158:159], v[46:47]
	v_pk_mul_f32 v[48:49], v[156:157], v[48:49]
	v_pk_mul_f32 v[50:51], v[154:155], v[42:43]
	v_pk_mul_f32 v[42:43], v[152:153], v[40:41]
	v_cvt_pk_bf16_f32 v40, v48, v49
	v_cvt_pk_bf16_f32 v41, v46, v47
	v_pk_add_f32 v[30:31], v[30:31], v[130:131]
	v_pk_add_f32 v[28:29], v[28:29], v[128:129]
	v_cvt_pk_bf16_f32 v42, v42, v43
	v_cvt_pk_bf16_f32 v43, v50, v51
	global_store_dwordx4 v[44:45], v[40:43], off
	v_pk_add_f32 v[38:39], v[38:39], v[134:135]
	v_pk_add_f32 v[36:37], v[36:37], v[132:133]
	v_pk_mul_f32 v[40:41], v[138:139], v[30:31]
	v_pk_mul_f32 v[30:31], v[136:137], v[28:29]
	v_pk_mul_f32 v[38:39], v[142:143], v[38:39]
	v_pk_mul_f32 v[36:37], v[140:141], v[36:37]
	v_pk_add_f32 v[32:33], v[32:33], v[148:149]
	v_cvt_pk_bf16_f32 v28, v36, v37
	v_cvt_pk_bf16_f32 v29, v38, v39
	v_cvt_pk_bf16_f32 v30, v30, v31
	v_cvt_pk_bf16_f32 v31, v40, v41
	global_store_dwordx4 v[44:45], v[28:31], off offset:256
	v_pk_add_f32 v[26:27], v[26:27], v[146:147]
	v_pk_add_f32 v[24:25], v[24:25], v[144:145]
	v_pk_add_f32 v[30:31], v[34:35], v[150:151]
	v_lshl_add_u64 v[28:29], v[182:183], 0, v[186:187]
	v_pk_mul_f32 v[30:31], v[158:159], v[30:31]
	v_pk_mul_f32 v[32:33], v[156:157], v[32:33]
	v_pk_mul_f32 v[34:35], v[154:155], v[26:27]
	v_pk_mul_f32 v[26:27], v[152:153], v[24:25]
	v_cvt_pk_bf16_f32 v24, v32, v33
	v_cvt_pk_bf16_f32 v25, v30, v31
	v_pk_add_f32 v[14:15], v[14:15], v[130:131]
	v_pk_add_f32 v[12:13], v[12:13], v[128:129]
	v_cvt_pk_bf16_f32 v26, v26, v27
	v_cvt_pk_bf16_f32 v27, v34, v35
	global_store_dwordx4 v[28:29], v[24:27], off
	v_pk_add_f32 v[22:23], v[22:23], v[134:135]
	v_pk_add_f32 v[20:21], v[20:21], v[132:133]
	v_pk_mul_f32 v[24:25], v[138:139], v[14:15]
	v_pk_mul_f32 v[14:15], v[136:137], v[12:13]
	v_pk_mul_f32 v[22:23], v[142:143], v[22:23]
	v_pk_mul_f32 v[20:21], v[140:141], v[20:21]
	v_pk_add_f32 v[16:17], v[16:17], v[148:149]
	v_cvt_pk_bf16_f32 v12, v20, v21
	v_cvt_pk_bf16_f32 v13, v22, v23
	v_cvt_pk_bf16_f32 v14, v14, v15
	v_cvt_pk_bf16_f32 v15, v24, v25
	global_store_dwordx4 v[28:29], v[12:15], off offset:256
	v_pk_add_f32 v[10:11], v[10:11], v[146:147]
	v_pk_add_f32 v[8:9], v[8:9], v[144:145]
	v_pk_add_f32 v[14:15], v[18:19], v[150:151]
	v_lshl_add_u64 v[12:13], v[184:185], 0, v[186:187]
	v_pk_mul_f32 v[14:15], v[158:159], v[14:15]
	v_pk_mul_f32 v[16:17], v[156:157], v[16:17]
	v_pk_mul_f32 v[18:19], v[154:155], v[10:11]
	v_pk_mul_f32 v[10:11], v[152:153], v[8:9]
	v_cvt_pk_bf16_f32 v8, v16, v17
	v_cvt_pk_bf16_f32 v9, v14, v15
	v_pk_add_f32 v[2:3], v[2:3], v[130:131]
	v_pk_add_f32 v[0:1], v[0:1], v[128:129]
	v_cvt_pk_bf16_f32 v10, v10, v11
	v_cvt_pk_bf16_f32 v11, v18, v19
	global_store_dwordx4 v[12:13], v[8:11], off
	v_pk_add_f32 v[6:7], v[6:7], v[134:135]
	v_pk_add_f32 v[4:5], v[4:5], v[132:133]
	v_pk_mul_f32 v[8:9], v[138:139], v[2:3]
	v_pk_mul_f32 v[2:3], v[136:137], v[0:1]
	v_pk_mul_f32 v[6:7], v[142:143], v[6:7]
	v_pk_mul_f32 v[4:5], v[140:141], v[4:5]
	s_nop 0
	v_cvt_pk_bf16_f32 v0, v4, v5
	v_cvt_pk_bf16_f32 v1, v6, v7
	v_cvt_pk_bf16_f32 v2, v2, v3
	v_cvt_pk_bf16_f32 v3, v8, v9
	global_store_dwordx4 v[12:13], v[0:3], off offset:256
	s_cbranch_vccz .LBB0_870
	s_waitcnt vmcnt(0)
	s_cmpk_gt_u32 s12, 0xff
	s_cbranch_scc1 .LBB0_875
	s_barrier

.LBB0_932:
	ds_read_b128 v[148:151], v131
	ds_read_b128 v[152:155], v131 offset:1024
	ds_read_b128 v[156:159], v131 offset:2048
	ds_read_b128 v[160:163], v131 offset:3072
	ds_read_b128 v[164:167], v136
	ds_read_b128 v[168:171], v136 offset:1024
	ds_read_b128 v[172:175], v136 offset:2048
	ds_read_b128 v[176:179], v136 offset:3072
	s_add_u32 s18, s14, s16
	s_addc_u32 s19, s15, s17
	s_add_u32 s18, s18, 0xb000100
	s_addc_u32 s19, s19, 0
	s_add_u32 s28, s27, s16
	s_addc_u32 s29, s52, s17
	s_cmpk_eq_i32 s16, 0x400
	s_cselect_b32 s41, s7, s19
	s_cselect_b32 s40, s6, s18
	s_cselect_b32 s19, s1, s29
	s_cselect_b32 s18, s0, s28
	s_mov_b32 m0, s54
	v_lshl_add_u64 v[214:215], v[120:121], 0, s[16:17]
	ds_read_b128 v[180:183], v137
	ds_read_b128 v[184:187], v137 offset:1024
	ds_read_b128 v[190:193], v137 offset:2048
	ds_read_b128 v[194:197], v137 offset:3072
	ds_read_b128 v[198:201], v137 offset:4096
	ds_read_b128 v[202:205], v137 offset:5120
	ds_read_b128 v[206:209], v137 offset:6144
	ds_read_b128 v[210:213], v137 offset:7168
	global_load_lds_dwordx4 v[214:215], off
	v_lshl_add_u64 v[214:215], v[122:123], 0, s[16:17]
	s_mov_b32 m0, s55
	s_nop 0
	global_load_lds_dwordx4 v[214:215], off
	s_waitcnt vmcnt(8)
	s_waitcnt lgkmcnt(0)
	s_barrier
	s_setprio 1
	s_waitcnt lgkmcnt(0)
	v_mfma_f32_16x16x32_bf16 v[144:147], v[148:151], v[180:183], v[144:147]
	v_mfma_f32_16x16x32_bf16 v[140:143], v[156:159], v[180:183], v[140:143]
	v_mfma_f32_16x16x32_bf16 v[132:135], v[148:151], v[190:193], v[132:135]
	v_mfma_f32_16x16x32_bf16 v[124:127], v[156:159], v[190:193], v[124:127]
	v_mfma_f32_16x16x32_bf16 v[116:119], v[148:151], v[198:201], v[116:119]
	v_mfma_f32_16x16x32_bf16 v[112:115], v[156:159], v[198:201], v[112:115]
	v_mfma_f32_16x16x32_bf16 v[100:103], v[148:151], v[206:209], v[100:103]
	v_mfma_f32_16x16x32_bf16 v[96:99], v[156:159], v[206:209], v[96:99]
	v_mfma_f32_16x16x32_bf16 v[144:147], v[152:155], v[184:187], v[144:147]
	v_mfma_f32_16x16x32_bf16 v[140:143], v[160:163], v[184:187], v[140:143]
	v_mfma_f32_16x16x32_bf16 v[132:135], v[152:155], v[194:197], v[132:135]
	v_mfma_f32_16x16x32_bf16 v[124:127], v[160:163], v[194:197], v[124:127]
	v_mfma_f32_16x16x32_bf16 v[116:119], v[152:155], v[202:205], v[116:119]
	v_mfma_f32_16x16x32_bf16 v[112:115], v[160:163], v[202:205], v[112:115]
	v_mfma_f32_16x16x32_bf16 v[100:103], v[152:155], v[210:213], v[100:103]
	v_mfma_f32_16x16x32_bf16 v[96:99], v[160:163], v[210:213], v[96:99]
	s_setprio 0
	s_setprio 1
	v_mfma_f32_16x16x32_bf16 v[60:63], v[164:167], v[180:183], v[60:63]
	v_mfma_f32_16x16x32_bf16 v[56:59], v[172:175], v[180:183], v[56:59]
	v_mfma_f32_16x16x32_bf16 v[52:55], v[164:167], v[190:193], v[52:55]
	v_mfma_f32_16x16x32_bf16 v[48:51], v[172:175], v[190:193], v[48:51]
	v_mfma_f32_16x16x32_bf16 v[44:47], v[164:167], v[198:201], v[44:47]
	v_mfma_f32_16x16x32_bf16 v[40:43], v[172:175], v[198:201], v[40:43]
	v_mfma_f32_16x16x32_bf16 v[36:39], v[164:167], v[206:209], v[36:39]
	v_mfma_f32_16x16x32_bf16 v[32:35], v[172:175], v[206:209], v[32:35]
	v_mfma_f32_16x16x32_bf16 v[60:63], v[168:171], v[184:187], v[60:63]
	v_mfma_f32_16x16x32_bf16 v[56:59], v[176:179], v[184:187], v[56:59]
	v_mfma_f32_16x16x32_bf16 v[52:55], v[168:171], v[194:197], v[52:55]
	v_mfma_f32_16x16x32_bf16 v[48:51], v[176:179], v[194:197], v[48:51]
	v_mfma_f32_16x16x32_bf16 v[44:47], v[168:171], v[202:205], v[44:47]
	v_mfma_f32_16x16x32_bf16 v[40:43], v[176:179], v[202:205], v[40:43]
	v_mfma_f32_16x16x32_bf16 v[36:39], v[168:171], v[210:213], v[36:39]
	v_mfma_f32_16x16x32_bf16 v[32:35], v[176:179], v[210:213], v[32:35]
	s_setprio 0
	s_barrier
	s_mov_b32 m0, s56
	v_lshl_add_u64 v[214:215], s[18:19], 0, v[108:109]
	s_add_u32 s28, s18, 0x28000
	ds_read_b128 v[180:183], v137 offset:16384
	ds_read_b128 v[184:187], v137 offset:17408
	ds_read_b128 v[190:193], v137 offset:18432
	ds_read_b128 v[194:197], v137 offset:19456
	ds_read_b128 v[198:201], v137 offset:20480
	ds_read_b128 v[202:205], v137 offset:21504
	ds_read_b128 v[206:209], v137 offset:22528
	ds_read_b128 v[210:213], v137 offset:23552
	global_load_lds_dwordx4 v[214:215], off
	v_lshl_add_u64 v[216:217], s[18:19], 0, v[104:105]
	s_mov_b32 m0, s57
	s_addc_u32 s29, s19, 0
	global_load_lds_dwordx4 v[216:217], off
	v_lshl_add_u64 v[218:219], s[28:29], 0, v[108:109]
	s_mov_b32 m0, s58
	v_lshl_add_u64 v[220:221], s[40:41], 0, v[106:107]
	global_load_lds_dwordx4 v[218:219], off
	v_lshl_add_u64 v[218:219], s[28:29], 0, v[104:105]
	s_mov_b32 m0, s59
	s_nop 0
	global_load_lds_dwordx4 v[218:219], off
	v_lshl_add_u64 v[218:219], s[40:41], 0, v[110:111]
	s_mov_b32 m0, s34
	s_nop 0
	global_load_lds_dwordx4 v[218:219], off
	s_mov_b32 m0, s35
	s_nop 0
	global_load_lds_dwordx4 v[220:221], off
	s_waitcnt vmcnt(8)
	s_waitcnt lgkmcnt(0)
	s_nop 0
	s_barrier
	s_setprio 1
	s_waitcnt lgkmcnt(0)
	v_mfma_f32_16x16x32_bf16 v[92:95], v[148:151], v[180:183], v[92:95]
	v_mfma_f32_16x16x32_bf16 v[88:91], v[156:159], v[180:183], v[88:91]
	v_mfma_f32_16x16x32_bf16 v[84:87], v[148:151], v[190:193], v[84:87]
	v_mfma_f32_16x16x32_bf16 v[80:83], v[156:159], v[190:193], v[80:83]
	v_mfma_f32_16x16x32_bf16 v[76:79], v[148:151], v[198:201], v[76:79]
	v_mfma_f32_16x16x32_bf16 v[72:75], v[156:159], v[198:201], v[72:75]
	v_mfma_f32_16x16x32_bf16 v[68:71], v[148:151], v[206:209], v[68:71]
	v_mfma_f32_16x16x32_bf16 v[64:67], v[156:159], v[206:209], v[64:67]
	v_mfma_f32_16x16x32_bf16 v[92:95], v[152:155], v[184:187], v[92:95]
	v_mfma_f32_16x16x32_bf16 v[88:91], v[160:163], v[184:187], v[88:91]
	v_mfma_f32_16x16x32_bf16 v[84:87], v[152:155], v[194:197], v[84:87]
	v_mfma_f32_16x16x32_bf16 v[80:83], v[160:163], v[194:197], v[80:83]
	v_mfma_f32_16x16x32_bf16 v[76:79], v[152:155], v[202:205], v[76:79]
	v_mfma_f32_16x16x32_bf16 v[72:75], v[160:163], v[202:205], v[72:75]
	v_mfma_f32_16x16x32_bf16 v[68:71], v[152:155], v[210:213], v[68:71]
	v_mfma_f32_16x16x32_bf16 v[64:67], v[160:163], v[210:213], v[64:67]
	s_setprio 0
	s_setprio 1
	v_mfma_f32_16x16x32_bf16 v[28:31], v[164:167], v[180:183], v[28:31]
	v_mfma_f32_16x16x32_bf16 v[24:27], v[172:175], v[180:183], v[24:27]
	v_mfma_f32_16x16x32_bf16 v[20:23], v[164:167], v[190:193], v[20:23]
	v_mfma_f32_16x16x32_bf16 v[16:19], v[172:175], v[190:193], v[16:19]
	v_mfma_f32_16x16x32_bf16 v[12:15], v[164:167], v[198:201], v[12:15]
	v_mfma_f32_16x16x32_bf16 v[8:11], v[172:175], v[198:201], v[8:11]
	v_mfma_f32_16x16x32_bf16 v[4:7], v[164:167], v[206:209], v[4:7]
	v_mfma_f32_16x16x32_bf16 v[0:3], v[172:175], v[206:209], v[0:3]
	v_mfma_f32_16x16x32_bf16 v[28:31], v[168:171], v[184:187], v[28:31]
	v_mfma_f32_16x16x32_bf16 v[24:27], v[176:179], v[184:187], v[24:27]
	v_mfma_f32_16x16x32_bf16 v[20:23], v[168:171], v[194:197], v[20:23]
	v_mfma_f32_16x16x32_bf16 v[16:19], v[176:179], v[194:197], v[16:19]
	v_mfma_f32_16x16x32_bf16 v[12:15], v[168:171], v[202:205], v[12:15]
	v_mfma_f32_16x16x32_bf16 v[8:11], v[176:179], v[202:205], v[8:11]
	v_mfma_f32_16x16x32_bf16 v[4:7], v[168:171], v[210:213], v[4:7]
	v_mfma_f32_16x16x32_bf16 v[0:3], v[176:179], v[210:213], v[0:3]
	s_setprio 0
	s_barrier
	ds_read_b128 v[148:151], v138
	ds_read_b128 v[152:155], v138 offset:1024
	ds_read_b128 v[156:159], v138 offset:2048
	ds_read_b128 v[160:163], v138 offset:3072
	ds_read_b128 v[164:167], v139
	ds_read_b128 v[168:171], v139 offset:1024
	ds_read_b128 v[172:175], v139 offset:2048
	ds_read_b128 v[176:179], v139 offset:3072
	s_add_u32 s28, s40, 0x28000
	s_addc_u32 s29, s41, 0
	s_mov_b32 m0, s42
	v_lshl_add_u64 v[222:223], s[28:29], 0, v[110:111]
	ds_read_b128 v[180:183], v137 offset:32768
	ds_read_b128 v[184:187], v137 offset:33792
	ds_read_b128 v[190:193], v137 offset:34816
	ds_read_b128 v[194:197], v137 offset:35840
	ds_read_b128 v[198:201], v137 offset:36864
	ds_read_b128 v[202:205], v137 offset:37888
	ds_read_b128 v[206:209], v137 offset:38912
	ds_read_b128 v[210:213], v137 offset:39936
	global_load_lds_dwordx4 v[222:223], off
	v_lshl_add_u64 v[222:223], s[28:29], 0, v[106:107]
	s_mov_b32 m0, s43
	s_nop 0
	global_load_lds_dwordx4 v[222:223], off
	s_waitcnt vmcnt(8)
	s_waitcnt lgkmcnt(0)
	s_nop 0
	s_barrier
	s_setprio 1
	s_waitcnt lgkmcnt(0)
	v_mfma_f32_16x16x32_bf16 v[144:147], v[148:151], v[180:183], v[144:147]
	v_mfma_f32_16x16x32_bf16 v[140:143], v[156:159], v[180:183], v[140:143]
	v_mfma_f32_16x16x32_bf16 v[132:135], v[148:151], v[190:193], v[132:135]
	v_mfma_f32_16x16x32_bf16 v[124:127], v[156:159], v[190:193], v[124:127]
	v_mfma_f32_16x16x32_bf16 v[116:119], v[148:151], v[198:201], v[116:119]
	v_mfma_f32_16x16x32_bf16 v[112:115], v[156:159], v[198:201], v[112:115]
	v_mfma_f32_16x16x32_bf16 v[100:103], v[148:151], v[206:209], v[100:103]
	v_mfma_f32_16x16x32_bf16 v[96:99], v[156:159], v[206:209], v[96:99]
	v_mfma_f32_16x16x32_bf16 v[144:147], v[152:155], v[184:187], v[144:147]
	v_mfma_f32_16x16x32_bf16 v[140:143], v[160:163], v[184:187], v[140:143]
	v_mfma_f32_16x16x32_bf16 v[132:135], v[152:155], v[194:197], v[132:135]
	v_mfma_f32_16x16x32_bf16 v[124:127], v[160:163], v[194:197], v[124:127]
	v_mfma_f32_16x16x32_bf16 v[116:119], v[152:155], v[202:205], v[116:119]
	v_mfma_f32_16x16x32_bf16 v[112:115], v[160:163], v[202:205], v[112:115]
	v_mfma_f32_16x16x32_bf16 v[100:103], v[152:155], v[210:213], v[100:103]
	v_mfma_f32_16x16x32_bf16 v[96:99], v[160:163], v[210:213], v[96:99]
	s_setprio 0
	s_setprio 1
	v_mfma_f32_16x16x32_bf16 v[60:63], v[164:167], v[180:183], v[60:63]
	v_mfma_f32_16x16x32_bf16 v[56:59], v[172:175], v[180:183], v[56:59]
	v_mfma_f32_16x16x32_bf16 v[52:55], v[164:167], v[190:193], v[52:55]
	v_mfma_f32_16x16x32_bf16 v[48:51], v[172:175], v[190:193], v[48:51]
	v_mfma_f32_16x16x32_bf16 v[44:47], v[164:167], v[198:201], v[44:47]
	v_mfma_f32_16x16x32_bf16 v[40:43], v[172:175], v[198:201], v[40:43]
	v_mfma_f32_16x16x32_bf16 v[36:39], v[164:167], v[206:209], v[36:39]
	v_mfma_f32_16x16x32_bf16 v[32:35], v[172:175], v[206:209], v[32:35]
	v_mfma_f32_16x16x32_bf16 v[60:63], v[168:171], v[184:187], v[60:63]
	v_mfma_f32_16x16x32_bf16 v[56:59], v[176:179], v[184:187], v[56:59]
	v_mfma_f32_16x16x32_bf16 v[52:55], v[168:171], v[194:197], v[52:55]
	v_mfma_f32_16x16x32_bf16 v[48:51], v[176:179], v[194:197], v[48:51]
	v_mfma_f32_16x16x32_bf16 v[44:47], v[168:171], v[202:205], v[44:47]
	v_mfma_f32_16x16x32_bf16 v[40:43], v[176:179], v[202:205], v[40:43]
	v_mfma_f32_16x16x32_bf16 v[36:39], v[168:171], v[210:213], v[36:39]
	v_mfma_f32_16x16x32_bf16 v[32:35], v[176:179], v[210:213], v[32:35]
	s_setprio 0
	s_barrier
	s_mov_b32 m0, s60
	v_lshl_add_u64 v[214:215], v[214:215], 0, s[10:11]
	s_add_u32 s18, s18, 0x28080
	ds_read_b128 v[180:183], v137 offset:49152
	ds_read_b128 v[184:187], v137 offset:50176
	ds_read_b128 v[190:193], v137 offset:51200
	ds_read_b128 v[194:197], v137 offset:52224
	ds_read_b128 v[198:201], v137 offset:53248
	ds_read_b128 v[202:205], v137 offset:54272
	ds_read_b128 v[206:209], v137 offset:55296
	ds_read_b128 v[210:213], v137 offset:56320
	global_load_lds_dwordx4 v[214:215], off
	v_lshl_add_u64 v[214:215], v[216:217], 0, s[10:11]
	s_mov_b32 m0, s61
	s_addc_u32 s19, s19, 0
	global_load_lds_dwordx4 v[214:215], off
	v_lshl_add_u64 v[214:215], s[18:19], 0, v[108:109]
	s_mov_b32 m0, s62
	s_nop 0
	global_load_lds_dwordx4 v[214:215], off
	v_lshl_add_u64 v[214:215], s[18:19], 0, v[104:105]
	s_mov_b32 m0, s63
	s_nop 0
	global_load_lds_dwordx4 v[214:215], off
	v_lshl_add_u64 v[214:215], v[218:219], 0, s[10:11]
	s_mov_b32 m0, s50
	s_nop 0
	global_load_lds_dwordx4 v[214:215], off
	v_lshl_add_u64 v[214:215], v[220:221], 0, s[10:11]
	s_mov_b32 m0, s51
	s_nop 0
	global_load_lds_dwordx4 v[214:215], off
	s_waitcnt vmcnt(8)
	s_waitcnt lgkmcnt(0)
	s_barrier
	s_setprio 1
	s_waitcnt lgkmcnt(0)
	v_mfma_f32_16x16x32_bf16 v[92:95], v[148:151], v[180:183], v[92:95]
	v_mfma_f32_16x16x32_bf16 v[88:91], v[156:159], v[180:183], v[88:91]
	v_mfma_f32_16x16x32_bf16 v[84:87], v[148:151], v[190:193], v[84:87]
	v_mfma_f32_16x16x32_bf16 v[80:83], v[156:159], v[190:193], v[80:83]
	v_mfma_f32_16x16x32_bf16 v[76:79], v[148:151], v[198:201], v[76:79]
	v_mfma_f32_16x16x32_bf16 v[72:75], v[156:159], v[198:201], v[72:75]
	v_mfma_f32_16x16x32_bf16 v[68:71], v[148:151], v[206:209], v[68:71]
	v_mfma_f32_16x16x32_bf16 v[64:67], v[156:159], v[206:209], v[64:67]
	v_mfma_f32_16x16x32_bf16 v[92:95], v[152:155], v[184:187], v[92:95]
	v_mfma_f32_16x16x32_bf16 v[88:91], v[160:163], v[184:187], v[88:91]
	v_mfma_f32_16x16x32_bf16 v[84:87], v[152:155], v[194:197], v[84:87]
	v_mfma_f32_16x16x32_bf16 v[80:83], v[160:163], v[194:197], v[80:83]
	v_mfma_f32_16x16x32_bf16 v[76:79], v[152:155], v[202:205], v[76:79]
	v_mfma_f32_16x16x32_bf16 v[72:75], v[160:163], v[202:205], v[72:75]
	v_mfma_f32_16x16x32_bf16 v[68:71], v[152:155], v[210:213], v[68:71]
	v_mfma_f32_16x16x32_bf16 v[64:67], v[160:163], v[210:213], v[64:67]
	s_setprio 0
	s_setprio 1
	v_mfma_f32_16x16x32_bf16 v[28:31], v[164:167], v[180:183], v[28:31]
	v_mfma_f32_16x16x32_bf16 v[24:27], v[172:175], v[180:183], v[24:27]
	v_mfma_f32_16x16x32_bf16 v[20:23], v[164:167], v[190:193], v[20:23]
	v_mfma_f32_16x16x32_bf16 v[16:19], v[172:175], v[190:193], v[16:19]
	v_mfma_f32_16x16x32_bf16 v[12:15], v[164:167], v[198:201], v[12:15]
	v_mfma_f32_16x16x32_bf16 v[8:11], v[172:175], v[198:201], v[8:11]
	v_mfma_f32_16x16x32_bf16 v[4:7], v[164:167], v[206:209], v[4:7]
	v_mfma_f32_16x16x32_bf16 v[0:3], v[172:175], v[206:209], v[0:3]
	v_mfma_f32_16x16x32_bf16 v[28:31], v[168:171], v[184:187], v[28:31]
	v_mfma_f32_16x16x32_bf16 v[24:27], v[176:179], v[184:187], v[24:27]
	v_mfma_f32_16x16x32_bf16 v[20:23], v[168:171], v[194:197], v[20:23]
	v_mfma_f32_16x16x32_bf16 v[16:19], v[176:179], v[194:197], v[16:19]
	v_mfma_f32_16x16x32_bf16 v[12:15], v[168:171], v[202:205], v[12:15]
	v_mfma_f32_16x16x32_bf16 v[8:11], v[176:179], v[202:205], v[8:11]
	v_mfma_f32_16x16x32_bf16 v[4:7], v[168:171], v[210:213], v[4:7]
	v_mfma_f32_16x16x32_bf16 v[0:3], v[176:179], v[210:213], v[0:3]
	s_setprio 0
	s_barrier
	s_add_i32 s53, s53, 2
	s_add_u32 s16, s16, 0x100
	s_addc_u32 s17, s17, 0
	s_cmp_gt_u32 s53, 7
	s_cbranch_scc0 .LBB0_932
	v_lshl_or_b32 v104, s13, 8, v129
	v_or_b32_e32 v167, s47, v104
	v_lshlrev_b32_e32 v160, 1, v167
	v_mov_b32_e32 v161, 0
	v_lshl_add_u32 v166, s12, 8, v128
	v_lshl_add_u64 v[120:121], s[38:39], 0, v[160:161]
	s_movk_i32 s1, 0x500
	s_lshl_b32 s40, s3, 4
	v_readlane_b32 s48, v242, 40
	v_mad_i64_i32 v[104:105], s[6:7], v166, s1, v[120:121]
	s_ashr_i32 s41, s40, 31
	v_readlane_b32 s56, v242, 48
	v_readlane_b32 s57, v242, 49
	s_lshl_b32 s3, s3, 15
	s_lshl_b64 s[6:7], s[40:41], 2
	s_mov_b64 s[12:13], s[56:57]
	v_and_b32_e32 v177, 8, v130
	global_load_dwordx4 v[178:181], v[104:105], off
	s_add_u32 s42, s12, s6
	s_addc_u32 s43, s13, s7
	v_lshlrev_b32_e32 v168, 2, v177
	global_load_dwordx4 v[108:111], v168, s[42:43]
	global_load_dwordx4 v[104:107], v168, s[42:43] offset:16
	v_lshlrev_b32_e32 v122, 5, v166
	s_mov_b32 s12, 0xbf3a00e3
	v_or_b32_e32 v176, 16, v166
	v_or_b32_e32 v175, 32, v166
	v_or_b32_e32 v174, 48, v166
	v_add_u32_e32 v173, 0x80, v166
	v_add_u32_e32 v172, 0x90, v166
	v_add_u32_e32 v171, 0xa0, v166
	v_add_u32_e32 v170, 0xb0, v166
	v_subrev_u32_e32 v169, s3, v122
	v_lshrrev_b32_e32 v122, 4, v167
	v_mov_b64_e32 v[162:163], s[12:13]
	v_or_b32_e32 v164, v169, v122
	v_mad_i64_i32 v[122:123], s[12:13], v176, s1, v[120:121]
	v_mad_i64_i32 v[128:129], s[12:13], v175, s1, v[120:121]
	v_mad_i64_i32 v[130:131], s[12:13], v174, s1, v[120:121]
	v_mad_i64_i32 v[136:137], s[12:13], v173, s1, v[120:121]
	v_mad_i64_i32 v[138:139], s[12:13], v172, s1, v[120:121]
	v_mad_i64_i32 v[186:187], s[12:13], v171, s1, v[120:121]
	v_mad_i64_i32 v[120:121], s[12:13], v170, s1, v[120:121]
	global_load_dwordx4 v[182:185], v[122:123], off
	global_load_dwordx4 v[156:159], v[128:129], off
	global_load_dwordx4 v[152:155], v[130:131], off
	global_load_dwordx4 v[148:151], v[136:137], off
	s_nop 0
	global_load_dwordx4 v[136:139], v[138:139], off
	s_nop 0
	global_load_dwordx4 v[128:131], v[186:187], off
	s_nop 0
	global_load_dwordx4 v[120:123], v[120:121], off
	s_mov_b32 s10, 0x3e6d3388
	v_readlane_b32 s60, v242, 52
	v_readlane_b32 s61, v242, 53
	s_mov_b64 s[16:17], s[60:61]
	s_mov_b32 s0, 0x3f07dc22
	s_mov_b32 s18, 0xbf38aa3b
	s_mov_b32 s16, 0x3f35f0e3
	s_mov_b32 s6, 0xbe11a98e
	s_mov_b32 s14, 0x3e027906
	s_lshl_b64 s[40:41], s[40:41], 1
	s_cmpk_lt_u32 s46, 0x100
	v_readlane_b32 s49, v242, 41
	v_readlane_b32 s50, v242, 42
	v_readlane_b32 s51, v242, 43
	v_readlane_b32 s52, v242, 44
	v_readlane_b32 s53, v242, 45
	v_readlane_b32 s54, v242, 46
	v_readlane_b32 s55, v242, 47
	v_readlane_b32 s58, v242, 50
	v_readlane_b32 s59, v242, 51
	v_readlane_b32 s62, v242, 54
	v_readlane_b32 s63, v242, 55
	s_waitcnt vmcnt(0)
	v_lshlrev_b32_e32 v186, 16, v178
	v_and_b32_e32 v187, 0xffff0000, v178
	v_lshlrev_b32_e32 v178, 16, v179
	v_and_b32_e32 v179, 0xffff0000, v179
	v_pk_fma_f32 v[144:145], v[108:109], v[186:187], v[144:145]
	v_pk_fma_f32 v[146:147], v[110:111], v[178:179], v[146:147]
	v_and_b32_e32 v179, 0x7fffffff, v145
	v_and_b32_e32 v178, 0x7fffffff, v144
	v_pk_fma_f32 v[178:179], v[178:179], s[10:11], 1.0 op_sel_hi:[1,0,0]
	v_pk_mul_f32 v[186:187], v[144:145], v[144:145]
	v_rcp_f32_e32 v178, v178
	v_rcp_f32_e32 v179, v179
	v_lshlrev_b32_e32 v190, 16, v180
	v_and_b32_e32 v191, 0xffff0000, v180
	v_pk_mul_f32 v[186:187], v[186:187], s[18:19] op_sel_hi:[1,0]
	v_pk_fma_f32 v[192:193], v[178:179], s[0:1], v[162:163] op_sel_hi:[1,0,0]
	v_pk_fma_f32 v[140:141], v[104:105], v[190:191], v[140:141]
	v_and_b32_e32 v191, 0x7fffffff, v147
	v_and_b32_e32 v190, 0x7fffffff, v146
	v_exp_f32_e32 v186, v186
	v_exp_f32_e32 v187, v187
	v_pk_fma_f32 v[192:193], v[178:179], v[192:193], s[16:17] op_sel_hi:[1,1,0]
	v_pk_fma_f32 v[190:191], v[190:191], s[10:11], 1.0 op_sel_hi:[1,0,0]
	v_pk_fma_f32 v[192:193], v[178:179], v[192:193], s[6:7] op_sel_hi:[1,1,0]
	v_rcp_f32_e32 v190, v190
	v_rcp_f32_e32 v191, v191
	v_pk_fma_f32 v[192:193], v[178:179], v[192:193], s[14:15] op_sel_hi:[1,1,0]
	v_lshlrev_b32_e32 v180, 16, v181
	v_pk_mul_f32 v[178:179], v[178:179], v[192:193]
	v_and_b32_e32 v181, 0xffff0000, v181
	v_pk_mul_f32 v[178:179], v[186:187], v[178:179]
	v_pk_fma_f32 v[142:143], v[106:107], v[180:181], v[142:143]
	v_pk_mul_f32 v[180:181], v[146:147], v[146:147]
	v_pk_mul_f32 v[186:187], v[144:145], v[178:179]
	v_pk_fma_f32 v[178:179], v[144:145], v[178:179], v[144:145] neg_lo:[1,0,0] neg_hi:[1,0,0]
	v_cmp_gt_f32_e32 vcc, 0, v144
	v_pk_fma_f32 v[194:195], v[190:191], s[0:1], v[162:163] op_sel_hi:[1,0,0]
	s_nop 0
	v_cndmask_b32_e32 v160, v178, v186, vcc
	v_cmp_gt_f32_e32 vcc, 0, v145
	v_pk_mul_f32 v[144:145], v[180:181], s[18:19] op_sel_hi:[1,0]
	v_pk_fma_f32 v[194:195], v[190:191], v[194:195], s[16:17] op_sel_hi:[1,1,0]
	v_exp_f32_e32 v144, v144
	v_exp_f32_e32 v145, v145
	v_cndmask_b32_e32 v165, v179, v187, vcc
	v_pk_fma_f32 v[178:179], v[190:191], v[194:195], s[6:7] op_sel_hi:[1,1,0]
	v_and_b32_e32 v181, 0x7fffffff, v141
	v_and_b32_e32 v180, 0x7fffffff, v140
	v_pk_fma_f32 v[178:179], v[190:191], v[178:179], s[14:15] op_sel_hi:[1,1,0]
	v_pk_fma_f32 v[180:181], v[180:181], s[10:11], 1.0 op_sel_hi:[1,0,0]
	v_pk_mul_f32 v[178:179], v[190:191], v[178:179]
	v_rcp_f32_e32 v180, v180
	v_rcp_f32_e32 v181, v181
	v_pk_mul_f32 v[144:145], v[144:145], v[178:179]
	v_cmp_gt_f32_e32 vcc, 0, v146
	v_pk_mul_f32 v[178:179], v[146:147], v[144:145]
	v_pk_fma_f32 v[144:145], v[146:147], v[144:145], v[146:147] neg_lo:[1,0,0] neg_hi:[1,0,0]
	s_nop 0
	v_cndmask_b32_e32 v186, v144, v178, vcc
	v_cmp_gt_f32_e32 vcc, 0, v147
	v_pk_mul_f32 v[146:147], v[140:141], v[140:141]
	s_nop 0
	v_cndmask_b32_e32 v187, v145, v179, vcc
	v_pk_fma_f32 v[144:145], v[180:181], s[0:1], v[162:163] op_sel_hi:[1,0,0]
	v_pk_mul_f32 v[146:147], v[146:147], s[18:19] op_sel_hi:[1,0]
	v_pk_fma_f32 v[144:145], v[180:181], v[144:145], s[16:17] op_sel_hi:[1,1,0]
	v_exp_f32_e32 v146, v146
	v_pk_fma_f32 v[144:145], v[180:181], v[144:145], s[6:7] op_sel_hi:[1,1,0]
	v_exp_f32_e32 v147, v147
	v_pk_fma_f32 v[144:145], v[180:181], v[144:145], s[14:15] op_sel_hi:[1,1,0]
	v_cmp_gt_f32_e32 vcc, 0, v140
	v_pk_mul_f32 v[144:145], v[180:181], v[144:145]
	v_and_b32_e32 v181, 0x7fffffff, v143
	v_and_b32_e32 v180, 0x7fffffff, v142
	v_pk_fma_f32 v[180:181], v[180:181], s[10:11], 1.0 op_sel_hi:[1,0,0]
	v_pk_mul_f32 v[144:145], v[146:147], v[144:145]
	v_rcp_f32_e32 v180, v180
	v_rcp_f32_e32 v181, v181
	v_pk_mul_f32 v[146:147], v[140:141], v[144:145]
	v_pk_fma_f32 v[144:145], v[140:141], v[144:145], v[140:141] neg_lo:[1,0,0] neg_hi:[1,0,0]
	v_pk_mul_f32 v[178:179], v[142:143], v[142:143]
	v_cndmask_b32_e32 v146, v144, v146, vcc
	v_cmp_gt_f32_e32 vcc, 0, v141
	v_pk_fma_f32 v[140:141], v[180:181], s[0:1], v[162:163] op_sel_hi:[1,0,0]
	s_nop 0
	v_cndmask_b32_e32 v147, v145, v147, vcc
	v_pk_mul_f32 v[144:145], v[178:179], s[18:19] op_sel_hi:[1,0]
	v_pk_fma_f32 v[140:141], v[180:181], v[140:141], s[16:17] op_sel_hi:[1,1,0]
	v_exp_f32_e32 v144, v144
	v_exp_f32_e32 v145, v145
	v_pk_fma_f32 v[140:141], v[180:181], v[140:141], s[6:7] op_sel_hi:[1,1,0]
	v_cmp_gt_f32_e32 vcc, 0, v142
	v_pk_fma_f32 v[140:141], v[180:181], v[140:141], s[14:15] op_sel_hi:[1,1,0]
	s_nop 0
	v_pk_mul_f32 v[140:141], v[180:181], v[140:141]
	s_nop 0
	v_pk_mul_f32 v[140:141], v[144:145], v[140:141]
	s_nop 0
	v_pk_mul_f32 v[144:145], v[142:143], v[140:141]
	v_pk_fma_f32 v[140:141], v[142:143], v[140:141], v[142:143] neg_lo:[1,0,0] neg_hi:[1,0,0]
	s_nop 0
	v_cndmask_b32_e32 v144, v140, v144, vcc
	v_cmp_gt_f32_e32 vcc, 0, v143
	v_cvt_pk_bf16_f32 v140, v160, v165
	v_ashrrev_i32_e32 v165, 31, v164
	v_lshlrev_b32_e32 v160, 1, v177
	v_cndmask_b32_e32 v143, v141, v145, vcc
	v_cvt_pk_bf16_f32 v141, v186, v187
	v_cvt_pk_bf16_f32 v142, v146, v147
	v_cvt_pk_bf16_f32 v143, v144, v143
	v_lshlrev_b64 v[144:145], 10, v[164:165]
	v_lshl_add_u64 v[144:145], s[20:21], 0, v[144:145]
	v_lshl_add_u64 v[144:145], v[144:145], 0, s[40:41]
	v_lshl_add_u64 v[144:145], v[144:145], 0, v[160:161]
	global_store_dwordx4 v[144:145], v[140:143], off
	v_lshlrev_b32_e32 v144, 16, v184
	v_and_b32_e32 v145, 0xffff0000, v184
	v_lshlrev_b32_e32 v140, 16, v182
	v_and_b32_e32 v141, 0xffff0000, v182
	v_pk_fma_f32 v[132:133], v[108:109], v[140:141], v[132:133]
	v_lshlrev_b32_e32 v142, 16, v183
	v_and_b32_e32 v141, 0x7fffffff, v133
	v_and_b32_e32 v140, 0x7fffffff, v132
	v_pk_fma_f32 v[140:141], v[140:141], s[10:11], 1.0 op_sel_hi:[1,0,0]
	v_and_b32_e32 v143, 0xffff0000, v183
	v_rcp_f32_e32 v140, v140
	v_rcp_f32_e32 v141, v141
	v_pk_fma_f32 v[124:125], v[104:105], v[144:145], v[124:125]
	v_pk_mul_f32 v[144:145], v[132:133], v[132:133]
	v_pk_fma_f32 v[134:135], v[110:111], v[142:143], v[134:135]
	v_pk_fma_f32 v[142:143], v[140:141], s[0:1], v[162:163] op_sel_hi:[1,0,0]
	v_pk_mul_f32 v[144:145], v[144:145], s[18:19] op_sel_hi:[1,0]
	v_lshlrev_b32_e32 v146, 16, v185
	v_and_b32_e32 v147, 0xffff0000, v185
	v_pk_fma_f32 v[142:143], v[140:141], v[142:143], s[16:17] op_sel_hi:[1,1,0]
	v_exp_f32_e32 v144, v144
	v_exp_f32_e32 v145, v145
	v_pk_fma_f32 v[126:127], v[106:107], v[146:147], v[126:127]
	v_pk_fma_f32 v[142:143], v[140:141], v[142:143], s[6:7] op_sel_hi:[1,1,0]
	v_and_b32_e32 v147, 0x7fffffff, v135
	v_and_b32_e32 v146, 0x7fffffff, v134
	v_pk_fma_f32 v[142:143], v[140:141], v[142:143], s[14:15] op_sel_hi:[1,1,0]
	v_pk_fma_f32 v[146:147], v[146:147], s[10:11], 1.0 op_sel_hi:[1,0,0]
	v_pk_mul_f32 v[140:141], v[140:141], v[142:143]
	v_rcp_f32_e32 v146, v146
	v_rcp_f32_e32 v147, v147
	v_pk_mul_f32 v[140:141], v[144:145], v[140:141]
	v_cmp_gt_f32_e32 vcc, 0, v132
	v_pk_mul_f32 v[144:145], v[132:133], v[140:141]
	v_pk_fma_f32 v[140:141], v[132:133], v[140:141], v[132:133] neg_lo:[1,0,0] neg_hi:[1,0,0]
	v_pk_mul_f32 v[142:143], v[134:135], v[134:135]
	v_cndmask_b32_e32 v144, v140, v144, vcc
	v_cmp_gt_f32_e32 vcc, 0, v133
	v_pk_fma_f32 v[132:133], v[146:147], s[0:1], v[162:163] op_sel_hi:[1,0,0]
	s_nop 0
	v_cndmask_b32_e32 v145, v141, v145, vcc
	v_pk_mul_f32 v[140:141], v[142:143], s[18:19] op_sel_hi:[1,0]
	v_pk_fma_f32 v[132:133], v[146:147], v[132:133], s[16:17] op_sel_hi:[1,1,0]
	v_exp_f32_e32 v140, v140
	v_exp_f32_e32 v141, v141
	v_pk_fma_f32 v[132:133], v[146:147], v[132:133], s[6:7] op_sel_hi:[1,1,0]
	v_and_b32_e32 v143, 0x7fffffff, v125
	v_and_b32_e32 v142, 0x7fffffff, v124
	v_pk_fma_f32 v[132:133], v[146:147], v[132:133], s[14:15] op_sel_hi:[1,1,0]
	v_pk_fma_f32 v[142:143], v[142:143], s[10:11], 1.0 op_sel_hi:[1,0,0]
	v_pk_mul_f32 v[132:133], v[146:147], v[132:133]
	v_rcp_f32_e32 v142, v142
	v_rcp_f32_e32 v143, v143
	v_pk_mul_f32 v[132:133], v[140:141], v[132:133]
	v_cmp_gt_f32_e32 vcc, 0, v134
	v_pk_mul_f32 v[140:141], v[134:135], v[132:133]
	v_pk_fma_f32 v[132:133], v[134:135], v[132:133], v[134:135] neg_lo:[1,0,0] neg_hi:[1,0,0]
	s_nop 0
	v_cndmask_b32_e32 v146, v132, v140, vcc
	v_cmp_gt_f32_e32 vcc, 0, v135
	v_pk_mul_f32 v[134:135], v[124:125], v[124:125]
	s_nop 0
	v_cndmask_b32_e32 v147, v133, v141, vcc
	v_pk_fma_f32 v[132:133], v[142:143], s[0:1], v[162:163] op_sel_hi:[1,0,0]
	v_pk_mul_f32 v[134:135], v[134:135], s[18:19] op_sel_hi:[1,0]
	v_pk_fma_f32 v[132:133], v[142:143], v[132:133], s[16:17] op_sel_hi:[1,1,0]
	v_exp_f32_e32 v134, v134
	v_pk_fma_f32 v[132:133], v[142:143], v[132:133], s[6:7] op_sel_hi:[1,1,0]
	v_exp_f32_e32 v135, v135
	v_pk_fma_f32 v[132:133], v[142:143], v[132:133], s[14:15] op_sel_hi:[1,1,0]
	v_cmp_gt_f32_e32 vcc, 0, v124
	v_pk_mul_f32 v[132:133], v[142:143], v[132:133]
	v_and_b32_e32 v143, 0x7fffffff, v127
	v_and_b32_e32 v142, 0x7fffffff, v126
	v_pk_fma_f32 v[142:143], v[142:143], s[10:11], 1.0 op_sel_hi:[1,0,0]
	v_pk_mul_f32 v[132:133], v[134:135], v[132:133]
	v_rcp_f32_e32 v142, v142
	v_rcp_f32_e32 v143, v143
	v_pk_mul_f32 v[134:135], v[124:125], v[132:133]
	v_pk_fma_f32 v[132:133], v[124:125], v[132:133], v[124:125] neg_lo:[1,0,0] neg_hi:[1,0,0]
	v_pk_mul_f32 v[140:141], v[126:127], v[126:127]
	v_cndmask_b32_e32 v134, v132, v134, vcc
	v_cmp_gt_f32_e32 vcc, 0, v125
	v_pk_fma_f32 v[124:125], v[142:143], s[0:1], v[162:163] op_sel_hi:[1,0,0]
	s_nop 0
	v_cndmask_b32_e32 v135, v133, v135, vcc
	v_pk_mul_f32 v[132:133], v[140:141], s[18:19] op_sel_hi:[1,0]
	v_pk_fma_f32 v[124:125], v[142:143], v[124:125], s[16:17] op_sel_hi:[1,1,0]
	v_exp_f32_e32 v132, v132
	v_exp_f32_e32 v133, v133
	v_pk_fma_f32 v[124:125], v[142:143], v[124:125], s[6:7] op_sel_hi:[1,1,0]
	v_cmp_gt_f32_e32 vcc, 0, v126
	v_pk_fma_f32 v[124:125], v[142:143], v[124:125], s[14:15] op_sel_hi:[1,1,0]
	s_nop 0
	v_pk_mul_f32 v[124:125], v[142:143], v[124:125]
	s_nop 0
	v_pk_mul_f32 v[124:125], v[132:133], v[124:125]
	s_nop 0
	v_pk_mul_f32 v[132:133], v[126:127], v[124:125]
	v_pk_fma_f32 v[124:125], v[126:127], v[124:125], v[126:127] neg_lo:[1,0,0] neg_hi:[1,0,0]
	s_nop 0
	v_cndmask_b32_e32 v132, v124, v132, vcc
	v_cmp_gt_f32_e32 vcc, 0, v127
	v_cvt_pk_bf16_f32 v124, v144, v145
	s_nop 1
	v_cndmask_b32_e32 v127, v125, v133, vcc
	v_cvt_pk_bf16_f32 v125, v146, v147
	v_cvt_pk_bf16_f32 v126, v134, v135
	v_cvt_pk_bf16_f32 v127, v132, v127
	v_or_b32_e32 v132, 0x200, v164
	v_ashrrev_i32_e32 v133, 31, v132
	v_lshlrev_b64 v[132:133], 10, v[132:133]
	v_lshl_add_u64 v[132:133], s[20:21], 0, v[132:133]
	v_lshl_add_u64 v[132:133], v[132:133], 0, s[40:41]
	v_lshl_add_u64 v[132:133], v[132:133], 0, v[160:161]
	global_store_dwordx4 v[132:133], v[124:127], off
	v_lshlrev_b32_e32 v132, 16, v158
	v_and_b32_e32 v133, 0xffff0000, v158
	v_lshlrev_b32_e32 v124, 16, v156
	v_and_b32_e32 v125, 0xffff0000, v156
	v_pk_fma_f32 v[116:117], v[108:109], v[124:125], v[116:117]
	v_lshlrev_b32_e32 v126, 16, v157
	v_and_b32_e32 v125, 0x7fffffff, v117
	v_and_b32_e32 v124, 0x7fffffff, v116
	v_pk_fma_f32 v[124:125], v[124:125], s[10:11], 1.0 op_sel_hi:[1,0,0]
	v_and_b32_e32 v127, 0xffff0000, v157
	v_rcp_f32_e32 v124, v124
	v_rcp_f32_e32 v125, v125
	v_pk_fma_f32 v[112:113], v[104:105], v[132:133], v[112:113]
	v_pk_mul_f32 v[132:133], v[116:117], v[116:117]
	v_pk_fma_f32 v[118:119], v[110:111], v[126:127], v[118:119]
	v_pk_fma_f32 v[126:127], v[124:125], s[0:1], v[162:163] op_sel_hi:[1,0,0]
	v_pk_mul_f32 v[132:133], v[132:133], s[18:19] op_sel_hi:[1,0]
	v_lshlrev_b32_e32 v134, 16, v159
	v_and_b32_e32 v135, 0xffff0000, v159
	v_pk_fma_f32 v[126:127], v[124:125], v[126:127], s[16:17] op_sel_hi:[1,1,0]
	v_exp_f32_e32 v132, v132
	v_exp_f32_e32 v133, v133
	v_pk_fma_f32 v[114:115], v[106:107], v[134:135], v[114:115]
	v_pk_fma_f32 v[126:127], v[124:125], v[126:127], s[6:7] op_sel_hi:[1,1,0]
	v_and_b32_e32 v135, 0x7fffffff, v119
	v_and_b32_e32 v134, 0x7fffffff, v118
	v_pk_fma_f32 v[126:127], v[124:125], v[126:127], s[14:15] op_sel_hi:[1,1,0]
	v_pk_fma_f32 v[134:135], v[134:135], s[10:11], 1.0 op_sel_hi:[1,0,0]
	v_pk_mul_f32 v[124:125], v[124:125], v[126:127]
	v_rcp_f32_e32 v134, v134
	v_rcp_f32_e32 v135, v135
	v_pk_mul_f32 v[124:125], v[132:133], v[124:125]
	v_cmp_gt_f32_e32 vcc, 0, v116
	v_pk_mul_f32 v[132:133], v[116:117], v[124:125]
	v_pk_fma_f32 v[124:125], v[116:117], v[124:125], v[116:117] neg_lo:[1,0,0] neg_hi:[1,0,0]
	v_pk_mul_f32 v[126:127], v[118:119], v[118:119]
	v_cndmask_b32_e32 v132, v124, v132, vcc
	v_cmp_gt_f32_e32 vcc, 0, v117
	v_pk_fma_f32 v[116:117], v[134:135], s[0:1], v[162:163] op_sel_hi:[1,0,0]
	s_nop 0
	v_cndmask_b32_e32 v133, v125, v133, vcc
	v_pk_mul_f32 v[124:125], v[126:127], s[18:19] op_sel_hi:[1,0]
	v_pk_fma_f32 v[116:117], v[134:135], v[116:117], s[16:17] op_sel_hi:[1,1,0]
	v_exp_f32_e32 v124, v124
	v_exp_f32_e32 v125, v125
	v_pk_fma_f32 v[116:117], v[134:135], v[116:117], s[6:7] op_sel_hi:[1,1,0]
	v_and_b32_e32 v127, 0x7fffffff, v113
	v_and_b32_e32 v126, 0x7fffffff, v112
	v_pk_fma_f32 v[116:117], v[134:135], v[116:117], s[14:15] op_sel_hi:[1,1,0]
	v_pk_fma_f32 v[126:127], v[126:127], s[10:11], 1.0 op_sel_hi:[1,0,0]
	v_pk_mul_f32 v[116:117], v[134:135], v[116:117]
	v_rcp_f32_e32 v126, v126
	v_rcp_f32_e32 v127, v127
	v_pk_mul_f32 v[116:117], v[124:125], v[116:117]
	v_cmp_gt_f32_e32 vcc, 0, v118
	v_pk_mul_f32 v[124:125], v[118:119], v[116:117]
	v_pk_fma_f32 v[116:117], v[118:119], v[116:117], v[118:119] neg_lo:[1,0,0] neg_hi:[1,0,0]
	s_nop 0
	v_cndmask_b32_e32 v134, v116, v124, vcc
	v_cmp_gt_f32_e32 vcc, 0, v119
	v_pk_mul_f32 v[118:119], v[112:113], v[112:113]
	s_nop 0
	v_cndmask_b32_e32 v135, v117, v125, vcc
	v_pk_fma_f32 v[116:117], v[126:127], s[0:1], v[162:163] op_sel_hi:[1,0,0]
	v_pk_mul_f32 v[118:119], v[118:119], s[18:19] op_sel_hi:[1,0]
	v_pk_fma_f32 v[116:117], v[126:127], v[116:117], s[16:17] op_sel_hi:[1,1,0]
	v_exp_f32_e32 v118, v118
	v_pk_fma_f32 v[116:117], v[126:127], v[116:117], s[6:7] op_sel_hi:[1,1,0]
	v_exp_f32_e32 v119, v119
	v_pk_fma_f32 v[116:117], v[126:127], v[116:117], s[14:15] op_sel_hi:[1,1,0]
	v_cmp_gt_f32_e32 vcc, 0, v112
	v_pk_mul_f32 v[116:117], v[126:127], v[116:117]
	v_and_b32_e32 v127, 0x7fffffff, v115
	v_and_b32_e32 v126, 0x7fffffff, v114
	v_pk_fma_f32 v[126:127], v[126:127], s[10:11], 1.0 op_sel_hi:[1,0,0]
	v_pk_mul_f32 v[116:117], v[118:119], v[116:117]
	v_rcp_f32_e32 v126, v126
	v_rcp_f32_e32 v127, v127
	v_pk_mul_f32 v[118:119], v[112:113], v[116:117]
	v_pk_fma_f32 v[116:117], v[112:113], v[116:117], v[112:113] neg_lo:[1,0,0] neg_hi:[1,0,0]
	v_pk_mul_f32 v[124:125], v[114:115], v[114:115]
	v_cndmask_b32_e32 v118, v116, v118, vcc
	v_cmp_gt_f32_e32 vcc, 0, v113
	v_pk_fma_f32 v[112:113], v[126:127], s[0:1], v[162:163] op_sel_hi:[1,0,0]
	s_nop 0
	v_cndmask_b32_e32 v119, v117, v119, vcc
	v_pk_mul_f32 v[116:117], v[124:125], s[18:19] op_sel_hi:[1,0]
	v_pk_fma_f32 v[112:113], v[126:127], v[112:113], s[16:17] op_sel_hi:[1,1,0]
	v_exp_f32_e32 v116, v116
	v_exp_f32_e32 v117, v117
	v_pk_fma_f32 v[112:113], v[126:127], v[112:113], s[6:7] op_sel_hi:[1,1,0]
	v_cmp_gt_f32_e32 vcc, 0, v114
	v_pk_fma_f32 v[112:113], v[126:127], v[112:113], s[14:15] op_sel_hi:[1,1,0]
	s_nop 0
	v_pk_mul_f32 v[112:113], v[126:127], v[112:113]
	s_nop 0
	v_pk_mul_f32 v[112:113], v[116:117], v[112:113]
	s_nop 0
	v_pk_mul_f32 v[116:117], v[114:115], v[112:113]
	v_pk_fma_f32 v[112:113], v[114:115], v[112:113], v[114:115] neg_lo:[1,0,0] neg_hi:[1,0,0]
	s_nop 0
	v_cndmask_b32_e32 v116, v112, v116, vcc
	v_cmp_gt_f32_e32 vcc, 0, v115
	v_cvt_pk_bf16_f32 v112, v132, v133
	s_nop 1
	v_cndmask_b32_e32 v115, v113, v117, vcc
	v_cvt_pk_bf16_f32 v113, v134, v135
	v_cvt_pk_bf16_f32 v114, v118, v119
	v_cvt_pk_bf16_f32 v115, v116, v115
	v_or_b32_e32 v116, 0x400, v164
	v_ashrrev_i32_e32 v117, 31, v116
	v_lshlrev_b64 v[116:117], 10, v[116:117]
	v_lshl_add_u64 v[116:117], s[20:21], 0, v[116:117]
	v_lshl_add_u64 v[116:117], v[116:117], 0, s[40:41]
	v_lshl_add_u64 v[116:117], v[116:117], 0, v[160:161]
	global_store_dwordx4 v[116:117], v[112:115], off
	v_lshlrev_b32_e32 v116, 16, v154
	v_and_b32_e32 v117, 0xffff0000, v154
	v_lshlrev_b32_e32 v112, 16, v152
	v_and_b32_e32 v113, 0xffff0000, v152
	v_pk_fma_f32 v[100:101], v[108:109], v[112:113], v[100:101]
	v_lshlrev_b32_e32 v114, 16, v153
	v_and_b32_e32 v113, 0x7fffffff, v101
	v_and_b32_e32 v112, 0x7fffffff, v100
	v_pk_fma_f32 v[112:113], v[112:113], s[10:11], 1.0 op_sel_hi:[1,0,0]
	v_and_b32_e32 v115, 0xffff0000, v153
	v_rcp_f32_e32 v112, v112
	v_rcp_f32_e32 v113, v113
	v_pk_fma_f32 v[96:97], v[104:105], v[116:117], v[96:97]
	v_pk_mul_f32 v[116:117], v[100:101], v[100:101]
	v_pk_fma_f32 v[102:103], v[110:111], v[114:115], v[102:103]
	v_pk_fma_f32 v[114:115], v[112:113], s[0:1], v[162:163] op_sel_hi:[1,0,0]
	v_pk_mul_f32 v[116:117], v[116:117], s[18:19] op_sel_hi:[1,0]
	v_lshlrev_b32_e32 v118, 16, v155
	v_and_b32_e32 v119, 0xffff0000, v155
	v_pk_fma_f32 v[114:115], v[112:113], v[114:115], s[16:17] op_sel_hi:[1,1,0]
	v_exp_f32_e32 v116, v116
	v_exp_f32_e32 v117, v117
	v_pk_fma_f32 v[98:99], v[106:107], v[118:119], v[98:99]
	v_pk_fma_f32 v[114:115], v[112:113], v[114:115], s[6:7] op_sel_hi:[1,1,0]
	v_and_b32_e32 v119, 0x7fffffff, v103
	v_and_b32_e32 v118, 0x7fffffff, v102
	v_pk_fma_f32 v[114:115], v[112:113], v[114:115], s[14:15] op_sel_hi:[1,1,0]
	v_pk_fma_f32 v[118:119], v[118:119], s[10:11], 1.0 op_sel_hi:[1,0,0]
	v_pk_mul_f32 v[112:113], v[112:113], v[114:115]
	v_rcp_f32_e32 v118, v118
	v_rcp_f32_e32 v119, v119
	v_pk_mul_f32 v[112:113], v[116:117], v[112:113]
	v_cmp_gt_f32_e32 vcc, 0, v100
	v_pk_mul_f32 v[116:117], v[100:101], v[112:113]
	v_pk_fma_f32 v[112:113], v[100:101], v[112:113], v[100:101] neg_lo:[1,0,0] neg_hi:[1,0,0]
	v_pk_mul_f32 v[114:115], v[102:103], v[102:103]
	v_cndmask_b32_e32 v116, v112, v116, vcc
	v_cmp_gt_f32_e32 vcc, 0, v101
	v_pk_fma_f32 v[100:101], v[118:119], s[0:1], v[162:163] op_sel_hi:[1,0,0]
	s_nop 0
	v_cndmask_b32_e32 v117, v113, v117, vcc
	v_pk_mul_f32 v[112:113], v[114:115], s[18:19] op_sel_hi:[1,0]
	v_pk_fma_f32 v[100:101], v[118:119], v[100:101], s[16:17] op_sel_hi:[1,1,0]
	v_exp_f32_e32 v112, v112
	v_exp_f32_e32 v113, v113
	v_pk_fma_f32 v[100:101], v[118:119], v[100:101], s[6:7] op_sel_hi:[1,1,0]
	v_and_b32_e32 v115, 0x7fffffff, v97
	v_and_b32_e32 v114, 0x7fffffff, v96
	v_pk_fma_f32 v[100:101], v[118:119], v[100:101], s[14:15] op_sel_hi:[1,1,0]
	v_pk_fma_f32 v[114:115], v[114:115], s[10:11], 1.0 op_sel_hi:[1,0,0]
	v_pk_mul_f32 v[100:101], v[118:119], v[100:101]
	v_rcp_f32_e32 v114, v114
	v_rcp_f32_e32 v115, v115
	v_pk_mul_f32 v[100:101], v[112:113], v[100:101]
	v_cmp_gt_f32_e32 vcc, 0, v102
	v_pk_mul_f32 v[112:113], v[102:103], v[100:101]
	v_pk_fma_f32 v[100:101], v[102:103], v[100:101], v[102:103] neg_lo:[1,0,0] neg_hi:[1,0,0]
	s_nop 0
	v_cndmask_b32_e32 v118, v100, v112, vcc
	v_cmp_gt_f32_e32 vcc, 0, v103
	v_pk_mul_f32 v[102:103], v[96:97], v[96:97]
	s_nop 0
	v_cndmask_b32_e32 v119, v101, v113, vcc
	v_pk_fma_f32 v[100:101], v[114:115], s[0:1], v[162:163] op_sel_hi:[1,0,0]
	v_pk_mul_f32 v[102:103], v[102:103], s[18:19] op_sel_hi:[1,0]
	v_pk_fma_f32 v[100:101], v[114:115], v[100:101], s[16:17] op_sel_hi:[1,1,0]
	v_exp_f32_e32 v102, v102
	v_pk_fma_f32 v[100:101], v[114:115], v[100:101], s[6:7] op_sel_hi:[1,1,0]
	v_exp_f32_e32 v103, v103
	v_pk_fma_f32 v[100:101], v[114:115], v[100:101], s[14:15] op_sel_hi:[1,1,0]
	v_cmp_gt_f32_e32 vcc, 0, v96
	v_pk_mul_f32 v[100:101], v[114:115], v[100:101]
	v_and_b32_e32 v115, 0x7fffffff, v99
	v_and_b32_e32 v114, 0x7fffffff, v98
	v_pk_fma_f32 v[114:115], v[114:115], s[10:11], 1.0 op_sel_hi:[1,0,0]
	v_pk_mul_f32 v[100:101], v[102:103], v[100:101]
	v_rcp_f32_e32 v114, v114
	v_rcp_f32_e32 v115, v115
	v_pk_mul_f32 v[102:103], v[96:97], v[100:101]
	v_pk_fma_f32 v[100:101], v[96:97], v[100:101], v[96:97] neg_lo:[1,0,0] neg_hi:[1,0,0]
	v_pk_mul_f32 v[112:113], v[98:99], v[98:99]
	v_cndmask_b32_e32 v102, v100, v102, vcc
	v_cmp_gt_f32_e32 vcc, 0, v97
	v_pk_fma_f32 v[96:97], v[114:115], s[0:1], v[162:163] op_sel_hi:[1,0,0]
	s_nop 0
	v_cndmask_b32_e32 v103, v101, v103, vcc
	v_pk_mul_f32 v[100:101], v[112:113], s[18:19] op_sel_hi:[1,0]
	v_pk_fma_f32 v[96:97], v[114:115], v[96:97], s[16:17] op_sel_hi:[1,1,0]
	v_exp_f32_e32 v100, v100
	v_exp_f32_e32 v101, v101
	v_pk_fma_f32 v[96:97], v[114:115], v[96:97], s[6:7] op_sel_hi:[1,1,0]
	v_cmp_gt_f32_e32 vcc, 0, v98
	v_pk_fma_f32 v[96:97], v[114:115], v[96:97], s[14:15] op_sel_hi:[1,1,0]
	v_lshlrev_b32_e32 v112, 16, v151
	v_pk_mul_f32 v[96:97], v[114:115], v[96:97]
	v_and_b32_e32 v113, 0xffff0000, v151
	v_pk_mul_f32 v[96:97], v[100:101], v[96:97]
	v_pk_fma_f32 v[90:91], v[106:107], v[112:113], v[90:91]
	v_pk_mul_f32 v[100:101], v[98:99], v[96:97]
	v_pk_fma_f32 v[96:97], v[98:99], v[96:97], v[98:99] neg_lo:[1,0,0] neg_hi:[1,0,0]
	s_nop 0
	v_cndmask_b32_e32 v100, v96, v100, vcc
	v_cmp_gt_f32_e32 vcc, 0, v99
	v_cvt_pk_bf16_f32 v96, v116, v117
	s_nop 1
	v_cndmask_b32_e32 v99, v97, v101, vcc
	v_cvt_pk_bf16_f32 v97, v118, v119
	v_cvt_pk_bf16_f32 v98, v102, v103
	v_cvt_pk_bf16_f32 v99, v100, v99
	v_or_b32_e32 v100, 0x600, v164
	v_ashrrev_i32_e32 v101, 31, v100
	v_lshlrev_b64 v[100:101], 10, v[100:101]
	v_lshl_add_u64 v[100:101], s[20:21], 0, v[100:101]
	v_lshl_add_u64 v[100:101], v[100:101], 0, s[40:41]
	v_lshl_add_u64 v[100:101], v[100:101], 0, v[160:161]
	global_store_dwordx4 v[100:101], v[96:99], off
	v_lshlrev_b32_e32 v102, 16, v150
	v_and_b32_e32 v103, 0xffff0000, v150
	v_lshlrev_b32_e32 v98, 16, v148
	v_and_b32_e32 v99, 0xffff0000, v148
	v_pk_fma_f32 v[92:93], v[108:109], v[98:99], v[92:93]
	v_lshlrev_b32_e32 v100, 16, v149
	v_and_b32_e32 v99, 0x7fffffff, v93
	v_and_b32_e32 v98, 0x7fffffff, v92
	v_pk_fma_f32 v[98:99], v[98:99], s[10:11], 1.0 op_sel_hi:[1,0,0]
	v_and_b32_e32 v101, 0xffff0000, v149
	v_rcp_f32_e32 v98, v98
	v_rcp_f32_e32 v99, v99
	v_pk_fma_f32 v[88:89], v[104:105], v[102:103], v[88:89]
	v_pk_mul_f32 v[102:103], v[92:93], v[92:93]
	v_pk_fma_f32 v[94:95], v[110:111], v[100:101], v[94:95]
	v_pk_fma_f32 v[100:101], v[98:99], s[0:1], v[162:163] op_sel_hi:[1,0,0]
	v_pk_mul_f32 v[102:103], v[102:103], s[18:19] op_sel_hi:[1,0]
	v_pk_fma_f32 v[100:101], v[98:99], v[100:101], s[16:17] op_sel_hi:[1,1,0]
	v_exp_f32_e32 v102, v102
	v_exp_f32_e32 v103, v103
	v_pk_fma_f32 v[100:101], v[98:99], v[100:101], s[6:7] op_sel_hi:[1,1,0]
	v_and_b32_e32 v113, 0x7fffffff, v95
	v_and_b32_e32 v112, 0x7fffffff, v94
	v_pk_fma_f32 v[100:101], v[98:99], v[100:101], s[14:15] op_sel_hi:[1,1,0]
	v_pk_fma_f32 v[112:113], v[112:113], s[10:11], 1.0 op_sel_hi:[1,0,0]
	v_pk_mul_f32 v[98:99], v[98:99], v[100:101]
	v_rcp_f32_e32 v112, v112
	v_rcp_f32_e32 v113, v113
	v_pk_mul_f32 v[98:99], v[102:103], v[98:99]
	v_cmp_gt_f32_e32 vcc, 0, v92
	v_pk_mul_f32 v[102:103], v[92:93], v[98:99]
	v_pk_fma_f32 v[98:99], v[92:93], v[98:99], v[92:93] neg_lo:[1,0,0] neg_hi:[1,0,0]
	v_pk_mul_f32 v[100:101], v[94:95], v[94:95]
	v_cndmask_b32_e32 v97, v98, v102, vcc
	v_cmp_gt_f32_e32 vcc, 0, v93
	v_pk_fma_f32 v[92:93], v[112:113], s[0:1], v[162:163] op_sel_hi:[1,0,0]
	v_add_u32_e32 v96, 0x1000, v164
	v_cndmask_b32_e32 v102, v99, v103, vcc
	v_pk_mul_f32 v[98:99], v[100:101], s[18:19] op_sel_hi:[1,0]
	v_pk_fma_f32 v[92:93], v[112:113], v[92:93], s[16:17] op_sel_hi:[1,1,0]
	v_exp_f32_e32 v98, v98
	v_exp_f32_e32 v99, v99
	v_pk_fma_f32 v[92:93], v[112:113], v[92:93], s[6:7] op_sel_hi:[1,1,0]
	v_and_b32_e32 v101, 0x7fffffff, v89
	v_and_b32_e32 v100, 0x7fffffff, v88
	v_pk_fma_f32 v[92:93], v[112:113], v[92:93], s[14:15] op_sel_hi:[1,1,0]
	v_pk_fma_f32 v[100:101], v[100:101], s[10:11], 1.0 op_sel_hi:[1,0,0]
	v_pk_mul_f32 v[92:93], v[112:113], v[92:93]
	v_rcp_f32_e32 v100, v100
	v_rcp_f32_e32 v101, v101
	v_pk_mul_f32 v[92:93], v[98:99], v[92:93]
	v_cmp_gt_f32_e32 vcc, 0, v94
	v_pk_mul_f32 v[98:99], v[94:95], v[92:93]
	v_pk_fma_f32 v[92:93], v[94:95], v[92:93], v[94:95] neg_lo:[1,0,0] neg_hi:[1,0,0]
	s_nop 0
	v_cndmask_b32_e32 v103, v92, v98, vcc
	v_cmp_gt_f32_e32 vcc, 0, v95
	v_pk_mul_f32 v[94:95], v[88:89], v[88:89]
	s_nop 0
	v_cndmask_b32_e32 v112, v93, v99, vcc
	v_pk_fma_f32 v[92:93], v[100:101], s[0:1], v[162:163] op_sel_hi:[1,0,0]
	v_pk_mul_f32 v[94:95], v[94:95], s[18:19] op_sel_hi:[1,0]
	v_pk_fma_f32 v[92:93], v[100:101], v[92:93], s[16:17] op_sel_hi:[1,1,0]
	v_exp_f32_e32 v94, v94
	v_pk_fma_f32 v[92:93], v[100:101], v[92:93], s[6:7] op_sel_hi:[1,1,0]
	v_exp_f32_e32 v95, v95
	v_pk_fma_f32 v[92:93], v[100:101], v[92:93], s[14:15] op_sel_hi:[1,1,0]
	v_cmp_gt_f32_e32 vcc, 0, v88
	v_pk_mul_f32 v[92:93], v[100:101], v[92:93]
	v_and_b32_e32 v101, 0x7fffffff, v91
	v_and_b32_e32 v100, 0x7fffffff, v90
	v_pk_fma_f32 v[100:101], v[100:101], s[10:11], 1.0 op_sel_hi:[1,0,0]
	v_pk_mul_f32 v[92:93], v[94:95], v[92:93]
	v_rcp_f32_e32 v100, v100
	v_rcp_f32_e32 v101, v101
	v_pk_mul_f32 v[94:95], v[88:89], v[92:93]
	v_pk_fma_f32 v[92:93], v[88:89], v[92:93], v[88:89] neg_lo:[1,0,0] neg_hi:[1,0,0]
	v_pk_mul_f32 v[98:99], v[90:91], v[90:91]
	v_cndmask_b32_e32 v94, v92, v94, vcc
	v_cmp_gt_f32_e32 vcc, 0, v89
	v_pk_fma_f32 v[88:89], v[100:101], s[0:1], v[162:163] op_sel_hi:[1,0,0]
	s_nop 0
	v_cndmask_b32_e32 v95, v93, v95, vcc
	v_pk_mul_f32 v[92:93], v[98:99], s[18:19] op_sel_hi:[1,0]
	v_pk_fma_f32 v[88:89], v[100:101], v[88:89], s[16:17] op_sel_hi:[1,1,0]
	v_exp_f32_e32 v92, v92
	v_exp_f32_e32 v93, v93
	v_pk_fma_f32 v[88:89], v[100:101], v[88:89], s[6:7] op_sel_hi:[1,1,0]
	v_cmp_gt_f32_e32 vcc, 0, v90
	v_pk_fma_f32 v[88:89], v[100:101], v[88:89], s[14:15] op_sel_hi:[1,1,0]
	s_nop 0
	v_pk_mul_f32 v[88:89], v[100:101], v[88:89]
	s_nop 0
	v_pk_mul_f32 v[88:89], v[92:93], v[88:89]
	s_nop 0
	v_pk_mul_f32 v[92:93], v[90:91], v[88:89]
	v_pk_fma_f32 v[88:89], v[90:91], v[88:89], v[90:91] neg_lo:[1,0,0] neg_hi:[1,0,0]
	s_nop 0
	v_cndmask_b32_e32 v92, v88, v92, vcc
	v_cmp_gt_f32_e32 vcc, 0, v91
	v_cvt_pk_bf16_f32 v88, v97, v102
	v_ashrrev_i32_e32 v97, 31, v96
	s_nop 0
	v_cndmask_b32_e32 v91, v89, v93, vcc
	v_cvt_pk_bf16_f32 v89, v103, v112
	v_cvt_pk_bf16_f32 v90, v94, v95
	v_cvt_pk_bf16_f32 v91, v92, v91
	v_lshlrev_b64 v[92:93], 10, v[96:97]
	v_lshl_add_u64 v[92:93], s[20:21], 0, v[92:93]
	v_lshl_add_u64 v[92:93], v[92:93], 0, s[40:41]
	v_lshl_add_u64 v[92:93], v[92:93], 0, v[160:161]
	global_store_dwordx4 v[92:93], v[88:91], off
	v_lshlrev_b32_e32 v92, 16, v138
	v_and_b32_e32 v93, 0xffff0000, v138
	v_lshlrev_b32_e32 v88, 16, v136
	v_and_b32_e32 v89, 0xffff0000, v136
	v_pk_fma_f32 v[84:85], v[108:109], v[88:89], v[84:85]
	v_lshlrev_b32_e32 v90, 16, v137
	v_and_b32_e32 v89, 0x7fffffff, v85
	v_and_b32_e32 v88, 0x7fffffff, v84
	v_pk_fma_f32 v[88:89], v[88:89], s[10:11], 1.0 op_sel_hi:[1,0,0]
	v_and_b32_e32 v91, 0xffff0000, v137
	v_rcp_f32_e32 v88, v88
	v_rcp_f32_e32 v89, v89
	v_pk_fma_f32 v[80:81], v[104:105], v[92:93], v[80:81]
	v_pk_mul_f32 v[92:93], v[84:85], v[84:85]
	v_pk_fma_f32 v[86:87], v[110:111], v[90:91], v[86:87]
	v_pk_fma_f32 v[90:91], v[88:89], s[0:1], v[162:163] op_sel_hi:[1,0,0]
	v_pk_mul_f32 v[92:93], v[92:93], s[18:19] op_sel_hi:[1,0]
	v_lshlrev_b32_e32 v94, 16, v139
	v_and_b32_e32 v95, 0xffff0000, v139
	v_pk_fma_f32 v[90:91], v[88:89], v[90:91], s[16:17] op_sel_hi:[1,1,0]
	v_exp_f32_e32 v92, v92
	v_exp_f32_e32 v93, v93
	v_pk_fma_f32 v[82:83], v[106:107], v[94:95], v[82:83]
	v_pk_fma_f32 v[90:91], v[88:89], v[90:91], s[6:7] op_sel_hi:[1,1,0]
	v_and_b32_e32 v95, 0x7fffffff, v87
	v_and_b32_e32 v94, 0x7fffffff, v86
	v_pk_fma_f32 v[90:91], v[88:89], v[90:91], s[14:15] op_sel_hi:[1,1,0]
	v_pk_fma_f32 v[94:95], v[94:95], s[10:11], 1.0 op_sel_hi:[1,0,0]
	v_pk_mul_f32 v[88:89], v[88:89], v[90:91]
	v_rcp_f32_e32 v94, v94
	v_rcp_f32_e32 v95, v95
	v_pk_mul_f32 v[88:89], v[92:93], v[88:89]
	v_cmp_gt_f32_e32 vcc, 0, v84
	v_pk_mul_f32 v[92:93], v[84:85], v[88:89]
	v_pk_fma_f32 v[88:89], v[84:85], v[88:89], v[84:85] neg_lo:[1,0,0] neg_hi:[1,0,0]
	v_pk_mul_f32 v[90:91], v[86:87], v[86:87]
	v_cndmask_b32_e32 v92, v88, v92, vcc
	v_cmp_gt_f32_e32 vcc, 0, v85
	v_pk_fma_f32 v[84:85], v[94:95], s[0:1], v[162:163] op_sel_hi:[1,0,0]
	v_or_b32_e32 v96, 0x80, v167
	v_cndmask_b32_e32 v93, v89, v93, vcc
	v_pk_mul_f32 v[88:89], v[90:91], s[18:19] op_sel_hi:[1,0]
	v_pk_fma_f32 v[84:85], v[94:95], v[84:85], s[16:17] op_sel_hi:[1,1,0]
	v_exp_f32_e32 v88, v88
	v_exp_f32_e32 v89, v89
	v_pk_fma_f32 v[84:85], v[94:95], v[84:85], s[6:7] op_sel_hi:[1,1,0]
	v_and_b32_e32 v91, 0x7fffffff, v81
	v_and_b32_e32 v90, 0x7fffffff, v80
	v_pk_fma_f32 v[84:85], v[94:95], v[84:85], s[14:15] op_sel_hi:[1,1,0]
	v_pk_fma_f32 v[90:91], v[90:91], s[10:11], 1.0 op_sel_hi:[1,0,0]
	v_pk_mul_f32 v[84:85], v[94:95], v[84:85]
	v_rcp_f32_e32 v90, v90
	v_rcp_f32_e32 v91, v91
	v_pk_mul_f32 v[84:85], v[88:89], v[84:85]
	v_cmp_gt_f32_e32 vcc, 0, v86
	v_pk_mul_f32 v[88:89], v[86:87], v[84:85]
	v_pk_fma_f32 v[84:85], v[86:87], v[84:85], v[86:87] neg_lo:[1,0,0] neg_hi:[1,0,0]
	s_nop 0
	v_cndmask_b32_e32 v94, v84, v88, vcc
	v_cmp_gt_f32_e32 vcc, 0, v87
	v_pk_mul_f32 v[86:87], v[80:81], v[80:81]
	s_nop 0
	v_cndmask_b32_e32 v95, v85, v89, vcc
	v_pk_fma_f32 v[84:85], v[90:91], s[0:1], v[162:163] op_sel_hi:[1,0,0]
	v_pk_mul_f32 v[86:87], v[86:87], s[18:19] op_sel_hi:[1,0]
	v_pk_fma_f32 v[84:85], v[90:91], v[84:85], s[16:17] op_sel_hi:[1,1,0]
	v_exp_f32_e32 v86, v86
	v_pk_fma_f32 v[84:85], v[90:91], v[84:85], s[6:7] op_sel_hi:[1,1,0]
	v_exp_f32_e32 v87, v87
	v_pk_fma_f32 v[84:85], v[90:91], v[84:85], s[14:15] op_sel_hi:[1,1,0]
	v_cmp_gt_f32_e32 vcc, 0, v80
	v_pk_mul_f32 v[84:85], v[90:91], v[84:85]
	v_and_b32_e32 v91, 0x7fffffff, v83
	v_and_b32_e32 v90, 0x7fffffff, v82
	v_pk_fma_f32 v[90:91], v[90:91], s[10:11], 1.0 op_sel_hi:[1,0,0]
	v_pk_mul_f32 v[84:85], v[86:87], v[84:85]
	v_rcp_f32_e32 v90, v90
	v_rcp_f32_e32 v91, v91
	v_pk_mul_f32 v[86:87], v[80:81], v[84:85]
	v_pk_fma_f32 v[84:85], v[80:81], v[84:85], v[80:81] neg_lo:[1,0,0] neg_hi:[1,0,0]
	v_pk_mul_f32 v[88:89], v[82:83], v[82:83]
	v_cndmask_b32_e32 v86, v84, v86, vcc
	v_cmp_gt_f32_e32 vcc, 0, v81
	v_pk_fma_f32 v[80:81], v[90:91], s[0:1], v[162:163] op_sel_hi:[1,0,0]
	s_nop 0
	v_cndmask_b32_e32 v87, v85, v87, vcc
	v_pk_mul_f32 v[84:85], v[88:89], s[18:19] op_sel_hi:[1,0]
	v_pk_fma_f32 v[80:81], v[90:91], v[80:81], s[16:17] op_sel_hi:[1,1,0]
	v_exp_f32_e32 v84, v84
	v_exp_f32_e32 v85, v85
	v_pk_fma_f32 v[80:81], v[90:91], v[80:81], s[6:7] op_sel_hi:[1,1,0]
	v_cmp_gt_f32_e32 vcc, 0, v82
	v_pk_fma_f32 v[80:81], v[90:91], v[80:81], s[14:15] op_sel_hi:[1,1,0]
	s_nop 0
	v_pk_mul_f32 v[80:81], v[90:91], v[80:81]
	s_nop 0
	v_pk_mul_f32 v[80:81], v[84:85], v[80:81]
	s_nop 0
	v_pk_mul_f32 v[84:85], v[82:83], v[80:81]
	v_pk_fma_f32 v[80:81], v[82:83], v[80:81], v[82:83] neg_lo:[1,0,0] neg_hi:[1,0,0]
	s_nop 0
	v_cndmask_b32_e32 v84, v80, v84, vcc
	v_cmp_gt_f32_e32 vcc, 0, v83
	v_cvt_pk_bf16_f32 v80, v92, v93
	s_nop 1
	v_cndmask_b32_e32 v83, v81, v85, vcc
	v_cvt_pk_bf16_f32 v81, v94, v95
	v_cvt_pk_bf16_f32 v82, v86, v87
	v_cvt_pk_bf16_f32 v83, v84, v83
	v_add_u32_e32 v84, 0x1200, v164
	v_ashrrev_i32_e32 v85, 31, v84
	v_lshlrev_b64 v[84:85], 10, v[84:85]
	v_lshl_add_u64 v[84:85], s[20:21], 0, v[84:85]
	v_lshl_add_u64 v[84:85], v[84:85], 0, s[40:41]
	v_lshl_add_u64 v[84:85], v[84:85], 0, v[160:161]
	global_store_dwordx4 v[84:85], v[80:83], off
	v_lshlrev_b32_e32 v84, 16, v130
	v_and_b32_e32 v85, 0xffff0000, v130
	v_lshlrev_b32_e32 v80, 16, v128
	v_and_b32_e32 v81, 0xffff0000, v128
	v_pk_fma_f32 v[76:77], v[108:109], v[80:81], v[76:77]
	v_lshlrev_b32_e32 v82, 16, v129
	v_and_b32_e32 v81, 0x7fffffff, v77
	v_and_b32_e32 v80, 0x7fffffff, v76
	v_pk_fma_f32 v[80:81], v[80:81], s[10:11], 1.0 op_sel_hi:[1,0,0]
	v_and_b32_e32 v83, 0xffff0000, v129
	v_rcp_f32_e32 v80, v80
	v_rcp_f32_e32 v81, v81
	v_pk_fma_f32 v[72:73], v[104:105], v[84:85], v[72:73]
	v_pk_mul_f32 v[84:85], v[76:77], v[76:77]
	v_pk_fma_f32 v[78:79], v[110:111], v[82:83], v[78:79]
	v_pk_fma_f32 v[82:83], v[80:81], s[0:1], v[162:163] op_sel_hi:[1,0,0]
	v_pk_mul_f32 v[84:85], v[84:85], s[18:19] op_sel_hi:[1,0]
	v_lshlrev_b32_e32 v86, 16, v131
	v_and_b32_e32 v87, 0xffff0000, v131
	v_pk_fma_f32 v[82:83], v[80:81], v[82:83], s[16:17] op_sel_hi:[1,1,0]
	v_exp_f32_e32 v84, v84
	v_exp_f32_e32 v85, v85
	v_pk_fma_f32 v[74:75], v[106:107], v[86:87], v[74:75]
	v_pk_fma_f32 v[82:83], v[80:81], v[82:83], s[6:7] op_sel_hi:[1,1,0]
	v_and_b32_e32 v87, 0x7fffffff, v79
	v_and_b32_e32 v86, 0x7fffffff, v78
	v_pk_fma_f32 v[82:83], v[80:81], v[82:83], s[14:15] op_sel_hi:[1,1,0]
	v_pk_fma_f32 v[86:87], v[86:87], s[10:11], 1.0 op_sel_hi:[1,0,0]
	v_pk_mul_f32 v[80:81], v[80:81], v[82:83]
	v_rcp_f32_e32 v86, v86
	v_rcp_f32_e32 v87, v87
	v_pk_mul_f32 v[80:81], v[84:85], v[80:81]
	v_cmp_gt_f32_e32 vcc, 0, v76
	v_pk_mul_f32 v[84:85], v[76:77], v[80:81]
	v_pk_fma_f32 v[80:81], v[76:77], v[80:81], v[76:77] neg_lo:[1,0,0] neg_hi:[1,0,0]
	v_pk_mul_f32 v[82:83], v[78:79], v[78:79]
	v_cndmask_b32_e32 v84, v80, v84, vcc
	v_cmp_gt_f32_e32 vcc, 0, v77
	v_pk_fma_f32 v[76:77], v[86:87], s[0:1], v[162:163] op_sel_hi:[1,0,0]
	s_nop 0
	v_cndmask_b32_e32 v85, v81, v85, vcc
	v_pk_mul_f32 v[80:81], v[82:83], s[18:19] op_sel_hi:[1,0]
	v_pk_fma_f32 v[76:77], v[86:87], v[76:77], s[16:17] op_sel_hi:[1,1,0]
	v_exp_f32_e32 v80, v80
	v_exp_f32_e32 v81, v81
	v_pk_fma_f32 v[76:77], v[86:87], v[76:77], s[6:7] op_sel_hi:[1,1,0]
	v_and_b32_e32 v83, 0x7fffffff, v73
	v_and_b32_e32 v82, 0x7fffffff, v72
	v_pk_fma_f32 v[76:77], v[86:87], v[76:77], s[14:15] op_sel_hi:[1,1,0]
	v_pk_fma_f32 v[82:83], v[82:83], s[10:11], 1.0 op_sel_hi:[1,0,0]
	v_pk_mul_f32 v[76:77], v[86:87], v[76:77]
	v_rcp_f32_e32 v82, v82
	v_rcp_f32_e32 v83, v83
	v_pk_mul_f32 v[76:77], v[80:81], v[76:77]
	v_cmp_gt_f32_e32 vcc, 0, v78
	v_pk_mul_f32 v[80:81], v[78:79], v[76:77]
	v_pk_fma_f32 v[76:77], v[78:79], v[76:77], v[78:79] neg_lo:[1,0,0] neg_hi:[1,0,0]
	s_nop 0
	v_cndmask_b32_e32 v86, v76, v80, vcc
	v_cmp_gt_f32_e32 vcc, 0, v79
	v_pk_mul_f32 v[78:79], v[72:73], v[72:73]
	s_nop 0
	v_cndmask_b32_e32 v87, v77, v81, vcc
	v_pk_fma_f32 v[76:77], v[82:83], s[0:1], v[162:163] op_sel_hi:[1,0,0]
	v_pk_mul_f32 v[78:79], v[78:79], s[18:19] op_sel_hi:[1,0]
	v_pk_fma_f32 v[76:77], v[82:83], v[76:77], s[16:17] op_sel_hi:[1,1,0]
	v_exp_f32_e32 v78, v78
	v_pk_fma_f32 v[76:77], v[82:83], v[76:77], s[6:7] op_sel_hi:[1,1,0]
	v_exp_f32_e32 v79, v79
	v_pk_fma_f32 v[76:77], v[82:83], v[76:77], s[14:15] op_sel_hi:[1,1,0]
	v_cmp_gt_f32_e32 vcc, 0, v72
	v_pk_mul_f32 v[76:77], v[82:83], v[76:77]
	v_and_b32_e32 v83, 0x7fffffff, v75
	v_and_b32_e32 v82, 0x7fffffff, v74
	v_pk_fma_f32 v[82:83], v[82:83], s[10:11], 1.0 op_sel_hi:[1,0,0]
	v_pk_mul_f32 v[76:77], v[78:79], v[76:77]
	v_rcp_f32_e32 v82, v82
	v_rcp_f32_e32 v83, v83
	v_pk_mul_f32 v[78:79], v[72:73], v[76:77]
	v_pk_fma_f32 v[76:77], v[72:73], v[76:77], v[72:73] neg_lo:[1,0,0] neg_hi:[1,0,0]
	v_pk_mul_f32 v[80:81], v[74:75], v[74:75]
	v_cndmask_b32_e32 v78, v76, v78, vcc
	v_cmp_gt_f32_e32 vcc, 0, v73
	v_pk_fma_f32 v[72:73], v[82:83], s[0:1], v[162:163] op_sel_hi:[1,0,0]
	s_nop 0
	v_cndmask_b32_e32 v79, v77, v79, vcc
	v_pk_mul_f32 v[76:77], v[80:81], s[18:19] op_sel_hi:[1,0]
	v_pk_fma_f32 v[72:73], v[82:83], v[72:73], s[16:17] op_sel_hi:[1,1,0]
	v_exp_f32_e32 v76, v76
	v_exp_f32_e32 v77, v77
	v_pk_fma_f32 v[72:73], v[82:83], v[72:73], s[6:7] op_sel_hi:[1,1,0]
	v_cmp_gt_f32_e32 vcc, 0, v74
	v_pk_fma_f32 v[72:73], v[82:83], v[72:73], s[14:15] op_sel_hi:[1,1,0]
	s_nop 0
	v_pk_mul_f32 v[72:73], v[82:83], v[72:73]
	s_nop 0
	v_pk_mul_f32 v[72:73], v[76:77], v[72:73]
	s_nop 0
	v_pk_mul_f32 v[76:77], v[74:75], v[72:73]
	v_pk_fma_f32 v[72:73], v[74:75], v[72:73], v[74:75] neg_lo:[1,0,0] neg_hi:[1,0,0]
	s_nop 0
	v_cndmask_b32_e32 v76, v72, v76, vcc
	v_cmp_gt_f32_e32 vcc, 0, v75
	v_cvt_pk_bf16_f32 v72, v84, v85
	s_nop 1
	v_cndmask_b32_e32 v75, v73, v77, vcc
	v_cvt_pk_bf16_f32 v73, v86, v87
	v_cvt_pk_bf16_f32 v74, v78, v79
	v_cvt_pk_bf16_f32 v75, v76, v75
	v_add_u32_e32 v76, 0x1400, v164
	v_ashrrev_i32_e32 v77, 31, v76
	v_lshlrev_b64 v[76:77], 10, v[76:77]
	v_lshl_add_u64 v[76:77], s[20:21], 0, v[76:77]
	v_lshl_add_u64 v[76:77], v[76:77], 0, s[40:41]
	v_lshl_add_u64 v[76:77], v[76:77], 0, v[160:161]
	global_store_dwordx4 v[76:77], v[72:75], off
	v_lshlrev_b32_e32 v76, 16, v122
	v_and_b32_e32 v77, 0xffff0000, v122
	v_lshlrev_b32_e32 v72, 16, v120
	v_and_b32_e32 v73, 0xffff0000, v120
	v_pk_fma_f32 v[68:69], v[108:109], v[72:73], v[68:69]
	v_lshlrev_b32_e32 v74, 16, v121
	v_and_b32_e32 v73, 0x7fffffff, v69
	v_and_b32_e32 v72, 0x7fffffff, v68
	v_pk_fma_f32 v[72:73], v[72:73], s[10:11], 1.0 op_sel_hi:[1,0,0]
	v_and_b32_e32 v75, 0xffff0000, v121
	v_rcp_f32_e32 v72, v72
	v_rcp_f32_e32 v73, v73
	v_pk_fma_f32 v[64:65], v[104:105], v[76:77], v[64:65]
	v_pk_mul_f32 v[76:77], v[68:69], v[68:69]
	v_pk_fma_f32 v[70:71], v[110:111], v[74:75], v[70:71]
	v_pk_fma_f32 v[74:75], v[72:73], s[0:1], v[162:163] op_sel_hi:[1,0,0]
	v_pk_mul_f32 v[76:77], v[76:77], s[18:19] op_sel_hi:[1,0]
	v_lshlrev_b32_e32 v78, 16, v123
	v_and_b32_e32 v79, 0xffff0000, v123
	v_pk_fma_f32 v[74:75], v[72:73], v[74:75], s[16:17] op_sel_hi:[1,1,0]
	v_exp_f32_e32 v76, v76
	v_exp_f32_e32 v77, v77
	v_pk_fma_f32 v[66:67], v[106:107], v[78:79], v[66:67]
	v_pk_fma_f32 v[74:75], v[72:73], v[74:75], s[6:7] op_sel_hi:[1,1,0]
	v_and_b32_e32 v79, 0x7fffffff, v71
	v_and_b32_e32 v78, 0x7fffffff, v70
	v_pk_fma_f32 v[74:75], v[72:73], v[74:75], s[14:15] op_sel_hi:[1,1,0]
	v_pk_fma_f32 v[78:79], v[78:79], s[10:11], 1.0 op_sel_hi:[1,0,0]
	v_pk_mul_f32 v[72:73], v[72:73], v[74:75]
	v_rcp_f32_e32 v78, v78
	v_rcp_f32_e32 v79, v79
	v_pk_mul_f32 v[72:73], v[76:77], v[72:73]
	v_cmp_gt_f32_e32 vcc, 0, v68
	v_pk_mul_f32 v[76:77], v[68:69], v[72:73]
	v_pk_fma_f32 v[72:73], v[68:69], v[72:73], v[68:69] neg_lo:[1,0,0] neg_hi:[1,0,0]
	v_pk_mul_f32 v[74:75], v[70:71], v[70:71]
	v_cndmask_b32_e32 v76, v72, v76, vcc
	v_cmp_gt_f32_e32 vcc, 0, v69
	v_pk_fma_f32 v[68:69], v[78:79], s[0:1], v[162:163] op_sel_hi:[1,0,0]
	s_nop 0
	v_cndmask_b32_e32 v77, v73, v77, vcc
	v_pk_mul_f32 v[72:73], v[74:75], s[18:19] op_sel_hi:[1,0]
	v_pk_fma_f32 v[68:69], v[78:79], v[68:69], s[16:17] op_sel_hi:[1,1,0]
	v_exp_f32_e32 v72, v72
	v_exp_f32_e32 v73, v73
	v_pk_fma_f32 v[68:69], v[78:79], v[68:69], s[6:7] op_sel_hi:[1,1,0]
	v_and_b32_e32 v75, 0x7fffffff, v65
	v_and_b32_e32 v74, 0x7fffffff, v64
	v_pk_fma_f32 v[68:69], v[78:79], v[68:69], s[14:15] op_sel_hi:[1,1,0]
	v_pk_fma_f32 v[74:75], v[74:75], s[10:11], 1.0 op_sel_hi:[1,0,0]
	v_pk_mul_f32 v[68:69], v[78:79], v[68:69]
	v_rcp_f32_e32 v74, v74
	v_rcp_f32_e32 v75, v75
	v_pk_mul_f32 v[68:69], v[72:73], v[68:69]
	v_cmp_gt_f32_e32 vcc, 0, v70
	v_pk_mul_f32 v[72:73], v[70:71], v[68:69]
	v_pk_fma_f32 v[68:69], v[70:71], v[68:69], v[70:71] neg_lo:[1,0,0] neg_hi:[1,0,0]
	s_nop 0
	v_cndmask_b32_e32 v78, v68, v72, vcc
	v_cmp_gt_f32_e32 vcc, 0, v71
	v_pk_mul_f32 v[70:71], v[64:65], v[64:65]
	s_nop 0
	v_cndmask_b32_e32 v79, v69, v73, vcc
	v_pk_fma_f32 v[68:69], v[74:75], s[0:1], v[162:163] op_sel_hi:[1,0,0]
	v_pk_mul_f32 v[70:71], v[70:71], s[18:19] op_sel_hi:[1,0]
	v_pk_fma_f32 v[68:69], v[74:75], v[68:69], s[16:17] op_sel_hi:[1,1,0]
	v_exp_f32_e32 v70, v70
	v_pk_fma_f32 v[68:69], v[74:75], v[68:69], s[6:7] op_sel_hi:[1,1,0]
	v_exp_f32_e32 v71, v71
	v_pk_fma_f32 v[68:69], v[74:75], v[68:69], s[14:15] op_sel_hi:[1,1,0]
	v_cmp_gt_f32_e32 vcc, 0, v64
	v_pk_mul_f32 v[68:69], v[74:75], v[68:69]
	v_and_b32_e32 v75, 0x7fffffff, v67
	v_and_b32_e32 v74, 0x7fffffff, v66
	v_pk_fma_f32 v[74:75], v[74:75], s[10:11], 1.0 op_sel_hi:[1,0,0]
	v_pk_mul_f32 v[68:69], v[70:71], v[68:69]
	v_rcp_f32_e32 v74, v74
	v_rcp_f32_e32 v75, v75
	v_pk_mul_f32 v[70:71], v[64:65], v[68:69]
	v_pk_fma_f32 v[68:69], v[64:65], v[68:69], v[64:65] neg_lo:[1,0,0] neg_hi:[1,0,0]
	v_pk_mul_f32 v[72:73], v[66:67], v[66:67]
	v_cndmask_b32_e32 v70, v68, v70, vcc
	v_cmp_gt_f32_e32 vcc, 0, v65
	v_pk_fma_f32 v[64:65], v[74:75], s[0:1], v[162:163] op_sel_hi:[1,0,0]
	s_nop 0
	v_cndmask_b32_e32 v71, v69, v71, vcc
	v_pk_mul_f32 v[68:69], v[72:73], s[18:19] op_sel_hi:[1,0]
	v_pk_fma_f32 v[64:65], v[74:75], v[64:65], s[16:17] op_sel_hi:[1,1,0]
	v_exp_f32_e32 v68, v68
	v_exp_f32_e32 v69, v69
	v_pk_fma_f32 v[64:65], v[74:75], v[64:65], s[6:7] op_sel_hi:[1,1,0]
	v_cmp_gt_f32_e32 vcc, 0, v66
	v_pk_fma_f32 v[64:65], v[74:75], v[64:65], s[14:15] op_sel_hi:[1,1,0]
	v_mov_b64_e32 v[72:73], s[38:39]
	v_pk_mul_f32 v[64:65], v[74:75], v[64:65]
	v_lshlrev_b32_e32 v74, 1, v96
	v_pk_mul_f32 v[64:65], v[68:69], v[64:65]
	v_mov_b32_e32 v75, v161
	v_pk_mul_f32 v[68:69], v[66:67], v[64:65]
	v_pk_fma_f32 v[64:65], v[66:67], v[64:65], v[66:67] neg_lo:[1,0,0] neg_hi:[1,0,0]
	v_lshrrev_b32_e32 v96, 4, v96
	v_cndmask_b32_e32 v68, v64, v68, vcc
	v_cmp_gt_f32_e32 vcc, 0, v67
	v_cvt_pk_bf16_f32 v64, v76, v77
	v_mad_i64_i32 v[76:77], s[12:13], v176, s1, v[72:73]
	s_nop 0
	v_cndmask_b32_e32 v67, v65, v69, vcc
	v_cvt_pk_bf16_f32 v65, v78, v79
	v_cvt_pk_bf16_f32 v66, v70, v71
	v_cvt_pk_bf16_f32 v67, v68, v67
	v_add_u32_e32 v68, 0x1600, v164
	v_ashrrev_i32_e32 v69, 31, v68
	v_lshlrev_b64 v[68:69], 10, v[68:69]
	v_lshl_add_u64 v[68:69], s[20:21], 0, v[68:69]
	v_lshl_add_u64 v[68:69], v[68:69], 0, s[40:41]
	v_lshl_add_u64 v[68:69], v[68:69], 0, v[160:161]
	global_store_dwordx4 v[68:69], v[64:67], off
	v_lshl_add_u64 v[76:77], v[76:77], 0, v[74:75]
	v_mad_i64_i32 v[78:79], s[12:13], v174, s1, v[72:73]
	v_mad_i64_i32 v[64:65], s[12:13], v166, s1, v[72:73]
	v_lshl_add_u64 v[64:65], v[64:65], 0, v[74:75]
	global_load_dwordx4 v[98:101], v[64:65], off
	global_load_dwordx4 v[68:71], v168, s[42:43]
	s_nop 0
	global_load_dwordx4 v[64:67], v168, s[42:43] offset:16
	global_load_dwordx4 v[102:105], v[76:77], off
	v_mad_i64_i32 v[76:77], s[12:13], v175, s1, v[72:73]
	v_lshl_add_u64 v[76:77], v[76:77], 0, v[74:75]
	v_lshl_add_u64 v[78:79], v[78:79], 0, v[74:75]
	global_load_dwordx4 v[92:95], v[76:77], off
	global_load_dwordx4 v[88:91], v[78:79], off
	v_mad_i64_i32 v[76:77], s[12:13], v173, s1, v[72:73]
	v_lshl_add_u64 v[76:77], v[76:77], 0, v[74:75]
	v_mad_i64_i32 v[78:79], s[12:13], v172, s1, v[72:73]
	v_lshl_add_u64 v[78:79], v[78:79], 0, v[74:75]
	global_load_dwordx4 v[84:87], v[76:77], off
	global_load_dwordx4 v[80:83], v[78:79], off
	v_mad_i64_i32 v[76:77], s[12:13], v171, s1, v[72:73]
	v_mad_i64_i32 v[72:73], s[12:13], v170, s1, v[72:73]
	v_lshl_add_u64 v[76:77], v[76:77], 0, v[74:75]
	v_lshl_add_u64 v[72:73], v[72:73], 0, v[74:75]
	v_or_b32_e32 v96, v169, v96
	global_load_dwordx4 v[76:79], v[76:77], off
	s_nop 0
	global_load_dwordx4 v[72:75], v[72:73], off
	s_waitcnt vmcnt(9)
	v_lshlrev_b32_e32 v106, 16, v98
	v_and_b32_e32 v107, 0xffff0000, v98
	s_waitcnt vmcnt(8)
	v_pk_fma_f32 v[60:61], v[68:69], v[106:107], v[60:61]
	v_lshlrev_b32_e32 v108, 16, v100
	v_and_b32_e32 v107, 0x7fffffff, v61
	v_and_b32_e32 v106, 0x7fffffff, v60
	v_pk_fma_f32 v[106:107], v[106:107], s[10:11], 1.0 op_sel_hi:[1,0,0]
	v_and_b32_e32 v109, 0xffff0000, v100
	v_rcp_f32_e32 v106, v106
	v_rcp_f32_e32 v107, v107
	v_lshlrev_b32_e32 v100, 16, v101
	v_and_b32_e32 v101, 0xffff0000, v101
	v_lshlrev_b32_e32 v98, 16, v99
	v_and_b32_e32 v99, 0xffff0000, v99
	s_waitcnt vmcnt(7)
	v_pk_fma_f32 v[58:59], v[66:67], v[100:101], v[58:59]
	v_pk_mul_f32 v[100:101], v[60:61], v[60:61]
	v_pk_fma_f32 v[62:63], v[70:71], v[98:99], v[62:63]
	v_pk_fma_f32 v[98:99], v[106:107], s[0:1], v[162:163] op_sel_hi:[1,0,0]
	v_pk_mul_f32 v[100:101], v[100:101], s[18:19] op_sel_hi:[1,0]
	v_pk_fma_f32 v[98:99], v[106:107], v[98:99], s[16:17] op_sel_hi:[1,1,0]
	v_exp_f32_e32 v100, v100
	v_exp_f32_e32 v101, v101
	v_pk_fma_f32 v[56:57], v[64:65], v[108:109], v[56:57]
	v_pk_fma_f32 v[98:99], v[106:107], v[98:99], s[6:7] op_sel_hi:[1,1,0]
	v_and_b32_e32 v109, 0x7fffffff, v63
	v_and_b32_e32 v108, 0x7fffffff, v62
	v_pk_fma_f32 v[98:99], v[106:107], v[98:99], s[14:15] op_sel_hi:[1,1,0]
	v_pk_fma_f32 v[108:109], v[108:109], s[10:11], 1.0 op_sel_hi:[1,0,0]
	v_pk_mul_f32 v[98:99], v[106:107], v[98:99]
	v_rcp_f32_e32 v108, v108
	v_rcp_f32_e32 v109, v109
	v_pk_mul_f32 v[98:99], v[100:101], v[98:99]
	v_cmp_gt_f32_e32 vcc, 0, v60
	v_pk_mul_f32 v[100:101], v[60:61], v[98:99]
	v_pk_fma_f32 v[98:99], v[60:61], v[98:99], v[60:61] neg_lo:[1,0,0] neg_hi:[1,0,0]
	v_pk_mul_f32 v[106:107], v[62:63], v[62:63]
	v_cndmask_b32_e32 v97, v98, v100, vcc
	v_cmp_gt_f32_e32 vcc, 0, v61
	v_pk_fma_f32 v[60:61], v[108:109], s[0:1], v[162:163] op_sel_hi:[1,0,0]
	v_and_b32_e32 v100, 0x7fffffff, v56
	v_cndmask_b32_e32 v110, v99, v101, vcc
	v_pk_mul_f32 v[98:99], v[106:107], s[18:19] op_sel_hi:[1,0]
	v_pk_fma_f32 v[60:61], v[108:109], v[60:61], s[16:17] op_sel_hi:[1,1,0]
	v_exp_f32_e32 v98, v98
	v_exp_f32_e32 v99, v99
	v_pk_fma_f32 v[60:61], v[108:109], v[60:61], s[6:7] op_sel_hi:[1,1,0]
	v_and_b32_e32 v101, 0x7fffffff, v57
	v_pk_fma_f32 v[60:61], v[108:109], v[60:61], s[14:15] op_sel_hi:[1,1,0]
	v_pk_fma_f32 v[100:101], v[100:101], s[10:11], 1.0 op_sel_hi:[1,0,0]
	v_pk_mul_f32 v[60:61], v[108:109], v[60:61]
	v_rcp_f32_e32 v100, v100
	v_rcp_f32_e32 v101, v101
	v_pk_mul_f32 v[60:61], v[98:99], v[60:61]
	v_cmp_gt_f32_e32 vcc, 0, v62
	v_pk_mul_f32 v[98:99], v[62:63], v[60:61]
	v_pk_fma_f32 v[60:61], v[62:63], v[60:61], v[62:63] neg_lo:[1,0,0] neg_hi:[1,0,0]
	s_nop 0
	v_cndmask_b32_e32 v106, v60, v98, vcc
	v_cmp_gt_f32_e32 vcc, 0, v63
	v_pk_mul_f32 v[62:63], v[56:57], v[56:57]
	s_nop 0
	v_cndmask_b32_e32 v107, v61, v99, vcc
	v_pk_fma_f32 v[60:61], v[100:101], s[0:1], v[162:163] op_sel_hi:[1,0,0]
	v_pk_mul_f32 v[62:63], v[62:63], s[18:19] op_sel_hi:[1,0]
	v_pk_fma_f32 v[60:61], v[100:101], v[60:61], s[16:17] op_sel_hi:[1,1,0]
	v_exp_f32_e32 v62, v62
	v_pk_fma_f32 v[60:61], v[100:101], v[60:61], s[6:7] op_sel_hi:[1,1,0]
	v_exp_f32_e32 v63, v63
	v_pk_fma_f32 v[60:61], v[100:101], v[60:61], s[14:15] op_sel_hi:[1,1,0]
	v_cmp_gt_f32_e32 vcc, 0, v56
	v_pk_mul_f32 v[60:61], v[100:101], v[60:61]
	v_and_b32_e32 v101, 0x7fffffff, v59
	v_and_b32_e32 v100, 0x7fffffff, v58
	v_pk_fma_f32 v[100:101], v[100:101], s[10:11], 1.0 op_sel_hi:[1,0,0]
	v_pk_mul_f32 v[60:61], v[62:63], v[60:61]
	v_rcp_f32_e32 v100, v100
	v_rcp_f32_e32 v101, v101
	v_pk_mul_f32 v[62:63], v[56:57], v[60:61]
	v_pk_fma_f32 v[60:61], v[56:57], v[60:61], v[56:57] neg_lo:[1,0,0] neg_hi:[1,0,0]
	v_pk_mul_f32 v[98:99], v[58:59], v[58:59]
	v_cndmask_b32_e32 v62, v60, v62, vcc
	v_cmp_gt_f32_e32 vcc, 0, v57
	v_pk_fma_f32 v[56:57], v[100:101], s[0:1], v[162:163] op_sel_hi:[1,0,0]
	s_nop 0
	v_cndmask_b32_e32 v63, v61, v63, vcc
	v_pk_mul_f32 v[60:61], v[98:99], s[18:19] op_sel_hi:[1,0]
	v_pk_fma_f32 v[56:57], v[100:101], v[56:57], s[16:17] op_sel_hi:[1,1,0]
	v_exp_f32_e32 v60, v60
	v_exp_f32_e32 v61, v61
	v_pk_fma_f32 v[56:57], v[100:101], v[56:57], s[6:7] op_sel_hi:[1,1,0]
	v_cmp_gt_f32_e32 vcc, 0, v58
	v_pk_fma_f32 v[56:57], v[100:101], v[56:57], s[14:15] op_sel_hi:[1,1,0]
	s_nop 0
	v_pk_mul_f32 v[56:57], v[100:101], v[56:57]
	s_nop 0
	v_pk_mul_f32 v[56:57], v[60:61], v[56:57]
	s_nop 0
	v_pk_mul_f32 v[60:61], v[58:59], v[56:57]
	v_pk_fma_f32 v[56:57], v[58:59], v[56:57], v[58:59] neg_lo:[1,0,0] neg_hi:[1,0,0]
	s_nop 0
	v_cndmask_b32_e32 v60, v56, v60, vcc
	v_cmp_gt_f32_e32 vcc, 0, v59
	v_cvt_pk_bf16_f32 v56, v97, v110
	v_ashrrev_i32_e32 v97, 31, v96
	s_nop 0
	v_cndmask_b32_e32 v59, v57, v61, vcc
	v_cvt_pk_bf16_f32 v57, v106, v107
	v_cvt_pk_bf16_f32 v58, v62, v63
	v_cvt_pk_bf16_f32 v59, v60, v59
	v_lshlrev_b64 v[60:61], 10, v[96:97]
	v_lshl_add_u64 v[60:61], s[20:21], 0, v[60:61]
	v_lshl_add_u64 v[60:61], v[60:61], 0, s[40:41]
	v_lshl_add_u64 v[60:61], v[60:61], 0, v[160:161]
	global_store_dwordx4 v[60:61], v[56:59], off
	s_waitcnt vmcnt(7)
	v_lshlrev_b32_e32 v60, 16, v104
	v_and_b32_e32 v61, 0xffff0000, v104
	v_lshlrev_b32_e32 v56, 16, v102
	v_and_b32_e32 v57, 0xffff0000, v102
	v_pk_fma_f32 v[52:53], v[68:69], v[56:57], v[52:53]
	v_lshlrev_b32_e32 v58, 16, v103
	v_and_b32_e32 v57, 0x7fffffff, v53
	v_and_b32_e32 v56, 0x7fffffff, v52
	v_pk_fma_f32 v[56:57], v[56:57], s[10:11], 1.0 op_sel_hi:[1,0,0]
	v_and_b32_e32 v59, 0xffff0000, v103
	v_rcp_f32_e32 v56, v56
	v_rcp_f32_e32 v57, v57
	v_pk_fma_f32 v[48:49], v[64:65], v[60:61], v[48:49]
	v_pk_mul_f32 v[60:61], v[52:53], v[52:53]
	v_pk_fma_f32 v[54:55], v[70:71], v[58:59], v[54:55]
	v_pk_fma_f32 v[58:59], v[56:57], s[0:1], v[162:163] op_sel_hi:[1,0,0]
	v_pk_mul_f32 v[60:61], v[60:61], s[18:19] op_sel_hi:[1,0]
	v_lshlrev_b32_e32 v62, 16, v105
	v_and_b32_e32 v63, 0xffff0000, v105
	v_pk_fma_f32 v[58:59], v[56:57], v[58:59], s[16:17] op_sel_hi:[1,1,0]
	v_exp_f32_e32 v60, v60
	v_exp_f32_e32 v61, v61
	v_pk_fma_f32 v[50:51], v[66:67], v[62:63], v[50:51]
	v_pk_fma_f32 v[58:59], v[56:57], v[58:59], s[6:7] op_sel_hi:[1,1,0]
	v_and_b32_e32 v63, 0x7fffffff, v55
	v_and_b32_e32 v62, 0x7fffffff, v54
	v_pk_fma_f32 v[58:59], v[56:57], v[58:59], s[14:15] op_sel_hi:[1,1,0]
	v_pk_fma_f32 v[62:63], v[62:63], s[10:11], 1.0 op_sel_hi:[1,0,0]
	v_pk_mul_f32 v[56:57], v[56:57], v[58:59]
	v_rcp_f32_e32 v62, v62
	v_rcp_f32_e32 v63, v63
	v_pk_mul_f32 v[56:57], v[60:61], v[56:57]
	v_cmp_gt_f32_e32 vcc, 0, v52
	v_pk_mul_f32 v[60:61], v[52:53], v[56:57]
	v_pk_fma_f32 v[56:57], v[52:53], v[56:57], v[52:53] neg_lo:[1,0,0] neg_hi:[1,0,0]
	v_pk_mul_f32 v[58:59], v[54:55], v[54:55]
	v_cndmask_b32_e32 v60, v56, v60, vcc
	v_cmp_gt_f32_e32 vcc, 0, v53
	v_pk_fma_f32 v[52:53], v[62:63], s[0:1], v[162:163] op_sel_hi:[1,0,0]
	s_nop 0
	v_cndmask_b32_e32 v61, v57, v61, vcc
	v_pk_mul_f32 v[56:57], v[58:59], s[18:19] op_sel_hi:[1,0]
	v_pk_fma_f32 v[52:53], v[62:63], v[52:53], s[16:17] op_sel_hi:[1,1,0]
	v_exp_f32_e32 v56, v56
	v_exp_f32_e32 v57, v57
	v_pk_fma_f32 v[52:53], v[62:63], v[52:53], s[6:7] op_sel_hi:[1,1,0]
	v_and_b32_e32 v59, 0x7fffffff, v49
	v_and_b32_e32 v58, 0x7fffffff, v48
	v_pk_fma_f32 v[52:53], v[62:63], v[52:53], s[14:15] op_sel_hi:[1,1,0]
	v_pk_fma_f32 v[58:59], v[58:59], s[10:11], 1.0 op_sel_hi:[1,0,0]
	v_pk_mul_f32 v[52:53], v[62:63], v[52:53]
	v_rcp_f32_e32 v58, v58
	v_rcp_f32_e32 v59, v59
	v_pk_mul_f32 v[52:53], v[56:57], v[52:53]
	v_cmp_gt_f32_e32 vcc, 0, v54
	v_pk_mul_f32 v[56:57], v[54:55], v[52:53]
	v_pk_fma_f32 v[52:53], v[54:55], v[52:53], v[54:55] neg_lo:[1,0,0] neg_hi:[1,0,0]
	s_nop 0
	v_cndmask_b32_e32 v62, v52, v56, vcc
	v_cmp_gt_f32_e32 vcc, 0, v55
	v_pk_mul_f32 v[54:55], v[48:49], v[48:49]
	s_nop 0
	v_cndmask_b32_e32 v63, v53, v57, vcc
	v_pk_fma_f32 v[52:53], v[58:59], s[0:1], v[162:163] op_sel_hi:[1,0,0]
	v_pk_mul_f32 v[54:55], v[54:55], s[18:19] op_sel_hi:[1,0]
	v_pk_fma_f32 v[52:53], v[58:59], v[52:53], s[16:17] op_sel_hi:[1,1,0]
	v_exp_f32_e32 v54, v54
	v_pk_fma_f32 v[52:53], v[58:59], v[52:53], s[6:7] op_sel_hi:[1,1,0]
	v_exp_f32_e32 v55, v55
	v_pk_fma_f32 v[52:53], v[58:59], v[52:53], s[14:15] op_sel_hi:[1,1,0]
	v_cmp_gt_f32_e32 vcc, 0, v48
	v_pk_mul_f32 v[52:53], v[58:59], v[52:53]
	v_and_b32_e32 v59, 0x7fffffff, v51
	v_and_b32_e32 v58, 0x7fffffff, v50
	v_pk_fma_f32 v[58:59], v[58:59], s[10:11], 1.0 op_sel_hi:[1,0,0]
	v_pk_mul_f32 v[52:53], v[54:55], v[52:53]
	v_rcp_f32_e32 v58, v58
	v_rcp_f32_e32 v59, v59
	v_pk_mul_f32 v[54:55], v[48:49], v[52:53]
	v_pk_fma_f32 v[52:53], v[48:49], v[52:53], v[48:49] neg_lo:[1,0,0] neg_hi:[1,0,0]
	v_pk_mul_f32 v[56:57], v[50:51], v[50:51]
	v_cndmask_b32_e32 v54, v52, v54, vcc
	v_cmp_gt_f32_e32 vcc, 0, v49
	v_pk_fma_f32 v[48:49], v[58:59], s[0:1], v[162:163] op_sel_hi:[1,0,0]
	s_nop 0
	v_cndmask_b32_e32 v55, v53, v55, vcc
	v_pk_mul_f32 v[52:53], v[56:57], s[18:19] op_sel_hi:[1,0]
	v_pk_fma_f32 v[48:49], v[58:59], v[48:49], s[16:17] op_sel_hi:[1,1,0]
	v_exp_f32_e32 v52, v52
	v_exp_f32_e32 v53, v53
	v_pk_fma_f32 v[48:49], v[58:59], v[48:49], s[6:7] op_sel_hi:[1,1,0]
	v_cmp_gt_f32_e32 vcc, 0, v50
	v_pk_fma_f32 v[48:49], v[58:59], v[48:49], s[14:15] op_sel_hi:[1,1,0]
	s_nop 0
	v_pk_mul_f32 v[48:49], v[58:59], v[48:49]
	s_nop 0
	v_pk_mul_f32 v[48:49], v[52:53], v[48:49]
	s_nop 0
	v_pk_mul_f32 v[52:53], v[50:51], v[48:49]
	v_pk_fma_f32 v[48:49], v[50:51], v[48:49], v[50:51] neg_lo:[1,0,0] neg_hi:[1,0,0]
	s_nop 0
	v_cndmask_b32_e32 v52, v48, v52, vcc
	v_cmp_gt_f32_e32 vcc, 0, v51
	v_cvt_pk_bf16_f32 v48, v60, v61
	s_nop 1
	v_cndmask_b32_e32 v51, v49, v53, vcc
	v_cvt_pk_bf16_f32 v49, v62, v63
	v_cvt_pk_bf16_f32 v50, v54, v55
	v_cvt_pk_bf16_f32 v51, v52, v51
	v_or_b32_e32 v52, 0x200, v96
	v_ashrrev_i32_e32 v53, 31, v52
	v_lshlrev_b64 v[52:53], 10, v[52:53]
	v_lshl_add_u64 v[52:53], s[20:21], 0, v[52:53]
	v_lshl_add_u64 v[52:53], v[52:53], 0, s[40:41]
	v_lshl_add_u64 v[52:53], v[52:53], 0, v[160:161]
	global_store_dwordx4 v[52:53], v[48:51], off
	s_waitcnt vmcnt(7)
	v_lshlrev_b32_e32 v52, 16, v94
	v_and_b32_e32 v53, 0xffff0000, v94
	v_lshlrev_b32_e32 v48, 16, v92
	v_and_b32_e32 v49, 0xffff0000, v92
	v_pk_fma_f32 v[44:45], v[68:69], v[48:49], v[44:45]
	v_lshlrev_b32_e32 v50, 16, v93
	v_and_b32_e32 v49, 0x7fffffff, v45
	v_and_b32_e32 v48, 0x7fffffff, v44
	v_pk_fma_f32 v[48:49], v[48:49], s[10:11], 1.0 op_sel_hi:[1,0,0]
	v_and_b32_e32 v51, 0xffff0000, v93
	v_rcp_f32_e32 v48, v48
	v_rcp_f32_e32 v49, v49
	v_pk_fma_f32 v[40:41], v[64:65], v[52:53], v[40:41]
	v_pk_mul_f32 v[52:53], v[44:45], v[44:45]
	v_pk_fma_f32 v[46:47], v[70:71], v[50:51], v[46:47]
	v_pk_fma_f32 v[50:51], v[48:49], s[0:1], v[162:163] op_sel_hi:[1,0,0]
	v_pk_mul_f32 v[52:53], v[52:53], s[18:19] op_sel_hi:[1,0]
	v_lshlrev_b32_e32 v54, 16, v95
	v_and_b32_e32 v55, 0xffff0000, v95
	v_pk_fma_f32 v[50:51], v[48:49], v[50:51], s[16:17] op_sel_hi:[1,1,0]
	v_exp_f32_e32 v52, v52
	v_exp_f32_e32 v53, v53
	v_pk_fma_f32 v[42:43], v[66:67], v[54:55], v[42:43]
	v_pk_fma_f32 v[50:51], v[48:49], v[50:51], s[6:7] op_sel_hi:[1,1,0]
	v_and_b32_e32 v55, 0x7fffffff, v47
	v_and_b32_e32 v54, 0x7fffffff, v46
	v_pk_fma_f32 v[50:51], v[48:49], v[50:51], s[14:15] op_sel_hi:[1,1,0]
	v_pk_fma_f32 v[54:55], v[54:55], s[10:11], 1.0 op_sel_hi:[1,0,0]
	v_pk_mul_f32 v[48:49], v[48:49], v[50:51]
	v_rcp_f32_e32 v54, v54
	v_rcp_f32_e32 v55, v55
	v_pk_mul_f32 v[48:49], v[52:53], v[48:49]
	v_cmp_gt_f32_e32 vcc, 0, v44
	v_pk_mul_f32 v[52:53], v[44:45], v[48:49]
	v_pk_fma_f32 v[48:49], v[44:45], v[48:49], v[44:45] neg_lo:[1,0,0] neg_hi:[1,0,0]
	v_pk_mul_f32 v[50:51], v[46:47], v[46:47]
	v_cndmask_b32_e32 v52, v48, v52, vcc
	v_cmp_gt_f32_e32 vcc, 0, v45
	v_pk_fma_f32 v[44:45], v[54:55], s[0:1], v[162:163] op_sel_hi:[1,0,0]
	s_nop 0
	v_cndmask_b32_e32 v53, v49, v53, vcc
	v_pk_mul_f32 v[48:49], v[50:51], s[18:19] op_sel_hi:[1,0]
	v_pk_fma_f32 v[44:45], v[54:55], v[44:45], s[16:17] op_sel_hi:[1,1,0]
	v_exp_f32_e32 v48, v48
	v_exp_f32_e32 v49, v49
	v_pk_fma_f32 v[44:45], v[54:55], v[44:45], s[6:7] op_sel_hi:[1,1,0]
	v_and_b32_e32 v51, 0x7fffffff, v41
	v_and_b32_e32 v50, 0x7fffffff, v40
	v_pk_fma_f32 v[44:45], v[54:55], v[44:45], s[14:15] op_sel_hi:[1,1,0]
	v_pk_fma_f32 v[50:51], v[50:51], s[10:11], 1.0 op_sel_hi:[1,0,0]
	v_pk_mul_f32 v[44:45], v[54:55], v[44:45]
	v_rcp_f32_e32 v50, v50
	v_rcp_f32_e32 v51, v51
	v_pk_mul_f32 v[44:45], v[48:49], v[44:45]
	v_cmp_gt_f32_e32 vcc, 0, v46
	v_pk_mul_f32 v[48:49], v[46:47], v[44:45]
	v_pk_fma_f32 v[44:45], v[46:47], v[44:45], v[46:47] neg_lo:[1,0,0] neg_hi:[1,0,0]
	s_nop 0
	v_cndmask_b32_e32 v54, v44, v48, vcc
	v_cmp_gt_f32_e32 vcc, 0, v47
	v_pk_mul_f32 v[46:47], v[40:41], v[40:41]
	s_nop 0
	v_cndmask_b32_e32 v55, v45, v49, vcc
	v_pk_fma_f32 v[44:45], v[50:51], s[0:1], v[162:163] op_sel_hi:[1,0,0]
	v_pk_mul_f32 v[46:47], v[46:47], s[18:19] op_sel_hi:[1,0]
	v_pk_fma_f32 v[44:45], v[50:51], v[44:45], s[16:17] op_sel_hi:[1,1,0]
	v_exp_f32_e32 v46, v46
	v_pk_fma_f32 v[44:45], v[50:51], v[44:45], s[6:7] op_sel_hi:[1,1,0]
	v_exp_f32_e32 v47, v47
	v_pk_fma_f32 v[44:45], v[50:51], v[44:45], s[14:15] op_sel_hi:[1,1,0]
	v_cmp_gt_f32_e32 vcc, 0, v40
	v_pk_mul_f32 v[44:45], v[50:51], v[44:45]
	v_and_b32_e32 v51, 0x7fffffff, v43
	v_and_b32_e32 v50, 0x7fffffff, v42
	v_pk_fma_f32 v[50:51], v[50:51], s[10:11], 1.0 op_sel_hi:[1,0,0]
	v_pk_mul_f32 v[44:45], v[46:47], v[44:45]
	v_rcp_f32_e32 v50, v50
	v_rcp_f32_e32 v51, v51
	v_pk_mul_f32 v[46:47], v[40:41], v[44:45]
	v_pk_fma_f32 v[44:45], v[40:41], v[44:45], v[40:41] neg_lo:[1,0,0] neg_hi:[1,0,0]
	v_pk_mul_f32 v[48:49], v[42:43], v[42:43]
	v_cndmask_b32_e32 v46, v44, v46, vcc
	v_cmp_gt_f32_e32 vcc, 0, v41
	v_pk_fma_f32 v[40:41], v[50:51], s[0:1], v[162:163] op_sel_hi:[1,0,0]
	s_nop 0
	v_cndmask_b32_e32 v47, v45, v47, vcc
	v_pk_mul_f32 v[44:45], v[48:49], s[18:19] op_sel_hi:[1,0]
	v_pk_fma_f32 v[40:41], v[50:51], v[40:41], s[16:17] op_sel_hi:[1,1,0]
	v_exp_f32_e32 v44, v44
	v_exp_f32_e32 v45, v45
	v_pk_fma_f32 v[40:41], v[50:51], v[40:41], s[6:7] op_sel_hi:[1,1,0]
	v_cmp_gt_f32_e32 vcc, 0, v42
	v_pk_fma_f32 v[40:41], v[50:51], v[40:41], s[14:15] op_sel_hi:[1,1,0]
	s_nop 0
	v_pk_mul_f32 v[40:41], v[50:51], v[40:41]
	s_nop 0
	v_pk_mul_f32 v[40:41], v[44:45], v[40:41]
	s_nop 0
	v_pk_mul_f32 v[44:45], v[42:43], v[40:41]
	v_pk_fma_f32 v[40:41], v[42:43], v[40:41], v[42:43] neg_lo:[1,0,0] neg_hi:[1,0,0]
	s_nop 0
	v_cndmask_b32_e32 v44, v40, v44, vcc
	v_cmp_gt_f32_e32 vcc, 0, v43
	v_cvt_pk_bf16_f32 v40, v52, v53
	s_nop 1
	v_cndmask_b32_e32 v43, v41, v45, vcc
	v_cvt_pk_bf16_f32 v41, v54, v55
	v_cvt_pk_bf16_f32 v42, v46, v47
	v_cvt_pk_bf16_f32 v43, v44, v43
	v_or_b32_e32 v44, 0x400, v96
	v_ashrrev_i32_e32 v45, 31, v44
	v_lshlrev_b64 v[44:45], 10, v[44:45]
	v_lshl_add_u64 v[44:45], s[20:21], 0, v[44:45]
	v_lshl_add_u64 v[44:45], v[44:45], 0, s[40:41]
	v_lshl_add_u64 v[44:45], v[44:45], 0, v[160:161]
	global_store_dwordx4 v[44:45], v[40:43], off
	s_waitcnt vmcnt(7)
	v_lshlrev_b32_e32 v44, 16, v90
	v_and_b32_e32 v45, 0xffff0000, v90
	v_lshlrev_b32_e32 v40, 16, v88
	v_and_b32_e32 v41, 0xffff0000, v88
	v_pk_fma_f32 v[36:37], v[68:69], v[40:41], v[36:37]
	v_lshlrev_b32_e32 v42, 16, v89
	v_and_b32_e32 v41, 0x7fffffff, v37
	v_and_b32_e32 v40, 0x7fffffff, v36
	v_pk_fma_f32 v[40:41], v[40:41], s[10:11], 1.0 op_sel_hi:[1,0,0]
	v_and_b32_e32 v43, 0xffff0000, v89
	v_rcp_f32_e32 v40, v40
	v_rcp_f32_e32 v41, v41
	v_pk_fma_f32 v[32:33], v[64:65], v[44:45], v[32:33]
	v_pk_mul_f32 v[44:45], v[36:37], v[36:37]
	v_pk_fma_f32 v[38:39], v[70:71], v[42:43], v[38:39]
	v_pk_fma_f32 v[42:43], v[40:41], s[0:1], v[162:163] op_sel_hi:[1,0,0]
	v_pk_mul_f32 v[44:45], v[44:45], s[18:19] op_sel_hi:[1,0]
	v_lshlrev_b32_e32 v46, 16, v91
	v_and_b32_e32 v47, 0xffff0000, v91
	v_pk_fma_f32 v[42:43], v[40:41], v[42:43], s[16:17] op_sel_hi:[1,1,0]
	v_exp_f32_e32 v44, v44
	v_exp_f32_e32 v45, v45
	v_pk_fma_f32 v[34:35], v[66:67], v[46:47], v[34:35]
	v_pk_fma_f32 v[42:43], v[40:41], v[42:43], s[6:7] op_sel_hi:[1,1,0]
	v_and_b32_e32 v47, 0x7fffffff, v39
	v_and_b32_e32 v46, 0x7fffffff, v38
	v_pk_fma_f32 v[42:43], v[40:41], v[42:43], s[14:15] op_sel_hi:[1,1,0]
	v_pk_fma_f32 v[46:47], v[46:47], s[10:11], 1.0 op_sel_hi:[1,0,0]
	v_pk_mul_f32 v[40:41], v[40:41], v[42:43]
	v_rcp_f32_e32 v46, v46
	v_rcp_f32_e32 v47, v47
	v_pk_mul_f32 v[40:41], v[44:45], v[40:41]
	v_cmp_gt_f32_e32 vcc, 0, v36
	v_pk_mul_f32 v[44:45], v[36:37], v[40:41]
	v_pk_fma_f32 v[40:41], v[36:37], v[40:41], v[36:37] neg_lo:[1,0,0] neg_hi:[1,0,0]
	v_pk_mul_f32 v[42:43], v[38:39], v[38:39]
	v_cndmask_b32_e32 v44, v40, v44, vcc
	v_cmp_gt_f32_e32 vcc, 0, v37
	v_pk_fma_f32 v[36:37], v[46:47], s[0:1], v[162:163] op_sel_hi:[1,0,0]
	s_nop 0
	v_cndmask_b32_e32 v45, v41, v45, vcc
	v_pk_mul_f32 v[40:41], v[42:43], s[18:19] op_sel_hi:[1,0]
	v_pk_fma_f32 v[36:37], v[46:47], v[36:37], s[16:17] op_sel_hi:[1,1,0]
	v_exp_f32_e32 v40, v40
	v_exp_f32_e32 v41, v41
	v_pk_fma_f32 v[36:37], v[46:47], v[36:37], s[6:7] op_sel_hi:[1,1,0]
	v_and_b32_e32 v43, 0x7fffffff, v33
	v_and_b32_e32 v42, 0x7fffffff, v32
	v_pk_fma_f32 v[36:37], v[46:47], v[36:37], s[14:15] op_sel_hi:[1,1,0]
	v_pk_fma_f32 v[42:43], v[42:43], s[10:11], 1.0 op_sel_hi:[1,0,0]
	v_pk_mul_f32 v[36:37], v[46:47], v[36:37]
	v_rcp_f32_e32 v42, v42
	v_rcp_f32_e32 v43, v43
	v_pk_mul_f32 v[36:37], v[40:41], v[36:37]
	v_cmp_gt_f32_e32 vcc, 0, v38
	v_pk_mul_f32 v[40:41], v[38:39], v[36:37]
	v_pk_fma_f32 v[36:37], v[38:39], v[36:37], v[38:39] neg_lo:[1,0,0] neg_hi:[1,0,0]
	s_nop 0
	v_cndmask_b32_e32 v46, v36, v40, vcc
	v_cmp_gt_f32_e32 vcc, 0, v39
	v_pk_mul_f32 v[38:39], v[32:33], v[32:33]
	s_nop 0
	v_cndmask_b32_e32 v47, v37, v41, vcc
	v_pk_fma_f32 v[36:37], v[42:43], s[0:1], v[162:163] op_sel_hi:[1,0,0]
	v_pk_mul_f32 v[38:39], v[38:39], s[18:19] op_sel_hi:[1,0]
	v_pk_fma_f32 v[36:37], v[42:43], v[36:37], s[16:17] op_sel_hi:[1,1,0]
	v_exp_f32_e32 v38, v38
	v_pk_fma_f32 v[36:37], v[42:43], v[36:37], s[6:7] op_sel_hi:[1,1,0]
	v_exp_f32_e32 v39, v39
	v_pk_fma_f32 v[36:37], v[42:43], v[36:37], s[14:15] op_sel_hi:[1,1,0]
	v_cmp_gt_f32_e32 vcc, 0, v32
	v_pk_mul_f32 v[36:37], v[42:43], v[36:37]
	v_and_b32_e32 v43, 0x7fffffff, v35
	v_and_b32_e32 v42, 0x7fffffff, v34
	v_pk_fma_f32 v[42:43], v[42:43], s[10:11], 1.0 op_sel_hi:[1,0,0]
	v_pk_mul_f32 v[36:37], v[38:39], v[36:37]
	v_rcp_f32_e32 v42, v42
	v_rcp_f32_e32 v43, v43
	v_pk_mul_f32 v[38:39], v[32:33], v[36:37]
	v_pk_fma_f32 v[36:37], v[32:33], v[36:37], v[32:33] neg_lo:[1,0,0] neg_hi:[1,0,0]
	v_pk_mul_f32 v[40:41], v[34:35], v[34:35]
	v_cndmask_b32_e32 v38, v36, v38, vcc
	v_cmp_gt_f32_e32 vcc, 0, v33
	v_pk_fma_f32 v[32:33], v[42:43], s[0:1], v[162:163] op_sel_hi:[1,0,0]
	s_nop 0
	v_cndmask_b32_e32 v39, v37, v39, vcc
	v_pk_mul_f32 v[36:37], v[40:41], s[18:19] op_sel_hi:[1,0]
	v_pk_fma_f32 v[32:33], v[42:43], v[32:33], s[16:17] op_sel_hi:[1,1,0]
	v_exp_f32_e32 v36, v36
	v_exp_f32_e32 v37, v37
	v_pk_fma_f32 v[32:33], v[42:43], v[32:33], s[6:7] op_sel_hi:[1,1,0]
	v_cmp_gt_f32_e32 vcc, 0, v34
	v_pk_fma_f32 v[32:33], v[42:43], v[32:33], s[14:15] op_sel_hi:[1,1,0]
	s_waitcnt vmcnt(6)
	v_lshlrev_b32_e32 v40, 16, v87
	v_pk_mul_f32 v[32:33], v[42:43], v[32:33]
	v_and_b32_e32 v41, 0xffff0000, v87
	v_pk_mul_f32 v[32:33], v[36:37], v[32:33]
	v_pk_fma_f32 v[26:27], v[66:67], v[40:41], v[26:27]
	v_pk_mul_f32 v[36:37], v[34:35], v[32:33]
	v_pk_fma_f32 v[32:33], v[34:35], v[32:33], v[34:35] neg_lo:[1,0,0] neg_hi:[1,0,0]
	s_nop 0
	v_cndmask_b32_e32 v36, v32, v36, vcc
	v_cmp_gt_f32_e32 vcc, 0, v35
	v_cvt_pk_bf16_f32 v32, v44, v45
	s_nop 1
	v_cndmask_b32_e32 v35, v33, v37, vcc
	v_cvt_pk_bf16_f32 v33, v46, v47
	v_cvt_pk_bf16_f32 v34, v38, v39
	v_cvt_pk_bf16_f32 v35, v36, v35
	v_or_b32_e32 v36, 0x600, v96
	v_ashrrev_i32_e32 v37, 31, v36
	v_lshlrev_b64 v[36:37], 10, v[36:37]
	v_lshl_add_u64 v[36:37], s[20:21], 0, v[36:37]
	v_lshl_add_u64 v[36:37], v[36:37], 0, s[40:41]
	v_lshl_add_u64 v[36:37], v[36:37], 0, v[160:161]
	global_store_dwordx4 v[36:37], v[32:35], off
	v_lshlrev_b32_e32 v38, 16, v86
	v_and_b32_e32 v39, 0xffff0000, v86
	v_lshlrev_b32_e32 v34, 16, v84
	v_and_b32_e32 v35, 0xffff0000, v84
	v_pk_fma_f32 v[28:29], v[68:69], v[34:35], v[28:29]
	v_lshlrev_b32_e32 v36, 16, v85
	v_and_b32_e32 v35, 0x7fffffff, v29
	v_and_b32_e32 v34, 0x7fffffff, v28
	v_pk_fma_f32 v[34:35], v[34:35], s[10:11], 1.0 op_sel_hi:[1,0,0]
	v_and_b32_e32 v37, 0xffff0000, v85
	v_rcp_f32_e32 v34, v34
	v_rcp_f32_e32 v35, v35
	v_pk_fma_f32 v[24:25], v[64:65], v[38:39], v[24:25]
	v_pk_mul_f32 v[38:39], v[28:29], v[28:29]
	v_pk_fma_f32 v[30:31], v[70:71], v[36:37], v[30:31]
	v_pk_fma_f32 v[36:37], v[34:35], s[0:1], v[162:163] op_sel_hi:[1,0,0]
	v_pk_mul_f32 v[38:39], v[38:39], s[18:19] op_sel_hi:[1,0]
	v_pk_fma_f32 v[36:37], v[34:35], v[36:37], s[16:17] op_sel_hi:[1,1,0]
	v_exp_f32_e32 v38, v38
	v_exp_f32_e32 v39, v39
	v_pk_fma_f32 v[36:37], v[34:35], v[36:37], s[6:7] op_sel_hi:[1,1,0]
	v_and_b32_e32 v41, 0x7fffffff, v31
	v_and_b32_e32 v40, 0x7fffffff, v30
	v_pk_fma_f32 v[36:37], v[34:35], v[36:37], s[14:15] op_sel_hi:[1,1,0]
	v_pk_fma_f32 v[40:41], v[40:41], s[10:11], 1.0 op_sel_hi:[1,0,0]
	v_pk_mul_f32 v[34:35], v[34:35], v[36:37]
	v_rcp_f32_e32 v40, v40
	v_rcp_f32_e32 v41, v41
	v_pk_mul_f32 v[34:35], v[38:39], v[34:35]
	v_cmp_gt_f32_e32 vcc, 0, v28
	v_pk_mul_f32 v[38:39], v[28:29], v[34:35]
	v_pk_fma_f32 v[34:35], v[28:29], v[34:35], v[28:29] neg_lo:[1,0,0] neg_hi:[1,0,0]
	v_pk_mul_f32 v[36:37], v[30:31], v[30:31]
	v_cndmask_b32_e32 v33, v34, v38, vcc
	v_cmp_gt_f32_e32 vcc, 0, v29
	v_pk_fma_f32 v[28:29], v[40:41], s[0:1], v[162:163] op_sel_hi:[1,0,0]
	v_add_u32_e32 v32, 0x1000, v96
	v_cndmask_b32_e32 v38, v35, v39, vcc
	v_pk_mul_f32 v[34:35], v[36:37], s[18:19] op_sel_hi:[1,0]
	v_pk_fma_f32 v[28:29], v[40:41], v[28:29], s[16:17] op_sel_hi:[1,1,0]
	v_exp_f32_e32 v34, v34
	v_exp_f32_e32 v35, v35
	v_pk_fma_f32 v[28:29], v[40:41], v[28:29], s[6:7] op_sel_hi:[1,1,0]
	v_and_b32_e32 v37, 0x7fffffff, v25
	v_and_b32_e32 v36, 0x7fffffff, v24
	v_pk_fma_f32 v[28:29], v[40:41], v[28:29], s[14:15] op_sel_hi:[1,1,0]
	v_pk_fma_f32 v[36:37], v[36:37], s[10:11], 1.0 op_sel_hi:[1,0,0]
	v_pk_mul_f32 v[28:29], v[40:41], v[28:29]
	v_rcp_f32_e32 v36, v36
	v_rcp_f32_e32 v37, v37
	v_pk_mul_f32 v[28:29], v[34:35], v[28:29]
	v_cmp_gt_f32_e32 vcc, 0, v30
	v_pk_mul_f32 v[34:35], v[30:31], v[28:29]
	v_pk_fma_f32 v[28:29], v[30:31], v[28:29], v[30:31] neg_lo:[1,0,0] neg_hi:[1,0,0]
	s_nop 0
	v_cndmask_b32_e32 v39, v28, v34, vcc
	v_cmp_gt_f32_e32 vcc, 0, v31
	v_pk_mul_f32 v[30:31], v[24:25], v[24:25]
	s_nop 0
	v_cndmask_b32_e32 v40, v29, v35, vcc
	v_pk_fma_f32 v[28:29], v[36:37], s[0:1], v[162:163] op_sel_hi:[1,0,0]
	v_pk_mul_f32 v[30:31], v[30:31], s[18:19] op_sel_hi:[1,0]
	v_pk_fma_f32 v[28:29], v[36:37], v[28:29], s[16:17] op_sel_hi:[1,1,0]
	v_exp_f32_e32 v30, v30
	v_pk_fma_f32 v[28:29], v[36:37], v[28:29], s[6:7] op_sel_hi:[1,1,0]
	v_exp_f32_e32 v31, v31
	v_pk_fma_f32 v[28:29], v[36:37], v[28:29], s[14:15] op_sel_hi:[1,1,0]
	v_cmp_gt_f32_e32 vcc, 0, v24
	v_pk_mul_f32 v[28:29], v[36:37], v[28:29]
	v_and_b32_e32 v37, 0x7fffffff, v27
	v_and_b32_e32 v36, 0x7fffffff, v26
	v_pk_fma_f32 v[36:37], v[36:37], s[10:11], 1.0 op_sel_hi:[1,0,0]
	v_pk_mul_f32 v[28:29], v[30:31], v[28:29]
	v_rcp_f32_e32 v36, v36
	v_rcp_f32_e32 v37, v37
	v_pk_mul_f32 v[30:31], v[24:25], v[28:29]
	v_pk_fma_f32 v[28:29], v[24:25], v[28:29], v[24:25] neg_lo:[1,0,0] neg_hi:[1,0,0]
	v_pk_mul_f32 v[34:35], v[26:27], v[26:27]
	v_cndmask_b32_e32 v30, v28, v30, vcc
	v_cmp_gt_f32_e32 vcc, 0, v25
	v_pk_fma_f32 v[24:25], v[36:37], s[0:1], v[162:163] op_sel_hi:[1,0,0]
	s_nop 0
	v_cndmask_b32_e32 v31, v29, v31, vcc
	v_pk_mul_f32 v[28:29], v[34:35], s[18:19] op_sel_hi:[1,0]
	v_pk_fma_f32 v[24:25], v[36:37], v[24:25], s[16:17] op_sel_hi:[1,1,0]
	v_exp_f32_e32 v28, v28
	v_exp_f32_e32 v29, v29
	v_pk_fma_f32 v[24:25], v[36:37], v[24:25], s[6:7] op_sel_hi:[1,1,0]
	v_cmp_gt_f32_e32 vcc, 0, v26
	v_pk_fma_f32 v[24:25], v[36:37], v[24:25], s[14:15] op_sel_hi:[1,1,0]
	s_nop 0
	v_pk_mul_f32 v[24:25], v[36:37], v[24:25]
	s_nop 0
	v_pk_mul_f32 v[24:25], v[28:29], v[24:25]
	s_nop 0
	v_pk_mul_f32 v[28:29], v[26:27], v[24:25]
	v_pk_fma_f32 v[24:25], v[26:27], v[24:25], v[26:27] neg_lo:[1,0,0] neg_hi:[1,0,0]
	s_nop 0
	v_cndmask_b32_e32 v28, v24, v28, vcc
	v_cmp_gt_f32_e32 vcc, 0, v27
	v_cvt_pk_bf16_f32 v24, v33, v38
	v_ashrrev_i32_e32 v33, 31, v32
	s_nop 0
	v_cndmask_b32_e32 v27, v25, v29, vcc
	v_cvt_pk_bf16_f32 v25, v39, v40
	v_cvt_pk_bf16_f32 v26, v30, v31
	v_cvt_pk_bf16_f32 v27, v28, v27
	v_lshlrev_b64 v[28:29], 10, v[32:33]
	v_lshl_add_u64 v[28:29], s[20:21], 0, v[28:29]
	v_lshl_add_u64 v[28:29], v[28:29], 0, s[40:41]
	v_lshl_add_u64 v[28:29], v[28:29], 0, v[160:161]
	global_store_dwordx4 v[28:29], v[24:27], off
	s_waitcnt vmcnt(7)
	v_lshlrev_b32_e32 v28, 16, v82
	v_and_b32_e32 v29, 0xffff0000, v82
	v_lshlrev_b32_e32 v24, 16, v80
	v_and_b32_e32 v25, 0xffff0000, v80
	v_pk_fma_f32 v[20:21], v[68:69], v[24:25], v[20:21]
	v_lshlrev_b32_e32 v26, 16, v81
	v_and_b32_e32 v25, 0x7fffffff, v21
	v_and_b32_e32 v24, 0x7fffffff, v20
	v_pk_fma_f32 v[24:25], v[24:25], s[10:11], 1.0 op_sel_hi:[1,0,0]
	v_and_b32_e32 v27, 0xffff0000, v81
	v_rcp_f32_e32 v24, v24
	v_rcp_f32_e32 v25, v25
	v_pk_fma_f32 v[16:17], v[64:65], v[28:29], v[16:17]
	v_pk_mul_f32 v[28:29], v[20:21], v[20:21]
	v_pk_fma_f32 v[22:23], v[70:71], v[26:27], v[22:23]
	v_pk_fma_f32 v[26:27], v[24:25], s[0:1], v[162:163] op_sel_hi:[1,0,0]
	v_pk_mul_f32 v[28:29], v[28:29], s[18:19] op_sel_hi:[1,0]
	v_lshlrev_b32_e32 v30, 16, v83
	v_and_b32_e32 v31, 0xffff0000, v83
	v_pk_fma_f32 v[26:27], v[24:25], v[26:27], s[16:17] op_sel_hi:[1,1,0]
	v_exp_f32_e32 v28, v28
	v_exp_f32_e32 v29, v29
	v_pk_fma_f32 v[18:19], v[66:67], v[30:31], v[18:19]
	v_pk_fma_f32 v[26:27], v[24:25], v[26:27], s[6:7] op_sel_hi:[1,1,0]
	v_and_b32_e32 v31, 0x7fffffff, v23
	v_and_b32_e32 v30, 0x7fffffff, v22
	v_pk_fma_f32 v[26:27], v[24:25], v[26:27], s[14:15] op_sel_hi:[1,1,0]
	v_pk_fma_f32 v[30:31], v[30:31], s[10:11], 1.0 op_sel_hi:[1,0,0]
	v_pk_mul_f32 v[24:25], v[24:25], v[26:27]
	v_rcp_f32_e32 v30, v30
	v_rcp_f32_e32 v31, v31
	v_pk_mul_f32 v[24:25], v[28:29], v[24:25]
	v_cmp_gt_f32_e32 vcc, 0, v20
	v_pk_mul_f32 v[28:29], v[20:21], v[24:25]
	v_pk_fma_f32 v[24:25], v[20:21], v[24:25], v[20:21] neg_lo:[1,0,0] neg_hi:[1,0,0]
	v_pk_mul_f32 v[26:27], v[22:23], v[22:23]
	v_cndmask_b32_e32 v28, v24, v28, vcc
	v_cmp_gt_f32_e32 vcc, 0, v21
	v_pk_fma_f32 v[20:21], v[30:31], s[0:1], v[162:163] op_sel_hi:[1,0,0]
	s_nop 0
	v_cndmask_b32_e32 v29, v25, v29, vcc
	v_pk_mul_f32 v[24:25], v[26:27], s[18:19] op_sel_hi:[1,0]
	v_pk_fma_f32 v[20:21], v[30:31], v[20:21], s[16:17] op_sel_hi:[1,1,0]
	v_exp_f32_e32 v24, v24
	v_exp_f32_e32 v25, v25
	v_pk_fma_f32 v[20:21], v[30:31], v[20:21], s[6:7] op_sel_hi:[1,1,0]
	v_and_b32_e32 v27, 0x7fffffff, v17
	v_and_b32_e32 v26, 0x7fffffff, v16
	v_pk_fma_f32 v[20:21], v[30:31], v[20:21], s[14:15] op_sel_hi:[1,1,0]
	v_pk_fma_f32 v[26:27], v[26:27], s[10:11], 1.0 op_sel_hi:[1,0,0]
	v_pk_mul_f32 v[20:21], v[30:31], v[20:21]
	v_rcp_f32_e32 v26, v26
	v_rcp_f32_e32 v27, v27
	v_pk_mul_f32 v[20:21], v[24:25], v[20:21]
	v_cmp_gt_f32_e32 vcc, 0, v22
	v_pk_mul_f32 v[24:25], v[22:23], v[20:21]
	v_pk_fma_f32 v[20:21], v[22:23], v[20:21], v[22:23] neg_lo:[1,0,0] neg_hi:[1,0,0]
	s_nop 0
	v_cndmask_b32_e32 v30, v20, v24, vcc
	v_cmp_gt_f32_e32 vcc, 0, v23
	v_pk_mul_f32 v[22:23], v[16:17], v[16:17]
	s_nop 0
	v_cndmask_b32_e32 v31, v21, v25, vcc
	v_pk_fma_f32 v[20:21], v[26:27], s[0:1], v[162:163] op_sel_hi:[1,0,0]
	v_pk_mul_f32 v[22:23], v[22:23], s[18:19] op_sel_hi:[1,0]
	v_pk_fma_f32 v[20:21], v[26:27], v[20:21], s[16:17] op_sel_hi:[1,1,0]
	v_exp_f32_e32 v22, v22
	v_pk_fma_f32 v[20:21], v[26:27], v[20:21], s[6:7] op_sel_hi:[1,1,0]
	v_exp_f32_e32 v23, v23
	v_pk_fma_f32 v[20:21], v[26:27], v[20:21], s[14:15] op_sel_hi:[1,1,0]
	v_cmp_gt_f32_e32 vcc, 0, v16
	v_pk_mul_f32 v[20:21], v[26:27], v[20:21]
	v_and_b32_e32 v27, 0x7fffffff, v19
	v_and_b32_e32 v26, 0x7fffffff, v18
	v_pk_fma_f32 v[26:27], v[26:27], s[10:11], 1.0 op_sel_hi:[1,0,0]
	v_pk_mul_f32 v[20:21], v[22:23], v[20:21]
	v_rcp_f32_e32 v26, v26
	v_rcp_f32_e32 v27, v27
	v_pk_mul_f32 v[22:23], v[16:17], v[20:21]
	v_pk_fma_f32 v[20:21], v[16:17], v[20:21], v[16:17] neg_lo:[1,0,0] neg_hi:[1,0,0]
	v_pk_mul_f32 v[24:25], v[18:19], v[18:19]
	v_cndmask_b32_e32 v22, v20, v22, vcc
	v_cmp_gt_f32_e32 vcc, 0, v17
	v_pk_fma_f32 v[16:17], v[26:27], s[0:1], v[162:163] op_sel_hi:[1,0,0]
	s_nop 0
	v_cndmask_b32_e32 v23, v21, v23, vcc
	v_pk_mul_f32 v[20:21], v[24:25], s[18:19] op_sel_hi:[1,0]
	v_pk_fma_f32 v[16:17], v[26:27], v[16:17], s[16:17] op_sel_hi:[1,1,0]
	v_exp_f32_e32 v20, v20
	v_exp_f32_e32 v21, v21
	v_pk_fma_f32 v[16:17], v[26:27], v[16:17], s[6:7] op_sel_hi:[1,1,0]
	v_cmp_gt_f32_e32 vcc, 0, v18
	v_pk_fma_f32 v[16:17], v[26:27], v[16:17], s[14:15] op_sel_hi:[1,1,0]
	s_nop 0
	v_pk_mul_f32 v[16:17], v[26:27], v[16:17]
	s_nop 0
	v_pk_mul_f32 v[16:17], v[20:21], v[16:17]
	s_nop 0
	v_pk_mul_f32 v[20:21], v[18:19], v[16:17]
	v_pk_fma_f32 v[16:17], v[18:19], v[16:17], v[18:19] neg_lo:[1,0,0] neg_hi:[1,0,0]
	s_nop 0
	v_cndmask_b32_e32 v20, v16, v20, vcc
	v_cmp_gt_f32_e32 vcc, 0, v19
	v_cvt_pk_bf16_f32 v16, v28, v29
	s_nop 1
	v_cndmask_b32_e32 v19, v17, v21, vcc
	v_cvt_pk_bf16_f32 v17, v30, v31
	v_cvt_pk_bf16_f32 v18, v22, v23
	v_cvt_pk_bf16_f32 v19, v20, v19
	v_add_u32_e32 v20, 0x1200, v96
	v_ashrrev_i32_e32 v21, 31, v20
	v_lshlrev_b64 v[20:21], 10, v[20:21]
	v_lshl_add_u64 v[20:21], s[20:21], 0, v[20:21]
	v_lshl_add_u64 v[20:21], v[20:21], 0, s[40:41]
	v_lshl_add_u64 v[20:21], v[20:21], 0, v[160:161]
	global_store_dwordx4 v[20:21], v[16:19], off
	s_waitcnt vmcnt(7)
	v_lshlrev_b32_e32 v20, 16, v78
	v_and_b32_e32 v21, 0xffff0000, v78
	v_lshlrev_b32_e32 v16, 16, v76
	v_and_b32_e32 v17, 0xffff0000, v76
	v_pk_fma_f32 v[12:13], v[68:69], v[16:17], v[12:13]
	v_lshlrev_b32_e32 v18, 16, v77
	v_and_b32_e32 v17, 0x7fffffff, v13
	v_and_b32_e32 v16, 0x7fffffff, v12
	v_pk_fma_f32 v[16:17], v[16:17], s[10:11], 1.0 op_sel_hi:[1,0,0]
	v_and_b32_e32 v19, 0xffff0000, v77
	v_rcp_f32_e32 v16, v16
	v_rcp_f32_e32 v17, v17
	v_pk_fma_f32 v[8:9], v[64:65], v[20:21], v[8:9]
	v_pk_mul_f32 v[20:21], v[12:13], v[12:13]
	v_pk_fma_f32 v[14:15], v[70:71], v[18:19], v[14:15]
	v_pk_fma_f32 v[18:19], v[16:17], s[0:1], v[162:163] op_sel_hi:[1,0,0]
	v_pk_mul_f32 v[20:21], v[20:21], s[18:19] op_sel_hi:[1,0]
	v_lshlrev_b32_e32 v22, 16, v79
	v_and_b32_e32 v23, 0xffff0000, v79
	v_pk_fma_f32 v[18:19], v[16:17], v[18:19], s[16:17] op_sel_hi:[1,1,0]
	v_exp_f32_e32 v20, v20
	v_exp_f32_e32 v21, v21
	v_pk_fma_f32 v[10:11], v[66:67], v[22:23], v[10:11]
	v_pk_fma_f32 v[18:19], v[16:17], v[18:19], s[6:7] op_sel_hi:[1,1,0]
	v_and_b32_e32 v23, 0x7fffffff, v15
	v_and_b32_e32 v22, 0x7fffffff, v14
	v_pk_fma_f32 v[18:19], v[16:17], v[18:19], s[14:15] op_sel_hi:[1,1,0]
	v_pk_fma_f32 v[22:23], v[22:23], s[10:11], 1.0 op_sel_hi:[1,0,0]
	v_pk_mul_f32 v[16:17], v[16:17], v[18:19]
	v_rcp_f32_e32 v22, v22
	v_rcp_f32_e32 v23, v23
	v_pk_mul_f32 v[16:17], v[20:21], v[16:17]
	v_cmp_gt_f32_e32 vcc, 0, v12
	v_pk_mul_f32 v[20:21], v[12:13], v[16:17]
	v_pk_fma_f32 v[16:17], v[12:13], v[16:17], v[12:13] neg_lo:[1,0,0] neg_hi:[1,0,0]
	v_pk_mul_f32 v[18:19], v[14:15], v[14:15]
	v_cndmask_b32_e32 v20, v16, v20, vcc
	v_cmp_gt_f32_e32 vcc, 0, v13
	v_pk_fma_f32 v[12:13], v[22:23], s[0:1], v[162:163] op_sel_hi:[1,0,0]
	s_nop 0
	v_cndmask_b32_e32 v21, v17, v21, vcc
	v_pk_mul_f32 v[16:17], v[18:19], s[18:19] op_sel_hi:[1,0]
	v_pk_fma_f32 v[12:13], v[22:23], v[12:13], s[16:17] op_sel_hi:[1,1,0]
	v_exp_f32_e32 v16, v16
	v_exp_f32_e32 v17, v17
	v_pk_fma_f32 v[12:13], v[22:23], v[12:13], s[6:7] op_sel_hi:[1,1,0]
	v_and_b32_e32 v19, 0x7fffffff, v9
	v_and_b32_e32 v18, 0x7fffffff, v8
	v_pk_fma_f32 v[12:13], v[22:23], v[12:13], s[14:15] op_sel_hi:[1,1,0]
	v_pk_fma_f32 v[18:19], v[18:19], s[10:11], 1.0 op_sel_hi:[1,0,0]
	v_pk_mul_f32 v[12:13], v[22:23], v[12:13]
	v_rcp_f32_e32 v18, v18
	v_rcp_f32_e32 v19, v19
	v_pk_mul_f32 v[12:13], v[16:17], v[12:13]
	v_cmp_gt_f32_e32 vcc, 0, v14
	v_pk_mul_f32 v[16:17], v[14:15], v[12:13]
	v_pk_fma_f32 v[12:13], v[14:15], v[12:13], v[14:15] neg_lo:[1,0,0] neg_hi:[1,0,0]
	s_nop 0
	v_cndmask_b32_e32 v22, v12, v16, vcc
	v_cmp_gt_f32_e32 vcc, 0, v15
	v_pk_mul_f32 v[14:15], v[8:9], v[8:9]
	s_nop 0
	v_cndmask_b32_e32 v23, v13, v17, vcc
	v_pk_fma_f32 v[12:13], v[18:19], s[0:1], v[162:163] op_sel_hi:[1,0,0]
	v_pk_mul_f32 v[14:15], v[14:15], s[18:19] op_sel_hi:[1,0]
	v_pk_fma_f32 v[12:13], v[18:19], v[12:13], s[16:17] op_sel_hi:[1,1,0]
	v_exp_f32_e32 v14, v14
	v_pk_fma_f32 v[12:13], v[18:19], v[12:13], s[6:7] op_sel_hi:[1,1,0]
	v_exp_f32_e32 v15, v15
	v_pk_fma_f32 v[12:13], v[18:19], v[12:13], s[14:15] op_sel_hi:[1,1,0]
	v_cmp_gt_f32_e32 vcc, 0, v8
	v_pk_mul_f32 v[12:13], v[18:19], v[12:13]
	v_and_b32_e32 v19, 0x7fffffff, v11
	v_and_b32_e32 v18, 0x7fffffff, v10
	v_pk_fma_f32 v[18:19], v[18:19], s[10:11], 1.0 op_sel_hi:[1,0,0]
	v_pk_mul_f32 v[12:13], v[14:15], v[12:13]
	v_rcp_f32_e32 v18, v18
	v_rcp_f32_e32 v19, v19
	v_pk_mul_f32 v[14:15], v[8:9], v[12:13]
	v_pk_fma_f32 v[12:13], v[8:9], v[12:13], v[8:9] neg_lo:[1,0,0] neg_hi:[1,0,0]
	v_pk_mul_f32 v[16:17], v[10:11], v[10:11]
	v_cndmask_b32_e32 v14, v12, v14, vcc
	v_cmp_gt_f32_e32 vcc, 0, v9
	v_pk_fma_f32 v[8:9], v[18:19], s[0:1], v[162:163] op_sel_hi:[1,0,0]
	s_nop 0
	v_cndmask_b32_e32 v15, v13, v15, vcc
	v_pk_mul_f32 v[12:13], v[16:17], s[18:19] op_sel_hi:[1,0]
	v_pk_fma_f32 v[8:9], v[18:19], v[8:9], s[16:17] op_sel_hi:[1,1,0]
	v_exp_f32_e32 v12, v12
	v_exp_f32_e32 v13, v13
	v_pk_fma_f32 v[8:9], v[18:19], v[8:9], s[6:7] op_sel_hi:[1,1,0]
	v_cmp_gt_f32_e32 vcc, 0, v10
	v_pk_fma_f32 v[8:9], v[18:19], v[8:9], s[14:15] op_sel_hi:[1,1,0]
	s_nop 0
	v_pk_mul_f32 v[8:9], v[18:19], v[8:9]
	s_nop 0
	v_pk_mul_f32 v[8:9], v[12:13], v[8:9]
	s_nop 0
	v_pk_mul_f32 v[12:13], v[10:11], v[8:9]
	v_pk_fma_f32 v[8:9], v[10:11], v[8:9], v[10:11] neg_lo:[1,0,0] neg_hi:[1,0,0]
	s_nop 0
	v_cndmask_b32_e32 v12, v8, v12, vcc
	v_cmp_gt_f32_e32 vcc, 0, v11
	v_cvt_pk_bf16_f32 v8, v20, v21
	s_nop 1
	v_cndmask_b32_e32 v11, v9, v13, vcc
	v_cvt_pk_bf16_f32 v9, v22, v23
	v_cvt_pk_bf16_f32 v10, v14, v15
	v_cvt_pk_bf16_f32 v11, v12, v11
	v_add_u32_e32 v12, 0x1400, v96
	v_ashrrev_i32_e32 v13, 31, v12
	v_lshlrev_b64 v[12:13], 10, v[12:13]
	v_lshl_add_u64 v[12:13], s[20:21], 0, v[12:13]
	v_lshl_add_u64 v[12:13], v[12:13], 0, s[40:41]
	v_lshl_add_u64 v[12:13], v[12:13], 0, v[160:161]
	global_store_dwordx4 v[12:13], v[8:11], off
	s_waitcnt vmcnt(7)
	v_lshlrev_b32_e32 v12, 16, v74
	v_and_b32_e32 v13, 0xffff0000, v74
	v_lshlrev_b32_e32 v8, 16, v72
	v_and_b32_e32 v9, 0xffff0000, v72
	v_pk_fma_f32 v[4:5], v[68:69], v[8:9], v[4:5]
	v_lshlrev_b32_e32 v10, 16, v73
	v_and_b32_e32 v9, 0x7fffffff, v5
	v_and_b32_e32 v8, 0x7fffffff, v4
	v_pk_fma_f32 v[8:9], v[8:9], s[10:11], 1.0 op_sel_hi:[1,0,0]
	v_and_b32_e32 v11, 0xffff0000, v73
	v_rcp_f32_e32 v8, v8
	v_rcp_f32_e32 v9, v9
	v_pk_fma_f32 v[0:1], v[64:65], v[12:13], v[0:1]
	v_pk_mul_f32 v[12:13], v[4:5], v[4:5]
	v_pk_fma_f32 v[6:7], v[70:71], v[10:11], v[6:7]
	v_pk_fma_f32 v[10:11], v[8:9], s[0:1], v[162:163] op_sel_hi:[1,0,0]
	v_pk_mul_f32 v[12:13], v[12:13], s[18:19] op_sel_hi:[1,0]
	v_lshlrev_b32_e32 v14, 16, v75
	v_and_b32_e32 v15, 0xffff0000, v75
	v_pk_fma_f32 v[10:11], v[8:9], v[10:11], s[16:17] op_sel_hi:[1,1,0]
	v_exp_f32_e32 v12, v12
	v_exp_f32_e32 v13, v13
	v_pk_fma_f32 v[2:3], v[66:67], v[14:15], v[2:3]
	v_pk_fma_f32 v[10:11], v[8:9], v[10:11], s[6:7] op_sel_hi:[1,1,0]
	v_and_b32_e32 v15, 0x7fffffff, v7
	v_and_b32_e32 v14, 0x7fffffff, v6
	v_pk_fma_f32 v[10:11], v[8:9], v[10:11], s[14:15] op_sel_hi:[1,1,0]
	v_pk_fma_f32 v[14:15], v[14:15], s[10:11], 1.0 op_sel_hi:[1,0,0]
	v_pk_mul_f32 v[8:9], v[8:9], v[10:11]
	v_rcp_f32_e32 v14, v14
	v_rcp_f32_e32 v15, v15
	v_pk_mul_f32 v[8:9], v[12:13], v[8:9]
	v_cmp_gt_f32_e32 vcc, 0, v4
	v_pk_mul_f32 v[12:13], v[4:5], v[8:9]
	v_pk_fma_f32 v[8:9], v[4:5], v[8:9], v[4:5] neg_lo:[1,0,0] neg_hi:[1,0,0]
	v_pk_mul_f32 v[10:11], v[6:7], v[6:7]
	v_cndmask_b32_e32 v12, v8, v12, vcc
	v_cmp_gt_f32_e32 vcc, 0, v5
	v_pk_fma_f32 v[4:5], v[14:15], s[0:1], v[162:163] op_sel_hi:[1,0,0]
	s_nop 0
	v_cndmask_b32_e32 v13, v9, v13, vcc
	v_pk_mul_f32 v[8:9], v[10:11], s[18:19] op_sel_hi:[1,0]
	v_pk_fma_f32 v[4:5], v[14:15], v[4:5], s[16:17] op_sel_hi:[1,1,0]
	v_exp_f32_e32 v8, v8
	v_exp_f32_e32 v9, v9
	v_pk_fma_f32 v[4:5], v[14:15], v[4:5], s[6:7] op_sel_hi:[1,1,0]
	v_and_b32_e32 v11, 0x7fffffff, v1
	v_and_b32_e32 v10, 0x7fffffff, v0
	v_pk_fma_f32 v[4:5], v[14:15], v[4:5], s[14:15] op_sel_hi:[1,1,0]
	v_pk_fma_f32 v[10:11], v[10:11], s[10:11], 1.0 op_sel_hi:[1,0,0]
	v_pk_mul_f32 v[4:5], v[14:15], v[4:5]
	v_rcp_f32_e32 v10, v10
	v_rcp_f32_e32 v11, v11
	v_pk_mul_f32 v[4:5], v[8:9], v[4:5]
	v_cmp_gt_f32_e32 vcc, 0, v6
	v_pk_mul_f32 v[8:9], v[6:7], v[4:5]
	v_pk_fma_f32 v[4:5], v[6:7], v[4:5], v[6:7] neg_lo:[1,0,0] neg_hi:[1,0,0]
	s_nop 0
	v_cndmask_b32_e32 v14, v4, v8, vcc
	v_cmp_gt_f32_e32 vcc, 0, v7
	v_pk_mul_f32 v[6:7], v[0:1], v[0:1]
	s_nop 0
	v_cndmask_b32_e32 v15, v5, v9, vcc
	v_pk_fma_f32 v[4:5], v[10:11], s[0:1], v[162:163] op_sel_hi:[1,0,0]
	v_pk_mul_f32 v[6:7], v[6:7], s[18:19] op_sel_hi:[1,0]
	v_pk_fma_f32 v[4:5], v[10:11], v[4:5], s[16:17] op_sel_hi:[1,1,0]
	v_exp_f32_e32 v6, v6
	v_pk_fma_f32 v[4:5], v[10:11], v[4:5], s[6:7] op_sel_hi:[1,1,0]
	v_exp_f32_e32 v7, v7
	v_pk_fma_f32 v[4:5], v[10:11], v[4:5], s[14:15] op_sel_hi:[1,1,0]
	v_cmp_gt_f32_e32 vcc, 0, v0
	v_pk_mul_f32 v[4:5], v[10:11], v[4:5]
	v_and_b32_e32 v11, 0x7fffffff, v3
	v_and_b32_e32 v10, 0x7fffffff, v2
	v_pk_fma_f32 v[10:11], v[10:11], s[10:11], 1.0 op_sel_hi:[1,0,0]
	v_pk_mul_f32 v[4:5], v[6:7], v[4:5]
	v_rcp_f32_e32 v10, v10
	v_rcp_f32_e32 v11, v11
	v_pk_mul_f32 v[6:7], v[0:1], v[4:5]
	v_pk_fma_f32 v[4:5], v[0:1], v[4:5], v[0:1] neg_lo:[1,0,0] neg_hi:[1,0,0]
	v_pk_mul_f32 v[8:9], v[2:3], v[2:3]
	v_cndmask_b32_e32 v6, v4, v6, vcc
	v_cmp_gt_f32_e32 vcc, 0, v1
	v_pk_fma_f32 v[0:1], v[10:11], s[0:1], v[162:163] op_sel_hi:[1,0,0]
	s_nop 0
	v_cndmask_b32_e32 v7, v5, v7, vcc
	v_pk_mul_f32 v[4:5], v[8:9], s[18:19] op_sel_hi:[1,0]
	v_pk_fma_f32 v[0:1], v[10:11], v[0:1], s[16:17] op_sel_hi:[1,1,0]
	v_exp_f32_e32 v4, v4
	v_exp_f32_e32 v5, v5
	v_pk_fma_f32 v[0:1], v[10:11], v[0:1], s[6:7] op_sel_hi:[1,1,0]
	v_cmp_gt_f32_e32 vcc, 0, v2
	v_pk_fma_f32 v[0:1], v[10:11], v[0:1], s[14:15] op_sel_hi:[1,1,0]
	s_nop 0
	v_pk_mul_f32 v[0:1], v[10:11], v[0:1]
	s_nop 0
	v_pk_mul_f32 v[0:1], v[4:5], v[0:1]
	s_nop 0
	v_pk_mul_f32 v[4:5], v[2:3], v[0:1]
	v_pk_fma_f32 v[0:1], v[2:3], v[0:1], v[2:3] neg_lo:[1,0,0] neg_hi:[1,0,0]
	s_nop 0
	v_cndmask_b32_e32 v4, v0, v4, vcc
	v_cmp_gt_f32_e32 vcc, 0, v3
	v_cvt_pk_bf16_f32 v0, v12, v13
	s_nop 1
	v_cndmask_b32_e32 v3, v1, v5, vcc
	v_cvt_pk_bf16_f32 v1, v14, v15
	v_cvt_pk_bf16_f32 v2, v6, v7
	v_cvt_pk_bf16_f32 v3, v4, v3
	v_add_u32_e32 v4, 0x1600, v96
	v_ashrrev_i32_e32 v5, 31, v4
	v_lshlrev_b64 v[4:5], 10, v[4:5]
	v_lshl_add_u64 v[4:5], s[20:21], 0, v[4:5]
	v_lshl_add_u64 v[4:5], v[4:5], 0, s[40:41]
	v_lshl_add_u64 v[4:5], v[4:5], 0, v[160:161]
	global_store_dwordx4 v[4:5], v[0:3], off
	s_waitcnt vmcnt(0)
	s_cbranch_scc0 .LBB0_935
	s_barrier

.LBB0_953:
	ds_read_b128 v[144:147], v157
	ds_read_b128 v[148:151], v157 offset:1024
	ds_read_b128 v[160:163], v157 offset:2048
	ds_read_b128 v[164:167], v157 offset:3072
	ds_read_b128 v[168:171], v158
	ds_read_b128 v[172:175], v158 offset:1024
	ds_read_b128 v[176:179], v158 offset:2048
	ds_read_b128 v[180:183], v158 offset:3072
	s_add_u32 s28, s54, 0xfffe0080
	s_addc_u32 s29, s55, -1
	s_cmp_eq_u32 s78, 4
	s_cselect_b32 s59, s45, s29
	s_cselect_b32 s58, s66, s28
	s_cselect_b32 s57, s43, s77
	s_cselect_b32 s56, s67, s76
	v_lshl_add_u64 v[152:153], s[54:55], 0, v[136:137]
	s_add_i32 m0, s27, 0xc000
	ds_read_b128 v[184:187], v159
	ds_read_b128 v[190:193], v159 offset:1024
	ds_read_b128 v[194:197], v159 offset:2048
	ds_read_b128 v[198:201], v159 offset:3072
	ds_read_b128 v[202:205], v159 offset:4096
	ds_read_b128 v[206:209], v159 offset:5120
	ds_read_b128 v[210:213], v159 offset:6144
	ds_read_b128 v[214:217], v159 offset:7168
	global_load_lds_dwordx4 v[152:153], off
	v_lshl_add_u64 v[152:153], s[54:55], 0, v[138:139]
	s_add_i32 m0, s27, 0xe000
	s_nop 0
	global_load_lds_dwordx4 v[152:153], off
	s_waitcnt vmcnt(8)
	s_waitcnt lgkmcnt(0)
	s_nop 0
	s_barrier
	s_setprio 1
	s_waitcnt lgkmcnt(0)
	v_mfma_f32_16x16x32_bf16 v[124:127], v[144:147], v[184:187], v[124:127]
	v_mfma_f32_16x16x32_bf16 v[120:123], v[160:163], v[184:187], v[120:123]
	v_mfma_f32_16x16x32_bf16 v[116:119], v[144:147], v[194:197], v[116:119]
	v_mfma_f32_16x16x32_bf16 v[112:115], v[160:163], v[194:197], v[112:115]
	v_mfma_f32_16x16x32_bf16 v[92:95], v[144:147], v[202:205], v[92:95]
	v_mfma_f32_16x16x32_bf16 v[88:91], v[160:163], v[202:205], v[88:91]
	v_mfma_f32_16x16x32_bf16 v[76:79], v[144:147], v[210:213], v[76:79]
	v_mfma_f32_16x16x32_bf16 v[72:75], v[160:163], v[210:213], v[72:75]
	v_mfma_f32_16x16x32_bf16 v[124:127], v[148:151], v[190:193], v[124:127]
	v_mfma_f32_16x16x32_bf16 v[120:123], v[164:167], v[190:193], v[120:123]
	v_mfma_f32_16x16x32_bf16 v[116:119], v[148:151], v[198:201], v[116:119]
	v_mfma_f32_16x16x32_bf16 v[112:115], v[164:167], v[198:201], v[112:115]
	v_mfma_f32_16x16x32_bf16 v[92:95], v[148:151], v[206:209], v[92:95]
	v_mfma_f32_16x16x32_bf16 v[88:91], v[164:167], v[206:209], v[88:91]
	v_mfma_f32_16x16x32_bf16 v[76:79], v[148:151], v[214:217], v[76:79]
	v_mfma_f32_16x16x32_bf16 v[72:75], v[164:167], v[214:217], v[72:75]
	s_setprio 0
	s_setprio 1
	v_mfma_f32_16x16x32_bf16 v[108:111], v[168:171], v[184:187], v[108:111]
	v_mfma_f32_16x16x32_bf16 v[104:107], v[176:179], v[184:187], v[104:107]
	v_mfma_f32_16x16x32_bf16 v[100:103], v[168:171], v[194:197], v[100:103]
	v_mfma_f32_16x16x32_bf16 v[96:99], v[176:179], v[194:197], v[96:99]
	v_mfma_f32_16x16x32_bf16 v[84:87], v[168:171], v[202:205], v[84:87]
	v_mfma_f32_16x16x32_bf16 v[80:83], v[176:179], v[202:205], v[80:83]
	v_mfma_f32_16x16x32_bf16 v[68:71], v[168:171], v[210:213], v[68:71]
	v_mfma_f32_16x16x32_bf16 v[64:67], v[176:179], v[210:213], v[64:67]
	v_mfma_f32_16x16x32_bf16 v[108:111], v[172:175], v[190:193], v[108:111]
	v_mfma_f32_16x16x32_bf16 v[104:107], v[180:183], v[190:193], v[104:107]
	v_mfma_f32_16x16x32_bf16 v[100:103], v[172:175], v[198:201], v[100:103]
	v_mfma_f32_16x16x32_bf16 v[96:99], v[180:183], v[198:201], v[96:99]
	v_mfma_f32_16x16x32_bf16 v[84:87], v[172:175], v[206:209], v[84:87]
	v_mfma_f32_16x16x32_bf16 v[80:83], v[180:183], v[206:209], v[80:83]
	v_mfma_f32_16x16x32_bf16 v[68:71], v[172:175], v[214:217], v[68:71]
	v_mfma_f32_16x16x32_bf16 v[64:67], v[180:183], v[214:217], v[64:67]
	s_setprio 0
	s_barrier
	s_add_i32 s28, s63, s13
	v_lshl_add_u64 v[152:153], s[56:57], 0, v[130:131]
	s_mov_b32 m0, s28
	ds_read_b128 v[184:187], v159 offset:16384
	ds_read_b128 v[190:193], v159 offset:17408
	ds_read_b128 v[194:197], v159 offset:18432
	ds_read_b128 v[198:201], v159 offset:19456
	ds_read_b128 v[202:205], v159 offset:20480
	ds_read_b128 v[206:209], v159 offset:21504
	ds_read_b128 v[210:213], v159 offset:22528
	ds_read_b128 v[214:217], v159 offset:23552
	global_load_lds_dwordx4 v[152:153], off
	s_add_i32 m0, s28, 0x2000
	s_add_u32 s28, s56, 0x20000
	v_lshl_add_u64 v[218:219], s[56:57], 0, v[134:135]
	s_addc_u32 s29, s57, 0
	s_add_i32 s33, s64, s13
	global_load_lds_dwordx4 v[218:219], off
	v_lshl_add_u64 v[220:221], s[28:29], 0, v[130:131]
	s_mov_b32 m0, s33
	v_lshl_add_u64 v[222:223], s[58:59], 0, v[132:133]
	global_load_lds_dwordx4 v[220:221], off
	v_lshl_add_u64 v[220:221], s[28:29], 0, v[134:135]
	s_add_i32 m0, s33, 0x2000
	s_nop 0
	global_load_lds_dwordx4 v[220:221], off
	v_lshl_add_u64 v[220:221], s[58:59], 0, v[128:129]
	s_mov_b32 m0, s27
	s_nop 0
	global_load_lds_dwordx4 v[220:221], off
	s_mov_b32 m0, s34
	s_nop 0
	global_load_lds_dwordx4 v[222:223], off
	s_waitcnt vmcnt(8)
	s_waitcnt lgkmcnt(0)
	s_nop 0
	s_barrier
	s_setprio 1
	s_waitcnt lgkmcnt(0)
	v_mfma_f32_16x16x32_bf16 v[60:63], v[144:147], v[184:187], v[60:63]
	v_mfma_f32_16x16x32_bf16 v[56:59], v[160:163], v[184:187], v[56:59]
	v_mfma_f32_16x16x32_bf16 v[44:47], v[144:147], v[194:197], v[44:47]
	v_mfma_f32_16x16x32_bf16 v[40:43], v[160:163], v[194:197], v[40:43]
	v_mfma_f32_16x16x32_bf16 v[28:31], v[144:147], v[202:205], v[28:31]
	v_mfma_f32_16x16x32_bf16 v[24:27], v[160:163], v[202:205], v[24:27]
	v_mfma_f32_16x16x32_bf16 v[12:15], v[144:147], v[210:213], v[12:15]
	v_mfma_f32_16x16x32_bf16 v[8:11], v[160:163], v[210:213], v[8:11]
	v_mfma_f32_16x16x32_bf16 v[60:63], v[148:151], v[190:193], v[60:63]
	v_mfma_f32_16x16x32_bf16 v[56:59], v[164:167], v[190:193], v[56:59]
	v_mfma_f32_16x16x32_bf16 v[44:47], v[148:151], v[198:201], v[44:47]
	v_mfma_f32_16x16x32_bf16 v[40:43], v[164:167], v[198:201], v[40:43]
	v_mfma_f32_16x16x32_bf16 v[28:31], v[148:151], v[206:209], v[28:31]
	v_mfma_f32_16x16x32_bf16 v[24:27], v[164:167], v[206:209], v[24:27]
	v_mfma_f32_16x16x32_bf16 v[12:15], v[148:151], v[214:217], v[12:15]
	v_mfma_f32_16x16x32_bf16 v[8:11], v[164:167], v[214:217], v[8:11]
	s_setprio 0
	s_setprio 1
	v_mfma_f32_16x16x32_bf16 v[52:55], v[168:171], v[184:187], v[52:55]
	v_mfma_f32_16x16x32_bf16 v[48:51], v[176:179], v[184:187], v[48:51]
	v_mfma_f32_16x16x32_bf16 v[36:39], v[168:171], v[194:197], v[36:39]
	v_mfma_f32_16x16x32_bf16 v[32:35], v[176:179], v[194:197], v[32:35]
	v_mfma_f32_16x16x32_bf16 v[20:23], v[168:171], v[202:205], v[20:23]
	v_mfma_f32_16x16x32_bf16 v[16:19], v[176:179], v[202:205], v[16:19]
	v_mfma_f32_16x16x32_bf16 v[4:7], v[168:171], v[210:213], v[4:7]
	v_mfma_f32_16x16x32_bf16 v[0:3], v[176:179], v[210:213], v[0:3]
	v_mfma_f32_16x16x32_bf16 v[52:55], v[172:175], v[190:193], v[52:55]
	v_mfma_f32_16x16x32_bf16 v[48:51], v[180:183], v[190:193], v[48:51]
	v_mfma_f32_16x16x32_bf16 v[36:39], v[172:175], v[198:201], v[36:39]
	v_mfma_f32_16x16x32_bf16 v[32:35], v[180:183], v[198:201], v[32:35]
	v_mfma_f32_16x16x32_bf16 v[20:23], v[172:175], v[206:209], v[20:23]
	v_mfma_f32_16x16x32_bf16 v[16:19], v[180:183], v[206:209], v[16:19]
	v_mfma_f32_16x16x32_bf16 v[4:7], v[172:175], v[214:217], v[4:7]
	v_mfma_f32_16x16x32_bf16 v[0:3], v[180:183], v[214:217], v[0:3]
	s_setprio 0
	s_barrier
	s_add_i32 s33, 0, 0x18000
	s_add_i32 s79, 0, 0x1c000
	v_add_u32_e32 v164, s33, v155
	v_add_u32_e32 v180, s79, v155
	ds_read_b128 v[144:147], v164
	ds_read_b128 v[148:151], v164 offset:1024
	ds_read_b128 v[160:163], v164 offset:2048
	ds_read_b128 v[164:167], v164 offset:3072
	ds_read_b128 v[168:171], v180
	ds_read_b128 v[172:175], v180 offset:1024
	ds_read_b128 v[176:179], v180 offset:2048
	ds_read_b128 v[180:183], v180 offset:3072
	s_add_u32 s28, s58, 0x20000
	s_addc_u32 s29, s59, 0
	s_mov_b32 m0, s35
	v_lshl_add_u64 v[224:225], s[28:29], 0, v[128:129]
	ds_read_b128 v[184:187], v159 offset:32768
	ds_read_b128 v[190:193], v159 offset:33792
	ds_read_b128 v[194:197], v159 offset:34816
	ds_read_b128 v[198:201], v159 offset:35840
	ds_read_b128 v[202:205], v159 offset:36864
	ds_read_b128 v[206:209], v159 offset:37888
	ds_read_b128 v[210:213], v159 offset:38912
	ds_read_b128 v[214:217], v159 offset:39936
	global_load_lds_dwordx4 v[224:225], off
	v_lshl_add_u64 v[224:225], s[28:29], 0, v[132:133]
	s_mov_b32 m0, s53
	s_nop 0
	global_load_lds_dwordx4 v[224:225], off
	s_waitcnt vmcnt(8)
	s_waitcnt lgkmcnt(0)
	s_nop 0
	s_barrier
	s_setprio 1
	s_waitcnt lgkmcnt(0)
	v_mfma_f32_16x16x32_bf16 v[124:127], v[144:147], v[184:187], v[124:127]
	v_mfma_f32_16x16x32_bf16 v[120:123], v[160:163], v[184:187], v[120:123]
	v_mfma_f32_16x16x32_bf16 v[116:119], v[144:147], v[194:197], v[116:119]
	v_mfma_f32_16x16x32_bf16 v[112:115], v[160:163], v[194:197], v[112:115]
	v_mfma_f32_16x16x32_bf16 v[92:95], v[144:147], v[202:205], v[92:95]
	v_mfma_f32_16x16x32_bf16 v[88:91], v[160:163], v[202:205], v[88:91]
	v_mfma_f32_16x16x32_bf16 v[76:79], v[144:147], v[210:213], v[76:79]
	v_mfma_f32_16x16x32_bf16 v[72:75], v[160:163], v[210:213], v[72:75]
	v_mfma_f32_16x16x32_bf16 v[124:127], v[148:151], v[190:193], v[124:127]
	v_mfma_f32_16x16x32_bf16 v[120:123], v[164:167], v[190:193], v[120:123]
	v_mfma_f32_16x16x32_bf16 v[116:119], v[148:151], v[198:201], v[116:119]
	v_mfma_f32_16x16x32_bf16 v[112:115], v[164:167], v[198:201], v[112:115]
	v_mfma_f32_16x16x32_bf16 v[92:95], v[148:151], v[206:209], v[92:95]
	v_mfma_f32_16x16x32_bf16 v[88:91], v[164:167], v[206:209], v[88:91]
	v_mfma_f32_16x16x32_bf16 v[76:79], v[148:151], v[214:217], v[76:79]
	v_mfma_f32_16x16x32_bf16 v[72:75], v[164:167], v[214:217], v[72:75]
	s_setprio 0
	s_setprio 1
	v_mfma_f32_16x16x32_bf16 v[108:111], v[168:171], v[184:187], v[108:111]
	v_mfma_f32_16x16x32_bf16 v[104:107], v[176:179], v[184:187], v[104:107]
	v_mfma_f32_16x16x32_bf16 v[100:103], v[168:171], v[194:197], v[100:103]
	v_mfma_f32_16x16x32_bf16 v[96:99], v[176:179], v[194:197], v[96:99]
	v_mfma_f32_16x16x32_bf16 v[84:87], v[168:171], v[202:205], v[84:87]
	v_mfma_f32_16x16x32_bf16 v[80:83], v[176:179], v[202:205], v[80:83]
	v_mfma_f32_16x16x32_bf16 v[68:71], v[168:171], v[210:213], v[68:71]
	v_mfma_f32_16x16x32_bf16 v[64:67], v[176:179], v[210:213], v[64:67]
	v_mfma_f32_16x16x32_bf16 v[108:111], v[172:175], v[190:193], v[108:111]
	v_mfma_f32_16x16x32_bf16 v[104:107], v[180:183], v[190:193], v[104:107]
	v_mfma_f32_16x16x32_bf16 v[100:103], v[172:175], v[198:201], v[100:103]
	v_mfma_f32_16x16x32_bf16 v[96:99], v[180:183], v[198:201], v[96:99]
	v_mfma_f32_16x16x32_bf16 v[84:87], v[172:175], v[206:209], v[84:87]
	v_mfma_f32_16x16x32_bf16 v[80:83], v[180:183], v[206:209], v[80:83]
	v_mfma_f32_16x16x32_bf16 v[68:71], v[172:175], v[214:217], v[68:71]
	v_mfma_f32_16x16x32_bf16 v[64:67], v[180:183], v[214:217], v[64:67]
	s_setprio 0
	s_barrier
	s_add_i32 s28, s33, s13
	v_lshl_add_u64 v[152:153], v[152:153], 0, s[14:15]
	s_mov_b32 m0, s28
	ds_read_b128 v[184:187], v159 offset:49152
	ds_read_b128 v[190:193], v159 offset:50176
	ds_read_b128 v[194:197], v159 offset:51200
	ds_read_b128 v[198:201], v159 offset:52224
	ds_read_b128 v[202:205], v159 offset:53248
	ds_read_b128 v[206:209], v159 offset:54272
	ds_read_b128 v[210:213], v159 offset:55296
	ds_read_b128 v[214:217], v159 offset:56320
	global_load_lds_dwordx4 v[152:153], off
	s_add_i32 m0, s28, 0x2000
	s_add_u32 s28, s56, 0x20080
	v_lshl_add_u64 v[152:153], v[218:219], 0, s[14:15]
	s_addc_u32 s29, s57, 0
	s_add_i32 s33, s79, s13
	global_load_lds_dwordx4 v[152:153], off
	v_lshl_add_u64 v[152:153], s[28:29], 0, v[130:131]
	s_mov_b32 m0, s33
	s_nop 0
	global_load_lds_dwordx4 v[152:153], off
	v_lshl_add_u64 v[152:153], s[28:29], 0, v[134:135]
	s_add_i32 m0, s33, 0x2000
	s_nop 0
	global_load_lds_dwordx4 v[152:153], off
	v_lshl_add_u64 v[152:153], v[220:221], 0, s[14:15]
	s_mov_b32 m0, s61
	s_nop 0
	global_load_lds_dwordx4 v[152:153], off
	v_lshl_add_u64 v[152:153], v[222:223], 0, s[14:15]
	s_mov_b32 m0, s62
	s_nop 0
	global_load_lds_dwordx4 v[152:153], off
	s_waitcnt vmcnt(8)
	s_waitcnt lgkmcnt(0)
	s_barrier
	s_setprio 1
	s_waitcnt lgkmcnt(0)
	v_mfma_f32_16x16x32_bf16 v[60:63], v[144:147], v[184:187], v[60:63]
	v_mfma_f32_16x16x32_bf16 v[56:59], v[160:163], v[184:187], v[56:59]
	v_mfma_f32_16x16x32_bf16 v[44:47], v[144:147], v[194:197], v[44:47]
	v_mfma_f32_16x16x32_bf16 v[40:43], v[160:163], v[194:197], v[40:43]
	v_mfma_f32_16x16x32_bf16 v[28:31], v[144:147], v[202:205], v[28:31]
	v_mfma_f32_16x16x32_bf16 v[24:27], v[160:163], v[202:205], v[24:27]
	v_mfma_f32_16x16x32_bf16 v[12:15], v[144:147], v[210:213], v[12:15]
	v_mfma_f32_16x16x32_bf16 v[8:11], v[160:163], v[210:213], v[8:11]
	v_mfma_f32_16x16x32_bf16 v[60:63], v[148:151], v[190:193], v[60:63]
	v_mfma_f32_16x16x32_bf16 v[56:59], v[164:167], v[190:193], v[56:59]
	v_mfma_f32_16x16x32_bf16 v[44:47], v[148:151], v[198:201], v[44:47]
	v_mfma_f32_16x16x32_bf16 v[40:43], v[164:167], v[198:201], v[40:43]
	v_mfma_f32_16x16x32_bf16 v[28:31], v[148:151], v[206:209], v[28:31]
	v_mfma_f32_16x16x32_bf16 v[24:27], v[164:167], v[206:209], v[24:27]
	v_mfma_f32_16x16x32_bf16 v[12:15], v[148:151], v[214:217], v[12:15]
	v_mfma_f32_16x16x32_bf16 v[8:11], v[164:167], v[214:217], v[8:11]
	s_setprio 0
	s_setprio 1
	v_mfma_f32_16x16x32_bf16 v[52:55], v[168:171], v[184:187], v[52:55]
	v_mfma_f32_16x16x32_bf16 v[48:51], v[176:179], v[184:187], v[48:51]
	v_mfma_f32_16x16x32_bf16 v[36:39], v[168:171], v[194:197], v[36:39]
	v_mfma_f32_16x16x32_bf16 v[32:35], v[176:179], v[194:197], v[32:35]
	v_mfma_f32_16x16x32_bf16 v[20:23], v[168:171], v[202:205], v[20:23]
	v_mfma_f32_16x16x32_bf16 v[16:19], v[176:179], v[202:205], v[16:19]
	v_mfma_f32_16x16x32_bf16 v[4:7], v[168:171], v[210:213], v[4:7]
	v_mfma_f32_16x16x32_bf16 v[0:3], v[176:179], v[210:213], v[0:3]
	v_mfma_f32_16x16x32_bf16 v[52:55], v[172:175], v[190:193], v[52:55]
	v_mfma_f32_16x16x32_bf16 v[48:51], v[180:183], v[190:193], v[48:51]
	v_mfma_f32_16x16x32_bf16 v[36:39], v[172:175], v[198:201], v[36:39]
	v_mfma_f32_16x16x32_bf16 v[32:35], v[180:183], v[198:201], v[32:35]
	v_mfma_f32_16x16x32_bf16 v[20:23], v[172:175], v[206:209], v[20:23]
	v_mfma_f32_16x16x32_bf16 v[16:19], v[180:183], v[206:209], v[16:19]
	v_mfma_f32_16x16x32_bf16 v[4:7], v[172:175], v[214:217], v[4:7]
	v_mfma_f32_16x16x32_bf16 v[0:3], v[180:183], v[214:217], v[0:3]
	s_setprio 0
	s_barrier
	s_add_i32 s78, s78, 2
	s_add_u32 s54, s54, 0x100
	s_addc_u32 s55, s55, 0
	s_add_u32 s76, s76, 0x100
	s_addc_u32 s77, s77, 0
	s_cmp_gt_u32 s78, 5
	s_cbranch_scc0 .LBB0_953
	s_and_b64 vcc, exec, s[16:17]
	s_cbranch_vccz .LBB0_956
	s_barrier

.LBB0_1029:
	ds_read_b128 v[128:131], v169
	ds_read_b128 v[132:135], v169 offset:1024
	ds_read_b128 v[136:139], v169 offset:2048
	ds_read_b128 v[140:143], v169 offset:3072
	ds_read_b128 v[160:163], v170
	ds_read_b128 v[172:175], v170 offset:1024
	ds_read_b128 v[176:179], v170 offset:2048
	ds_read_b128 v[180:183], v170 offset:3072
	s_add_u32 s28, s44, 0xfffe0080
	s_addc_u32 s29, s45, -1
	s_cmp_eq_u32 s64, 4
	s_cselect_b32 s51, s37, s29
	s_cselect_b32 s50, s60, s28
	s_cselect_b32 s47, s19, s63
	s_cselect_b32 s46, s61, s62
	v_lshl_add_u64 v[164:165], s[44:45], 0, v[152:153]
	s_add_i32 m0, s17, 0xc000
	ds_read_b128 v[184:187], v171
	ds_read_b128 v[190:193], v171 offset:1024
	ds_read_b128 v[194:197], v171 offset:2048
	ds_read_b128 v[198:201], v171 offset:3072
	ds_read_b128 v[202:205], v171 offset:4096
	ds_read_b128 v[206:209], v171 offset:5120
	ds_read_b128 v[210:213], v171 offset:6144
	ds_read_b128 v[214:217], v171 offset:7168
	global_load_lds_dwordx4 v[164:165], off
	v_lshl_add_u64 v[164:165], s[44:45], 0, v[154:155]
	s_add_i32 m0, s17, 0xe000
	s_nop 0
	global_load_lds_dwordx4 v[164:165], off
	s_waitcnt vmcnt(8)
	s_waitcnt lgkmcnt(0)
	s_barrier
	s_setprio 1
	s_waitcnt lgkmcnt(0)
	v_mfma_f32_16x16x32_bf16 v[124:127], v[128:131], v[184:187], v[124:127]
	v_mfma_f32_16x16x32_bf16 v[120:123], v[136:139], v[184:187], v[120:123]
	v_mfma_f32_16x16x32_bf16 v[116:119], v[128:131], v[194:197], v[116:119]
	v_mfma_f32_16x16x32_bf16 v[112:115], v[136:139], v[194:197], v[112:115]
	v_mfma_f32_16x16x32_bf16 v[92:95], v[128:131], v[202:205], v[92:95]
	v_mfma_f32_16x16x32_bf16 v[84:87], v[136:139], v[202:205], v[84:87]
	v_mfma_f32_16x16x32_bf16 v[76:79], v[128:131], v[210:213], v[76:79]
	v_mfma_f32_16x16x32_bf16 v[68:71], v[136:139], v[210:213], v[68:71]
	v_mfma_f32_16x16x32_bf16 v[124:127], v[132:135], v[190:193], v[124:127]
	v_mfma_f32_16x16x32_bf16 v[120:123], v[140:143], v[190:193], v[120:123]
	v_mfma_f32_16x16x32_bf16 v[116:119], v[132:135], v[198:201], v[116:119]
	v_mfma_f32_16x16x32_bf16 v[112:115], v[140:143], v[198:201], v[112:115]
	v_mfma_f32_16x16x32_bf16 v[92:95], v[132:135], v[206:209], v[92:95]
	v_mfma_f32_16x16x32_bf16 v[84:87], v[140:143], v[206:209], v[84:87]
	v_mfma_f32_16x16x32_bf16 v[76:79], v[132:135], v[214:217], v[76:79]
	v_mfma_f32_16x16x32_bf16 v[68:71], v[140:143], v[214:217], v[68:71]
	s_setprio 0
	s_setprio 1
	v_mfma_f32_16x16x32_bf16 v[108:111], v[160:163], v[184:187], v[108:111]
	v_mfma_f32_16x16x32_bf16 v[104:107], v[176:179], v[184:187], v[104:107]
	v_mfma_f32_16x16x32_bf16 v[100:103], v[160:163], v[194:197], v[100:103]
	v_mfma_f32_16x16x32_bf16 v[96:99], v[176:179], v[194:197], v[96:99]
	v_mfma_f32_16x16x32_bf16 v[88:91], v[160:163], v[202:205], v[88:91]
	v_mfma_f32_16x16x32_bf16 v[80:83], v[176:179], v[202:205], v[80:83]
	v_mfma_f32_16x16x32_bf16 v[72:75], v[160:163], v[210:213], v[72:75]
	v_mfma_f32_16x16x32_bf16 v[64:67], v[176:179], v[210:213], v[64:67]
	v_mfma_f32_16x16x32_bf16 v[108:111], v[172:175], v[190:193], v[108:111]
	v_mfma_f32_16x16x32_bf16 v[104:107], v[180:183], v[190:193], v[104:107]
	v_mfma_f32_16x16x32_bf16 v[100:103], v[172:175], v[198:201], v[100:103]
	v_mfma_f32_16x16x32_bf16 v[96:99], v[180:183], v[198:201], v[96:99]
	v_mfma_f32_16x16x32_bf16 v[88:91], v[172:175], v[206:209], v[88:91]
	v_mfma_f32_16x16x32_bf16 v[80:83], v[180:183], v[206:209], v[80:83]
	v_mfma_f32_16x16x32_bf16 v[72:75], v[172:175], v[214:217], v[72:75]
	v_mfma_f32_16x16x32_bf16 v[64:67], v[180:183], v[214:217], v[64:67]
	s_setprio 0
	s_barrier
	s_add_i32 s28, s54, s13
	v_lshl_add_u64 v[164:165], s[46:47], 0, v[146:147]
	s_mov_b32 m0, s28
	ds_read_b128 v[184:187], v171 offset:16384
	ds_read_b128 v[190:193], v171 offset:17408
	ds_read_b128 v[194:197], v171 offset:18432
	ds_read_b128 v[198:201], v171 offset:19456
	ds_read_b128 v[202:205], v171 offset:20480
	ds_read_b128 v[206:209], v171 offset:21504
	ds_read_b128 v[210:213], v171 offset:22528
	ds_read_b128 v[214:217], v171 offset:23552
	global_load_lds_dwordx4 v[164:165], off
	s_add_i32 m0, s28, 0x2000
	s_add_u32 s28, s46, 0x20000
	v_lshl_add_u64 v[218:219], s[46:47], 0, v[150:151]
	s_addc_u32 s29, s47, 0
	s_add_i32 s33, s55, s13
	global_load_lds_dwordx4 v[218:219], off
	v_lshl_add_u64 v[220:221], s[28:29], 0, v[146:147]
	s_mov_b32 m0, s33
	v_lshl_add_u64 v[222:223], s[50:51], 0, v[148:149]
	global_load_lds_dwordx4 v[220:221], off
	v_lshl_add_u64 v[220:221], s[28:29], 0, v[150:151]
	s_add_i32 m0, s33, 0x2000
	s_nop 0
	global_load_lds_dwordx4 v[220:221], off
	v_lshl_add_u64 v[220:221], s[50:51], 0, v[144:145]
	s_mov_b32 m0, s17
	s_nop 0
	global_load_lds_dwordx4 v[220:221], off
	s_mov_b32 m0, s27
	s_nop 0
	global_load_lds_dwordx4 v[222:223], off
	s_waitcnt vmcnt(8)
	s_waitcnt lgkmcnt(0)
	s_nop 0
	s_barrier
	s_setprio 1
	s_waitcnt lgkmcnt(0)
	v_mfma_f32_16x16x32_bf16 v[60:63], v[128:131], v[184:187], v[60:63]
	v_mfma_f32_16x16x32_bf16 v[52:55], v[136:139], v[184:187], v[52:55]
	v_mfma_f32_16x16x32_bf16 v[44:47], v[128:131], v[194:197], v[44:47]
	v_mfma_f32_16x16x32_bf16 v[36:39], v[136:139], v[194:197], v[36:39]
	v_mfma_f32_16x16x32_bf16 v[28:31], v[128:131], v[202:205], v[28:31]
	v_mfma_f32_16x16x32_bf16 v[20:23], v[136:139], v[202:205], v[20:23]
	v_mfma_f32_16x16x32_bf16 v[12:15], v[128:131], v[210:213], v[12:15]
	v_mfma_f32_16x16x32_bf16 v[4:7], v[136:139], v[210:213], v[4:7]
	v_mfma_f32_16x16x32_bf16 v[60:63], v[132:135], v[190:193], v[60:63]
	v_mfma_f32_16x16x32_bf16 v[52:55], v[140:143], v[190:193], v[52:55]
	v_mfma_f32_16x16x32_bf16 v[44:47], v[132:135], v[198:201], v[44:47]
	v_mfma_f32_16x16x32_bf16 v[36:39], v[140:143], v[198:201], v[36:39]
	v_mfma_f32_16x16x32_bf16 v[28:31], v[132:135], v[206:209], v[28:31]
	v_mfma_f32_16x16x32_bf16 v[20:23], v[140:143], v[206:209], v[20:23]
	v_mfma_f32_16x16x32_bf16 v[12:15], v[132:135], v[214:217], v[12:15]
	v_mfma_f32_16x16x32_bf16 v[4:7], v[140:143], v[214:217], v[4:7]
	s_setprio 0
	s_setprio 1
	v_mfma_f32_16x16x32_bf16 v[56:59], v[160:163], v[184:187], v[56:59]
	v_mfma_f32_16x16x32_bf16 v[48:51], v[176:179], v[184:187], v[48:51]
	v_mfma_f32_16x16x32_bf16 v[40:43], v[160:163], v[194:197], v[40:43]
	v_mfma_f32_16x16x32_bf16 v[32:35], v[176:179], v[194:197], v[32:35]
	v_mfma_f32_16x16x32_bf16 v[24:27], v[160:163], v[202:205], v[24:27]
	v_mfma_f32_16x16x32_bf16 v[16:19], v[176:179], v[202:205], v[16:19]
	v_mfma_f32_16x16x32_bf16 v[8:11], v[160:163], v[210:213], v[8:11]
	v_mfma_f32_16x16x32_bf16 v[0:3], v[176:179], v[210:213], v[0:3]
	v_mfma_f32_16x16x32_bf16 v[56:59], v[172:175], v[190:193], v[56:59]
	v_mfma_f32_16x16x32_bf16 v[48:51], v[180:183], v[190:193], v[48:51]
	v_mfma_f32_16x16x32_bf16 v[40:43], v[172:175], v[198:201], v[40:43]
	v_mfma_f32_16x16x32_bf16 v[32:35], v[180:183], v[198:201], v[32:35]
	v_mfma_f32_16x16x32_bf16 v[24:27], v[172:175], v[206:209], v[24:27]
	v_mfma_f32_16x16x32_bf16 v[16:19], v[180:183], v[206:209], v[16:19]
	v_mfma_f32_16x16x32_bf16 v[8:11], v[172:175], v[214:217], v[8:11]
	v_mfma_f32_16x16x32_bf16 v[0:3], v[180:183], v[214:217], v[0:3]
	s_setprio 0
	s_barrier
	s_add_i32 s33, 0, 0x18000
	s_add_i32 s65, 0, 0x1c000
	v_add_u32_e32 v140, s33, v167
	v_add_u32_e32 v180, s65, v167
	ds_read_b128 v[128:131], v140
	ds_read_b128 v[132:135], v140 offset:1024
	ds_read_b128 v[136:139], v140 offset:2048
	ds_read_b128 v[140:143], v140 offset:3072
	ds_read_b128 v[160:163], v180
	ds_read_b128 v[172:175], v180 offset:1024
	ds_read_b128 v[176:179], v180 offset:2048
	ds_read_b128 v[180:183], v180 offset:3072
	s_add_u32 s28, s50, 0x20000
	s_addc_u32 s29, s51, 0
	s_mov_b32 m0, s34
	v_lshl_add_u64 v[224:225], s[28:29], 0, v[144:145]
	ds_read_b128 v[184:187], v171 offset:32768
	ds_read_b128 v[190:193], v171 offset:33792
	ds_read_b128 v[194:197], v171 offset:34816
	ds_read_b128 v[198:201], v171 offset:35840
	ds_read_b128 v[202:205], v171 offset:36864
	ds_read_b128 v[206:209], v171 offset:37888
	ds_read_b128 v[210:213], v171 offset:38912
	ds_read_b128 v[214:217], v171 offset:39936
	global_load_lds_dwordx4 v[224:225], off
	v_lshl_add_u64 v[224:225], s[28:29], 0, v[148:149]
	s_mov_b32 m0, s35
	s_nop 0
	global_load_lds_dwordx4 v[224:225], off
	s_waitcnt vmcnt(8)
	s_waitcnt lgkmcnt(0)
	s_nop 0
	s_barrier
	s_setprio 1
	s_waitcnt lgkmcnt(0)
	v_mfma_f32_16x16x32_bf16 v[124:127], v[128:131], v[184:187], v[124:127]
	v_mfma_f32_16x16x32_bf16 v[120:123], v[136:139], v[184:187], v[120:123]
	v_mfma_f32_16x16x32_bf16 v[116:119], v[128:131], v[194:197], v[116:119]
	v_mfma_f32_16x16x32_bf16 v[112:115], v[136:139], v[194:197], v[112:115]
	v_mfma_f32_16x16x32_bf16 v[92:95], v[128:131], v[202:205], v[92:95]
	v_mfma_f32_16x16x32_bf16 v[84:87], v[136:139], v[202:205], v[84:87]
	v_mfma_f32_16x16x32_bf16 v[76:79], v[128:131], v[210:213], v[76:79]
	v_mfma_f32_16x16x32_bf16 v[68:71], v[136:139], v[210:213], v[68:71]
	v_mfma_f32_16x16x32_bf16 v[124:127], v[132:135], v[190:193], v[124:127]
	v_mfma_f32_16x16x32_bf16 v[120:123], v[140:143], v[190:193], v[120:123]
	v_mfma_f32_16x16x32_bf16 v[116:119], v[132:135], v[198:201], v[116:119]
	v_mfma_f32_16x16x32_bf16 v[112:115], v[140:143], v[198:201], v[112:115]
	v_mfma_f32_16x16x32_bf16 v[92:95], v[132:135], v[206:209], v[92:95]
	v_mfma_f32_16x16x32_bf16 v[84:87], v[140:143], v[206:209], v[84:87]
	v_mfma_f32_16x16x32_bf16 v[76:79], v[132:135], v[214:217], v[76:79]
	v_mfma_f32_16x16x32_bf16 v[68:71], v[140:143], v[214:217], v[68:71]
	s_setprio 0
	s_setprio 1
	v_mfma_f32_16x16x32_bf16 v[108:111], v[160:163], v[184:187], v[108:111]
	v_mfma_f32_16x16x32_bf16 v[104:107], v[176:179], v[184:187], v[104:107]
	v_mfma_f32_16x16x32_bf16 v[100:103], v[160:163], v[194:197], v[100:103]
	v_mfma_f32_16x16x32_bf16 v[96:99], v[176:179], v[194:197], v[96:99]
	v_mfma_f32_16x16x32_bf16 v[88:91], v[160:163], v[202:205], v[88:91]
	v_mfma_f32_16x16x32_bf16 v[80:83], v[176:179], v[202:205], v[80:83]
	v_mfma_f32_16x16x32_bf16 v[72:75], v[160:163], v[210:213], v[72:75]
	v_mfma_f32_16x16x32_bf16 v[64:67], v[176:179], v[210:213], v[64:67]
	v_mfma_f32_16x16x32_bf16 v[108:111], v[172:175], v[190:193], v[108:111]
	v_mfma_f32_16x16x32_bf16 v[104:107], v[180:183], v[190:193], v[104:107]
	v_mfma_f32_16x16x32_bf16 v[100:103], v[172:175], v[198:201], v[100:103]
	v_mfma_f32_16x16x32_bf16 v[96:99], v[180:183], v[198:201], v[96:99]
	v_mfma_f32_16x16x32_bf16 v[88:91], v[172:175], v[206:209], v[88:91]
	v_mfma_f32_16x16x32_bf16 v[80:83], v[180:183], v[206:209], v[80:83]
	v_mfma_f32_16x16x32_bf16 v[72:75], v[172:175], v[214:217], v[72:75]
	v_mfma_f32_16x16x32_bf16 v[64:67], v[180:183], v[214:217], v[64:67]
	s_setprio 0
	s_barrier
	s_add_i32 s28, s33, s13
	v_lshl_add_u64 v[164:165], v[164:165], 0, s[10:11]
	s_mov_b32 m0, s28
	ds_read_b128 v[184:187], v171 offset:49152
	ds_read_b128 v[190:193], v171 offset:50176
	ds_read_b128 v[194:197], v171 offset:51200
	ds_read_b128 v[198:201], v171 offset:52224
	ds_read_b128 v[202:205], v171 offset:53248
	ds_read_b128 v[206:209], v171 offset:54272
	ds_read_b128 v[210:213], v171 offset:55296
	ds_read_b128 v[214:217], v171 offset:56320
	global_load_lds_dwordx4 v[164:165], off
	s_add_i32 m0, s28, 0x2000
	s_add_u32 s28, s46, 0x20080
	v_lshl_add_u64 v[164:165], v[218:219], 0, s[10:11]
	s_addc_u32 s29, s47, 0
	s_add_i32 s33, s65, s13
	global_load_lds_dwordx4 v[164:165], off
	v_lshl_add_u64 v[164:165], s[28:29], 0, v[146:147]
	s_mov_b32 m0, s33
	s_nop 0
	global_load_lds_dwordx4 v[164:165], off
	v_lshl_add_u64 v[164:165], s[28:29], 0, v[150:151]
	s_add_i32 m0, s33, 0x2000
	s_nop 0
	global_load_lds_dwordx4 v[164:165], off
	v_lshl_add_u64 v[164:165], v[220:221], 0, s[10:11]
	s_mov_b32 m0, s52
	s_nop 0
	global_load_lds_dwordx4 v[164:165], off
	v_lshl_add_u64 v[164:165], v[222:223], 0, s[10:11]
	s_mov_b32 m0, s53
	s_nop 0
	global_load_lds_dwordx4 v[164:165], off
	s_waitcnt vmcnt(8)
	s_waitcnt lgkmcnt(0)
	s_barrier
	s_setprio 1
	s_waitcnt lgkmcnt(0)
	v_mfma_f32_16x16x32_bf16 v[60:63], v[128:131], v[184:187], v[60:63]
	v_mfma_f32_16x16x32_bf16 v[52:55], v[136:139], v[184:187], v[52:55]
	v_mfma_f32_16x16x32_bf16 v[44:47], v[128:131], v[194:197], v[44:47]
	v_mfma_f32_16x16x32_bf16 v[36:39], v[136:139], v[194:197], v[36:39]
	v_mfma_f32_16x16x32_bf16 v[28:31], v[128:131], v[202:205], v[28:31]
	v_mfma_f32_16x16x32_bf16 v[20:23], v[136:139], v[202:205], v[20:23]
	v_mfma_f32_16x16x32_bf16 v[12:15], v[128:131], v[210:213], v[12:15]
	v_mfma_f32_16x16x32_bf16 v[4:7], v[136:139], v[210:213], v[4:7]
	v_mfma_f32_16x16x32_bf16 v[60:63], v[132:135], v[190:193], v[60:63]
	v_mfma_f32_16x16x32_bf16 v[52:55], v[140:143], v[190:193], v[52:55]
	v_mfma_f32_16x16x32_bf16 v[44:47], v[132:135], v[198:201], v[44:47]
	v_mfma_f32_16x16x32_bf16 v[36:39], v[140:143], v[198:201], v[36:39]
	v_mfma_f32_16x16x32_bf16 v[28:31], v[132:135], v[206:209], v[28:31]
	v_mfma_f32_16x16x32_bf16 v[20:23], v[140:143], v[206:209], v[20:23]
	v_mfma_f32_16x16x32_bf16 v[12:15], v[132:135], v[214:217], v[12:15]
	v_mfma_f32_16x16x32_bf16 v[4:7], v[140:143], v[214:217], v[4:7]
	s_setprio 0
	s_setprio 1
	v_mfma_f32_16x16x32_bf16 v[56:59], v[160:163], v[184:187], v[56:59]
	v_mfma_f32_16x16x32_bf16 v[48:51], v[176:179], v[184:187], v[48:51]
	v_mfma_f32_16x16x32_bf16 v[40:43], v[160:163], v[194:197], v[40:43]
	v_mfma_f32_16x16x32_bf16 v[32:35], v[176:179], v[194:197], v[32:35]
	v_mfma_f32_16x16x32_bf16 v[24:27], v[160:163], v[202:205], v[24:27]
	v_mfma_f32_16x16x32_bf16 v[16:19], v[176:179], v[202:205], v[16:19]
	v_mfma_f32_16x16x32_bf16 v[8:11], v[160:163], v[210:213], v[8:11]
	v_mfma_f32_16x16x32_bf16 v[0:3], v[176:179], v[210:213], v[0:3]
	v_mfma_f32_16x16x32_bf16 v[56:59], v[172:175], v[190:193], v[56:59]
	v_mfma_f32_16x16x32_bf16 v[48:51], v[180:183], v[190:193], v[48:51]
	v_mfma_f32_16x16x32_bf16 v[40:43], v[172:175], v[198:201], v[40:43]
	v_mfma_f32_16x16x32_bf16 v[32:35], v[180:183], v[198:201], v[32:35]
	v_mfma_f32_16x16x32_bf16 v[24:27], v[172:175], v[206:209], v[24:27]
	v_mfma_f32_16x16x32_bf16 v[16:19], v[180:183], v[206:209], v[16:19]
	v_mfma_f32_16x16x32_bf16 v[8:11], v[172:175], v[214:217], v[8:11]
	v_mfma_f32_16x16x32_bf16 v[0:3], v[180:183], v[214:217], v[0:3]
	s_setprio 0
	s_barrier
	s_add_i32 s64, s64, 2
	s_add_u32 s44, s44, 0x100
	s_addc_u32 s45, s45, 0
	s_add_u32 s62, s62, 0x100
	s_addc_u32 s63, s63, 0
	s_cmp_gt_u32 s64, 5
	s_cbranch_scc0 .LBB0_1029
	s_and_b64 vcc, exec, s[14:15]
	s_cbranch_vccz .LBB0_1032
	s_barrier

.LBB0_1068:
	s_andn2_saveexec_b64 s[10:11], s[10:11]
	s_cbranch_execz .LBB0_1088
	s_mov_b64 s[10:11], exec
	s_cmp_lg_u32 s98, 0
	s_cbranch_scc1 .LBB0_1085
	buffer_wbl2 sc1
	s_waitcnt lgkmcnt(0)
	s_waitcnt vmcnt(0)
	v_mbcnt_lo_u32_b32 v1, s10, 0
	v_mbcnt_hi_u32_b32 v1, s11, v1
	v_cmp_eq_u32_e32 vcc, 0, v1
	s_and_saveexec_b64 s[14:15], vcc
	s_cbranch_execz .LBB0_1071
	s_bcnt1_i32_b64 s3, s[10:11]
	v_mov_b32_e32 v2, 0x5c3000
	v_mov_b32_e32 v3, s3
	global_atomic_add v2, v2, v3, s[72:73] offset:1024 sc0

.LBB0_1105:
	ds_read_b128 v[128:131], v181
	ds_read_b128 v[132:135], v181 offset:1024
	ds_read_b128 v[136:139], v181 offset:2048
	ds_read_b128 v[140:143], v181 offset:3072
	ds_read_b128 v[144:147], v182
	ds_read_b128 v[148:151], v182 offset:1024
	ds_read_b128 v[168:171], v182 offset:2048
	ds_read_b128 v[172:175], v182 offset:3072
	s_add_u32 s28, s42, 0xfffe0080
	s_addc_u32 s29, s43, -1
	s_cmp_eq_u32 s58, 4
	s_cselect_b32 s47, s19, s29
	s_cselect_b32 s46, s54, s28
	s_cselect_b32 s45, s17, s57
	s_cselect_b32 s44, s55, s56
	v_lshl_add_u64 v[176:177], s[42:43], 0, v[160:161]
	s_add_i32 m0, s27, 0xc000
	ds_read_b128 v[184:187], v183
	ds_read_b128 v[190:193], v183 offset:1024
	ds_read_b128 v[194:197], v183 offset:2048
	ds_read_b128 v[198:201], v183 offset:3072
	ds_read_b128 v[202:205], v183 offset:4096
	ds_read_b128 v[206:209], v183 offset:5120
	ds_read_b128 v[210:213], v183 offset:6144
	ds_read_b128 v[214:217], v183 offset:7168
	global_load_lds_dwordx4 v[176:177], off
	v_lshl_add_u64 v[176:177], s[42:43], 0, v[162:163]
	s_add_i32 m0, s27, 0xe000
	s_nop 0
	global_load_lds_dwordx4 v[176:177], off
	s_waitcnt vmcnt(8)
	s_waitcnt lgkmcnt(0)
	s_barrier
	s_setprio 1
	s_waitcnt lgkmcnt(0)
	v_mfma_f32_16x16x32_bf16 v[124:127], v[128:131], v[184:187], v[124:127]
	v_mfma_f32_16x16x32_bf16 v[120:123], v[136:139], v[184:187], v[120:123]
	v_mfma_f32_16x16x32_bf16 v[108:111], v[128:131], v[194:197], v[108:111]
	v_mfma_f32_16x16x32_bf16 v[104:107], v[136:139], v[194:197], v[104:107]
	v_mfma_f32_16x16x32_bf16 v[92:95], v[128:131], v[202:205], v[92:95]
	v_mfma_f32_16x16x32_bf16 v[88:91], v[136:139], v[202:205], v[88:91]
	v_mfma_f32_16x16x32_bf16 v[76:79], v[128:131], v[210:213], v[76:79]
	v_mfma_f32_16x16x32_bf16 v[72:75], v[136:139], v[210:213], v[72:75]
	v_mfma_f32_16x16x32_bf16 v[124:127], v[132:135], v[190:193], v[124:127]
	v_mfma_f32_16x16x32_bf16 v[120:123], v[140:143], v[190:193], v[120:123]
	v_mfma_f32_16x16x32_bf16 v[108:111], v[132:135], v[198:201], v[108:111]
	v_mfma_f32_16x16x32_bf16 v[104:107], v[140:143], v[198:201], v[104:107]
	v_mfma_f32_16x16x32_bf16 v[92:95], v[132:135], v[206:209], v[92:95]
	v_mfma_f32_16x16x32_bf16 v[88:91], v[140:143], v[206:209], v[88:91]
	v_mfma_f32_16x16x32_bf16 v[76:79], v[132:135], v[214:217], v[76:79]
	v_mfma_f32_16x16x32_bf16 v[72:75], v[140:143], v[214:217], v[72:75]
	s_setprio 0
	s_setprio 1
	v_mfma_f32_16x16x32_bf16 v[116:119], v[144:147], v[184:187], v[116:119]
	v_mfma_f32_16x16x32_bf16 v[112:115], v[168:171], v[184:187], v[112:115]
	v_mfma_f32_16x16x32_bf16 v[100:103], v[144:147], v[194:197], v[100:103]
	v_mfma_f32_16x16x32_bf16 v[96:99], v[168:171], v[194:197], v[96:99]
	v_mfma_f32_16x16x32_bf16 v[84:87], v[144:147], v[202:205], v[84:87]
	v_mfma_f32_16x16x32_bf16 v[80:83], v[168:171], v[202:205], v[80:83]
	v_mfma_f32_16x16x32_bf16 v[68:71], v[144:147], v[210:213], v[68:71]
	v_mfma_f32_16x16x32_bf16 v[64:67], v[168:171], v[210:213], v[64:67]
	v_mfma_f32_16x16x32_bf16 v[116:119], v[148:151], v[190:193], v[116:119]
	v_mfma_f32_16x16x32_bf16 v[112:115], v[172:175], v[190:193], v[112:115]
	v_mfma_f32_16x16x32_bf16 v[100:103], v[148:151], v[198:201], v[100:103]
	v_mfma_f32_16x16x32_bf16 v[96:99], v[172:175], v[198:201], v[96:99]
	v_mfma_f32_16x16x32_bf16 v[84:87], v[148:151], v[206:209], v[84:87]
	v_mfma_f32_16x16x32_bf16 v[80:83], v[172:175], v[206:209], v[80:83]
	v_mfma_f32_16x16x32_bf16 v[68:71], v[148:151], v[214:217], v[68:71]
	v_mfma_f32_16x16x32_bf16 v[64:67], v[172:175], v[214:217], v[64:67]
	s_setprio 0
	s_barrier
	s_add_i32 s28, s51, s13
	v_lshl_add_u64 v[176:177], s[44:45], 0, v[154:155]
	s_mov_b32 m0, s28
	ds_read_b128 v[184:187], v183 offset:16384
	ds_read_b128 v[190:193], v183 offset:17408
	ds_read_b128 v[194:197], v183 offset:18432
	ds_read_b128 v[198:201], v183 offset:19456
	ds_read_b128 v[202:205], v183 offset:20480
	ds_read_b128 v[206:209], v183 offset:21504
	ds_read_b128 v[210:213], v183 offset:22528
	ds_read_b128 v[214:217], v183 offset:23552
	global_load_lds_dwordx4 v[176:177], off
	s_add_i32 m0, s28, 0x2000
	s_add_u32 s28, s44, 0x20000
	v_lshl_add_u64 v[218:219], s[44:45], 0, v[158:159]
	s_addc_u32 s29, s45, 0
	s_add_i32 s33, s52, s13
	global_load_lds_dwordx4 v[218:219], off
	v_lshl_add_u64 v[220:221], s[28:29], 0, v[154:155]
	s_mov_b32 m0, s33
	v_lshl_add_u64 v[222:223], s[46:47], 0, v[156:157]
	global_load_lds_dwordx4 v[220:221], off
	v_lshl_add_u64 v[220:221], s[28:29], 0, v[158:159]
	s_add_i32 m0, s33, 0x2000
	s_nop 0
	global_load_lds_dwordx4 v[220:221], off
	v_lshl_add_u64 v[220:221], s[46:47], 0, v[152:153]
	s_mov_b32 m0, s27
	s_nop 0
	global_load_lds_dwordx4 v[220:221], off
	s_mov_b32 m0, s34
	s_nop 0
	global_load_lds_dwordx4 v[222:223], off
	s_waitcnt vmcnt(8)
	s_waitcnt lgkmcnt(0)
	s_nop 0
	s_barrier
	s_setprio 1
	s_waitcnt lgkmcnt(0)
	v_mfma_f32_16x16x32_bf16 v[60:63], v[128:131], v[184:187], v[60:63]
	v_mfma_f32_16x16x32_bf16 v[56:59], v[136:139], v[184:187], v[56:59]
	v_mfma_f32_16x16x32_bf16 v[44:47], v[128:131], v[194:197], v[44:47]
	v_mfma_f32_16x16x32_bf16 v[40:43], v[136:139], v[194:197], v[40:43]
	v_mfma_f32_16x16x32_bf16 v[28:31], v[128:131], v[202:205], v[28:31]
	v_mfma_f32_16x16x32_bf16 v[24:27], v[136:139], v[202:205], v[24:27]
	v_mfma_f32_16x16x32_bf16 v[12:15], v[128:131], v[210:213], v[12:15]
	v_mfma_f32_16x16x32_bf16 v[8:11], v[136:139], v[210:213], v[8:11]
	v_mfma_f32_16x16x32_bf16 v[60:63], v[132:135], v[190:193], v[60:63]
	v_mfma_f32_16x16x32_bf16 v[56:59], v[140:143], v[190:193], v[56:59]
	v_mfma_f32_16x16x32_bf16 v[44:47], v[132:135], v[198:201], v[44:47]
	v_mfma_f32_16x16x32_bf16 v[40:43], v[140:143], v[198:201], v[40:43]
	v_mfma_f32_16x16x32_bf16 v[28:31], v[132:135], v[206:209], v[28:31]
	v_mfma_f32_16x16x32_bf16 v[24:27], v[140:143], v[206:209], v[24:27]
	v_mfma_f32_16x16x32_bf16 v[12:15], v[132:135], v[214:217], v[12:15]
	v_mfma_f32_16x16x32_bf16 v[8:11], v[140:143], v[214:217], v[8:11]
	s_setprio 0
	s_setprio 1
	v_mfma_f32_16x16x32_bf16 v[52:55], v[144:147], v[184:187], v[52:55]
	v_mfma_f32_16x16x32_bf16 v[48:51], v[168:171], v[184:187], v[48:51]
	v_mfma_f32_16x16x32_bf16 v[36:39], v[144:147], v[194:197], v[36:39]
	v_mfma_f32_16x16x32_bf16 v[32:35], v[168:171], v[194:197], v[32:35]
	v_mfma_f32_16x16x32_bf16 v[20:23], v[144:147], v[202:205], v[20:23]
	v_mfma_f32_16x16x32_bf16 v[16:19], v[168:171], v[202:205], v[16:19]
	v_mfma_f32_16x16x32_bf16 v[4:7], v[144:147], v[210:213], v[4:7]
	v_mfma_f32_16x16x32_bf16 v[0:3], v[168:171], v[210:213], v[0:3]
	v_mfma_f32_16x16x32_bf16 v[52:55], v[148:151], v[190:193], v[52:55]
	v_mfma_f32_16x16x32_bf16 v[48:51], v[172:175], v[190:193], v[48:51]
	v_mfma_f32_16x16x32_bf16 v[36:39], v[148:151], v[198:201], v[36:39]
	v_mfma_f32_16x16x32_bf16 v[32:35], v[172:175], v[198:201], v[32:35]
	v_mfma_f32_16x16x32_bf16 v[20:23], v[148:151], v[206:209], v[20:23]
	v_mfma_f32_16x16x32_bf16 v[16:19], v[172:175], v[206:209], v[16:19]
	v_mfma_f32_16x16x32_bf16 v[4:7], v[148:151], v[214:217], v[4:7]
	v_mfma_f32_16x16x32_bf16 v[0:3], v[172:175], v[214:217], v[0:3]
	s_setprio 0
	s_barrier
	s_add_i32 s33, 0, 0x18000
	s_add_i32 s59, 0, 0x1c000
	v_add_u32_e32 v140, s33, v179
	v_add_u32_e32 v172, s59, v179
	ds_read_b128 v[128:131], v140
	ds_read_b128 v[132:135], v140 offset:1024
	ds_read_b128 v[136:139], v140 offset:2048
	ds_read_b128 v[140:143], v140 offset:3072
	ds_read_b128 v[144:147], v172
	ds_read_b128 v[148:151], v172 offset:1024
	ds_read_b128 v[168:171], v172 offset:2048
	ds_read_b128 v[172:175], v172 offset:3072
	s_add_u32 s28, s46, 0x20000
	s_addc_u32 s29, s47, 0
	s_mov_b32 m0, s35
	v_lshl_add_u64 v[224:225], s[28:29], 0, v[152:153]
	ds_read_b128 v[184:187], v183 offset:32768
	ds_read_b128 v[190:193], v183 offset:33792
	ds_read_b128 v[194:197], v183 offset:34816
	ds_read_b128 v[198:201], v183 offset:35840
	ds_read_b128 v[202:205], v183 offset:36864
	ds_read_b128 v[206:209], v183 offset:37888
	ds_read_b128 v[210:213], v183 offset:38912
	ds_read_b128 v[214:217], v183 offset:39936
	global_load_lds_dwordx4 v[224:225], off
	v_lshl_add_u64 v[224:225], s[28:29], 0, v[156:157]
	s_mov_b32 m0, s41
	s_nop 0
	global_load_lds_dwordx4 v[224:225], off
	s_waitcnt vmcnt(8)
	s_waitcnt lgkmcnt(0)
	s_nop 0
	s_barrier
	s_setprio 1
	s_waitcnt lgkmcnt(0)
	v_mfma_f32_16x16x32_bf16 v[124:127], v[128:131], v[184:187], v[124:127]
	v_mfma_f32_16x16x32_bf16 v[120:123], v[136:139], v[184:187], v[120:123]
	v_mfma_f32_16x16x32_bf16 v[108:111], v[128:131], v[194:197], v[108:111]
	v_mfma_f32_16x16x32_bf16 v[104:107], v[136:139], v[194:197], v[104:107]
	v_mfma_f32_16x16x32_bf16 v[92:95], v[128:131], v[202:205], v[92:95]
	v_mfma_f32_16x16x32_bf16 v[88:91], v[136:139], v[202:205], v[88:91]
	v_mfma_f32_16x16x32_bf16 v[76:79], v[128:131], v[210:213], v[76:79]
	v_mfma_f32_16x16x32_bf16 v[72:75], v[136:139], v[210:213], v[72:75]
	v_mfma_f32_16x16x32_bf16 v[124:127], v[132:135], v[190:193], v[124:127]
	v_mfma_f32_16x16x32_bf16 v[120:123], v[140:143], v[190:193], v[120:123]
	v_mfma_f32_16x16x32_bf16 v[108:111], v[132:135], v[198:201], v[108:111]
	v_mfma_f32_16x16x32_bf16 v[104:107], v[140:143], v[198:201], v[104:107]
	v_mfma_f32_16x16x32_bf16 v[92:95], v[132:135], v[206:209], v[92:95]
	v_mfma_f32_16x16x32_bf16 v[88:91], v[140:143], v[206:209], v[88:91]
	v_mfma_f32_16x16x32_bf16 v[76:79], v[132:135], v[214:217], v[76:79]
	v_mfma_f32_16x16x32_bf16 v[72:75], v[140:143], v[214:217], v[72:75]
	s_setprio 0
	s_setprio 1
	v_mfma_f32_16x16x32_bf16 v[116:119], v[144:147], v[184:187], v[116:119]
	v_mfma_f32_16x16x32_bf16 v[112:115], v[168:171], v[184:187], v[112:115]
	v_mfma_f32_16x16x32_bf16 v[100:103], v[144:147], v[194:197], v[100:103]
	v_mfma_f32_16x16x32_bf16 v[96:99], v[168:171], v[194:197], v[96:99]
	v_mfma_f32_16x16x32_bf16 v[84:87], v[144:147], v[202:205], v[84:87]
	v_mfma_f32_16x16x32_bf16 v[80:83], v[168:171], v[202:205], v[80:83]
	v_mfma_f32_16x16x32_bf16 v[68:71], v[144:147], v[210:213], v[68:71]
	v_mfma_f32_16x16x32_bf16 v[64:67], v[168:171], v[210:213], v[64:67]
	v_mfma_f32_16x16x32_bf16 v[116:119], v[148:151], v[190:193], v[116:119]
	v_mfma_f32_16x16x32_bf16 v[112:115], v[172:175], v[190:193], v[112:115]
	v_mfma_f32_16x16x32_bf16 v[100:103], v[148:151], v[198:201], v[100:103]
	v_mfma_f32_16x16x32_bf16 v[96:99], v[172:175], v[198:201], v[96:99]
	v_mfma_f32_16x16x32_bf16 v[84:87], v[148:151], v[206:209], v[84:87]
	v_mfma_f32_16x16x32_bf16 v[80:83], v[172:175], v[206:209], v[80:83]
	v_mfma_f32_16x16x32_bf16 v[68:71], v[148:151], v[214:217], v[68:71]
	v_mfma_f32_16x16x32_bf16 v[64:67], v[172:175], v[214:217], v[64:67]
	s_setprio 0
	s_barrier
	s_add_i32 s28, s33, s13
	v_lshl_add_u64 v[176:177], v[176:177], 0, s[10:11]
	s_mov_b32 m0, s28
	ds_read_b128 v[184:187], v183 offset:49152
	ds_read_b128 v[190:193], v183 offset:50176
	ds_read_b128 v[194:197], v183 offset:51200
	ds_read_b128 v[198:201], v183 offset:52224
	ds_read_b128 v[202:205], v183 offset:53248
	ds_read_b128 v[206:209], v183 offset:54272
	ds_read_b128 v[210:213], v183 offset:55296
	ds_read_b128 v[214:217], v183 offset:56320
	global_load_lds_dwordx4 v[176:177], off
	s_add_i32 m0, s28, 0x2000
	s_add_u32 s28, s44, 0x20080
	v_lshl_add_u64 v[176:177], v[218:219], 0, s[10:11]
	s_addc_u32 s29, s45, 0
	s_add_i32 s33, s59, s13
	global_load_lds_dwordx4 v[176:177], off
	v_lshl_add_u64 v[176:177], s[28:29], 0, v[154:155]
	s_mov_b32 m0, s33
	s_nop 0
	global_load_lds_dwordx4 v[176:177], off
	v_lshl_add_u64 v[176:177], s[28:29], 0, v[158:159]
	s_add_i32 m0, s33, 0x2000
	s_nop 0
	global_load_lds_dwordx4 v[176:177], off
	v_lshl_add_u64 v[176:177], v[220:221], 0, s[10:11]
	s_mov_b32 m0, s49
	s_nop 0
	global_load_lds_dwordx4 v[176:177], off
	v_lshl_add_u64 v[176:177], v[222:223], 0, s[10:11]
	s_mov_b32 m0, s50
	s_nop 0
	global_load_lds_dwordx4 v[176:177], off
	s_waitcnt vmcnt(8)
	s_waitcnt lgkmcnt(0)
	s_barrier
	s_setprio 1
	s_waitcnt lgkmcnt(0)
	v_mfma_f32_16x16x32_bf16 v[60:63], v[128:131], v[184:187], v[60:63]
	v_mfma_f32_16x16x32_bf16 v[56:59], v[136:139], v[184:187], v[56:59]
	v_mfma_f32_16x16x32_bf16 v[44:47], v[128:131], v[194:197], v[44:47]
	v_mfma_f32_16x16x32_bf16 v[40:43], v[136:139], v[194:197], v[40:43]
	v_mfma_f32_16x16x32_bf16 v[28:31], v[128:131], v[202:205], v[28:31]
	v_mfma_f32_16x16x32_bf16 v[24:27], v[136:139], v[202:205], v[24:27]
	v_mfma_f32_16x16x32_bf16 v[12:15], v[128:131], v[210:213], v[12:15]
	v_mfma_f32_16x16x32_bf16 v[8:11], v[136:139], v[210:213], v[8:11]
	v_mfma_f32_16x16x32_bf16 v[60:63], v[132:135], v[190:193], v[60:63]
	v_mfma_f32_16x16x32_bf16 v[56:59], v[140:143], v[190:193], v[56:59]
	v_mfma_f32_16x16x32_bf16 v[44:47], v[132:135], v[198:201], v[44:47]
	v_mfma_f32_16x16x32_bf16 v[40:43], v[140:143], v[198:201], v[40:43]
	v_mfma_f32_16x16x32_bf16 v[28:31], v[132:135], v[206:209], v[28:31]
	v_mfma_f32_16x16x32_bf16 v[24:27], v[140:143], v[206:209], v[24:27]
	v_mfma_f32_16x16x32_bf16 v[12:15], v[132:135], v[214:217], v[12:15]
	v_mfma_f32_16x16x32_bf16 v[8:11], v[140:143], v[214:217], v[8:11]
	s_setprio 0
	s_setprio 1
	v_mfma_f32_16x16x32_bf16 v[52:55], v[144:147], v[184:187], v[52:55]
	v_mfma_f32_16x16x32_bf16 v[48:51], v[168:171], v[184:187], v[48:51]
	v_mfma_f32_16x16x32_bf16 v[36:39], v[144:147], v[194:197], v[36:39]
	v_mfma_f32_16x16x32_bf16 v[32:35], v[168:171], v[194:197], v[32:35]
	v_mfma_f32_16x16x32_bf16 v[20:23], v[144:147], v[202:205], v[20:23]
	v_mfma_f32_16x16x32_bf16 v[16:19], v[168:171], v[202:205], v[16:19]
	v_mfma_f32_16x16x32_bf16 v[4:7], v[144:147], v[210:213], v[4:7]
	v_mfma_f32_16x16x32_bf16 v[0:3], v[168:171], v[210:213], v[0:3]
	v_mfma_f32_16x16x32_bf16 v[52:55], v[148:151], v[190:193], v[52:55]
	v_mfma_f32_16x16x32_bf16 v[48:51], v[172:175], v[190:193], v[48:51]
	v_mfma_f32_16x16x32_bf16 v[36:39], v[148:151], v[198:201], v[36:39]
	v_mfma_f32_16x16x32_bf16 v[32:35], v[172:175], v[198:201], v[32:35]
	v_mfma_f32_16x16x32_bf16 v[20:23], v[148:151], v[206:209], v[20:23]
	v_mfma_f32_16x16x32_bf16 v[16:19], v[172:175], v[206:209], v[16:19]
	v_mfma_f32_16x16x32_bf16 v[4:7], v[148:151], v[214:217], v[4:7]
	v_mfma_f32_16x16x32_bf16 v[0:3], v[172:175], v[214:217], v[0:3]
	s_setprio 0
	s_barrier
	s_add_i32 s58, s58, 2
	s_add_u32 s42, s42, 0x100
	s_addc_u32 s43, s43, 0
	s_add_u32 s56, s56, 0x100
	s_addc_u32 s57, s57, 0
	s_cmp_gt_u32 s58, 5
	s_cbranch_scc0 .LBB0_1105
	s_and_b64 vcc, exec, s[14:15]
	s_cbranch_vccz .LBB0_1108
	s_barrier

.LBB0_1144:
	s_andn2_saveexec_b64 s[8:9], s[8:9]
	s_cbranch_execz .LBB0_1164
	s_mov_b64 s[8:9], exec
	s_cmp_lg_u32 s98, 0
	s_cbranch_scc1 .LBB0_1161
	buffer_wbl2 sc1
	s_waitcnt lgkmcnt(0)
	s_waitcnt vmcnt(0)
	v_mbcnt_lo_u32_b32 v1, s8, 0
	v_mbcnt_hi_u32_b32 v1, s9, v1
	v_cmp_eq_u32_e32 vcc, 0, v1
	s_and_saveexec_b64 s[10:11], vcc
	s_cbranch_execz .LBB0_1147
	s_bcnt1_i32_b64 s3, s[8:9]
	v_mov_b32_e32 v2, 0x5c3000
	v_mov_b32_e32 v3, s3
	global_atomic_add v2, v2, v3, s[72:73] offset:1024 sc0

.LBB0_1181:
	ds_read_b128 v[152:155], v149
	ds_read_b128 v[156:159], v149 offset:1024
	ds_read_b128 v[160:163], v149 offset:2048
	ds_read_b128 v[164:167], v149 offset:3072
	ds_read_b128 v[168:171], v150
	ds_read_b128 v[172:175], v150 offset:1024
	ds_read_b128 v[176:179], v150 offset:2048
	ds_read_b128 v[180:183], v150 offset:3072
	s_add_u32 s28, s48, 0xfffc0080
	s_addc_u32 s29, s49, -1
	s_cmp_eq_u32 s76, 12
	s_cselect_b32 s53, s41, s29
	s_cselect_b32 s52, s64, s28
	s_cselect_b32 s51, s39, s67
	s_cselect_b32 s50, s65, s66
	v_lshl_add_u64 v[144:145], s[48:49], 0, v[136:137]
	s_add_i32 m0, s27, 0xc000
	ds_read_b128 v[184:187], v151
	ds_read_b128 v[190:193], v151 offset:1024
	ds_read_b128 v[194:197], v151 offset:2048
	ds_read_b128 v[198:201], v151 offset:3072
	ds_read_b128 v[202:205], v151 offset:4096
	ds_read_b128 v[206:209], v151 offset:5120
	ds_read_b128 v[210:213], v151 offset:6144
	ds_read_b128 v[214:217], v151 offset:7168
	global_load_lds_dwordx4 v[144:145], off
	v_lshl_add_u64 v[144:145], s[48:49], 0, v[138:139]
	s_add_i32 m0, s27, 0xe000
	s_nop 0
	global_load_lds_dwordx4 v[144:145], off
	s_waitcnt vmcnt(8)
	s_waitcnt lgkmcnt(0)
	s_barrier
	s_setprio 1
	s_waitcnt lgkmcnt(0)
	v_mfma_f32_16x16x32_bf16 v[124:127], v[152:155], v[184:187], v[124:127]
	v_mfma_f32_16x16x32_bf16 v[120:123], v[160:163], v[184:187], v[120:123]
	v_mfma_f32_16x16x32_bf16 v[116:119], v[152:155], v[194:197], v[116:119]
	v_mfma_f32_16x16x32_bf16 v[108:111], v[160:163], v[194:197], v[108:111]
	v_mfma_f32_16x16x32_bf16 v[100:103], v[152:155], v[202:205], v[100:103]
	v_mfma_f32_16x16x32_bf16 v[92:95], v[160:163], v[202:205], v[92:95]
	v_mfma_f32_16x16x32_bf16 v[84:87], v[152:155], v[210:213], v[84:87]
	v_mfma_f32_16x16x32_bf16 v[76:79], v[160:163], v[210:213], v[76:79]
	v_mfma_f32_16x16x32_bf16 v[124:127], v[156:159], v[190:193], v[124:127]
	v_mfma_f32_16x16x32_bf16 v[120:123], v[164:167], v[190:193], v[120:123]
	v_mfma_f32_16x16x32_bf16 v[116:119], v[156:159], v[198:201], v[116:119]
	v_mfma_f32_16x16x32_bf16 v[108:111], v[164:167], v[198:201], v[108:111]
	v_mfma_f32_16x16x32_bf16 v[100:103], v[156:159], v[206:209], v[100:103]
	v_mfma_f32_16x16x32_bf16 v[92:95], v[164:167], v[206:209], v[92:95]
	v_mfma_f32_16x16x32_bf16 v[84:87], v[156:159], v[214:217], v[84:87]
	v_mfma_f32_16x16x32_bf16 v[76:79], v[164:167], v[214:217], v[76:79]
	s_setprio 0
	s_setprio 1
	v_mfma_f32_16x16x32_bf16 v[112:115], v[168:171], v[184:187], v[112:115]
	v_mfma_f32_16x16x32_bf16 v[104:107], v[176:179], v[184:187], v[104:107]
	v_mfma_f32_16x16x32_bf16 v[96:99], v[168:171], v[194:197], v[96:99]
	v_mfma_f32_16x16x32_bf16 v[88:91], v[176:179], v[194:197], v[88:91]
	v_mfma_f32_16x16x32_bf16 v[80:83], v[168:171], v[202:205], v[80:83]
	v_mfma_f32_16x16x32_bf16 v[72:75], v[176:179], v[202:205], v[72:75]
	v_mfma_f32_16x16x32_bf16 v[68:71], v[168:171], v[210:213], v[68:71]
	v_mfma_f32_16x16x32_bf16 v[64:67], v[176:179], v[210:213], v[64:67]
	v_mfma_f32_16x16x32_bf16 v[112:115], v[172:175], v[190:193], v[112:115]
	v_mfma_f32_16x16x32_bf16 v[104:107], v[180:183], v[190:193], v[104:107]
	v_mfma_f32_16x16x32_bf16 v[96:99], v[172:175], v[198:201], v[96:99]
	v_mfma_f32_16x16x32_bf16 v[88:91], v[180:183], v[198:201], v[88:91]
	v_mfma_f32_16x16x32_bf16 v[80:83], v[172:175], v[206:209], v[80:83]
	v_mfma_f32_16x16x32_bf16 v[72:75], v[180:183], v[206:209], v[72:75]
	v_mfma_f32_16x16x32_bf16 v[68:71], v[172:175], v[214:217], v[68:71]
	v_mfma_f32_16x16x32_bf16 v[64:67], v[180:183], v[214:217], v[64:67]
	s_setprio 0
	s_barrier
	s_add_i32 s28, s57, s13
	v_lshl_add_u64 v[144:145], s[50:51], 0, v[130:131]
	s_mov_b32 m0, s28
	ds_read_b128 v[184:187], v151 offset:16384
	ds_read_b128 v[190:193], v151 offset:17408
	ds_read_b128 v[194:197], v151 offset:18432
	ds_read_b128 v[198:201], v151 offset:19456
	ds_read_b128 v[202:205], v151 offset:20480
	ds_read_b128 v[206:209], v151 offset:21504
	ds_read_b128 v[210:213], v151 offset:22528
	ds_read_b128 v[214:217], v151 offset:23552
	global_load_lds_dwordx4 v[144:145], off
	s_add_i32 m0, s28, 0x2000
	s_add_u32 s28, s50, 0x40000
	v_lshl_add_u64 v[218:219], s[50:51], 0, v[134:135]
	s_addc_u32 s29, s51, 0
	s_add_i32 s33, s58, s13
	global_load_lds_dwordx4 v[218:219], off
	v_lshl_add_u64 v[220:221], s[28:29], 0, v[130:131]
	s_mov_b32 m0, s33
	v_lshl_add_u64 v[222:223], s[52:53], 0, v[132:133]
	global_load_lds_dwordx4 v[220:221], off
	v_lshl_add_u64 v[220:221], s[28:29], 0, v[134:135]
	s_add_i32 m0, s33, 0x2000
	s_nop 0
	global_load_lds_dwordx4 v[220:221], off
	v_lshl_add_u64 v[220:221], s[52:53], 0, v[128:129]
	s_mov_b32 m0, s27
	s_nop 0
	global_load_lds_dwordx4 v[220:221], off
	s_mov_b32 m0, s34
	s_nop 0
	global_load_lds_dwordx4 v[222:223], off
	s_waitcnt vmcnt(8)
	s_waitcnt lgkmcnt(0)
	s_nop 0
	s_barrier
	s_setprio 1
	s_waitcnt lgkmcnt(0)
	v_mfma_f32_16x16x32_bf16 v[60:63], v[152:155], v[184:187], v[60:63]
	v_mfma_f32_16x16x32_bf16 v[56:59], v[160:163], v[184:187], v[56:59]
	v_mfma_f32_16x16x32_bf16 v[52:55], v[152:155], v[194:197], v[52:55]
	v_mfma_f32_16x16x32_bf16 v[44:47], v[160:163], v[194:197], v[44:47]
	v_mfma_f32_16x16x32_bf16 v[36:39], v[152:155], v[202:205], v[36:39]
	v_mfma_f32_16x16x32_bf16 v[28:31], v[160:163], v[202:205], v[28:31]
	v_mfma_f32_16x16x32_bf16 v[20:23], v[152:155], v[210:213], v[20:23]
	v_mfma_f32_16x16x32_bf16 v[12:15], v[160:163], v[210:213], v[12:15]
	v_mfma_f32_16x16x32_bf16 v[60:63], v[156:159], v[190:193], v[60:63]
	v_mfma_f32_16x16x32_bf16 v[56:59], v[164:167], v[190:193], v[56:59]
	v_mfma_f32_16x16x32_bf16 v[52:55], v[156:159], v[198:201], v[52:55]
	v_mfma_f32_16x16x32_bf16 v[44:47], v[164:167], v[198:201], v[44:47]
	v_mfma_f32_16x16x32_bf16 v[36:39], v[156:159], v[206:209], v[36:39]
	v_mfma_f32_16x16x32_bf16 v[28:31], v[164:167], v[206:209], v[28:31]
	v_mfma_f32_16x16x32_bf16 v[20:23], v[156:159], v[214:217], v[20:23]
	v_mfma_f32_16x16x32_bf16 v[12:15], v[164:167], v[214:217], v[12:15]
	s_setprio 0
	s_setprio 1
	v_mfma_f32_16x16x32_bf16 v[48:51], v[168:171], v[184:187], v[48:51]
	v_mfma_f32_16x16x32_bf16 v[40:43], v[176:179], v[184:187], v[40:43]
	v_mfma_f32_16x16x32_bf16 v[32:35], v[168:171], v[194:197], v[32:35]
	v_mfma_f32_16x16x32_bf16 v[24:27], v[176:179], v[194:197], v[24:27]
	v_mfma_f32_16x16x32_bf16 v[16:19], v[168:171], v[202:205], v[16:19]
	v_mfma_f32_16x16x32_bf16 v[8:11], v[176:179], v[202:205], v[8:11]
	v_mfma_f32_16x16x32_bf16 v[4:7], v[168:171], v[210:213], v[4:7]
	v_mfma_f32_16x16x32_bf16 v[0:3], v[176:179], v[210:213], v[0:3]
	v_mfma_f32_16x16x32_bf16 v[48:51], v[172:175], v[190:193], v[48:51]
	v_mfma_f32_16x16x32_bf16 v[40:43], v[180:183], v[190:193], v[40:43]
	v_mfma_f32_16x16x32_bf16 v[32:35], v[172:175], v[198:201], v[32:35]
	v_mfma_f32_16x16x32_bf16 v[24:27], v[180:183], v[198:201], v[24:27]
	v_mfma_f32_16x16x32_bf16 v[16:19], v[172:175], v[206:209], v[16:19]
	v_mfma_f32_16x16x32_bf16 v[8:11], v[180:183], v[206:209], v[8:11]
	v_mfma_f32_16x16x32_bf16 v[4:7], v[172:175], v[214:217], v[4:7]
	v_mfma_f32_16x16x32_bf16 v[0:3], v[180:183], v[214:217], v[0:3]
	s_setprio 0
	s_barrier
	s_add_i32 s33, 0, 0x18000
	s_add_i32 s77, 0, 0x1c000
	v_add_u32_e32 v164, s33, v147
	v_add_u32_e32 v180, s77, v147
	ds_read_b128 v[152:155], v164
	ds_read_b128 v[156:159], v164 offset:1024
	ds_read_b128 v[160:163], v164 offset:2048
	ds_read_b128 v[164:167], v164 offset:3072
	ds_read_b128 v[168:171], v180
	ds_read_b128 v[172:175], v180 offset:1024
	ds_read_b128 v[176:179], v180 offset:2048
	ds_read_b128 v[180:183], v180 offset:3072
	s_add_u32 s28, s52, 0x40000
	s_addc_u32 s29, s53, 0
	s_mov_b32 m0, s35
	v_lshl_add_u64 v[224:225], s[28:29], 0, v[128:129]
	ds_read_b128 v[184:187], v151 offset:32768
	ds_read_b128 v[190:193], v151 offset:33792
	ds_read_b128 v[194:197], v151 offset:34816
	ds_read_b128 v[198:201], v151 offset:35840
	ds_read_b128 v[202:205], v151 offset:36864
	ds_read_b128 v[206:209], v151 offset:37888
	ds_read_b128 v[210:213], v151 offset:38912
	ds_read_b128 v[214:217], v151 offset:39936
	global_load_lds_dwordx4 v[224:225], off
	v_lshl_add_u64 v[224:225], s[28:29], 0, v[132:133]
	s_mov_b32 m0, s47
	s_nop 0
	global_load_lds_dwordx4 v[224:225], off
	s_waitcnt vmcnt(8)
	s_waitcnt lgkmcnt(0)
	s_nop 0
	s_barrier
	s_setprio 1
	s_waitcnt lgkmcnt(0)
	v_mfma_f32_16x16x32_bf16 v[124:127], v[152:155], v[184:187], v[124:127]
	v_mfma_f32_16x16x32_bf16 v[120:123], v[160:163], v[184:187], v[120:123]
	v_mfma_f32_16x16x32_bf16 v[116:119], v[152:155], v[194:197], v[116:119]
	v_mfma_f32_16x16x32_bf16 v[108:111], v[160:163], v[194:197], v[108:111]
	v_mfma_f32_16x16x32_bf16 v[100:103], v[152:155], v[202:205], v[100:103]
	v_mfma_f32_16x16x32_bf16 v[92:95], v[160:163], v[202:205], v[92:95]
	v_mfma_f32_16x16x32_bf16 v[84:87], v[152:155], v[210:213], v[84:87]
	v_mfma_f32_16x16x32_bf16 v[76:79], v[160:163], v[210:213], v[76:79]
	v_mfma_f32_16x16x32_bf16 v[124:127], v[156:159], v[190:193], v[124:127]
	v_mfma_f32_16x16x32_bf16 v[120:123], v[164:167], v[190:193], v[120:123]
	v_mfma_f32_16x16x32_bf16 v[116:119], v[156:159], v[198:201], v[116:119]
	v_mfma_f32_16x16x32_bf16 v[108:111], v[164:167], v[198:201], v[108:111]
	v_mfma_f32_16x16x32_bf16 v[100:103], v[156:159], v[206:209], v[100:103]
	v_mfma_f32_16x16x32_bf16 v[92:95], v[164:167], v[206:209], v[92:95]
	v_mfma_f32_16x16x32_bf16 v[84:87], v[156:159], v[214:217], v[84:87]
	v_mfma_f32_16x16x32_bf16 v[76:79], v[164:167], v[214:217], v[76:79]
	s_setprio 0
	s_setprio 1
	v_mfma_f32_16x16x32_bf16 v[112:115], v[168:171], v[184:187], v[112:115]
	v_mfma_f32_16x16x32_bf16 v[104:107], v[176:179], v[184:187], v[104:107]
	v_mfma_f32_16x16x32_bf16 v[96:99], v[168:171], v[194:197], v[96:99]
	v_mfma_f32_16x16x32_bf16 v[88:91], v[176:179], v[194:197], v[88:91]
	v_mfma_f32_16x16x32_bf16 v[80:83], v[168:171], v[202:205], v[80:83]
	v_mfma_f32_16x16x32_bf16 v[72:75], v[176:179], v[202:205], v[72:75]
	v_mfma_f32_16x16x32_bf16 v[68:71], v[168:171], v[210:213], v[68:71]
	v_mfma_f32_16x16x32_bf16 v[64:67], v[176:179], v[210:213], v[64:67]
	v_mfma_f32_16x16x32_bf16 v[112:115], v[172:175], v[190:193], v[112:115]
	v_mfma_f32_16x16x32_bf16 v[104:107], v[180:183], v[190:193], v[104:107]
	v_mfma_f32_16x16x32_bf16 v[96:99], v[172:175], v[198:201], v[96:99]
	v_mfma_f32_16x16x32_bf16 v[88:91], v[180:183], v[198:201], v[88:91]
	v_mfma_f32_16x16x32_bf16 v[80:83], v[172:175], v[206:209], v[80:83]
	v_mfma_f32_16x16x32_bf16 v[72:75], v[180:183], v[206:209], v[72:75]
	v_mfma_f32_16x16x32_bf16 v[68:71], v[172:175], v[214:217], v[68:71]
	v_mfma_f32_16x16x32_bf16 v[64:67], v[180:183], v[214:217], v[64:67]
	s_setprio 0
	s_barrier
	s_add_i32 s28, s33, s13
	v_lshl_add_u64 v[144:145], v[144:145], 0, s[10:11]
	s_mov_b32 m0, s28
	ds_read_b128 v[184:187], v151 offset:49152
	ds_read_b128 v[190:193], v151 offset:50176
	ds_read_b128 v[194:197], v151 offset:51200
	ds_read_b128 v[198:201], v151 offset:52224
	ds_read_b128 v[202:205], v151 offset:53248
	ds_read_b128 v[206:209], v151 offset:54272
	ds_read_b128 v[210:213], v151 offset:55296
	ds_read_b128 v[214:217], v151 offset:56320
	global_load_lds_dwordx4 v[144:145], off
	s_add_i32 m0, s28, 0x2000
	s_add_u32 s28, s50, 0x40080
	v_lshl_add_u64 v[144:145], v[218:219], 0, s[10:11]
	s_addc_u32 s29, s51, 0
	s_add_i32 s33, s77, s13
	global_load_lds_dwordx4 v[144:145], off
	v_lshl_add_u64 v[144:145], s[28:29], 0, v[130:131]
	s_mov_b32 m0, s33
	s_nop 0
	global_load_lds_dwordx4 v[144:145], off
	v_lshl_add_u64 v[144:145], s[28:29], 0, v[134:135]
	s_add_i32 m0, s33, 0x2000
	s_nop 0
	global_load_lds_dwordx4 v[144:145], off
	v_lshl_add_u64 v[144:145], v[220:221], 0, s[10:11]
	s_mov_b32 m0, s55
	s_nop 0
	global_load_lds_dwordx4 v[144:145], off
	v_lshl_add_u64 v[144:145], v[222:223], 0, s[10:11]
	s_mov_b32 m0, s56
	s_nop 0
	global_load_lds_dwordx4 v[144:145], off
	s_waitcnt vmcnt(8)
	s_waitcnt lgkmcnt(0)
	s_barrier
	s_setprio 1
	s_waitcnt lgkmcnt(0)
	v_mfma_f32_16x16x32_bf16 v[60:63], v[152:155], v[184:187], v[60:63]
	v_mfma_f32_16x16x32_bf16 v[56:59], v[160:163], v[184:187], v[56:59]
	v_mfma_f32_16x16x32_bf16 v[52:55], v[152:155], v[194:197], v[52:55]
	v_mfma_f32_16x16x32_bf16 v[44:47], v[160:163], v[194:197], v[44:47]
	v_mfma_f32_16x16x32_bf16 v[36:39], v[152:155], v[202:205], v[36:39]
	v_mfma_f32_16x16x32_bf16 v[28:31], v[160:163], v[202:205], v[28:31]
	v_mfma_f32_16x16x32_bf16 v[20:23], v[152:155], v[210:213], v[20:23]
	v_mfma_f32_16x16x32_bf16 v[12:15], v[160:163], v[210:213], v[12:15]
	v_mfma_f32_16x16x32_bf16 v[60:63], v[156:159], v[190:193], v[60:63]
	v_mfma_f32_16x16x32_bf16 v[56:59], v[164:167], v[190:193], v[56:59]
	v_mfma_f32_16x16x32_bf16 v[52:55], v[156:159], v[198:201], v[52:55]
	v_mfma_f32_16x16x32_bf16 v[44:47], v[164:167], v[198:201], v[44:47]
	v_mfma_f32_16x16x32_bf16 v[36:39], v[156:159], v[206:209], v[36:39]
	v_mfma_f32_16x16x32_bf16 v[28:31], v[164:167], v[206:209], v[28:31]
	v_mfma_f32_16x16x32_bf16 v[20:23], v[156:159], v[214:217], v[20:23]
	v_mfma_f32_16x16x32_bf16 v[12:15], v[164:167], v[214:217], v[12:15]
	s_setprio 0
	s_setprio 1
	v_mfma_f32_16x16x32_bf16 v[48:51], v[168:171], v[184:187], v[48:51]
	v_mfma_f32_16x16x32_bf16 v[40:43], v[176:179], v[184:187], v[40:43]
	v_mfma_f32_16x16x32_bf16 v[32:35], v[168:171], v[194:197], v[32:35]
	v_mfma_f32_16x16x32_bf16 v[24:27], v[176:179], v[194:197], v[24:27]
	v_mfma_f32_16x16x32_bf16 v[16:19], v[168:171], v[202:205], v[16:19]
	v_mfma_f32_16x16x32_bf16 v[8:11], v[176:179], v[202:205], v[8:11]
	v_mfma_f32_16x16x32_bf16 v[4:7], v[168:171], v[210:213], v[4:7]
	v_mfma_f32_16x16x32_bf16 v[0:3], v[176:179], v[210:213], v[0:3]
	v_mfma_f32_16x16x32_bf16 v[48:51], v[172:175], v[190:193], v[48:51]
	v_mfma_f32_16x16x32_bf16 v[40:43], v[180:183], v[190:193], v[40:43]
	v_mfma_f32_16x16x32_bf16 v[32:35], v[172:175], v[198:201], v[32:35]
	v_mfma_f32_16x16x32_bf16 v[24:27], v[180:183], v[198:201], v[24:27]
	v_mfma_f32_16x16x32_bf16 v[16:19], v[172:175], v[206:209], v[16:19]
	v_mfma_f32_16x16x32_bf16 v[8:11], v[180:183], v[206:209], v[8:11]
	v_mfma_f32_16x16x32_bf16 v[4:7], v[172:175], v[214:217], v[4:7]
	v_mfma_f32_16x16x32_bf16 v[0:3], v[180:183], v[214:217], v[0:3]
	s_setprio 0
	s_barrier
	s_add_i32 s76, s76, 2
	s_add_u32 s48, s48, 0x100
	s_addc_u32 s49, s49, 0
	s_add_u32 s66, s66, 0x100
	s_addc_u32 s67, s67, 0
	s_cmp_gt_u32 s76, 13
	s_cbranch_scc0 .LBB0_1181
	s_and_b64 vcc, exec, s[14:15]
	s_cbranch_vccz .LBB0_1184
	s_barrier

.LBB0_1302:
	s_lshl_b32 s8, s8, 5
	s_and_b32 s14, s8, 0x60
	s_mov_b64 s[8:9], 0x80
	s_add_i32 m0, s34, 0x18000
	v_lshl_add_u64 v[6:7], v[6:7], 0, s[8:9]
	s_lshl_b32 s11, s10, 13
	s_lshl_b32 s18, s14, 7
	s_waitcnt vmcnt(2)
	s_barrier
	global_load_lds_dwordx4 v[6:7], off
	v_lshl_add_u64 v[4:5], v[4:5], 0, s[8:9]
	s_add_i32 m0, s34, 0x1a000
	s_add_i32 s46, s34, 0x8000
	s_add_i32 s47, s34, 0xa000
	global_load_lds_dwordx4 v[4:5], off
	v_lshl_add_u64 v[0:1], v[0:1], 0, s[8:9]
	s_mov_b32 m0, s46
	s_add_u32 s16, s40, 0x40080
	global_load_lds_dwordx4 v[0:1], off
	v_lshl_add_u64 v[0:1], v[2:3], 0, s[8:9]
	s_mov_b32 m0, s47
	s_addc_u32 s17, s41, 0
	global_load_lds_dwordx4 v[0:1], off
	s_add_i32 m0, s34, 0x1c000
	v_lshl_add_u64 v[0:1], s[16:17], 0, v[132:133]
	global_load_lds_dwordx4 v[0:1], off
	v_lshl_add_u64 v[0:1], s[16:17], 0, v[128:129]
	s_add_i32 m0, s34, 0x1e000
	s_cmpk_lt_u32 s1, 0x100
	global_load_lds_dwordx4 v[0:1], off
	v_lshrrev_b32_e32 v1, 1, v8
	v_and_b32_e32 v1, 24, v1
	v_and_b32_e32 v0, 15, v8
	v_lshlrev_b32_e32 v2, 1, v1
	v_lshl_or_b32 v144, s10, 6, v0
	v_lshl_or_b32 v0, v0, 6, v2
	v_lshlrev_b32_e32 v2, 2, v8
	v_and_b32_e32 v2, 32, v2
	v_bitop3_b32 v3, v0, s11, v2 bitop3:0xde
	v_bitop3_b32 v145, v0, s18, v2 bitop3:0xde
	v_lshlrev_b32_e32 v0, 14, v13
	v_and_b32_e32 v0, 0xffff8000, v0
	v_or_b32_e32 v146, s14, v1
	v_and_b32_e32 v227, 64, v146
	v_and_b32_e32 v146, 63, v146
	v_lshlrev_b32_e32 v146, 1, v146
	v_lshl_or_b32 v146, v227, 9, v146
	v_lshl_add_u32 v0, v12, 11, v0
	v_and_b32_e32 v1, 1, v13
	v_lshl_or_b32 v0, v1, 6, v0
	v_lshl_add_u32 v136, v14, 1, v0
	v_lshlrev_b32_e32 v0, 14, v9
	v_and_b32_e32 v0, 0xffff8000, v0
	s_waitcnt vmcnt(6)
	v_lshl_add_u32 v0, v10, 11, v0
	v_and_b32_e32 v1, 1, v9
	s_cselect_b64 s[10:11], -1, 0
	v_lshl_or_b32 v0, v1, 6, v0
	s_add_i32 s48, 0, 0x10000
	s_add_i32 s49, 0, 0x14000
	s_sext_i32_i16 s51, s0
	v_mov_b32_e32 v137, v133
	v_lshl_add_u32 v138, v11, 1, v0
	v_mov_b32_e32 v139, v133
	v_mov_b64_e32 v[140:141], 0xb00
	v_mov_b64_e32 v[142:143], 0xaff
	v_add_u32_e32 v147, s48, v145
	v_add_u32_e32 v148, s49, v145
	v_add_u32_e32 v149, 0, v3
	s_mov_b32 s14, 0xbfb8aa3b
	s_movk_i32 s50, 0x80
	s_barrier
	s_waitcnt vmcnt(0)
	s_branch .LBB0_1305

.LBB0_1308:
	ds_read_b128 v[150:153], v147
	ds_read_b128 v[154:157], v147 offset:1024
	ds_read_b128 v[158:161], v147 offset:2048
	ds_read_b128 v[162:165], v147 offset:3072
	ds_read_b128 v[166:169], v148
	ds_read_b128 v[170:173], v148 offset:1024
	ds_read_b128 v[174:177], v148 offset:2048
	ds_read_b128 v[178:181], v148 offset:3072
	s_add_u32 s33, s38, 0xfffc0080
	s_addc_u32 s40, s39, -1
	s_cmp_eq_u32 s56, 12
	s_cselect_b32 s43, s19, s40
	s_cselect_b32 s42, s52, s33
	s_cselect_b32 s41, s17, s55
	s_cselect_b32 s40, s53, s54
	v_lshl_add_u64 v[186:187], s[38:39], 0, v[136:137]
	s_add_i32 m0, s34, 0xc000
	ds_read_b128 v[182:185], v149
	ds_read_b128 v[190:193], v149 offset:1024
	ds_read_b128 v[194:197], v149 offset:2048
	ds_read_b128 v[198:201], v149 offset:3072
	ds_read_b128 v[202:205], v149 offset:4096
	ds_read_b128 v[206:209], v149 offset:5120
	ds_read_b128 v[210:213], v149 offset:6144
	ds_read_b128 v[214:217], v149 offset:7168
	global_load_lds_dwordx4 v[186:187], off
	v_lshl_add_u64 v[186:187], s[38:39], 0, v[138:139]
	s_add_i32 m0, s34, 0xe000
	s_nop 0
	global_load_lds_dwordx4 v[186:187], off
	s_waitcnt vmcnt(8)
	s_waitcnt lgkmcnt(0)
	s_barrier
	s_setprio 1
	s_waitcnt lgkmcnt(0)
	v_mfma_f32_16x16x32_bf16 v[124:127], v[150:153], v[182:185], v[124:127]
	v_mfma_f32_16x16x32_bf16 v[116:119], v[158:161], v[182:185], v[116:119]
	v_mfma_f32_16x16x32_bf16 v[108:111], v[150:153], v[194:197], v[108:111]
	v_mfma_f32_16x16x32_bf16 v[100:103], v[158:161], v[194:197], v[100:103]
	v_mfma_f32_16x16x32_bf16 v[92:95], v[150:153], v[202:205], v[92:95]
	v_mfma_f32_16x16x32_bf16 v[84:87], v[158:161], v[202:205], v[84:87]
	v_mfma_f32_16x16x32_bf16 v[76:79], v[150:153], v[210:213], v[76:79]
	v_mfma_f32_16x16x32_bf16 v[68:71], v[158:161], v[210:213], v[68:71]
	v_mfma_f32_16x16x32_bf16 v[124:127], v[154:157], v[190:193], v[124:127]
	v_mfma_f32_16x16x32_bf16 v[116:119], v[162:165], v[190:193], v[116:119]
	v_mfma_f32_16x16x32_bf16 v[108:111], v[154:157], v[198:201], v[108:111]
	v_mfma_f32_16x16x32_bf16 v[100:103], v[162:165], v[198:201], v[100:103]
	v_mfma_f32_16x16x32_bf16 v[92:95], v[154:157], v[206:209], v[92:95]
	v_mfma_f32_16x16x32_bf16 v[84:87], v[162:165], v[206:209], v[84:87]
	v_mfma_f32_16x16x32_bf16 v[76:79], v[154:157], v[214:217], v[76:79]
	v_mfma_f32_16x16x32_bf16 v[68:71], v[162:165], v[214:217], v[68:71]
	s_setprio 0
	s_setprio 1
	v_mfma_f32_16x16x32_bf16 v[120:123], v[166:169], v[182:185], v[120:123]
	v_mfma_f32_16x16x32_bf16 v[112:115], v[174:177], v[182:185], v[112:115]
	v_mfma_f32_16x16x32_bf16 v[104:107], v[166:169], v[194:197], v[104:107]
	v_mfma_f32_16x16x32_bf16 v[96:99], v[174:177], v[194:197], v[96:99]
	v_mfma_f32_16x16x32_bf16 v[88:91], v[166:169], v[202:205], v[88:91]
	v_mfma_f32_16x16x32_bf16 v[80:83], v[174:177], v[202:205], v[80:83]
	v_mfma_f32_16x16x32_bf16 v[72:75], v[166:169], v[210:213], v[72:75]
	v_mfma_f32_16x16x32_bf16 v[64:67], v[174:177], v[210:213], v[64:67]
	v_mfma_f32_16x16x32_bf16 v[120:123], v[170:173], v[190:193], v[120:123]
	v_mfma_f32_16x16x32_bf16 v[112:115], v[178:181], v[190:193], v[112:115]
	v_mfma_f32_16x16x32_bf16 v[104:107], v[170:173], v[198:201], v[104:107]
	v_mfma_f32_16x16x32_bf16 v[96:99], v[178:181], v[198:201], v[96:99]
	v_mfma_f32_16x16x32_bf16 v[88:91], v[170:173], v[206:209], v[88:91]
	v_mfma_f32_16x16x32_bf16 v[80:83], v[178:181], v[206:209], v[80:83]
	v_mfma_f32_16x16x32_bf16 v[72:75], v[170:173], v[214:217], v[72:75]
	v_mfma_f32_16x16x32_bf16 v[64:67], v[178:181], v[214:217], v[64:67]
	s_setprio 0
	s_barrier
	s_add_i32 s33, s48, s13
	v_lshl_add_u64 v[186:187], s[40:41], 0, v[132:133]
	s_mov_b32 m0, s33
	ds_read_b128 v[182:185], v149 offset:16384
	ds_read_b128 v[190:193], v149 offset:17408
	ds_read_b128 v[194:197], v149 offset:18432
	ds_read_b128 v[198:201], v149 offset:19456
	ds_read_b128 v[202:205], v149 offset:20480
	ds_read_b128 v[206:209], v149 offset:21504
	ds_read_b128 v[210:213], v149 offset:22528
	ds_read_b128 v[214:217], v149 offset:23552
	global_load_lds_dwordx4 v[186:187], off
	s_add_i32 m0, s33, 0x2000
	s_add_u32 s58, s40, 0x40000
	v_lshl_add_u64 v[218:219], s[40:41], 0, v[128:129]
	s_addc_u32 s59, s41, 0
	s_add_i32 s33, s49, s13
	global_load_lds_dwordx4 v[218:219], off
	v_lshl_add_u64 v[220:221], s[58:59], 0, v[132:133]
	s_mov_b32 m0, s33
	v_lshl_add_u64 v[222:223], s[42:43], 0, v[130:131]
	global_load_lds_dwordx4 v[220:221], off
	v_lshl_add_u64 v[220:221], s[58:59], 0, v[128:129]
	s_add_i32 m0, s33, 0x2000
	s_nop 0
	global_load_lds_dwordx4 v[220:221], off
	v_lshl_add_u64 v[220:221], s[42:43], 0, v[134:135]
	s_mov_b32 m0, s34
	s_nop 0
	global_load_lds_dwordx4 v[220:221], off
	s_mov_b32 m0, s35
	s_nop 0
	global_load_lds_dwordx4 v[222:223], off
	s_waitcnt vmcnt(8)
	s_waitcnt lgkmcnt(0)
	s_nop 0
	s_barrier
	s_setprio 1
	s_waitcnt lgkmcnt(0)
	v_mfma_f32_16x16x32_bf16 v[60:63], v[150:153], v[182:185], v[60:63]
	v_mfma_f32_16x16x32_bf16 v[52:55], v[158:161], v[182:185], v[52:55]
	v_mfma_f32_16x16x32_bf16 v[44:47], v[150:153], v[194:197], v[44:47]
	v_mfma_f32_16x16x32_bf16 v[36:39], v[158:161], v[194:197], v[36:39]
	v_mfma_f32_16x16x32_bf16 v[28:31], v[150:153], v[202:205], v[28:31]
	v_mfma_f32_16x16x32_bf16 v[20:23], v[158:161], v[202:205], v[20:23]
	v_mfma_f32_16x16x32_bf16 v[12:15], v[150:153], v[210:213], v[12:15]
	v_mfma_f32_16x16x32_bf16 v[4:7], v[158:161], v[210:213], v[4:7]
	v_mfma_f32_16x16x32_bf16 v[60:63], v[154:157], v[190:193], v[60:63]
	v_mfma_f32_16x16x32_bf16 v[52:55], v[162:165], v[190:193], v[52:55]
	v_mfma_f32_16x16x32_bf16 v[44:47], v[154:157], v[198:201], v[44:47]
	v_mfma_f32_16x16x32_bf16 v[36:39], v[162:165], v[198:201], v[36:39]
	v_mfma_f32_16x16x32_bf16 v[28:31], v[154:157], v[206:209], v[28:31]
	v_mfma_f32_16x16x32_bf16 v[20:23], v[162:165], v[206:209], v[20:23]
	v_mfma_f32_16x16x32_bf16 v[12:15], v[154:157], v[214:217], v[12:15]
	v_mfma_f32_16x16x32_bf16 v[4:7], v[162:165], v[214:217], v[4:7]
	s_setprio 0
	s_setprio 1
	v_mfma_f32_16x16x32_bf16 v[56:59], v[166:169], v[182:185], v[56:59]
	v_mfma_f32_16x16x32_bf16 v[48:51], v[174:177], v[182:185], v[48:51]
	v_mfma_f32_16x16x32_bf16 v[40:43], v[166:169], v[194:197], v[40:43]
	v_mfma_f32_16x16x32_bf16 v[32:35], v[174:177], v[194:197], v[32:35]
	v_mfma_f32_16x16x32_bf16 v[24:27], v[166:169], v[202:205], v[24:27]
	v_mfma_f32_16x16x32_bf16 v[16:19], v[174:177], v[202:205], v[16:19]
	v_mfma_f32_16x16x32_bf16 v[8:11], v[166:169], v[210:213], v[8:11]
	v_mfma_f32_16x16x32_bf16 v[0:3], v[174:177], v[210:213], v[0:3]
	v_mfma_f32_16x16x32_bf16 v[56:59], v[170:173], v[190:193], v[56:59]
	v_mfma_f32_16x16x32_bf16 v[48:51], v[178:181], v[190:193], v[48:51]
	v_mfma_f32_16x16x32_bf16 v[40:43], v[170:173], v[198:201], v[40:43]
	v_mfma_f32_16x16x32_bf16 v[32:35], v[178:181], v[198:201], v[32:35]
	v_mfma_f32_16x16x32_bf16 v[24:27], v[170:173], v[206:209], v[24:27]
	v_mfma_f32_16x16x32_bf16 v[16:19], v[178:181], v[206:209], v[16:19]
	v_mfma_f32_16x16x32_bf16 v[8:11], v[170:173], v[214:217], v[8:11]
	v_mfma_f32_16x16x32_bf16 v[0:3], v[178:181], v[214:217], v[0:3]
	s_setprio 0
	s_barrier
	s_add_i32 s33, 0, 0x18000
	s_add_i32 s57, 0, 0x1c000
	v_add_u32_e32 v162, s33, v145
	v_add_u32_e32 v178, s57, v145
	ds_read_b128 v[150:153], v162
	ds_read_b128 v[154:157], v162 offset:1024
	ds_read_b128 v[158:161], v162 offset:2048
	ds_read_b128 v[162:165], v162 offset:3072
	ds_read_b128 v[166:169], v178
	ds_read_b128 v[170:173], v178 offset:1024
	ds_read_b128 v[174:177], v178 offset:2048
	ds_read_b128 v[178:181], v178 offset:3072
	s_add_u32 s42, s42, 0x40000
	s_addc_u32 s43, s43, 0
	s_mov_b32 m0, s37
	v_lshl_add_u64 v[224:225], s[42:43], 0, v[134:135]
	ds_read_b128 v[182:185], v149 offset:32768
	ds_read_b128 v[190:193], v149 offset:33792
	ds_read_b128 v[194:197], v149 offset:34816
	ds_read_b128 v[198:201], v149 offset:35840
	ds_read_b128 v[202:205], v149 offset:36864
	ds_read_b128 v[206:209], v149 offset:37888
	ds_read_b128 v[210:213], v149 offset:38912
	ds_read_b128 v[214:217], v149 offset:39936
	global_load_lds_dwordx4 v[224:225], off
	v_lshl_add_u64 v[224:225], s[42:43], 0, v[130:131]
	s_mov_b32 m0, s44
	s_nop 0
	global_load_lds_dwordx4 v[224:225], off
	s_waitcnt vmcnt(8)
	s_waitcnt lgkmcnt(0)
	s_nop 0
	s_barrier
	s_setprio 1
	s_waitcnt lgkmcnt(0)
	v_mfma_f32_16x16x32_bf16 v[124:127], v[150:153], v[182:185], v[124:127]
	v_mfma_f32_16x16x32_bf16 v[116:119], v[158:161], v[182:185], v[116:119]
	v_mfma_f32_16x16x32_bf16 v[108:111], v[150:153], v[194:197], v[108:111]
	v_mfma_f32_16x16x32_bf16 v[100:103], v[158:161], v[194:197], v[100:103]
	v_mfma_f32_16x16x32_bf16 v[92:95], v[150:153], v[202:205], v[92:95]
	v_mfma_f32_16x16x32_bf16 v[84:87], v[158:161], v[202:205], v[84:87]
	v_mfma_f32_16x16x32_bf16 v[76:79], v[150:153], v[210:213], v[76:79]
	v_mfma_f32_16x16x32_bf16 v[68:71], v[158:161], v[210:213], v[68:71]
	v_mfma_f32_16x16x32_bf16 v[124:127], v[154:157], v[190:193], v[124:127]
	v_mfma_f32_16x16x32_bf16 v[116:119], v[162:165], v[190:193], v[116:119]
	v_mfma_f32_16x16x32_bf16 v[108:111], v[154:157], v[198:201], v[108:111]
	v_mfma_f32_16x16x32_bf16 v[100:103], v[162:165], v[198:201], v[100:103]
	v_mfma_f32_16x16x32_bf16 v[92:95], v[154:157], v[206:209], v[92:95]
	v_mfma_f32_16x16x32_bf16 v[84:87], v[162:165], v[206:209], v[84:87]
	v_mfma_f32_16x16x32_bf16 v[76:79], v[154:157], v[214:217], v[76:79]
	v_mfma_f32_16x16x32_bf16 v[68:71], v[162:165], v[214:217], v[68:71]
	s_setprio 0
	s_setprio 1
	v_mfma_f32_16x16x32_bf16 v[120:123], v[166:169], v[182:185], v[120:123]
	v_mfma_f32_16x16x32_bf16 v[112:115], v[174:177], v[182:185], v[112:115]
	v_mfma_f32_16x16x32_bf16 v[104:107], v[166:169], v[194:197], v[104:107]
	v_mfma_f32_16x16x32_bf16 v[96:99], v[174:177], v[194:197], v[96:99]
	v_mfma_f32_16x16x32_bf16 v[88:91], v[166:169], v[202:205], v[88:91]
	v_mfma_f32_16x16x32_bf16 v[80:83], v[174:177], v[202:205], v[80:83]
	v_mfma_f32_16x16x32_bf16 v[72:75], v[166:169], v[210:213], v[72:75]
	v_mfma_f32_16x16x32_bf16 v[64:67], v[174:177], v[210:213], v[64:67]
	v_mfma_f32_16x16x32_bf16 v[120:123], v[170:173], v[190:193], v[120:123]
	v_mfma_f32_16x16x32_bf16 v[112:115], v[178:181], v[190:193], v[112:115]
	v_mfma_f32_16x16x32_bf16 v[104:107], v[170:173], v[198:201], v[104:107]
	v_mfma_f32_16x16x32_bf16 v[96:99], v[178:181], v[198:201], v[96:99]
	v_mfma_f32_16x16x32_bf16 v[88:91], v[170:173], v[206:209], v[88:91]
	v_mfma_f32_16x16x32_bf16 v[80:83], v[178:181], v[206:209], v[80:83]
	v_mfma_f32_16x16x32_bf16 v[72:75], v[170:173], v[214:217], v[72:75]
	v_mfma_f32_16x16x32_bf16 v[64:67], v[178:181], v[214:217], v[64:67]
	s_setprio 0
	s_barrier
	s_add_i32 s33, s33, s13
	v_lshl_add_u64 v[186:187], v[186:187], 0, s[8:9]
	s_mov_b32 m0, s33
	ds_read_b128 v[182:185], v149 offset:49152
	ds_read_b128 v[190:193], v149 offset:50176
	ds_read_b128 v[194:197], v149 offset:51200
	ds_read_b128 v[198:201], v149 offset:52224
	ds_read_b128 v[202:205], v149 offset:53248
	ds_read_b128 v[206:209], v149 offset:54272
	ds_read_b128 v[210:213], v149 offset:55296
	ds_read_b128 v[214:217], v149 offset:56320
	global_load_lds_dwordx4 v[186:187], off
	s_add_i32 m0, s33, 0x2000
	s_add_u32 s40, s40, 0x40080
	v_lshl_add_u64 v[186:187], v[218:219], 0, s[8:9]
	s_addc_u32 s41, s41, 0
	s_add_i32 s33, s57, s13
	global_load_lds_dwordx4 v[186:187], off
	v_lshl_add_u64 v[186:187], s[40:41], 0, v[132:133]
	s_mov_b32 m0, s33
	s_nop 0
	global_load_lds_dwordx4 v[186:187], off
	v_lshl_add_u64 v[186:187], s[40:41], 0, v[128:129]
	s_add_i32 m0, s33, 0x2000
	s_nop 0
	global_load_lds_dwordx4 v[186:187], off
	v_lshl_add_u64 v[186:187], v[220:221], 0, s[8:9]
	s_mov_b32 m0, s46
	s_nop 0
	global_load_lds_dwordx4 v[186:187], off
	v_lshl_add_u64 v[186:187], v[222:223], 0, s[8:9]
	s_mov_b32 m0, s47
	s_nop 0
	global_load_lds_dwordx4 v[186:187], off
	s_waitcnt vmcnt(8)
	s_waitcnt lgkmcnt(0)
	s_barrier
	s_setprio 1
	s_waitcnt lgkmcnt(0)
	v_mfma_f32_16x16x32_bf16 v[60:63], v[150:153], v[182:185], v[60:63]
	v_mfma_f32_16x16x32_bf16 v[52:55], v[158:161], v[182:185], v[52:55]
	v_mfma_f32_16x16x32_bf16 v[44:47], v[150:153], v[194:197], v[44:47]
	v_mfma_f32_16x16x32_bf16 v[36:39], v[158:161], v[194:197], v[36:39]
	v_mfma_f32_16x16x32_bf16 v[28:31], v[150:153], v[202:205], v[28:31]
	v_mfma_f32_16x16x32_bf16 v[20:23], v[158:161], v[202:205], v[20:23]
	v_mfma_f32_16x16x32_bf16 v[12:15], v[150:153], v[210:213], v[12:15]
	v_mfma_f32_16x16x32_bf16 v[4:7], v[158:161], v[210:213], v[4:7]
	v_mfma_f32_16x16x32_bf16 v[60:63], v[154:157], v[190:193], v[60:63]
	v_mfma_f32_16x16x32_bf16 v[52:55], v[162:165], v[190:193], v[52:55]
	v_mfma_f32_16x16x32_bf16 v[44:47], v[154:157], v[198:201], v[44:47]
	v_mfma_f32_16x16x32_bf16 v[36:39], v[162:165], v[198:201], v[36:39]
	v_mfma_f32_16x16x32_bf16 v[28:31], v[154:157], v[206:209], v[28:31]
	v_mfma_f32_16x16x32_bf16 v[20:23], v[162:165], v[206:209], v[20:23]
	v_mfma_f32_16x16x32_bf16 v[12:15], v[154:157], v[214:217], v[12:15]
	v_mfma_f32_16x16x32_bf16 v[4:7], v[162:165], v[214:217], v[4:7]
	s_setprio 0
	s_setprio 1
	v_mfma_f32_16x16x32_bf16 v[56:59], v[166:169], v[182:185], v[56:59]
	v_mfma_f32_16x16x32_bf16 v[48:51], v[174:177], v[182:185], v[48:51]
	v_mfma_f32_16x16x32_bf16 v[40:43], v[166:169], v[194:197], v[40:43]
	v_mfma_f32_16x16x32_bf16 v[32:35], v[174:177], v[194:197], v[32:35]
	v_mfma_f32_16x16x32_bf16 v[24:27], v[166:169], v[202:205], v[24:27]
	v_mfma_f32_16x16x32_bf16 v[16:19], v[174:177], v[202:205], v[16:19]
	v_mfma_f32_16x16x32_bf16 v[8:11], v[166:169], v[210:213], v[8:11]
	v_mfma_f32_16x16x32_bf16 v[0:3], v[174:177], v[210:213], v[0:3]
	v_mfma_f32_16x16x32_bf16 v[56:59], v[170:173], v[190:193], v[56:59]
	v_mfma_f32_16x16x32_bf16 v[48:51], v[178:181], v[190:193], v[48:51]
	v_mfma_f32_16x16x32_bf16 v[40:43], v[170:173], v[198:201], v[40:43]
	v_mfma_f32_16x16x32_bf16 v[32:35], v[178:181], v[198:201], v[32:35]
	v_mfma_f32_16x16x32_bf16 v[24:27], v[170:173], v[206:209], v[24:27]
	v_mfma_f32_16x16x32_bf16 v[16:19], v[178:181], v[206:209], v[16:19]
	v_mfma_f32_16x16x32_bf16 v[8:11], v[170:173], v[214:217], v[8:11]
	v_mfma_f32_16x16x32_bf16 v[0:3], v[178:181], v[214:217], v[0:3]
	s_setprio 0
	s_barrier
	s_add_i32 s56, s56, 2
	s_add_u32 s38, s38, 0x100
	s_addc_u32 s39, s39, 0
	s_add_u32 s54, s54, 0x100
	s_addc_u32 s55, s55, 0
	s_cmp_gt_u32 s56, 13
	s_cbranch_scc0 .LBB0_1308
	s_and_b64 vcc, exec, s[10:11]
	s_cbranch_vccz .LBB0_1311
	s_barrier
.LBB0_1311:
	v_pk_mul_f32 v[122:123], v[126:127], v[122:123]
	v_pk_mul_f32 v[126:127], v[126:127], s[14:15] op_sel_hi:[1,0]
	v_pk_mul_f32 v[120:121], v[124:125], v[120:121]
	v_exp_f32_e32 v126, v126
	v_exp_f32_e32 v127, v127
	v_pk_mul_f32 v[124:125], v[124:125], s[14:15] op_sel_hi:[1,0]
	v_pk_mul_f32 v[154:155], v[118:119], s[14:15] op_sel_hi:[1,0]
	v_exp_f32_e32 v124, v124
	v_pk_add_f32 v[126:127], v[126:127], 1.0 op_sel_hi:[1,0]
	v_exp_f32_e32 v125, v125
	v_rcp_f32_e32 v126, v126
	v_rcp_f32_e32 v127, v127
	v_exp_f32_e32 v154, v154
	v_pk_add_f32 v[124:125], v[124:125], 1.0 op_sel_hi:[1,0]
	v_exp_f32_e32 v155, v155
	v_pk_mul_f32 v[122:123], v[126:127], v[122:123]
	v_pk_mul_f32 v[126:127], v[116:117], s[14:15] op_sel_hi:[1,0]
	v_rcp_f32_e32 v124, v124
	v_rcp_f32_e32 v125, v125
	v_exp_f32_e32 v126, v126
	v_exp_f32_e32 v127, v127
	v_pk_mul_f32 v[106:107], v[110:111], v[106:107]
	v_pk_mul_f32 v[110:111], v[110:111], s[14:15] op_sel_hi:[1,0]
	v_pk_mul_f32 v[120:121], v[124:125], v[120:121]
	v_pk_add_f32 v[124:125], v[126:127], 1.0 op_sel_hi:[1,0]
	v_exp_f32_e32 v110, v110
	v_exp_f32_e32 v111, v111
	v_rcp_f32_e32 v124, v124
	v_pk_add_f32 v[126:127], v[154:155], 1.0 op_sel_hi:[1,0]
	v_rcp_f32_e32 v125, v125
	v_rcp_f32_e32 v126, v126
	v_rcp_f32_e32 v127, v127
	v_pk_mul_f32 v[112:113], v[116:117], v[112:113]
	v_pk_mul_f32 v[104:105], v[108:109], v[104:105]
	v_pk_mul_f32 v[108:109], v[108:109], s[14:15] op_sel_hi:[1,0]
	v_pk_add_f32 v[110:111], v[110:111], 1.0 op_sel_hi:[1,0]
	v_lshl_or_b32 v152, s51, 16, v146
	v_pk_mul_f32 v[114:115], v[118:119], v[114:115]
	v_pk_mul_f32 v[112:113], v[124:125], v[112:113]
	v_exp_f32_e32 v108, v108
	v_exp_f32_e32 v109, v109
	v_rcp_f32_e32 v110, v110
	v_rcp_f32_e32 v111, v111
	s_mul_i32 s32, s36, 0x2c00
	v_add_u32_e32 v150, s32, v144
	v_ashrrev_i32_e32 v153, 31, v152
	v_pk_mul_f32 v[114:115], v[126:127], v[114:115]
	v_cvt_pk_bf16_f32 v116, v120, v121
	v_cvt_pk_bf16_f32 v117, v122, v123
	v_cvt_pk_bf16_f32 v118, v112, v113
	v_mov_b64_e32 v[112:113], s[20:21]
	v_cvt_pk_bf16_f32 v119, v114, v115
	v_mad_i64_i32 v[120:121], s[38:39], v150, s50, v[112:113]
	v_lshlrev_b64 v[114:115], 0, v[152:153]
	v_lshl_add_u64 v[120:121], v[120:121], 0, v[114:115]
	global_store_dwordx4 v[120:121], v[116:119], off
	v_pk_add_f32 v[108:109], v[108:109], 1.0 op_sel_hi:[1,0]
	v_pk_mul_f32 v[106:107], v[110:111], v[106:107]
	v_pk_mul_f32 v[110:111], v[100:101], s[14:15] op_sel_hi:[1,0]
	v_pk_mul_f32 v[116:117], v[102:103], s[14:15] op_sel_hi:[1,0]
	v_rcp_f32_e32 v108, v108
	v_rcp_f32_e32 v109, v109
	v_exp_f32_e32 v110, v110
	v_exp_f32_e32 v111, v111
	v_exp_f32_e32 v116, v116
	v_exp_f32_e32 v117, v117
	v_pk_mul_f32 v[90:91], v[94:95], v[90:91]
	v_pk_mul_f32 v[94:95], v[94:95], s[14:15] op_sel_hi:[1,0]
	v_pk_mul_f32 v[104:105], v[108:109], v[104:105]
	v_exp_f32_e32 v94, v94
	v_exp_f32_e32 v95, v95
	v_pk_add_f32 v[108:109], v[110:111], 1.0 op_sel_hi:[1,0]
	v_pk_add_f32 v[110:111], v[116:117], 1.0 op_sel_hi:[1,0]
	v_rcp_f32_e32 v108, v108
	v_rcp_f32_e32 v110, v110
	v_rcp_f32_e32 v111, v111
	v_rcp_f32_e32 v109, v109
	v_pk_mul_f32 v[88:89], v[92:93], v[88:89]
	v_pk_mul_f32 v[92:93], v[92:93], s[14:15] op_sel_hi:[1,0]
	v_pk_add_f32 v[94:95], v[94:95], 1.0 op_sel_hi:[1,0]
	v_pk_mul_f32 v[98:99], v[102:103], v[98:99]
	v_pk_mul_f32 v[96:97], v[100:101], v[96:97]
	v_exp_f32_e32 v92, v92
	v_exp_f32_e32 v93, v93
	v_rcp_f32_e32 v94, v94
	v_rcp_f32_e32 v95, v95
	v_pk_mul_f32 v[100:101], v[110:111], v[98:99]
	v_pk_mul_f32 v[98:99], v[108:109], v[96:97]
	v_or_b32_e32 v102, 16, v150
	v_cvt_pk_bf16_f32 v96, v104, v105
	v_cvt_pk_bf16_f32 v97, v106, v107
	v_cvt_pk_bf16_f32 v98, v98, v99
	v_cvt_pk_bf16_f32 v99, v100, v101
	v_mad_i64_i32 v[100:101], s[38:39], v102, s50, v[112:113]
	v_lshl_add_u64 v[100:101], v[100:101], 0, v[114:115]
	global_store_dwordx4 v[100:101], v[96:99], off
	v_pk_add_f32 v[92:93], v[92:93], 1.0 op_sel_hi:[1,0]
	v_pk_mul_f32 v[90:91], v[94:95], v[90:91]
	v_pk_mul_f32 v[94:95], v[84:85], s[14:15] op_sel_hi:[1,0]
	v_pk_mul_f32 v[96:97], v[86:87], s[14:15] op_sel_hi:[1,0]
	v_rcp_f32_e32 v92, v92
	v_rcp_f32_e32 v93, v93
	v_exp_f32_e32 v94, v94
	v_exp_f32_e32 v95, v95
	v_exp_f32_e32 v96, v96
	v_exp_f32_e32 v97, v97
	v_pk_mul_f32 v[74:75], v[78:79], v[74:75]
	v_pk_mul_f32 v[78:79], v[78:79], s[14:15] op_sel_hi:[1,0]
	v_pk_mul_f32 v[88:89], v[92:93], v[88:89]
	v_exp_f32_e32 v78, v78
	v_exp_f32_e32 v79, v79
	v_pk_add_f32 v[92:93], v[94:95], 1.0 op_sel_hi:[1,0]
	v_pk_add_f32 v[94:95], v[96:97], 1.0 op_sel_hi:[1,0]
	v_rcp_f32_e32 v92, v92
	v_rcp_f32_e32 v94, v94
	v_rcp_f32_e32 v95, v95
	v_rcp_f32_e32 v93, v93
	v_pk_mul_f32 v[72:73], v[76:77], v[72:73]
	v_pk_mul_f32 v[76:77], v[76:77], s[14:15] op_sel_hi:[1,0]
	v_pk_add_f32 v[78:79], v[78:79], 1.0 op_sel_hi:[1,0]
	v_pk_mul_f32 v[82:83], v[86:87], v[82:83]
	v_pk_mul_f32 v[80:81], v[84:85], v[80:81]
	v_exp_f32_e32 v76, v76
	v_exp_f32_e32 v77, v77
	v_rcp_f32_e32 v78, v78
	v_rcp_f32_e32 v79, v79
	v_pk_mul_f32 v[84:85], v[94:95], v[82:83]
	v_pk_mul_f32 v[82:83], v[92:93], v[80:81]
	v_or_b32_e32 v86, 32, v150
	v_cvt_pk_bf16_f32 v80, v88, v89
	v_cvt_pk_bf16_f32 v81, v90, v91
	v_cvt_pk_bf16_f32 v82, v82, v83
	v_cvt_pk_bf16_f32 v83, v84, v85
	v_mad_i64_i32 v[84:85], s[38:39], v86, s50, v[112:113]
	v_lshl_add_u64 v[84:85], v[84:85], 0, v[114:115]
	global_store_dwordx4 v[84:85], v[80:83], off
	v_pk_add_f32 v[76:77], v[76:77], 1.0 op_sel_hi:[1,0]
	v_pk_mul_f32 v[74:75], v[78:79], v[74:75]
	v_pk_mul_f32 v[78:79], v[68:69], s[14:15] op_sel_hi:[1,0]
	v_pk_mul_f32 v[80:81], v[70:71], s[14:15] op_sel_hi:[1,0]
	v_rcp_f32_e32 v76, v76
	v_rcp_f32_e32 v77, v77
	v_exp_f32_e32 v78, v78
	v_exp_f32_e32 v79, v79
	v_exp_f32_e32 v80, v80
	v_exp_f32_e32 v81, v81
	v_pk_mul_f32 v[58:59], v[62:63], v[58:59]
	v_pk_mul_f32 v[62:63], v[62:63], s[14:15] op_sel_hi:[1,0]
	v_pk_mul_f32 v[72:73], v[76:77], v[72:73]
	v_exp_f32_e32 v62, v62
	v_exp_f32_e32 v63, v63
	v_pk_add_f32 v[76:77], v[78:79], 1.0 op_sel_hi:[1,0]
	v_pk_add_f32 v[78:79], v[80:81], 1.0 op_sel_hi:[1,0]
	v_rcp_f32_e32 v76, v76
	v_rcp_f32_e32 v78, v78
	v_rcp_f32_e32 v79, v79
	v_rcp_f32_e32 v77, v77
	v_pk_mul_f32 v[56:57], v[60:61], v[56:57]
	v_pk_mul_f32 v[60:61], v[60:61], s[14:15] op_sel_hi:[1,0]
	v_pk_add_f32 v[62:63], v[62:63], 1.0 op_sel_hi:[1,0]
	v_pk_mul_f32 v[66:67], v[70:71], v[66:67]
	v_pk_mul_f32 v[64:65], v[68:69], v[64:65]
	v_exp_f32_e32 v60, v60
	v_exp_f32_e32 v61, v61
	v_rcp_f32_e32 v62, v62
	v_rcp_f32_e32 v63, v63
	v_pk_mul_f32 v[68:69], v[78:79], v[66:67]
	v_pk_mul_f32 v[66:67], v[76:77], v[64:65]
	v_or_b32_e32 v70, 48, v150
	v_cvt_pk_bf16_f32 v64, v72, v73
	v_cvt_pk_bf16_f32 v65, v74, v75
	v_cvt_pk_bf16_f32 v66, v66, v67
	v_cvt_pk_bf16_f32 v67, v68, v69
	v_mad_i64_i32 v[68:69], s[38:39], v70, s50, v[112:113]
	v_lshl_add_u64 v[68:69], v[68:69], 0, v[114:115]
	global_store_dwordx4 v[68:69], v[64:67], off
	v_pk_add_f32 v[60:61], v[60:61], 1.0 op_sel_hi:[1,0]
	v_pk_mul_f32 v[58:59], v[62:63], v[58:59]
	v_pk_mul_f32 v[62:63], v[52:53], s[14:15] op_sel_hi:[1,0]
	v_pk_mul_f32 v[64:65], v[54:55], s[14:15] op_sel_hi:[1,0]
	v_rcp_f32_e32 v60, v60
	v_rcp_f32_e32 v61, v61
	v_exp_f32_e32 v62, v62
	v_exp_f32_e32 v63, v63
	v_exp_f32_e32 v64, v64
	v_exp_f32_e32 v65, v65
	v_pk_mul_f32 v[42:43], v[46:47], v[42:43]
	v_pk_mul_f32 v[46:47], v[46:47], s[14:15] op_sel_hi:[1,0]
	v_pk_mul_f32 v[56:57], v[60:61], v[56:57]
	v_exp_f32_e32 v46, v46
	v_exp_f32_e32 v47, v47
	v_pk_add_f32 v[60:61], v[62:63], 1.0 op_sel_hi:[1,0]
	v_pk_add_f32 v[62:63], v[64:65], 1.0 op_sel_hi:[1,0]
	v_rcp_f32_e32 v60, v60
	v_rcp_f32_e32 v62, v62
	v_rcp_f32_e32 v63, v63
	v_rcp_f32_e32 v61, v61
	v_pk_mul_f32 v[40:41], v[44:45], v[40:41]
	v_pk_mul_f32 v[44:45], v[44:45], s[14:15] op_sel_hi:[1,0]
	v_pk_add_f32 v[46:47], v[46:47], 1.0 op_sel_hi:[1,0]
	v_pk_mul_f32 v[50:51], v[54:55], v[50:51]
	v_pk_mul_f32 v[48:49], v[52:53], v[48:49]
	v_exp_f32_e32 v44, v44
	v_exp_f32_e32 v45, v45
	v_rcp_f32_e32 v46, v46
	v_rcp_f32_e32 v47, v47
	v_add_u32_e32 v66, 0x80, v150
	v_pk_mul_f32 v[52:53], v[62:63], v[50:51]
	v_pk_mul_f32 v[50:51], v[60:61], v[48:49]
	v_cvt_pk_bf16_f32 v48, v56, v57
	v_cvt_pk_bf16_f32 v49, v58, v59
	v_pk_add_f32 v[44:45], v[44:45], 1.0 op_sel_hi:[1,0]
	v_cvt_pk_bf16_f32 v50, v50, v51
	v_cvt_pk_bf16_f32 v51, v52, v53
	v_mad_i64_i32 v[52:53], s[38:39], v66, s50, v[112:113]
	v_lshl_add_u64 v[52:53], v[52:53], 0, v[114:115]
	global_store_dwordx4 v[52:53], v[48:51], off
	v_pk_mul_f32 v[42:43], v[46:47], v[42:43]
	v_pk_mul_f32 v[46:47], v[36:37], s[14:15] op_sel_hi:[1,0]
	v_pk_mul_f32 v[48:49], v[38:39], s[14:15] op_sel_hi:[1,0]
	v_rcp_f32_e32 v44, v44
	v_rcp_f32_e32 v45, v45
	v_exp_f32_e32 v46, v46
	v_exp_f32_e32 v47, v47
	v_exp_f32_e32 v48, v48
	v_exp_f32_e32 v49, v49
	v_pk_mul_f32 v[26:27], v[30:31], v[26:27]
	v_pk_mul_f32 v[30:31], v[30:31], s[14:15] op_sel_hi:[1,0]
	v_pk_mul_f32 v[40:41], v[44:45], v[40:41]
	v_exp_f32_e32 v30, v30
	v_exp_f32_e32 v31, v31
	v_pk_add_f32 v[44:45], v[46:47], 1.0 op_sel_hi:[1,0]
	v_pk_add_f32 v[46:47], v[48:49], 1.0 op_sel_hi:[1,0]
	v_rcp_f32_e32 v44, v44
	v_rcp_f32_e32 v46, v46
	v_rcp_f32_e32 v47, v47
	v_rcp_f32_e32 v45, v45
	v_pk_mul_f32 v[24:25], v[28:29], v[24:25]
	v_pk_mul_f32 v[28:29], v[28:29], s[14:15] op_sel_hi:[1,0]
	v_pk_add_f32 v[30:31], v[30:31], 1.0 op_sel_hi:[1,0]
	v_pk_mul_f32 v[34:35], v[38:39], v[34:35]
	v_pk_mul_f32 v[32:33], v[36:37], v[32:33]
	v_exp_f32_e32 v28, v28
	v_exp_f32_e32 v29, v29
	v_rcp_f32_e32 v30, v30
	v_rcp_f32_e32 v31, v31
	v_pk_mul_f32 v[36:37], v[46:47], v[34:35]
	v_pk_mul_f32 v[34:35], v[44:45], v[32:33]
	v_add_u32_e32 v38, 0x90, v150
	v_cvt_pk_bf16_f32 v32, v40, v41
	v_cvt_pk_bf16_f32 v33, v42, v43
	v_cvt_pk_bf16_f32 v34, v34, v35
	v_cvt_pk_bf16_f32 v35, v36, v37
	v_mad_i64_i32 v[36:37], s[38:39], v38, s50, v[112:113]
	v_lshl_add_u64 v[36:37], v[36:37], 0, v[114:115]
	global_store_dwordx4 v[36:37], v[32:35], off
	v_pk_add_f32 v[28:29], v[28:29], 1.0 op_sel_hi:[1,0]
	v_pk_mul_f32 v[26:27], v[30:31], v[26:27]
	v_pk_mul_f32 v[30:31], v[20:21], s[14:15] op_sel_hi:[1,0]
	v_pk_mul_f32 v[32:33], v[22:23], s[14:15] op_sel_hi:[1,0]
	v_rcp_f32_e32 v28, v28
	v_rcp_f32_e32 v29, v29
	v_exp_f32_e32 v30, v30
	v_exp_f32_e32 v31, v31
	v_exp_f32_e32 v32, v32
	v_exp_f32_e32 v33, v33
	v_pk_mul_f32 v[10:11], v[14:15], v[10:11]
	v_pk_mul_f32 v[14:15], v[14:15], s[14:15] op_sel_hi:[1,0]
	v_pk_mul_f32 v[24:25], v[28:29], v[24:25]
	v_exp_f32_e32 v14, v14
	v_exp_f32_e32 v15, v15
	v_pk_add_f32 v[28:29], v[30:31], 1.0 op_sel_hi:[1,0]
	v_pk_add_f32 v[30:31], v[32:33], 1.0 op_sel_hi:[1,0]
	v_rcp_f32_e32 v28, v28
	v_rcp_f32_e32 v30, v30
	v_rcp_f32_e32 v31, v31
	v_rcp_f32_e32 v29, v29
	v_pk_mul_f32 v[8:9], v[12:13], v[8:9]
	v_pk_mul_f32 v[12:13], v[12:13], s[14:15] op_sel_hi:[1,0]
	v_pk_add_f32 v[14:15], v[14:15], 1.0 op_sel_hi:[1,0]
	v_pk_mul_f32 v[18:19], v[22:23], v[18:19]
	v_pk_mul_f32 v[16:17], v[20:21], v[16:17]
	v_exp_f32_e32 v12, v12
	v_exp_f32_e32 v13, v13
	v_rcp_f32_e32 v14, v14
	v_rcp_f32_e32 v15, v15
	v_pk_mul_f32 v[20:21], v[30:31], v[18:19]
	v_pk_mul_f32 v[18:19], v[28:29], v[16:17]
	v_add_u32_e32 v22, 0xa0, v150
	v_cvt_pk_bf16_f32 v16, v24, v25
	v_cvt_pk_bf16_f32 v17, v26, v27
	v_cvt_pk_bf16_f32 v18, v18, v19
	v_cvt_pk_bf16_f32 v19, v20, v21
	v_mad_i64_i32 v[20:21], s[38:39], v22, s50, v[112:113]
	v_lshl_add_u64 v[20:21], v[20:21], 0, v[114:115]
	global_store_dwordx4 v[20:21], v[16:19], off
	v_pk_add_f32 v[12:13], v[12:13], 1.0 op_sel_hi:[1,0]
	v_pk_mul_f32 v[10:11], v[14:15], v[10:11]
	v_pk_mul_f32 v[14:15], v[4:5], s[14:15] op_sel_hi:[1,0]
	v_pk_mul_f32 v[16:17], v[6:7], s[14:15] op_sel_hi:[1,0]
	v_rcp_f32_e32 v12, v12
	v_rcp_f32_e32 v13, v13
	v_exp_f32_e32 v14, v14
	v_exp_f32_e32 v15, v15
	v_exp_f32_e32 v16, v16
	v_exp_f32_e32 v17, v17
	v_pk_mul_f32 v[8:9], v[12:13], v[8:9]
	v_pk_add_f32 v[12:13], v[14:15], 1.0 op_sel_hi:[1,0]
	v_pk_mul_f32 v[2:3], v[6:7], v[2:3]
	v_pk_add_f32 v[14:15], v[16:17], 1.0 op_sel_hi:[1,0]
	v_rcp_f32_e32 v12, v12
	v_rcp_f32_e32 v14, v14
	v_rcp_f32_e32 v15, v15
	v_rcp_f32_e32 v13, v13
	v_pk_mul_f32 v[0:1], v[4:5], v[0:1]
	v_add_u32_e32 v6, 0xb0, v150
	v_pk_mul_f32 v[4:5], v[14:15], v[2:3]
	v_pk_mul_f32 v[2:3], v[12:13], v[0:1]
	v_cvt_pk_bf16_f32 v0, v8, v9
	v_cvt_pk_bf16_f32 v1, v10, v11
	s_andn2_b64 vcc, exec, s[0:1]
	v_cvt_pk_bf16_f32 v2, v2, v3
	v_cvt_pk_bf16_f32 v3, v4, v5
	v_mad_i64_i32 v[4:5], s[38:39], v6, s50, v[112:113]
	v_lshl_add_u64 v[4:5], v[4:5], 0, v[114:115]
	s_mov_b64 s[0:1], -1
	global_store_dwordx4 v[4:5], v[0:3], off
	s_cbranch_vccnz .LBB0_1304
	s_andn2_b64 vcc, exec, s[4:5]
	s_cbranch_vccnz .LBB0_1303
	s_barrier
	s_branch .LBB0_1303

.LBB0_1372:
	v_ashrrev_i32_e32 v1, 31, v8
	v_lshrrev_b32_e32 v1, 26, v1
	v_add_u32_e32 v1, v8, v1
	v_ashrrev_i32_e32 v9, 6, v1
	v_bfe_i32 v1, v8, 27, 1
	v_lshlrev_b32_e32 v0, 4, v8
	v_lshrrev_b32_e32 v1, 22, v1
	v_add_u32_e32 v1, v0, v1
	v_and_b32_e32 v1, 0xfffffc00, v1
	v_sub_u32_e32 v1, v0, v1
	v_lshrrev_b32_e32 v2, 4, v1
	v_bitop3_b32 v1, v2, v1, 32 bitop3:0x6c
	v_ashrrev_i32_e32 v3, 31, v1
	v_lshrrev_b32_e32 v3, 26, v3
	v_lshlrev_b32_e32 v2, 3, v9
	v_add_u32_e32 v3, v1, v3
	v_and_b32_e32 v2, -16, v2
	v_ashrrev_i32_e32 v11, 6, v3
	v_and_b32_e32 v3, 0xc0, v3
	v_add_u32_e32 v2, v11, v2
	v_lshlrev_b32_e32 v4, 5, v9
	v_sub_u32_e32 v1, v1, v3
	v_mov_b32_e32 v3, 1
	v_and_b32_e32 v10, 32, v4
	v_ashrrev_i16_sdwa v1, v3, sext(v1) dst_sel:DWORD dst_unused:UNUSED_PAD src0_sel:DWORD src1_sel:BYTE_0
	v_lshlrev_b32_e32 v4, 1, v2
	v_lshrrev_b32_e32 v5, 2, v2
	v_and_b32_e32 v6, 3, v11
	s_mov_b32 s5, 0xffffe0
	v_bfe_i32 v12, v1, 0, 16
	v_and_b32_e32 v4, 24, v4
	v_and_b32_e32 v5, 4, v5
	v_and_or_b32 v6, v2, s5, v6
	s_movk_i32 s0, 0xb00
	v_add_u32_e32 v1, v10, v12
	v_or3_b32 v4, v6, v5, v4
	v_mul_lo_u32 v2, v2, s0
	s_add_u32 s3, s72, 0x2e00000
	v_add_lshl_u32 v128, v1, v2, 1
	v_mul_u32_u24_e32 v2, 0xb00, v4
	v_add_u32_e32 v0, 0x2000, v0
	s_addc_u32 s12, s73, 0
	v_add_lshl_u32 v130, v2, v1, 1
	v_ashrrev_i32_e32 v1, 31, v0
	s_add_i32 s6, s6, s7
	v_lshrrev_b32_e32 v1, 22, v1
	s_ashr_i32 s7, s6, 31
	v_add_u32_e32 v1, v0, v1
	s_lshr_b32 s7, s7, 27
	v_ashrrev_i32_e32 v13, 10, v1
	s_add_i32 s7, s6, s7
	v_mul_i32_i24_e32 v1, 0x400, v13
	s_ashr_i32 s8, s7, 5
	s_and_b32 s7, s7, 0xffe0
	v_sub_u32_e32 v0, v0, v1
	s_sub_i32 s6, s6, s7
	v_lshrrev_b32_e32 v1, 4, v0
	s_bfe_i32 s7, s6, 0x80000
	v_bitop3_b32 v0, v1, v0, 32 bitop3:0x6c
	s_bfe_u32 s7, s7, 0x3000c
	v_ashrrev_i32_e32 v2, 31, v0
	s_add_i32 s7, s6, s7
	v_lshrrev_b32_e32 v2, 26, v2
	s_bfe_i32 s9, s7, 0x80000
	s_and_b32 s7, s7, 0xf8
	v_lshlrev_b32_e32 v1, 3, v13
	v_add_u32_e32 v2, v0, v2
	s_sub_i32 s6, s6, s7
	v_and_b32_e32 v1, -16, v1
	v_ashrrev_i32_e32 v14, 6, v2
	v_lshlrev_b32_e32 v4, 5, v13
	s_lshl_b32 s8, s8, 3
	s_sext_i32_i16 s9, s9
	s_sext_i32_i8 s6, s6
	s_ashr_i32 s1, s4, 6
	v_add_u32_e32 v1, v14, v1
	v_and_b32_e32 v15, 32, v4
	v_and_b32_e32 v2, 0xc0, v2
	v_and_b32_e32 v4, 3, v14
	s_add_i32 s55, s8, s6
	s_ashr_i32 s6, s9, 3
	v_sub_u32_e32 v0, v0, v2
	v_and_or_b32 v4, v1, s5, v4
	s_ashr_i32 s5, s4, 8
	s_lshl_b32 s13, s1, 10
	s_lshr_b32 s10, s9, 3
	s_mul_hi_i32 s7, s6, 0x160000
	s_mul_i32 s6, s6, 0x160000
	v_ashrrev_i16_sdwa v0, v3, sext(v0) dst_sel:DWORD dst_unused:UNUSED_PAD src0_sel:DWORD src1_sel:BYTE_0
	v_lshlrev_b32_e32 v2, 1, v1
	v_lshrrev_b32_e32 v3, 2, v1
	s_add_u32 s36, s3, s6
	v_bfe_i32 v16, v0, 0, 16
	v_and_b32_e32 v2, 24, v2
	v_and_b32_e32 v3, 4, v3
	s_addc_u32 s37, s12, s7
	s_add_i32 s34, s13, 0
	v_add_u32_e32 v0, v15, v16
	v_or3_b32 v2, v4, v3, v2
	v_mul_lo_u32 v1, v1, s0
	s_add_i32 m0, s34, 0x10000
	v_add_lshl_u32 v132, v0, v1, 1
	v_mul_u32_u24_e32 v1, 0xb00, v2
	global_load_lds_dwordx4 v130, s[36:37]
	s_add_i32 m0, s34, 0x12000
	v_add_lshl_u32 v134, v1, v0, 1
	s_add_u32 s6, s36, 0xb0000
	global_load_lds_dwordx4 v134, s[36:37]
	s_addc_u32 s7, s37, 0
	s_add_i32 m0, s34, 0x14000
	s_mul_i32 s11, s55, 0x160000
	global_load_lds_dwordx4 v130, s[6:7]
	s_add_i32 m0, s34, 0x16000
	s_mul_hi_i32 s8, s55, 0x160000
	s_add_u32 s28, s20, s11
	s_addc_u32 s29, s21, s8
	s_add_i32 s35, s34, 0x2000
	global_load_lds_dwordx4 v134, s[6:7]
	s_mov_b32 m0, s34
	s_add_u32 s6, s28, 0x4000
	v_and_b32_e32 v229, 63, v188
	v_lshrrev_b32_e32 v230, 6, v188
	v_lshrrev_b32_e32 v231, 2, v229
	v_lshlrev_b32_e32 v231, 7, v231
	v_and_b32_e32 v232, 3, v229
	v_lshlrev_b32_e32 v232, 4, v232
	v_lshrrev_b32_e32 v233, 5, v229
	v_lshlrev_b32_e32 v233, 5, v233
	v_xor_b32_e32 v232, v232, v233
	v_or_b32_e32 v231, v231, v232
	v_lshrrev_b32_e32 v232, 1, v230
	v_lshl_or_b32 v231, v232, 11, v231
	v_and_b32_e32 v232, 1, v230
	v_lshl_or_b32 v128, v232, 6, v231
	v_add_u32_e32 v132, 0x2000, v128
	global_load_lds_dwordx4 v128, s[28:29]
	s_mov_b32 m0, s35
	s_addc_u32 s7, s29, 0
	s_add_i32 s42, s34, 0x4000
	global_load_lds_dwordx4 v132, s[28:29]
	s_mov_b32 m0, s42
	s_add_i32 s43, s34, 0x6000
	global_load_lds_dwordx4 v128, s[6:7]
	s_mov_b32 m0, s43
	v_mov_b32_e32 v131, 0
	global_load_lds_dwordx4 v132, s[6:7]
	v_mov_b32_e32 v135, v131
	v_mov_b32_e32 v129, v131
	v_mov_b32_e32 v133, v131
	s_cmp_eq_u32 s5, 1
	s_mov_b32 s44, 0
	v_lshl_add_u64 v[6:7], s[36:37], 0, v[130:131]
	v_lshl_add_u64 v[4:5], s[36:37], 0, v[134:135]
	v_lshl_add_u64 v[0:1], s[28:29], 0, v[128:129]
	s_cselect_b64 s[6:7], -1, 0
	s_cmp_lg_u32 s5, 1
	v_lshl_add_u64 v[2:3], s[28:29], 0, v[132:133]
	s_cbranch_scc1 .LBB0_1374
	s_barrier
.LBB0_1374:
	s_lshl_b32 s1, s1, 5
	s_mov_b64 s[8:9], 0x80
	s_mov_b64 s[92:93], 0x8000
	s_and_b32 s1, s1, 0x60
	s_add_i32 m0, s34, 0x18000
	v_lshl_add_u64 v[6:7], v[6:7], 0, s[8:9]
	s_lshl_b32 s11, s5, 13
	s_lshl_b32 s16, s1, 7
	s_waitcnt vmcnt(2)
	s_barrier
	global_load_lds_dwordx4 v[6:7], off
	v_lshl_add_u64 v[4:5], v[4:5], 0, s[8:9]
	s_add_i32 m0, s34, 0x1a000
	s_add_i32 s45, s34, 0x8000
	s_add_i32 s46, s34, 0xa000
	global_load_lds_dwordx4 v[4:5], off
	v_lshl_add_u64 v[0:1], v[0:1], 0, s[92:93]
	s_mov_b32 m0, s45
	s_add_u32 s14, s36, 0xb0080
	global_load_lds_dwordx4 v[0:1], off
	v_lshl_add_u64 v[0:1], v[2:3], 0, s[92:93]
	s_mov_b32 m0, s46
	s_addc_u32 s15, s37, 0
	global_load_lds_dwordx4 v[0:1], off
	s_add_i32 m0, s34, 0x1c000
	v_lshl_add_u64 v[0:1], s[14:15], 0, v[130:131]
	global_load_lds_dwordx4 v[0:1], off
	v_lshl_add_u64 v[0:1], s[14:15], 0, v[134:135]
	s_add_i32 m0, s34, 0x1e000
	s_cmpk_lt_u32 s4, 0x100
	global_load_lds_dwordx4 v[0:1], off
	v_lshrrev_b32_e32 v1, 1, v8
	v_and_b32_e32 v1, 24, v1
	v_and_b32_e32 v0, 15, v8
	v_lshlrev_b32_e32 v2, 1, v1
	v_lshl_or_b32 v146, s5, 6, v0
	v_lshl_or_b32 v0, v0, 6, v2
	v_lshlrev_b32_e32 v2, 2, v8
	v_and_b32_e32 v2, 32, v2
	v_bitop3_b32 v3, v0, s11, v2 bitop3:0xde
	v_bitop3_b32 v147, v0, s16, v2 bitop3:0xde
	v_or_b32_e32 v148, s1, v1
	v_lshrrev_b32_e32 v1, 1, v9
	v_mul_lo_u32 v0, v11, s0
	s_mov_b32 s1, 0xb000
	v_mad_u64_u32 v[0:1], s[4:5], v1, s1, v[0:1]
	v_or_b32_e32 v0, v0, v10
	s_mov_b64 s[14:15], 0xb0080
	v_add_lshl_u32 v0, v0, v12, 1
	v_mov_b32_e32 v1, v131
	v_lshl_add_u64 v[136:137], v[0:1], 0, s[14:15]
	v_add_u32_e32 v136, 0xc000, v128
	v_mov_b32_e32 v137, 0
	v_lshrrev_b32_e32 v1, 1, v13
	v_mul_lo_u32 v0, v14, s0
	v_mad_u64_u32 v[0:1], s[0:1], v1, s1, v[0:1]
	s_waitcnt vmcnt(6)
	v_or_b32_e32 v0, v0, v15
	s_sext_i32_i8 s56, s10
	s_cselect_b64 s[10:11], -1, 0
	v_add_lshl_u32 v0, v0, v16, 1
	v_mov_b32_e32 v1, v131
	s_add_i32 s47, 0, 0x10000
	s_add_i32 s48, 0, 0x14000
	v_lshl_add_u64 v[138:139], v[0:1], 0, s[14:15]
	v_add_u32_e32 v138, 0xc000, v132
	v_mov_b32_e32 v139, 0
	v_mov_b64_e32 v[140:141], 0x200
	v_mov_b64_e32 v[142:143], 0x1ff
	v_add_u32_e32 v149, s47, v147
	v_add_u32_e32 v150, s48, v147
	v_add_u32_e32 v151, 0, v3
	s_mov_b64 s[14:15], 0x40000
	s_mov_b32 s49, 0x40000
	s_mov_b64 s[16:17], 0x48000
	s_mov_b32 s50, 0x48000
	s_mov_b64 s[18:19], 0x50000
	s_mov_b32 s51, 0x50000
	s_mov_b64 s[24:25], 0x58000
	s_mov_b32 s52, 0x58000
	s_barrier
	s_branch .LBB0_1377

.LBB0_1388:
	ds_read_b128 v[152:155], v149
	ds_read_b128 v[156:159], v149 offset:1024
	ds_read_b128 v[160:163], v149 offset:2048
	ds_read_b128 v[164:167], v149 offset:3072
	ds_read_b128 v[168:171], v150
	ds_read_b128 v[172:175], v150 offset:1024
	ds_read_b128 v[176:179], v150 offset:2048
	ds_read_b128 v[180:183], v150 offset:3072
	s_add_u32 s36, s28, 0x10000
	s_addc_u32 s37, s29, 0
	s_cmp_eq_u32 s59, 40
	s_cselect_b32 s41, s5, s37
	s_cselect_b32 s40, s4, s36
	s_cselect_b32 s39, s27, s58
	s_cselect_b32 s38, s26, s57
	v_lshl_add_u64 v[144:145], s[28:29], 0, v[136:137]
	s_add_i32 m0, s34, 0xc000
	ds_read_b128 v[184:187], v151
	ds_read_b128 v[190:193], v151 offset:1024
	ds_read_b128 v[194:197], v151 offset:2048
	ds_read_b128 v[198:201], v151 offset:3072
	ds_read_b128 v[202:205], v151 offset:4096
	ds_read_b128 v[206:209], v151 offset:5120
	ds_read_b128 v[210:213], v151 offset:6144
	ds_read_b128 v[214:217], v151 offset:7168
	global_load_lds_dwordx4 v[144:145], off
	v_lshl_add_u64 v[144:145], s[28:29], 0, v[138:139]
	s_add_i32 m0, s34, 0xe000
	s_nop 0
	global_load_lds_dwordx4 v[144:145], off
	s_waitcnt vmcnt(8)
	s_waitcnt lgkmcnt(0)
	s_barrier
	s_setprio 1
	s_waitcnt lgkmcnt(0)
	v_mfma_f32_16x16x32_bf16 v[124:127], v[152:155], v[184:187], v[124:127]
	v_mfma_f32_16x16x32_bf16 v[120:123], v[160:163], v[184:187], v[120:123]
	v_mfma_f32_16x16x32_bf16 v[116:119], v[152:155], v[194:197], v[116:119]
	v_mfma_f32_16x16x32_bf16 v[108:111], v[160:163], v[194:197], v[108:111]
	v_mfma_f32_16x16x32_bf16 v[100:103], v[152:155], v[202:205], v[100:103]
	v_mfma_f32_16x16x32_bf16 v[92:95], v[160:163], v[202:205], v[92:95]
	v_mfma_f32_16x16x32_bf16 v[84:87], v[152:155], v[210:213], v[84:87]
	v_mfma_f32_16x16x32_bf16 v[76:79], v[160:163], v[210:213], v[76:79]
	v_mfma_f32_16x16x32_bf16 v[124:127], v[156:159], v[190:193], v[124:127]
	v_mfma_f32_16x16x32_bf16 v[120:123], v[164:167], v[190:193], v[120:123]
	v_mfma_f32_16x16x32_bf16 v[116:119], v[156:159], v[198:201], v[116:119]
	v_mfma_f32_16x16x32_bf16 v[108:111], v[164:167], v[198:201], v[108:111]
	v_mfma_f32_16x16x32_bf16 v[100:103], v[156:159], v[206:209], v[100:103]
	v_mfma_f32_16x16x32_bf16 v[92:95], v[164:167], v[206:209], v[92:95]
	v_mfma_f32_16x16x32_bf16 v[84:87], v[156:159], v[214:217], v[84:87]
	v_mfma_f32_16x16x32_bf16 v[76:79], v[164:167], v[214:217], v[76:79]
	s_setprio 0
	s_setprio 1
	v_mfma_f32_16x16x32_bf16 v[112:115], v[168:171], v[184:187], v[112:115]
	v_mfma_f32_16x16x32_bf16 v[104:107], v[176:179], v[184:187], v[104:107]
	v_mfma_f32_16x16x32_bf16 v[96:99], v[168:171], v[194:197], v[96:99]
	v_mfma_f32_16x16x32_bf16 v[88:91], v[176:179], v[194:197], v[88:91]
	v_mfma_f32_16x16x32_bf16 v[80:83], v[168:171], v[202:205], v[80:83]
	v_mfma_f32_16x16x32_bf16 v[72:75], v[176:179], v[202:205], v[72:75]
	v_mfma_f32_16x16x32_bf16 v[68:71], v[168:171], v[210:213], v[68:71]
	v_mfma_f32_16x16x32_bf16 v[64:67], v[176:179], v[210:213], v[64:67]
	v_mfma_f32_16x16x32_bf16 v[112:115], v[172:175], v[190:193], v[112:115]
	v_mfma_f32_16x16x32_bf16 v[104:107], v[180:183], v[190:193], v[104:107]
	v_mfma_f32_16x16x32_bf16 v[96:99], v[172:175], v[198:201], v[96:99]
	v_mfma_f32_16x16x32_bf16 v[88:91], v[180:183], v[198:201], v[88:91]
	v_mfma_f32_16x16x32_bf16 v[80:83], v[172:175], v[206:209], v[80:83]
	v_mfma_f32_16x16x32_bf16 v[72:75], v[180:183], v[206:209], v[72:75]
	v_mfma_f32_16x16x32_bf16 v[68:71], v[172:175], v[214:217], v[68:71]
	v_mfma_f32_16x16x32_bf16 v[64:67], v[180:183], v[214:217], v[64:67]
	s_setprio 0
	s_barrier
	s_add_i32 s28, s47, s13
	v_lshl_add_u64 v[144:145], s[38:39], 0, v[130:131]
	s_mov_b32 m0, s28
	ds_read_b128 v[184:187], v151 offset:16384
	ds_read_b128 v[190:193], v151 offset:17408
	ds_read_b128 v[194:197], v151 offset:18432
	ds_read_b128 v[198:201], v151 offset:19456
	ds_read_b128 v[202:205], v151 offset:20480
	ds_read_b128 v[206:209], v151 offset:21504
	ds_read_b128 v[210:213], v151 offset:22528
	ds_read_b128 v[214:217], v151 offset:23552
	global_load_lds_dwordx4 v[144:145], off
	s_add_i32 m0, s28, 0x2000
	s_add_u32 s28, s38, 0xb0000
	v_lshl_add_u64 v[218:219], s[38:39], 0, v[134:135]
	s_addc_u32 s29, s39, 0
	s_add_i32 s33, s48, s13
	global_load_lds_dwordx4 v[218:219], off
	v_lshl_add_u64 v[220:221], s[28:29], 0, v[130:131]
	s_mov_b32 m0, s33
	v_lshl_add_u64 v[222:223], s[40:41], 0, v[132:133]
	global_load_lds_dwordx4 v[220:221], off
	v_lshl_add_u64 v[220:221], s[28:29], 0, v[134:135]
	s_add_i32 m0, s33, 0x2000
	s_nop 0
	global_load_lds_dwordx4 v[220:221], off
	v_lshl_add_u64 v[220:221], s[40:41], 0, v[128:129]
	s_mov_b32 m0, s34
	s_nop 0
	global_load_lds_dwordx4 v[220:221], off
	s_mov_b32 m0, s35
	s_nop 0
	global_load_lds_dwordx4 v[222:223], off
	s_waitcnt vmcnt(8)
	s_waitcnt lgkmcnt(0)
	s_nop 0
	s_barrier
	s_setprio 1
	s_waitcnt lgkmcnt(0)
	v_mfma_f32_16x16x32_bf16 v[60:63], v[152:155], v[184:187], v[60:63]
	v_mfma_f32_16x16x32_bf16 v[56:59], v[160:163], v[184:187], v[56:59]
	v_mfma_f32_16x16x32_bf16 v[52:55], v[152:155], v[194:197], v[52:55]
	v_mfma_f32_16x16x32_bf16 v[44:47], v[160:163], v[194:197], v[44:47]
	v_mfma_f32_16x16x32_bf16 v[36:39], v[152:155], v[202:205], v[36:39]
	v_mfma_f32_16x16x32_bf16 v[28:31], v[160:163], v[202:205], v[28:31]
	v_mfma_f32_16x16x32_bf16 v[20:23], v[152:155], v[210:213], v[20:23]
	v_mfma_f32_16x16x32_bf16 v[12:15], v[160:163], v[210:213], v[12:15]
	v_mfma_f32_16x16x32_bf16 v[60:63], v[156:159], v[190:193], v[60:63]
	v_mfma_f32_16x16x32_bf16 v[56:59], v[164:167], v[190:193], v[56:59]
	v_mfma_f32_16x16x32_bf16 v[52:55], v[156:159], v[198:201], v[52:55]
	v_mfma_f32_16x16x32_bf16 v[44:47], v[164:167], v[198:201], v[44:47]
	v_mfma_f32_16x16x32_bf16 v[36:39], v[156:159], v[206:209], v[36:39]
	v_mfma_f32_16x16x32_bf16 v[28:31], v[164:167], v[206:209], v[28:31]
	v_mfma_f32_16x16x32_bf16 v[20:23], v[156:159], v[214:217], v[20:23]
	v_mfma_f32_16x16x32_bf16 v[12:15], v[164:167], v[214:217], v[12:15]
	s_setprio 0
	s_setprio 1
	v_mfma_f32_16x16x32_bf16 v[48:51], v[168:171], v[184:187], v[48:51]
	v_mfma_f32_16x16x32_bf16 v[40:43], v[176:179], v[184:187], v[40:43]
	v_mfma_f32_16x16x32_bf16 v[32:35], v[168:171], v[194:197], v[32:35]
	v_mfma_f32_16x16x32_bf16 v[24:27], v[176:179], v[194:197], v[24:27]
	v_mfma_f32_16x16x32_bf16 v[16:19], v[168:171], v[202:205], v[16:19]
	v_mfma_f32_16x16x32_bf16 v[8:11], v[176:179], v[202:205], v[8:11]
	v_mfma_f32_16x16x32_bf16 v[4:7], v[168:171], v[210:213], v[4:7]
	v_mfma_f32_16x16x32_bf16 v[0:3], v[176:179], v[210:213], v[0:3]
	v_mfma_f32_16x16x32_bf16 v[48:51], v[172:175], v[190:193], v[48:51]
	v_mfma_f32_16x16x32_bf16 v[40:43], v[180:183], v[190:193], v[40:43]
	v_mfma_f32_16x16x32_bf16 v[32:35], v[172:175], v[198:201], v[32:35]
	v_mfma_f32_16x16x32_bf16 v[24:27], v[180:183], v[198:201], v[24:27]
	v_mfma_f32_16x16x32_bf16 v[16:19], v[172:175], v[206:209], v[16:19]
	v_mfma_f32_16x16x32_bf16 v[8:11], v[180:183], v[206:209], v[8:11]
	v_mfma_f32_16x16x32_bf16 v[4:7], v[172:175], v[214:217], v[4:7]
	v_mfma_f32_16x16x32_bf16 v[0:3], v[180:183], v[214:217], v[0:3]
	s_setprio 0
	s_barrier
	s_add_i32 s33, 0, 0x18000
	s_add_i32 s60, 0, 0x1c000
	v_add_u32_e32 v164, s33, v147
	v_add_u32_e32 v180, s60, v147
	ds_read_b128 v[152:155], v164
	ds_read_b128 v[156:159], v164 offset:1024
	ds_read_b128 v[160:163], v164 offset:2048
	ds_read_b128 v[164:167], v164 offset:3072
	ds_read_b128 v[168:171], v180
	ds_read_b128 v[172:175], v180 offset:1024
	ds_read_b128 v[176:179], v180 offset:2048
	ds_read_b128 v[180:183], v180 offset:3072
	s_add_u32 s28, s40, 0x4000
	s_addc_u32 s29, s41, 0
	s_mov_b32 m0, s42
	v_lshl_add_u64 v[224:225], s[28:29], 0, v[128:129]
	ds_read_b128 v[184:187], v151 offset:32768
	ds_read_b128 v[190:193], v151 offset:33792
	ds_read_b128 v[194:197], v151 offset:34816
	ds_read_b128 v[198:201], v151 offset:35840
	ds_read_b128 v[202:205], v151 offset:36864
	ds_read_b128 v[206:209], v151 offset:37888
	ds_read_b128 v[210:213], v151 offset:38912
	ds_read_b128 v[214:217], v151 offset:39936
	global_load_lds_dwordx4 v[224:225], off
	v_lshl_add_u64 v[224:225], s[28:29], 0, v[132:133]
	s_mov_b32 m0, s43
	s_nop 0
	global_load_lds_dwordx4 v[224:225], off
	s_waitcnt vmcnt(8)
	s_waitcnt lgkmcnt(0)
	s_nop 0
	s_barrier
	s_setprio 1
	s_waitcnt lgkmcnt(0)
	v_mfma_f32_16x16x32_bf16 v[124:127], v[152:155], v[184:187], v[124:127]
	v_mfma_f32_16x16x32_bf16 v[120:123], v[160:163], v[184:187], v[120:123]
	v_mfma_f32_16x16x32_bf16 v[116:119], v[152:155], v[194:197], v[116:119]
	v_mfma_f32_16x16x32_bf16 v[108:111], v[160:163], v[194:197], v[108:111]
	v_mfma_f32_16x16x32_bf16 v[100:103], v[152:155], v[202:205], v[100:103]
	v_mfma_f32_16x16x32_bf16 v[92:95], v[160:163], v[202:205], v[92:95]
	v_mfma_f32_16x16x32_bf16 v[84:87], v[152:155], v[210:213], v[84:87]
	v_mfma_f32_16x16x32_bf16 v[76:79], v[160:163], v[210:213], v[76:79]
	v_mfma_f32_16x16x32_bf16 v[124:127], v[156:159], v[190:193], v[124:127]
	v_mfma_f32_16x16x32_bf16 v[120:123], v[164:167], v[190:193], v[120:123]
	v_mfma_f32_16x16x32_bf16 v[116:119], v[156:159], v[198:201], v[116:119]
	v_mfma_f32_16x16x32_bf16 v[108:111], v[164:167], v[198:201], v[108:111]
	v_mfma_f32_16x16x32_bf16 v[100:103], v[156:159], v[206:209], v[100:103]
	v_mfma_f32_16x16x32_bf16 v[92:95], v[164:167], v[206:209], v[92:95]
	v_mfma_f32_16x16x32_bf16 v[84:87], v[156:159], v[214:217], v[84:87]
	v_mfma_f32_16x16x32_bf16 v[76:79], v[164:167], v[214:217], v[76:79]
	s_setprio 0
	s_setprio 1
	v_mfma_f32_16x16x32_bf16 v[112:115], v[168:171], v[184:187], v[112:115]
	v_mfma_f32_16x16x32_bf16 v[104:107], v[176:179], v[184:187], v[104:107]
	v_mfma_f32_16x16x32_bf16 v[96:99], v[168:171], v[194:197], v[96:99]
	v_mfma_f32_16x16x32_bf16 v[88:91], v[176:179], v[194:197], v[88:91]
	v_mfma_f32_16x16x32_bf16 v[80:83], v[168:171], v[202:205], v[80:83]
	v_mfma_f32_16x16x32_bf16 v[72:75], v[176:179], v[202:205], v[72:75]
	v_mfma_f32_16x16x32_bf16 v[68:71], v[168:171], v[210:213], v[68:71]
	v_mfma_f32_16x16x32_bf16 v[64:67], v[176:179], v[210:213], v[64:67]
	v_mfma_f32_16x16x32_bf16 v[112:115], v[172:175], v[190:193], v[112:115]
	v_mfma_f32_16x16x32_bf16 v[104:107], v[180:183], v[190:193], v[104:107]
	v_mfma_f32_16x16x32_bf16 v[96:99], v[172:175], v[198:201], v[96:99]
	v_mfma_f32_16x16x32_bf16 v[88:91], v[180:183], v[198:201], v[88:91]
	v_mfma_f32_16x16x32_bf16 v[80:83], v[172:175], v[206:209], v[80:83]
	v_mfma_f32_16x16x32_bf16 v[72:75], v[180:183], v[206:209], v[72:75]
	v_mfma_f32_16x16x32_bf16 v[68:71], v[172:175], v[214:217], v[68:71]
	v_mfma_f32_16x16x32_bf16 v[64:67], v[180:183], v[214:217], v[64:67]
	s_setprio 0
	s_barrier
	s_add_i32 s28, s33, s13
	v_lshl_add_u64 v[144:145], v[144:145], 0, s[8:9]
	s_mov_b32 m0, s28
	ds_read_b128 v[184:187], v151 offset:49152
	ds_read_b128 v[190:193], v151 offset:50176
	ds_read_b128 v[194:197], v151 offset:51200
	ds_read_b128 v[198:201], v151 offset:52224
	ds_read_b128 v[202:205], v151 offset:53248
	ds_read_b128 v[206:209], v151 offset:54272
	ds_read_b128 v[210:213], v151 offset:55296
	ds_read_b128 v[214:217], v151 offset:56320
	global_load_lds_dwordx4 v[144:145], off
	s_add_i32 m0, s28, 0x2000
	s_add_u32 s28, s38, 0xb0080
	v_lshl_add_u64 v[144:145], v[218:219], 0, s[8:9]
	s_addc_u32 s29, s39, 0
	s_add_i32 s33, s60, s13
	global_load_lds_dwordx4 v[144:145], off
	v_lshl_add_u64 v[144:145], s[28:29], 0, v[130:131]
	s_mov_b32 m0, s33
	s_nop 0
	global_load_lds_dwordx4 v[144:145], off
	v_lshl_add_u64 v[144:145], s[28:29], 0, v[134:135]
	s_add_i32 m0, s33, 0x2000
	s_nop 0
	global_load_lds_dwordx4 v[144:145], off
	v_lshl_add_u64 v[144:145], v[220:221], 0, s[92:93]
	s_mov_b32 m0, s45
	s_nop 0
	global_load_lds_dwordx4 v[144:145], off
	v_lshl_add_u64 v[144:145], v[222:223], 0, s[92:93]
	s_mov_b32 m0, s46
	s_nop 0
	global_load_lds_dwordx4 v[144:145], off
	s_waitcnt vmcnt(8)
	s_waitcnt lgkmcnt(0)
	s_barrier
	s_setprio 1
	s_waitcnt lgkmcnt(0)
	v_mfma_f32_16x16x32_bf16 v[60:63], v[152:155], v[184:187], v[60:63]
	v_mfma_f32_16x16x32_bf16 v[56:59], v[160:163], v[184:187], v[56:59]
	v_mfma_f32_16x16x32_bf16 v[52:55], v[152:155], v[194:197], v[52:55]
	v_mfma_f32_16x16x32_bf16 v[44:47], v[160:163], v[194:197], v[44:47]
	v_mfma_f32_16x16x32_bf16 v[36:39], v[152:155], v[202:205], v[36:39]
	v_mfma_f32_16x16x32_bf16 v[28:31], v[160:163], v[202:205], v[28:31]
	v_mfma_f32_16x16x32_bf16 v[20:23], v[152:155], v[210:213], v[20:23]
	v_mfma_f32_16x16x32_bf16 v[12:15], v[160:163], v[210:213], v[12:15]
	v_mfma_f32_16x16x32_bf16 v[60:63], v[156:159], v[190:193], v[60:63]
	v_mfma_f32_16x16x32_bf16 v[56:59], v[164:167], v[190:193], v[56:59]
	v_mfma_f32_16x16x32_bf16 v[52:55], v[156:159], v[198:201], v[52:55]
	v_mfma_f32_16x16x32_bf16 v[44:47], v[164:167], v[198:201], v[44:47]
	v_mfma_f32_16x16x32_bf16 v[36:39], v[156:159], v[206:209], v[36:39]
	v_mfma_f32_16x16x32_bf16 v[28:31], v[164:167], v[206:209], v[28:31]
	v_mfma_f32_16x16x32_bf16 v[20:23], v[156:159], v[214:217], v[20:23]
	v_mfma_f32_16x16x32_bf16 v[12:15], v[164:167], v[214:217], v[12:15]
	s_setprio 0
	s_setprio 1
	v_mfma_f32_16x16x32_bf16 v[48:51], v[168:171], v[184:187], v[48:51]
	v_mfma_f32_16x16x32_bf16 v[40:43], v[176:179], v[184:187], v[40:43]
	v_mfma_f32_16x16x32_bf16 v[32:35], v[168:171], v[194:197], v[32:35]
	v_mfma_f32_16x16x32_bf16 v[24:27], v[176:179], v[194:197], v[24:27]
	v_mfma_f32_16x16x32_bf16 v[16:19], v[168:171], v[202:205], v[16:19]
	v_mfma_f32_16x16x32_bf16 v[8:11], v[176:179], v[202:205], v[8:11]
	v_mfma_f32_16x16x32_bf16 v[4:7], v[168:171], v[210:213], v[4:7]
	v_mfma_f32_16x16x32_bf16 v[0:3], v[176:179], v[210:213], v[0:3]
	v_mfma_f32_16x16x32_bf16 v[48:51], v[172:175], v[190:193], v[48:51]
	v_mfma_f32_16x16x32_bf16 v[40:43], v[180:183], v[190:193], v[40:43]
	v_mfma_f32_16x16x32_bf16 v[32:35], v[172:175], v[198:201], v[32:35]
	v_mfma_f32_16x16x32_bf16 v[24:27], v[180:183], v[198:201], v[24:27]
	v_mfma_f32_16x16x32_bf16 v[16:19], v[172:175], v[206:209], v[16:19]
	v_mfma_f32_16x16x32_bf16 v[8:11], v[180:183], v[206:209], v[8:11]
	v_mfma_f32_16x16x32_bf16 v[4:7], v[172:175], v[214:217], v[4:7]
	v_mfma_f32_16x16x32_bf16 v[0:3], v[180:183], v[214:217], v[0:3]
	s_setprio 0
	s_barrier
	s_add_i32 s59, s59, 2
	s_add_u32 s57, s57, 0x100
	s_addc_u32 s58, s58, 0
	s_cmp_gt_u32 s59, 41
	s_mov_b64 s[28:29], s[36:37]
	s_cbranch_scc0 .LBB0_1388
	s_and_b64 vcc, exec, s[10:11]
	s_cbranch_vccz .LBB0_1391
	s_barrier

.LBB0_1427:
	s_andn2_saveexec_b64 s[4:5], s[4:5]
	s_cbranch_execz .LBB0_1447
	s_mov_b64 s[4:5], exec
	s_cmp_lg_u32 s98, 0
	s_cbranch_scc1 .LBB0_1444
	buffer_wbl2 sc1
	s_waitcnt lgkmcnt(0)
	s_waitcnt vmcnt(0)
	v_mbcnt_lo_u32_b32 v1, s4, 0
	v_mbcnt_hi_u32_b32 v1, s5, v1
	v_cmp_eq_u32_e32 vcc, 0, v1
	s_and_saveexec_b64 s[6:7], vcc
	s_cbranch_execz .LBB0_1430
	s_bcnt1_i32_b64 s4, s[4:5]
	v_mov_b32_e32 v2, 0x5c3000
	v_mov_b32_e32 v3, s4
	global_atomic_add v2, v2, v3, s[72:73] offset:1024 sc0

	.amdhsa_kernel _Z8mega_fwd4Args
		.amdhsa_group_segment_fixed_size 0
		.amdhsa_private_segment_fixed_size 0
		.amdhsa_kernarg_size 504
		.amdhsa_user_sgpr_count 2
		.amdhsa_user_sgpr_dispatch_ptr 0
		.amdhsa_user_sgpr_queue_ptr 0
		.amdhsa_user_sgpr_kernarg_segment_ptr 1
		.amdhsa_user_sgpr_dispatch_id 0
		.amdhsa_user_sgpr_kernarg_preload_length 0
		.amdhsa_user_sgpr_kernarg_preload_offset 0
		.amdhsa_user_sgpr_private_segment_size 0
		.amdhsa_uses_dynamic_stack 0
		.amdhsa_enable_private_segment 0
		.amdhsa_system_sgpr_workgroup_id_x 1
		.amdhsa_system_sgpr_workgroup_id_y 0
		.amdhsa_system_sgpr_workgroup_id_z 0
		.amdhsa_system_sgpr_workgroup_info 0
		.amdhsa_system_vgpr_workitem_id 2
		.amdhsa_next_free_vgpr 243
		.amdhsa_next_free_sgpr 100
		.amdhsa_accum_offset 244
		.amdhsa_reserve_vcc 1
		.amdhsa_float_round_mode_32 0
		.amdhsa_float_round_mode_16_64 0
		.amdhsa_float_denorm_mode_32 3
		.amdhsa_float_denorm_mode_16_64 3
		.amdhsa_dx10_clamp 1
		.amdhsa_ieee_mode 1
		.amdhsa_fp16_overflow 0
		.amdhsa_tg_split 0
		.amdhsa_exception_fp_ieee_invalid_op 0
		.amdhsa_exception_fp_denorm_src 0
		.amdhsa_exception_fp_ieee_div_zero 0
		.amdhsa_exception_fp_ieee_overflow 0
		.amdhsa_exception_fp_ieee_underflow 0
		.amdhsa_exception_fp_ieee_inexact 0
		.amdhsa_exception_int_div_zero 0
	.end_amdhsa_kernel

amdhsa.kernels:
  - .agpr_count:     0
    .args:
      - .offset:         0
        .size:           248
        .value_kind:     by_value
      - .offset:         248
        .size:           4
        .value_kind:     hidden_block_count_x
      - .offset:         252
        .size:           4
        .value_kind:     hidden_block_count_y
      - .offset:         256
        .size:           4
        .value_kind:     hidden_block_count_z
      - .offset:         260
        .size:           2
        .value_kind:     hidden_group_size_x
      - .offset:         262
        .size:           2
        .value_kind:     hidden_group_size_y
      - .offset:         264
        .size:           2
        .value_kind:     hidden_group_size_z
      - .offset:         266
        .size:           2
        .value_kind:     hidden_remainder_x
      - .offset:         268
        .size:           2
        .value_kind:     hidden_remainder_y
      - .offset:         270
        .size:           2
        .value_kind:     hidden_remainder_z
      - .offset:         288
        .size:           8
        .value_kind:     hidden_global_offset_x
      - .offset:         296
        .size:           8
        .value_kind:     hidden_global_offset_y
      - .offset:         304
        .size:           8
        .value_kind:     hidden_global_offset_z
      - .offset:         312
        .size:           2
        .value_kind:     hidden_grid_dims
      - .offset:         336
        .size:           8
        .value_kind:     hidden_multigrid_sync_arg
      - .offset:         368
        .size:           4
        .value_kind:     hidden_dynamic_lds_size
    .group_segment_fixed_size: 0
    .kernarg_segment_align: 8
    .kernarg_segment_size: 504
    .language:       OpenCL C
    .language_version:
      - 2
      - 0
    .max_flat_workgroup_size: 512
    .name:           _Z8mega_fwd4Args
    .private_segment_fixed_size: 0
    .sgpr_count:     106
    .sgpr_spill_count: 59
    .symbol:         _Z8mega_fwd4Args.kd
    .uniform_work_group_size: 1
    .uses_dynamic_stack: false
    .vgpr_count:     243
    .vgpr_spill_count: 0
    .wavefront_size: 64
